# rg gates: bias pre-scaled by -log2e so the sigmoid argument is one v_pk_fma_f32 (was pk_add + pk_mul); gelu tanh argument scale as one pk_mul by -2*log2e*sqrt(2/pi)
# speedup vs baseline: 1.0060x; 1.0060x over previous
; #define LAS __attribute__((address_space(3)))
; template <bool FINAL>
; __device__ __forceinline__ void rg_item(PREF p, int l, int item, LAS unsigned char* wl, int lane) {
;     const bf16_t* __restrict__ P = (const bf16_t*)(p.ws + WS_GP);
;     const int h = item & 7, rest = item >> 3;
;     const int ci = rest < 512 ? 4 + (rest & 255) : ((rest - 512) & 3), b = rest < 512 ? (rest >> 8) : ((rest - 512) >> 2);
;     const int seq_row0 = ci < 4 ? TL + b * 256 : b * 16384;
;     const int t0 = ci < 4 ? ci * 64 : (ci - 4) * 64;
;     const int seqlen = ci < 4 ? 256 : 16384;
;     const int ch = h * 64 + lane;
;     LAS bf16_t* sXc = (LAS bf16_t*)wl;
;     LAS float* stg = (LAS float*)(wl + 9216);
;     {
;         const float cw0 = p.conv_w[(l * 4 + 0) * 512 + ch], cw1 = p.conv_w[(l * 4 + 1) * 512 + ch], cw2 = p.conv_w[(l * 4 + 2) * 512 + ch], cw3 = p.conv_w[(l * 4 + 3) * 512 + ch];
;         const float cb = p.conv_b[l * 512 + ch];
;         float xv[67]; unsigned xr_[67];
; #pragma unroll
;         for (int i = 0; i < 67; ++i) { const int t = t0 - 2 + i; const int tc = t < 0 ? 0 : (t >= seqlen ? seqlen - 1 : t);
;             xr_[i] = P[(size_t)(seq_row0 + tc) * PW + ch]; }
.Lrg7_dec:
	s_add_i32 s15, s11, s10
	s_mul_i32 s36, s9, 0x104
	s_add_i32 s36, s36, s8
	s_lshl_b32 s36, s36, 12
	s_cmp_eq_u32 s10, 0
	s_cselect_b32 s37, 0, -1
	s_add_i32 s38, s10, 64
	s_cmp_eq_u32 s38, s14
	s_cselect_b32 s38, 0, -1
	s_bfe_u32 s44, s44, 0x30006
	s_mul_i32 s44, s44, 0x4800
	v_lshl_or_b32 v234, s7, 6, v233
	v_lshlrev_b32_e32 v235, 2, v234
	v_lshlrev_b32_e32 v234, 1, v234
	v_and_b32_e32 v236, 15, v233
	v_lshrrev_b32_e32 v241, 4, v233
	s_movk_i32 s39, 0x90
	v_mul_u32_u24_e32 v237, 0x90, v236
	v_lshl_add_u32 v237, v241, 4, v237
	v_lshlrev_b32_e32 v238, 7, v236
	v_lshl_add_u32 v238, v241, 4, v238
	v_lshlrev_b32_e32 v239, 10, v241
	v_lshl_add_u32 v239, v236, 2, v239
	v_mov_b32_e32 v241, v238
	v_add_u32_e32 v236, s44, v237
	s_add_i32 s39, s44, 0x2400
	v_add_u32_e32 v237, s39, v239
	v_add_u32_e32 v238, 0x1000, v237
	v_lshl_add_u32 v239, v233, 2, s44
	v_lshl_add_u32 v240, v233, 1, s44
	s_add_i32 s39, s15, -2
	s_mul_hi_i32 s83, s39, 0x1600
	s_mul_i32 s82, s39, 0x1600
	s_waitcnt lgkmcnt(0)
	s_add_u32 s82, s82, s0
	s_addc_u32 s83, s83, s1
	s_add_u32 s82, s82, 0xbc00000
	s_addc_u32 s83, s83, 0
	global_load_ushort v158, v234, s[82:83]
	s_add_u32 s82, s82, 0x1600
	s_addc_u32 s83, s83, 0
	global_load_ushort v159, v234, s[82:83]
	s_add_u32 s82, s82, 0x1600
	s_addc_u32 s83, s83, 0
	global_load_ushort v160, v234, s[82:83]
	s_add_u32 s82, s82, 0x1600
	s_addc_u32 s83, s83, 0
	global_load_ushort v161, v234, s[82:83]
	s_add_u32 s82, s82, 0x1600
	s_addc_u32 s83, s83, 0
	global_load_ushort v162, v234, s[82:83]
	s_add_u32 s82, s82, 0x1600
	s_addc_u32 s83, s83, 0
	global_load_ushort v163, v234, s[82:83]
	s_add_u32 s82, s82, 0x1600
	s_addc_u32 s83, s83, 0
	global_load_ushort v164, v234, s[82:83]
	s_add_u32 s82, s82, 0x1600
	s_addc_u32 s83, s83, 0
	global_load_ushort v165, v234, s[82:83]
	s_add_u32 s82, s82, 0x1600
	s_addc_u32 s83, s83, 0
	global_load_ushort v166, v234, s[82:83]
	s_add_u32 s82, s82, 0x1600
	s_addc_u32 s83, s83, 0
	global_load_ushort v167, v234, s[82:83]
	s_add_u32 s82, s82, 0x1600
	s_addc_u32 s83, s83, 0
	global_load_ushort v168, v234, s[82:83]
	s_add_u32 s82, s82, 0x1600
	s_addc_u32 s83, s83, 0
	global_load_ushort v169, v234, s[82:83]
	s_add_u32 s82, s82, 0x1600
	s_addc_u32 s83, s83, 0
	global_load_ushort v170, v234, s[82:83]
	s_add_u32 s82, s82, 0x1600
	s_addc_u32 s83, s83, 0
	global_load_ushort v171, v234, s[82:83]
	s_add_u32 s82, s82, 0x1600
	s_addc_u32 s83, s83, 0
	global_load_ushort v172, v234, s[82:83]
	s_add_u32 s82, s82, 0x1600
	s_addc_u32 s83, s83, 0
	global_load_ushort v173, v234, s[82:83]
	s_add_u32 s82, s82, 0x1600
	s_addc_u32 s83, s83, 0
	global_load_ushort v174, v234, s[82:83]
	s_add_u32 s82, s82, 0x1600
	s_addc_u32 s83, s83, 0
	global_load_ushort v175, v234, s[82:83]
	s_add_u32 s82, s82, 0x1600
	s_addc_u32 s83, s83, 0
	global_load_ushort v176, v234, s[82:83]
	s_add_u32 s82, s82, 0x1600
	s_addc_u32 s83, s83, 0
	global_load_ushort v177, v234, s[82:83]
	s_add_u32 s82, s82, 0x1600
	s_addc_u32 s83, s83, 0
	global_load_ushort v178, v234, s[82:83]
	s_add_u32 s82, s82, 0x1600
	s_addc_u32 s83, s83, 0
	global_load_ushort v179, v234, s[82:83]
	s_add_u32 s82, s82, 0x1600
	s_addc_u32 s83, s83, 0
	global_load_ushort v180, v234, s[82:83]
	s_add_u32 s82, s82, 0x1600
	s_addc_u32 s83, s83, 0
	global_load_ushort v181, v234, s[82:83]
	s_add_u32 s82, s82, 0x1600
	s_addc_u32 s83, s83, 0
	global_load_ushort v182, v234, s[82:83]
	s_add_u32 s82, s82, 0x1600
	s_addc_u32 s83, s83, 0
	global_load_ushort v183, v234, s[82:83]
	s_add_u32 s82, s82, 0x1600
	s_addc_u32 s83, s83, 0
	global_load_ushort v184, v234, s[82:83]
	s_add_u32 s82, s82, 0x1600
	s_addc_u32 s83, s83, 0
	global_load_ushort v185, v234, s[82:83]
	s_add_u32 s82, s82, 0x1600
	s_addc_u32 s83, s83, 0
	global_load_ushort v186, v234, s[82:83]
	s_add_u32 s82, s82, 0x1600
	s_addc_u32 s83, s83, 0
	global_load_ushort v187, v234, s[82:83]
	s_add_u32 s82, s82, 0x1600
	s_addc_u32 s83, s83, 0
	global_load_ushort v188, v234, s[82:83]
	s_add_u32 s82, s82, 0x1600
	s_addc_u32 s83, s83, 0
	global_load_ushort v189, v234, s[82:83]
	s_add_u32 s82, s82, 0x1600
	s_addc_u32 s83, s83, 0
	global_load_ushort v190, v234, s[82:83]
	s_add_u32 s82, s82, 0x1600
	s_addc_u32 s83, s83, 0
	global_load_ushort v191, v234, s[82:83]
	s_add_u32 s82, s82, 0x1600
	s_addc_u32 s83, s83, 0
	global_load_ushort v192, v234, s[82:83]
	s_add_u32 s82, s82, 0x1600
	s_addc_u32 s83, s83, 0
	global_load_ushort v193, v234, s[82:83]
	s_add_u32 s82, s82, 0x1600
	s_addc_u32 s83, s83, 0
	global_load_ushort v194, v234, s[82:83]
	s_add_u32 s82, s82, 0x1600
	s_addc_u32 s83, s83, 0
	global_load_ushort v195, v234, s[82:83]
	s_add_u32 s82, s82, 0x1600
	s_addc_u32 s83, s83, 0
	global_load_ushort v196, v234, s[82:83]
	s_add_u32 s82, s82, 0x1600
	s_addc_u32 s83, s83, 0
	global_load_ushort v197, v234, s[82:83]
	s_add_u32 s82, s82, 0x1600
	s_addc_u32 s83, s83, 0
	global_load_ushort v198, v234, s[82:83]
	s_add_u32 s82, s82, 0x1600
	s_addc_u32 s83, s83, 0
	global_load_ushort v199, v234, s[82:83]
	s_add_u32 s82, s82, 0x1600
	s_addc_u32 s83, s83, 0
	global_load_ushort v200, v234, s[82:83]
	s_add_u32 s82, s82, 0x1600
	s_addc_u32 s83, s83, 0
	global_load_ushort v201, v234, s[82:83]
	s_add_u32 s82, s82, 0x1600
	s_addc_u32 s83, s83, 0
	global_load_ushort v202, v234, s[82:83]
	s_add_u32 s82, s82, 0x1600
	s_addc_u32 s83, s83, 0
	global_load_ushort v203, v234, s[82:83]
	s_add_u32 s82, s82, 0x1600
	s_addc_u32 s83, s83, 0
	global_load_ushort v204, v234, s[82:83]
	s_add_u32 s82, s82, 0x1600
	s_addc_u32 s83, s83, 0
	global_load_ushort v205, v234, s[82:83]
	s_add_u32 s82, s82, 0x1600
	s_addc_u32 s83, s83, 0
	global_load_ushort v206, v234, s[82:83]
	s_add_u32 s82, s82, 0x1600
; __device__ __forceinline__ float rcpf_(float x) { return __builtin_amdgcn_rcpf(x); }
; template <bool FINAL, int D>
; __device__ __forceinline__ void rg_dir(PREF p, int l, int h, int ch, int sidx, int rowbase  , LAS bf16_t* sXc, LAS float* stg, int lane) {
;     ...
;     const float ba = p.rg_ba[(l * 2 + D) * 512 + ch], bi = p.rg_bi[(l * 2 + D) * 512 + ch], lam = p.rg_lam[(l * 2 + D) * 512 + ch];
;     const float e_ = __expf(-lam), u_ = 1.f + e_;
;     const float l1p = (u_ == 1.f) ? e_ : __logf(u_) * e_ * rcpf_(u_ - 1.f);
;     const float sp8 = -8.f * 1.4426950408889634f * l1p;
;     float hc = FINAL ? RGC[sidx] : 0.f, Ap = 1.f;
;     bf16x8 Br[4][2], Bi[4][2];
; #pragma unroll
;     for (int nt = 0; nt < 4; ++nt) { const int o0 = (nt * 16 + (lane & 15)) * 64 + (lane >> 4) * 8;
;         Br[nt][0] = *(const bf16x8*)(wr_ + o0); Br[nt][1] = *(const bf16x8*)(wr_ + o0 + 32); Bi[nt][0] = *(const bf16x8*)(wi_ + o0); Bi[nt][1] = *(const bf16x8*)(wi_ + o0 + 32); }
; template <bool FINAL>
; __device__ __forceinline__ void rg_item(PREF p, int l, int item, LAS unsigned char* wl, int lane) {
;     ...
;         const float cw0 = p.conv_w[(l * 4 + 0) * 512 + ch], cw1 = p.conv_w[(l * 4 + 1) * 512 + ch], cw2 = p.conv_w[(l * 4 + 2) * 512 + ch], cw3 = p.conv_w[(l * 4 + 3) * 512 + ch];
;         const float cb = p.conv_b[l * 512 + ch];
;         float xv[67]; unsigned xr_[67];
; #pragma unroll
;         for (int i = 0; i < 67; ++i) { const int t = t0 - 2 + i; const int tc = t < 0 ? 0 : (t >= seqlen ? seqlen - 1 : t);
;             xr_[i] = P[(size_t)(seq_row0 + tc) * PW + ch]; }
;         __builtin_amdgcn_sched_barrier(0);
; #pragma unroll
;         for (int i = 0; i < 67; ++i) { const int t = t0 - 2 + i; const int tc = t < 0 ? 0 : (t >= seqlen ? seqlen - 1 : t); xv[i] = (t == tc) ? bf2f(xr_[i]) : 0.f; }
	s_addc_u32 s83, s83, 0
	global_load_ushort v207, v234, s[82:83]
	s_add_u32 s82, s82, 0x1600
	s_addc_u32 s83, s83, 0
	global_load_ushort v208, v234, s[82:83]
	s_add_u32 s82, s82, 0x1600
	s_addc_u32 s83, s83, 0
	global_load_ushort v209, v234, s[82:83]
	s_add_u32 s82, s82, 0x1600
	s_addc_u32 s83, s83, 0
	global_load_ushort v210, v234, s[82:83]
	s_add_u32 s82, s82, 0x1600
	s_addc_u32 s83, s83, 0
	global_load_ushort v211, v234, s[82:83]
	s_add_u32 s82, s82, 0x1600
	s_addc_u32 s83, s83, 0
	global_load_ushort v212, v234, s[82:83]
	s_add_u32 s82, s82, 0x1600
	s_addc_u32 s83, s83, 0
	global_load_ushort v213, v234, s[82:83]
	s_add_u32 s82, s82, 0x1600
	s_addc_u32 s83, s83, 0
	global_load_ushort v214, v234, s[82:83]
	s_add_u32 s82, s82, 0x1600
	s_addc_u32 s83, s83, 0
	global_load_ushort v215, v234, s[82:83]
	s_add_u32 s82, s82, 0x1600
	s_addc_u32 s83, s83, 0
	global_load_ushort v216, v234, s[82:83]
	s_add_u32 s82, s82, 0x1600
	s_addc_u32 s83, s83, 0
	global_load_ushort v217, v234, s[82:83]
	s_add_u32 s82, s82, 0x1600
	s_addc_u32 s83, s83, 0
	global_load_ushort v218, v234, s[82:83]
	s_add_u32 s82, s82, 0x1600
	s_addc_u32 s83, s83, 0
	global_load_ushort v219, v234, s[82:83]
	s_add_u32 s82, s82, 0x1600
	s_addc_u32 s83, s83, 0
	global_load_ushort v222, v234, s[82:83]
	s_add_u32 s82, s82, 0x1600
	s_addc_u32 s83, s83, 0
	global_load_ushort v223, v234, s[82:83]
	s_add_u32 s82, s82, 0x1600
	s_addc_u32 s83, s83, 0
	global_load_ushort v140, v234, s[82:83]
	s_add_u32 s82, s82, 0x1600
	s_addc_u32 s83, s83, 0
	global_load_ushort v141, v234, s[82:83]
	s_add_u32 s82, s82, 0x1600
	s_addc_u32 s83, s83, 0
	global_load_ushort v232, v234, s[82:83]
	s_lshl_b32 s39, s47, 13
	s_add_u32 s72, s72, s39
	s_addc_u32 s73, s73, 0
	global_load_dword v40, v235, s[72:73]
	global_load_dword v41, v235, s[72:73] offset:2048
	s_add_u32 s72, s72, 0x1000
	s_addc_u32 s73, s73, 0
	global_load_dword v42, v235, s[72:73]
	global_load_dword v43, v235, s[72:73] offset:2048
	s_lshl_b32 s39, s47, 11
	s_add_u32 s74, s74, s39
	s_addc_u32 s75, s75, 0
	global_load_dword v44, v235, s[74:75]
	s_lshl_b32 s39, s47, 12
	s_add_u32 s76, s76, s39
	s_addc_u32 s77, s77, 0
	s_add_u32 s78, s78, s39
	s_addc_u32 s79, s79, 0
	s_add_u32 s80, s80, s39
	s_addc_u32 s81, s81, 0
	s_add_u32 s96, s0, 0xa00000
	s_addc_u32 s97, s1, 0
	s_add_u32 s96, s96, s36
	s_addc_u32 s97, s97, 0
	s_lshl_b32 s39, s47, 5
	s_add_i32 s39, s39, s7
	s_lshl_b32 s39, s39, 13
	s_add_u32 s92, s0, 0x300000
	s_addc_u32 s93, s1, 0
	s_add_u32 s92, s92, s39
	s_addc_u32 s93, s93, 0
	global_load_dword v45, v235, s[76:77]
	global_load_dword v46, v235, s[78:79]
	global_load_dword v47, v235, s[80:81]
	global_load_dword v250, v235, s[96:97]
	s_add_u32 s90, s92, 0x0
	s_addc_u32 s91, s93, 0
	global_load_dwordx4 v[80:83], v241, s[90:91]
	global_load_dwordx4 v[84:87], v241, s[90:91] offset:64
	global_load_dwordx4 v[88:91], v241, s[90:91] offset:2048
	global_load_dwordx4 v[92:95], v241, s[90:91] offset:2112
	s_add_u32 s90, s92, 0x1000
	s_addc_u32 s91, s93, 0
	global_load_dwordx4 v[96:99], v241, s[90:91]
	global_load_dwordx4 v[100:103], v241, s[90:91] offset:64
	global_load_dwordx4 v[104:107], v241, s[90:91] offset:2048
	global_load_dwordx4 v[108:111], v241, s[90:91] offset:2112
	s_add_u32 s90, s92, 0x10000
	s_addc_u32 s91, s93, 0
	global_load_dwordx4 v[112:115], v241, s[90:91]
	global_load_dwordx4 v[116:119], v241, s[90:91] offset:64
	global_load_dwordx4 v[120:123], v241, s[90:91] offset:2048
	global_load_dwordx4 v[124:127], v241, s[90:91] offset:2112
	s_add_u32 s90, s92, 0x11000
	s_addc_u32 s91, s93, 0
	global_load_dwordx4 v[128:131], v241, s[90:91]
	global_load_dwordx4 v[132:135], v241, s[90:91] offset:64
	global_load_dwordx4 v[136:139], v241, s[90:91] offset:2048
	global_load_dwordx4 v[228:231], v241, s[90:91] offset:2112
	s_waitcnt vmcnt(20)
	v_lshlrev_b32_e32 v158, 16, v158
	v_lshlrev_b32_e32 v159, 16, v159
	v_lshlrev_b32_e32 v160, 16, v160
	v_lshlrev_b32_e32 v161, 16, v161
	v_lshlrev_b32_e32 v162, 16, v162
	v_lshlrev_b32_e32 v163, 16, v163
	v_lshlrev_b32_e32 v164, 16, v164
	v_lshlrev_b32_e32 v165, 16, v165
	v_lshlrev_b32_e32 v166, 16, v166
	v_lshlrev_b32_e32 v167, 16, v167
	v_lshlrev_b32_e32 v168, 16, v168
	v_lshlrev_b32_e32 v169, 16, v169
	v_lshlrev_b32_e32 v170, 16, v170
	v_lshlrev_b32_e32 v171, 16, v171
	v_lshlrev_b32_e32 v172, 16, v172
	v_lshlrev_b32_e32 v173, 16, v173
	v_lshlrev_b32_e32 v174, 16, v174
	v_lshlrev_b32_e32 v175, 16, v175
	v_lshlrev_b32_e32 v176, 16, v176
	v_lshlrev_b32_e32 v177, 16, v177
	v_lshlrev_b32_e32 v178, 16, v178
	v_lshlrev_b32_e32 v179, 16, v179
	v_lshlrev_b32_e32 v180, 16, v180
	v_lshlrev_b32_e32 v181, 16, v181
	v_lshlrev_b32_e32 v182, 16, v182
	v_lshlrev_b32_e32 v183, 16, v183
	v_lshlrev_b32_e32 v184, 16, v184
	v_lshlrev_b32_e32 v185, 16, v185
	v_lshlrev_b32_e32 v186, 16, v186
	v_lshlrev_b32_e32 v187, 16, v187
	v_lshlrev_b32_e32 v188, 16, v188
	v_lshlrev_b32_e32 v189, 16, v189
	v_lshlrev_b32_e32 v190, 16, v190
	v_lshlrev_b32_e32 v191, 16, v191
	v_lshlrev_b32_e32 v192, 16, v192
	v_lshlrev_b32_e32 v193, 16, v193
	v_lshlrev_b32_e32 v194, 16, v194
	v_lshlrev_b32_e32 v195, 16, v195
	v_lshlrev_b32_e32 v196, 16, v196
	v_lshlrev_b32_e32 v197, 16, v197
	v_lshlrev_b32_e32 v198, 16, v198
	v_lshlrev_b32_e32 v199, 16, v199
	v_lshlrev_b32_e32 v200, 16, v200
	v_lshlrev_b32_e32 v201, 16, v201
	v_lshlrev_b32_e32 v202, 16, v202
	v_lshlrev_b32_e32 v203, 16, v203
	v_lshlrev_b32_e32 v204, 16, v204
	v_lshlrev_b32_e32 v205, 16, v205
	v_lshlrev_b32_e32 v206, 16, v206
	v_lshlrev_b32_e32 v207, 16, v207
	v_lshlrev_b32_e32 v208, 16, v208
	v_lshlrev_b32_e32 v209, 16, v209
	v_lshlrev_b32_e32 v210, 16, v210
	v_lshlrev_b32_e32 v211, 16, v211
; __device__ __forceinline__ unsigned f2bf(float f) { unsigned r; asm("v_cvt_pk_bf16_f32 %0, %1, %1" : "=v"(r) : "v"(f)); return r & 0xffffu; }
; template <bool FINAL>
; __device__ __forceinline__ void rg_item(PREF p, int l, int item, LAS unsigned char* wl, int lane) {
;     ...
;         for (int i = 0; i < 67; ++i) { const int t = t0 - 2 + i; const int tc = t < 0 ? 0 : (t >= seqlen ? seqlen - 1 : t); xv[i] = (t == tc) ? bf2f(xr_[i]) : 0.f; }
; #pragma unroll
;         for (int tt = 0; tt < 64; ++tt) { const float xc = xv[tt] * cw0 + xv[tt + 1] * cw1 + xv[tt + 2] * cw2 + xv[tt + 3] * cw3 + cb; sXc[tt * 72 + lane] = (bf16_t)f2bf(xc); }
	v_lshlrev_b32_e32 v212, 16, v212
	v_lshlrev_b32_e32 v213, 16, v213
	v_lshlrev_b32_e32 v214, 16, v214
	v_lshlrev_b32_e32 v215, 16, v215
	v_lshlrev_b32_e32 v216, 16, v216
	v_lshlrev_b32_e32 v217, 16, v217
	v_lshlrev_b32_e32 v218, 16, v218
	v_lshlrev_b32_e32 v219, 16, v219
	v_lshlrev_b32_e32 v222, 16, v222
	v_lshlrev_b32_e32 v223, 16, v223
	v_lshlrev_b32_e32 v140, 16, v140
	v_lshlrev_b32_e32 v141, 16, v141
	v_lshlrev_b32_e32 v232, 16, v232
	v_and_b32_e32 v158, s37, v158
	v_and_b32_e32 v159, s37, v159
	v_and_b32_e32 v232, s38, v232
	v_mul_f32_e32 v32, v41, v159
	v_mul_f32_e32 v33, v41, v160
	v_mul_f32_e32 v34, v41, v161
	v_mul_f32_e32 v35, v41, v162
	v_mul_f32_e32 v36, v41, v163
	v_mul_f32_e32 v37, v41, v164
	v_mul_f32_e32 v38, v41, v165
	v_mul_f32_e32 v39, v41, v166
	v_fmac_f32_e32 v32, v40, v158
	v_fmac_f32_e32 v33, v40, v159
	v_fmac_f32_e32 v34, v40, v160
	v_fmac_f32_e32 v35, v40, v161
	v_fmac_f32_e32 v36, v40, v162
	v_fmac_f32_e32 v37, v40, v163
	v_fmac_f32_e32 v38, v40, v164
	v_fmac_f32_e32 v39, v40, v165
	v_fmac_f32_e32 v32, v42, v160
	v_fmac_f32_e32 v33, v42, v161
	v_fmac_f32_e32 v34, v42, v162
	v_fmac_f32_e32 v35, v42, v163
	v_fmac_f32_e32 v36, v42, v164
	v_fmac_f32_e32 v37, v42, v165
	v_fmac_f32_e32 v38, v42, v166
	v_fmac_f32_e32 v39, v42, v167
	v_fmac_f32_e32 v32, v43, v161
	v_fmac_f32_e32 v33, v43, v162
	v_fmac_f32_e32 v34, v43, v163
	v_fmac_f32_e32 v35, v43, v164
	v_fmac_f32_e32 v36, v43, v165
	v_fmac_f32_e32 v37, v43, v166
	v_fmac_f32_e32 v38, v43, v167
	v_fmac_f32_e32 v39, v43, v168
	v_add_f32_e32 v32, v44, v32
	v_add_f32_e32 v33, v44, v33
	v_add_f32_e32 v34, v44, v34
	v_add_f32_e32 v35, v44, v35
	v_add_f32_e32 v36, v44, v36
	v_add_f32_e32 v37, v44, v37
	v_add_f32_e32 v38, v44, v38
	v_add_f32_e32 v39, v44, v39
	v_cvt_pk_bf16_f32 v32, v32, v33
	v_cvt_pk_bf16_f32 v34, v34, v35
	v_cvt_pk_bf16_f32 v36, v36, v37
	v_cvt_pk_bf16_f32 v38, v38, v39
	ds_write_b16 v240, v32 offset:0
	ds_write_b16_d16_hi v240, v32 offset:144
	ds_write_b16 v240, v34 offset:288
	ds_write_b16_d16_hi v240, v34 offset:432
	ds_write_b16 v240, v36 offset:576
	ds_write_b16_d16_hi v240, v36 offset:720
	ds_write_b16 v240, v38 offset:864
	ds_write_b16_d16_hi v240, v38 offset:1008
	v_mul_f32_e32 v32, v41, v167
	v_mul_f32_e32 v33, v41, v168
	v_mul_f32_e32 v34, v41, v169
	v_mul_f32_e32 v35, v41, v170
	v_mul_f32_e32 v36, v41, v171
	v_mul_f32_e32 v37, v41, v172
	v_mul_f32_e32 v38, v41, v173
	v_mul_f32_e32 v39, v41, v174
	v_fmac_f32_e32 v32, v40, v166
	v_fmac_f32_e32 v33, v40, v167
	v_fmac_f32_e32 v34, v40, v168
	v_fmac_f32_e32 v35, v40, v169
	v_fmac_f32_e32 v36, v40, v170
	v_fmac_f32_e32 v37, v40, v171
	v_fmac_f32_e32 v38, v40, v172
	v_fmac_f32_e32 v39, v40, v173
	v_fmac_f32_e32 v32, v42, v168
	v_fmac_f32_e32 v33, v42, v169
	v_fmac_f32_e32 v34, v42, v170
	v_fmac_f32_e32 v35, v42, v171
	v_fmac_f32_e32 v36, v42, v172
	v_fmac_f32_e32 v37, v42, v173
	v_fmac_f32_e32 v38, v42, v174
	v_fmac_f32_e32 v39, v42, v175
	v_fmac_f32_e32 v32, v43, v169
	v_fmac_f32_e32 v33, v43, v170
	v_fmac_f32_e32 v34, v43, v171
	v_fmac_f32_e32 v35, v43, v172
	v_fmac_f32_e32 v36, v43, v173
	v_fmac_f32_e32 v37, v43, v174
	v_fmac_f32_e32 v38, v43, v175
	v_fmac_f32_e32 v39, v43, v176
	v_add_f32_e32 v32, v44, v32
	v_add_f32_e32 v33, v44, v33
	v_add_f32_e32 v34, v44, v34
	v_add_f32_e32 v35, v44, v35
	v_add_f32_e32 v36, v44, v36
	v_add_f32_e32 v37, v44, v37
	v_add_f32_e32 v38, v44, v38
	v_add_f32_e32 v39, v44, v39
	v_cvt_pk_bf16_f32 v32, v32, v33
	v_cvt_pk_bf16_f32 v34, v34, v35
	v_cvt_pk_bf16_f32 v36, v36, v37
	v_cvt_pk_bf16_f32 v38, v38, v39
	ds_write_b16 v240, v32 offset:1152
	ds_write_b16_d16_hi v240, v32 offset:1296
	ds_write_b16 v240, v34 offset:1440
	ds_write_b16_d16_hi v240, v34 offset:1584
	ds_write_b16 v240, v36 offset:1728
	ds_write_b16_d16_hi v240, v36 offset:1872
	ds_write_b16 v240, v38 offset:2016
	ds_write_b16_d16_hi v240, v38 offset:2160
	v_mul_f32_e32 v32, v41, v175
	v_mul_f32_e32 v33, v41, v176
	v_mul_f32_e32 v34, v41, v177
	v_mul_f32_e32 v35, v41, v178
	v_mul_f32_e32 v36, v41, v179
	v_mul_f32_e32 v37, v41, v180
	v_mul_f32_e32 v38, v41, v181
	v_mul_f32_e32 v39, v41, v182
	v_fmac_f32_e32 v32, v40, v174
	v_fmac_f32_e32 v33, v40, v175
	v_fmac_f32_e32 v34, v40, v176
	v_fmac_f32_e32 v35, v40, v177
	v_fmac_f32_e32 v36, v40, v178
	v_fmac_f32_e32 v37, v40, v179
	v_fmac_f32_e32 v38, v40, v180
	v_fmac_f32_e32 v39, v40, v181
	v_fmac_f32_e32 v32, v42, v176
	v_fmac_f32_e32 v33, v42, v177
	v_fmac_f32_e32 v34, v42, v178
	v_fmac_f32_e32 v35, v42, v179
	v_fmac_f32_e32 v36, v42, v180
	v_fmac_f32_e32 v37, v42, v181
	v_fmac_f32_e32 v38, v42, v182
	v_fmac_f32_e32 v39, v42, v183
	v_fmac_f32_e32 v32, v43, v177
	v_fmac_f32_e32 v33, v43, v178
	v_fmac_f32_e32 v34, v43, v179
	v_fmac_f32_e32 v35, v43, v180
	v_fmac_f32_e32 v36, v43, v181
	v_fmac_f32_e32 v37, v43, v182
	v_fmac_f32_e32 v38, v43, v183
	v_fmac_f32_e32 v39, v43, v184
	v_add_f32_e32 v32, v44, v32
	v_add_f32_e32 v33, v44, v33
	v_add_f32_e32 v34, v44, v34
	v_add_f32_e32 v35, v44, v35
	v_add_f32_e32 v36, v44, v36
	v_add_f32_e32 v37, v44, v37
	v_add_f32_e32 v38, v44, v38
	v_add_f32_e32 v39, v44, v39
	v_cvt_pk_bf16_f32 v32, v32, v33
	v_cvt_pk_bf16_f32 v34, v34, v35
	v_cvt_pk_bf16_f32 v36, v36, v37
	v_cvt_pk_bf16_f32 v38, v38, v39
	ds_write_b16 v240, v32 offset:2304
	ds_write_b16_d16_hi v240, v32 offset:2448
	ds_write_b16 v240, v34 offset:2592
	ds_write_b16_d16_hi v240, v34 offset:2736
	ds_write_b16 v240, v36 offset:2880
	ds_write_b16_d16_hi v240, v36 offset:3024
	ds_write_b16 v240, v38 offset:3168
	ds_write_b16_d16_hi v240, v38 offset:3312
	v_mul_f32_e32 v32, v41, v183
	v_mul_f32_e32 v33, v41, v184
	v_mul_f32_e32 v34, v41, v185
	v_mul_f32_e32 v35, v41, v186
; __device__ __forceinline__ unsigned f2bf(float f) { unsigned r; asm("v_cvt_pk_bf16_f32 %0, %1, %1" : "=v"(r) : "v"(f)); return r & 0xffffu; }
; template <bool FINAL>
; __device__ __forceinline__ void rg_item(PREF p, int l, int item, LAS unsigned char* wl, int lane) {
;     ...
;         for (int tt = 0; tt < 64; ++tt) { const float xc = xv[tt] * cw0 + xv[tt + 1] * cw1 + xv[tt + 2] * cw2 + xv[tt + 3] * cw3 + cb; sXc[tt * 72 + lane] = (bf16_t)f2bf(xc); }
	v_mul_f32_e32 v36, v41, v187
	v_mul_f32_e32 v37, v41, v188
	v_mul_f32_e32 v38, v41, v189
	v_mul_f32_e32 v39, v41, v190
	v_fmac_f32_e32 v32, v40, v182
	v_fmac_f32_e32 v33, v40, v183
	v_fmac_f32_e32 v34, v40, v184
	v_fmac_f32_e32 v35, v40, v185
	v_fmac_f32_e32 v36, v40, v186
	v_fmac_f32_e32 v37, v40, v187
	v_fmac_f32_e32 v38, v40, v188
	v_fmac_f32_e32 v39, v40, v189
	v_fmac_f32_e32 v32, v42, v184
	v_fmac_f32_e32 v33, v42, v185
	v_fmac_f32_e32 v34, v42, v186
	v_fmac_f32_e32 v35, v42, v187
	v_fmac_f32_e32 v36, v42, v188
	v_fmac_f32_e32 v37, v42, v189
	v_fmac_f32_e32 v38, v42, v190
	v_fmac_f32_e32 v39, v42, v191
	v_fmac_f32_e32 v32, v43, v185
	v_fmac_f32_e32 v33, v43, v186
	v_fmac_f32_e32 v34, v43, v187
	v_fmac_f32_e32 v35, v43, v188
	v_fmac_f32_e32 v36, v43, v189
	v_fmac_f32_e32 v37, v43, v190
	v_fmac_f32_e32 v38, v43, v191
	v_fmac_f32_e32 v39, v43, v192
	v_add_f32_e32 v32, v44, v32
	v_add_f32_e32 v33, v44, v33
	v_add_f32_e32 v34, v44, v34
	v_add_f32_e32 v35, v44, v35
	v_add_f32_e32 v36, v44, v36
	v_add_f32_e32 v37, v44, v37
	v_add_f32_e32 v38, v44, v38
	v_add_f32_e32 v39, v44, v39
	v_cvt_pk_bf16_f32 v32, v32, v33
	v_cvt_pk_bf16_f32 v34, v34, v35
	v_cvt_pk_bf16_f32 v36, v36, v37
	v_cvt_pk_bf16_f32 v38, v38, v39
	ds_write_b16 v240, v32 offset:3456
	ds_write_b16_d16_hi v240, v32 offset:3600
	ds_write_b16 v240, v34 offset:3744
	ds_write_b16_d16_hi v240, v34 offset:3888
	ds_write_b16 v240, v36 offset:4032
	ds_write_b16_d16_hi v240, v36 offset:4176
	ds_write_b16 v240, v38 offset:4320
	ds_write_b16_d16_hi v240, v38 offset:4464
	v_mul_f32_e32 v32, v41, v191
	v_mul_f32_e32 v33, v41, v192
	v_mul_f32_e32 v34, v41, v193
	v_mul_f32_e32 v35, v41, v194
	v_mul_f32_e32 v36, v41, v195
	v_mul_f32_e32 v37, v41, v196
	v_mul_f32_e32 v38, v41, v197
	v_mul_f32_e32 v39, v41, v198
	v_fmac_f32_e32 v32, v40, v190
	v_fmac_f32_e32 v33, v40, v191
	v_fmac_f32_e32 v34, v40, v192
	v_fmac_f32_e32 v35, v40, v193
	v_fmac_f32_e32 v36, v40, v194
	v_fmac_f32_e32 v37, v40, v195
	v_fmac_f32_e32 v38, v40, v196
	v_fmac_f32_e32 v39, v40, v197
	v_fmac_f32_e32 v32, v42, v192
	v_fmac_f32_e32 v33, v42, v193
	v_fmac_f32_e32 v34, v42, v194
	v_fmac_f32_e32 v35, v42, v195
	v_fmac_f32_e32 v36, v42, v196
	v_fmac_f32_e32 v37, v42, v197
	v_fmac_f32_e32 v38, v42, v198
	v_fmac_f32_e32 v39, v42, v199
	v_fmac_f32_e32 v32, v43, v193
	v_fmac_f32_e32 v33, v43, v194
	v_fmac_f32_e32 v34, v43, v195
	v_fmac_f32_e32 v35, v43, v196
	v_fmac_f32_e32 v36, v43, v197
	v_fmac_f32_e32 v37, v43, v198
	v_fmac_f32_e32 v38, v43, v199
	v_fmac_f32_e32 v39, v43, v200
	v_add_f32_e32 v32, v44, v32
	v_add_f32_e32 v33, v44, v33
	v_add_f32_e32 v34, v44, v34
	v_add_f32_e32 v35, v44, v35
	v_add_f32_e32 v36, v44, v36
	v_add_f32_e32 v37, v44, v37
	v_add_f32_e32 v38, v44, v38
	v_add_f32_e32 v39, v44, v39
	v_cvt_pk_bf16_f32 v32, v32, v33
	v_cvt_pk_bf16_f32 v34, v34, v35
	v_cvt_pk_bf16_f32 v36, v36, v37
	v_cvt_pk_bf16_f32 v38, v38, v39
	ds_write_b16 v240, v32 offset:4608
	ds_write_b16_d16_hi v240, v32 offset:4752
	ds_write_b16 v240, v34 offset:4896
	ds_write_b16_d16_hi v240, v34 offset:5040
	ds_write_b16 v240, v36 offset:5184
	ds_write_b16_d16_hi v240, v36 offset:5328
	ds_write_b16 v240, v38 offset:5472
	ds_write_b16_d16_hi v240, v38 offset:5616
	v_mul_f32_e32 v32, v41, v199
	v_mul_f32_e32 v33, v41, v200
	v_mul_f32_e32 v34, v41, v201
	v_mul_f32_e32 v35, v41, v202
	v_mul_f32_e32 v36, v41, v203
	v_mul_f32_e32 v37, v41, v204
	v_mul_f32_e32 v38, v41, v205
	v_mul_f32_e32 v39, v41, v206
	v_fmac_f32_e32 v32, v40, v198
	v_fmac_f32_e32 v33, v40, v199
	v_fmac_f32_e32 v34, v40, v200
	v_fmac_f32_e32 v35, v40, v201
	v_fmac_f32_e32 v36, v40, v202
	v_fmac_f32_e32 v37, v40, v203
	v_fmac_f32_e32 v38, v40, v204
	v_fmac_f32_e32 v39, v40, v205
	v_fmac_f32_e32 v32, v42, v200
	v_fmac_f32_e32 v33, v42, v201
	v_fmac_f32_e32 v34, v42, v202
	v_fmac_f32_e32 v35, v42, v203
	v_fmac_f32_e32 v36, v42, v204
	v_fmac_f32_e32 v37, v42, v205
	v_fmac_f32_e32 v38, v42, v206
	v_fmac_f32_e32 v39, v42, v207
	v_fmac_f32_e32 v32, v43, v201
	v_fmac_f32_e32 v33, v43, v202
	v_fmac_f32_e32 v34, v43, v203
	v_fmac_f32_e32 v35, v43, v204
	v_fmac_f32_e32 v36, v43, v205
	v_fmac_f32_e32 v37, v43, v206
	v_fmac_f32_e32 v38, v43, v207
	v_fmac_f32_e32 v39, v43, v208
	v_add_f32_e32 v32, v44, v32
	v_add_f32_e32 v33, v44, v33
	v_add_f32_e32 v34, v44, v34
	v_add_f32_e32 v35, v44, v35
	v_add_f32_e32 v36, v44, v36
	v_add_f32_e32 v37, v44, v37
	v_add_f32_e32 v38, v44, v38
	v_add_f32_e32 v39, v44, v39
	v_cvt_pk_bf16_f32 v32, v32, v33
	v_cvt_pk_bf16_f32 v34, v34, v35
	v_cvt_pk_bf16_f32 v36, v36, v37
	v_cvt_pk_bf16_f32 v38, v38, v39
	ds_write_b16 v240, v32 offset:5760
	ds_write_b16_d16_hi v240, v32 offset:5904
	ds_write_b16 v240, v34 offset:6048
	ds_write_b16_d16_hi v240, v34 offset:6192
	ds_write_b16 v240, v36 offset:6336
	ds_write_b16_d16_hi v240, v36 offset:6480
	ds_write_b16 v240, v38 offset:6624
	ds_write_b16_d16_hi v240, v38 offset:6768
	v_mul_f32_e32 v32, v41, v207
	v_mul_f32_e32 v33, v41, v208
	v_mul_f32_e32 v34, v41, v209
	v_mul_f32_e32 v35, v41, v210
	v_mul_f32_e32 v36, v41, v211
	v_mul_f32_e32 v37, v41, v212
	v_mul_f32_e32 v38, v41, v213
	v_mul_f32_e32 v39, v41, v214
	v_fmac_f32_e32 v32, v40, v206
	v_fmac_f32_e32 v33, v40, v207
	v_fmac_f32_e32 v34, v40, v208
	v_fmac_f32_e32 v35, v40, v209
	v_fmac_f32_e32 v36, v40, v210
	v_fmac_f32_e32 v37, v40, v211
	v_fmac_f32_e32 v38, v40, v212
	v_fmac_f32_e32 v39, v40, v213
	v_fmac_f32_e32 v32, v42, v208
	v_fmac_f32_e32 v33, v42, v209
	v_fmac_f32_e32 v34, v42, v210
	v_fmac_f32_e32 v35, v42, v211
	v_fmac_f32_e32 v36, v42, v212
	v_fmac_f32_e32 v37, v42, v213
	v_fmac_f32_e32 v38, v42, v214
	v_fmac_f32_e32 v39, v42, v215
	v_fmac_f32_e32 v32, v43, v209
; __device__ __forceinline__ unsigned f2bf(float f) { unsigned r; asm("v_cvt_pk_bf16_f32 %0, %1, %1" : "=v"(r) : "v"(f)); return r & 0xffffu; }
; __device__ __forceinline__ float rcpf_(float x) { return __builtin_amdgcn_rcpf(x); }
; template <bool FINAL, int D>
; __device__ __forceinline__ void rg_dir(PREF p, int l, int h, int ch, int sidx, int rowbase  , LAS bf16_t* sXc, LAS float* stg, int lane) {
;     ...
;     const float ba = p.rg_ba[(l * 2 + D) * 512 + ch], bi = p.rg_bi[(l * 2 + D) * 512 + ch], lam = p.rg_lam[(l * 2 + D) * 512 + ch];
;     const float e_ = __expf(-lam), u_ = 1.f + e_;
;     const float l1p = (u_ == 1.f) ? e_ : __logf(u_) * e_ * rcpf_(u_ - 1.f);
;     const float sp8 = -8.f * 1.4426950408889634f * l1p;
;     float hc = FINAL ? RGC[sidx] : 0.f, Ap = 1.f;
;     bf16x8 Br[4][2], Bi[4][2];
; #pragma unroll
;     for (int nt = 0; nt < 4; ++nt) { const int o0 = (nt * 16 + (lane & 15)) * 64 + (lane >> 4) * 8;
;         Br[nt][0] = *(const bf16x8*)(wr_ + o0); Br[nt][1] = *(const bf16x8*)(wr_ + o0 + 32); Bi[nt][0] = *(const bf16x8*)(wi_ + o0); Bi[nt][1] = *(const bf16x8*)(wi_ + o0 + 32); }
;     if (FINAL && D == 1) asm volatile("s_waitcnt vmcnt(0)" ::: "memory");
; #pragma unroll 1
;     for (int mi = 0; mi < 4; ++mi) { const int mt = D ? 3 - mi : mi;
;         float grv[16], hfv[16];
;         if (FINAL && D == 1) {
; #pragma unroll
;             for (int ti = 0; ti < 16; ++ti) { const size_t row = (size_t)(rowbase + mt * 16 + 15 - ti); grv[ti] = __builtin_bit_cast(float, (unsigned)P[row * PW + 512 + ch]); hfv[ti] = __builtin_bit_cast(float, (unsigned)TMP[row * 512 + ch]); }
; template <bool FINAL>
; __device__ __forceinline__ void rg_item(PREF p, int l, int item, LAS unsigned char* wl, int lane) {
;     ...
;         for (int tt = 0; tt < 64; ++tt) { const float xc = xv[tt] * cw0 + xv[tt + 1] * cw1 + xv[tt + 2] * cw2 + xv[tt + 3] * cw3 + cb; sXc[tt * 72 + lane] = (bf16_t)f2bf(xc); }
	v_fmac_f32_e32 v33, v43, v210
	v_fmac_f32_e32 v34, v43, v211
	v_fmac_f32_e32 v35, v43, v212
	v_fmac_f32_e32 v36, v43, v213
	v_fmac_f32_e32 v37, v43, v214
	v_fmac_f32_e32 v38, v43, v215
	v_fmac_f32_e32 v39, v43, v216
	v_add_f32_e32 v32, v44, v32
	v_add_f32_e32 v33, v44, v33
	v_add_f32_e32 v34, v44, v34
	v_add_f32_e32 v35, v44, v35
	v_add_f32_e32 v36, v44, v36
	v_add_f32_e32 v37, v44, v37
	v_add_f32_e32 v38, v44, v38
	v_add_f32_e32 v39, v44, v39
	v_cvt_pk_bf16_f32 v32, v32, v33
	v_cvt_pk_bf16_f32 v34, v34, v35
	v_cvt_pk_bf16_f32 v36, v36, v37
	v_cvt_pk_bf16_f32 v38, v38, v39
	ds_write_b16 v240, v32 offset:6912
	ds_write_b16_d16_hi v240, v32 offset:7056
	ds_write_b16 v240, v34 offset:7200
	ds_write_b16_d16_hi v240, v34 offset:7344
	ds_write_b16 v240, v36 offset:7488
	ds_write_b16_d16_hi v240, v36 offset:7632
	ds_write_b16 v240, v38 offset:7776
	ds_write_b16_d16_hi v240, v38 offset:7920
	v_mul_f32_e32 v32, v41, v215
	v_mul_f32_e32 v33, v41, v216
	v_mul_f32_e32 v34, v41, v217
	v_mul_f32_e32 v35, v41, v218
	v_mul_f32_e32 v36, v41, v219
	v_mul_f32_e32 v37, v41, v222
	v_mul_f32_e32 v38, v41, v223
	v_mul_f32_e32 v39, v41, v140
	v_fmac_f32_e32 v32, v40, v214
	v_fmac_f32_e32 v33, v40, v215
	v_fmac_f32_e32 v34, v40, v216
	v_fmac_f32_e32 v35, v40, v217
	v_fmac_f32_e32 v36, v40, v218
	v_fmac_f32_e32 v37, v40, v219
	v_fmac_f32_e32 v38, v40, v222
	v_fmac_f32_e32 v39, v40, v223
	v_fmac_f32_e32 v32, v42, v216
	v_fmac_f32_e32 v33, v42, v217
	v_fmac_f32_e32 v34, v42, v218
	v_fmac_f32_e32 v35, v42, v219
	v_fmac_f32_e32 v36, v42, v222
	v_fmac_f32_e32 v37, v42, v223
	v_fmac_f32_e32 v38, v42, v140
	v_fmac_f32_e32 v39, v42, v141
	v_fmac_f32_e32 v32, v43, v217
	v_fmac_f32_e32 v33, v43, v218
	v_fmac_f32_e32 v34, v43, v219
	v_fmac_f32_e32 v35, v43, v222
	v_fmac_f32_e32 v36, v43, v223
	v_fmac_f32_e32 v37, v43, v140
	v_fmac_f32_e32 v38, v43, v141
	v_fmac_f32_e32 v39, v43, v232
	v_add_f32_e32 v32, v44, v32
	v_add_f32_e32 v33, v44, v33
	v_add_f32_e32 v34, v44, v34
	v_add_f32_e32 v35, v44, v35
	v_add_f32_e32 v36, v44, v36
	v_add_f32_e32 v37, v44, v37
	v_add_f32_e32 v38, v44, v38
	v_add_f32_e32 v39, v44, v39
	v_cvt_pk_bf16_f32 v32, v32, v33
	v_cvt_pk_bf16_f32 v34, v34, v35
	v_cvt_pk_bf16_f32 v36, v36, v37
	v_cvt_pk_bf16_f32 v38, v38, v39
	ds_write_b16 v240, v32 offset:8064
	ds_write_b16_d16_hi v240, v32 offset:8208
	ds_write_b16 v240, v34 offset:8352
	ds_write_b16_d16_hi v240, v34 offset:8496
	ds_write_b16 v240, v36 offset:8640
	ds_write_b16_d16_hi v240, v36 offset:8784
	ds_write_b16 v240, v38 offset:8928
	ds_write_b16_d16_hi v240, v38 offset:9072
	v_mov_b32_e32 v248, 0xbfb8aa3b
	v_mov_b32_e32 v249, 0xbfb8aa3b
	v_mov_b32_e32 v140, 0x3d372713
	v_mov_b32_e32 v141, 0x3d372713
	s_waitcnt vmcnt(16)
	s_mov_b32 s8, 0x800000
	s_mov_b32 s9, 0x3f317217
	s_mov_b32 s14, 0x7f800000
	v_mul_f32_e32 v32, 0xbfb8aa3b, v45
	v_exp_f32_e32 v32, v32
	s_nop 0
	v_add_f32_e32 v33, 1.0, v32
	v_cmp_gt_f32_e32 vcc, s8, v33
	s_nop 1
	v_cndmask_b32_e64 v34, 0, 32, vcc
	v_ldexp_f32 v34, v33, v34
	v_log_f32_e32 v34, v34
	v_cndmask_b32_e32 v36, 0, v226, vcc
	v_cmp_eq_f32_e32 vcc, 1.0, v33
	v_mul_f32_e32 v35, 0x3f317217, v34
	v_fma_f32 v35, v34, s9, -v35
	v_fmac_f32_e32 v35, 0x3377d1cf, v34
	v_fmac_f32_e32 v35, 0x3f317217, v34
	v_cmp_lt_f32_e64 s[10:11], |v34|, s14
	s_nop 1
	v_cndmask_b32_e64 v34, v34, v35, s[10:11]
	v_add_f32_e32 v35, -1.0, v33
	v_rcp_f32_e32 v35, v35
	v_sub_f32_e32 v34, v34, v36
	v_mul_f32_e32 v34, v32, v34
	v_mul_f32_e32 v34, v34, v35
	v_cndmask_b32_e32 v32, v34, v32, vcc
	v_mul_f32_e32 v246, 0xc138aa3b, v32
	v_mov_b32_e32 v247, v246
	v_mul_f32_e32 v242, 0xbfb8aa3b, v46
	v_mul_f32_e32 v244, 0xbfb8aa3b, v47
	v_mov_b32_e32 v243, v242
	v_mov_b32_e32 v245, v244
	s_waitcnt vmcnt(0)
	s_add_i32 s39, s15, 48
	s_mul_hi_u32 s83, s39, 0x1600
	s_mul_i32 s82, s39, 0x1600
	s_add_u32 s82, s82, s0
	s_addc_u32 s83, s83, s1
	s_add_u32 s82, s82, 0xbc00400
	s_addc_u32 s83, s83, 0
	global_load_ushort v190, v234, s[82:83]
	s_add_u32 s82, s82, 0x1600
	s_addc_u32 s83, s83, 0
	global_load_ushort v191, v234, s[82:83]
	s_add_u32 s82, s82, 0x1600
	s_addc_u32 s83, s83, 0
	global_load_ushort v192, v234, s[82:83]
	s_add_u32 s82, s82, 0x1600
	s_addc_u32 s83, s83, 0
	global_load_ushort v193, v234, s[82:83]
	s_add_u32 s82, s82, 0x1600
	s_addc_u32 s83, s83, 0
	global_load_ushort v194, v234, s[82:83]
	s_add_u32 s82, s82, 0x1600
	s_addc_u32 s83, s83, 0
	global_load_ushort v195, v234, s[82:83]
	s_add_u32 s82, s82, 0x1600
	s_addc_u32 s83, s83, 0
	global_load_ushort v196, v234, s[82:83]
	s_add_u32 s82, s82, 0x1600
	s_addc_u32 s83, s83, 0
	global_load_ushort v197, v234, s[82:83]
	s_add_u32 s82, s82, 0x1600
	s_addc_u32 s83, s83, 0
	global_load_ushort v198, v234, s[82:83]
	s_add_u32 s82, s82, 0x1600
	s_addc_u32 s83, s83, 0
	global_load_ushort v199, v234, s[82:83]
	s_add_u32 s82, s82, 0x1600
	s_addc_u32 s83, s83, 0
	global_load_ushort v200, v234, s[82:83]
	s_add_u32 s82, s82, 0x1600
	s_addc_u32 s83, s83, 0
	global_load_ushort v201, v234, s[82:83]
	s_add_u32 s82, s82, 0x1600
	s_addc_u32 s83, s83, 0
	global_load_ushort v202, v234, s[82:83]
	s_add_u32 s82, s82, 0x1600
	s_addc_u32 s83, s83, 0
	global_load_ushort v203, v234, s[82:83]
	s_add_u32 s82, s82, 0x1600
	s_addc_u32 s83, s83, 0
	global_load_ushort v204, v234, s[82:83]
	s_add_u32 s82, s82, 0x1600
	s_addc_u32 s83, s83, 0
	global_load_ushort v205, v234, s[82:83]
	ds_read_b128 v[32:35], v236 offset:0
	ds_read_b128 v[36:39], v236 offset:64
	s_waitcnt lgkmcnt(0)
; #define LAS __attribute__((address_space(3)))
; #define WAVE_SYNC() asm volatile("s_waitcnt lgkmcnt(0)" ::: "memory")
; __device__ __forceinline__ float sigmoid_f(float x) { return rcpf_(1.f + __expf(-x)); }
; __device__ __forceinline__ f32x4 mfma16(bf16x8 a, bf16x8 b, f32x4 c) { return __builtin_amdgcn_mfma_f32_16x16x32_bf16(a, b, c, 0, 0, 0); }
; template <bool FINAL, int D>
; __device__ __forceinline__ void rg_dir(PREF p, int l, int h, int ch, int sidx, int rowbase  , LAS bf16_t* sXc, LAS float* stg, int lane) {
;     ...
;         const bf16x8 A0 = *(const LAS bf16x8*)(sXc + (mt * 16 + (lane & 15)) * 72 + (lane >> 4) * 8), A1 = *(const LAS bf16x8*)(sXc + (mt * 16 + (lane & 15)) * 72 + 32 + (lane >> 4) * 8);
;         f32x4 ar[4], ai[4];
; #pragma unroll
;         for (int nt = 0; nt < 4; ++nt) { const f32x4 z = {0.f, 0.f, 0.f, 0.f};
;             ar[nt] = mfma16(A0, Br[nt][0], z); ar[nt] = mfma16(A1, Br[nt][1], ar[nt]); ai[nt] = mfma16(A0, Bi[nt][0], z); ai[nt] = mfma16(A1, Bi[nt][1], ai[nt]); }
;         WAVE_SYNC();
; #pragma unroll
;         for (int nt = 0; nt < 4; ++nt)
; #pragma unroll
;             for (int j = 0; j < 4; ++j) { const int o = ((lane >> 4) * 4 + j) * 64 + nt * 16 + (lane & 15); stg[o] = ar[nt][j]; stg[1024 + o] = ai[nt][j]; }
;         WAVE_SYNC();
;         float av[16], iv[16];
; #pragma unroll
;         for (int ti = 0; ti < 16; ++ti) { const int tk = D ? 15 - ti : ti;
;             const float zr = stg[tk * 64 + lane] + ba, zi = stg[1024 + tk * 64 + lane] + bi;
;             const float r = sigmoid_f(zr), ig = sigmoid_f(zi);
;             const float a = __builtin_amdgcn_exp2f(r * sp8);
;             const float xc = bf2f(sXc[(mt * 16 + tk) * 72 + lane]);
;             av[ti] = a; iv[ti] = __builtin_amdgcn_sqrtf(fmaxf(1.f - a * a, 0.f)) * ig * xc;
	v_mfma_f32_16x16x32_bf16 v[0:3], v[32:35], v[80:83], 0
	v_mfma_f32_16x16x32_bf16 v[4:7], v[32:35], v[88:91], 0
	v_mfma_f32_16x16x32_bf16 v[8:11], v[32:35], v[96:99], 0
	v_mfma_f32_16x16x32_bf16 v[12:15], v[32:35], v[104:107], 0
	v_mfma_f32_16x16x32_bf16 v[16:19], v[32:35], v[112:115], 0
	v_mfma_f32_16x16x32_bf16 v[20:23], v[32:35], v[120:123], 0
	v_mfma_f32_16x16x32_bf16 v[24:27], v[32:35], v[128:131], 0
	v_mfma_f32_16x16x32_bf16 v[28:31], v[32:35], v[136:139], 0
	v_mfma_f32_16x16x32_bf16 v[0:3], v[36:39], v[84:87], v[0:3]
	v_mfma_f32_16x16x32_bf16 v[4:7], v[36:39], v[92:95], v[4:7]
	v_mfma_f32_16x16x32_bf16 v[8:11], v[36:39], v[100:103], v[8:11]
	v_mfma_f32_16x16x32_bf16 v[12:15], v[36:39], v[108:111], v[12:15]
	v_mfma_f32_16x16x32_bf16 v[16:19], v[36:39], v[116:119], v[16:19]
	v_mfma_f32_16x16x32_bf16 v[20:23], v[36:39], v[124:127], v[20:23]
	v_mfma_f32_16x16x32_bf16 v[24:27], v[36:39], v[132:135], v[24:27]
	v_mfma_f32_16x16x32_bf16 v[28:31], v[36:39], v[228:231], v[28:31]
	s_nop 3
	ds_write2_b32 v237, v0, v4 offset0:0 offset1:16
	ds_write2_b32 v237, v8, v12 offset0:32 offset1:48
	ds_write2_b32 v237, v1, v5 offset0:64 offset1:80
	ds_write2_b32 v237, v9, v13 offset0:96 offset1:112
	ds_write2_b32 v237, v2, v6 offset0:128 offset1:144
	ds_write2_b32 v237, v10, v14 offset0:160 offset1:176
	ds_write2_b32 v237, v3, v7 offset0:192 offset1:208
	ds_write2_b32 v237, v11, v15 offset0:224 offset1:240
	ds_write2_b32 v238, v16, v20 offset0:0 offset1:16
	ds_write2_b32 v238, v24, v28 offset0:32 offset1:48
	ds_write2_b32 v238, v17, v21 offset0:64 offset1:80
	ds_write2_b32 v238, v25, v29 offset0:96 offset1:112
	ds_write2_b32 v238, v18, v22 offset0:128 offset1:144
	ds_write2_b32 v238, v26, v30 offset0:160 offset1:176
	ds_write2_b32 v238, v19, v23 offset0:192 offset1:208
	ds_write2_b32 v238, v27, v31 offset0:224 offset1:240
	s_waitcnt lgkmcnt(0)
	ds_read2st64_b32 v[0:1], v239 offset0:36 offset1:37
	ds_read2st64_b32 v[2:3], v239 offset0:38 offset1:39
	ds_read2st64_b32 v[4:5], v239 offset0:40 offset1:41
	ds_read2st64_b32 v[6:7], v239 offset0:42 offset1:43
	ds_read2st64_b32 v[8:9], v239 offset0:44 offset1:45
	ds_read2st64_b32 v[10:11], v239 offset0:46 offset1:47
	ds_read2st64_b32 v[12:13], v239 offset0:48 offset1:49
	ds_read2st64_b32 v[14:15], v239 offset0:50 offset1:51
	ds_read2st64_b32 v[16:17], v239 offset0:52 offset1:53
	ds_read2st64_b32 v[18:19], v239 offset0:54 offset1:55
	ds_read2st64_b32 v[20:21], v239 offset0:56 offset1:57
	ds_read2st64_b32 v[22:23], v239 offset0:58 offset1:59
	ds_read2st64_b32 v[24:25], v239 offset0:60 offset1:61
	ds_read2st64_b32 v[26:27], v239 offset0:62 offset1:63
	ds_read2st64_b32 v[28:29], v239 offset0:64 offset1:65
	ds_read2st64_b32 v[30:31], v239 offset0:66 offset1:67
	ds_read_u16 v48, v240 offset:0
	ds_read_u16 v49, v240 offset:144
	ds_read_u16 v50, v240 offset:288
	ds_read_u16 v51, v240 offset:432
	ds_read_u16 v52, v240 offset:576
	ds_read_u16 v53, v240 offset:720
	ds_read_u16 v54, v240 offset:864
	ds_read_u16 v55, v240 offset:1008
	ds_read_u16 v56, v240 offset:1152
	ds_read_u16 v57, v240 offset:1296
	ds_read_u16 v58, v240 offset:1440
	ds_read_u16 v59, v240 offset:1584
	ds_read_u16 v60, v240 offset:1728
	ds_read_u16 v61, v240 offset:1872
	ds_read_u16 v62, v240 offset:2016
	ds_read_u16 v63, v240 offset:2160
	s_waitcnt lgkmcnt(0)
	v_pk_fma_f32 v[0:1], v[0:1], v[248:249], v[242:243]
	v_pk_fma_f32 v[2:3], v[2:3], v[248:249], v[242:243]
	v_pk_fma_f32 v[4:5], v[4:5], v[248:249], v[242:243]
	v_pk_fma_f32 v[6:7], v[6:7], v[248:249], v[242:243]
	v_pk_fma_f32 v[8:9], v[8:9], v[248:249], v[242:243]
	v_pk_fma_f32 v[10:11], v[10:11], v[248:249], v[242:243]
	v_pk_fma_f32 v[12:13], v[12:13], v[248:249], v[242:243]
	v_pk_fma_f32 v[14:15], v[14:15], v[248:249], v[242:243]
	v_pk_fma_f32 v[16:17], v[16:17], v[248:249], v[244:245]
	v_pk_fma_f32 v[18:19], v[18:19], v[248:249], v[244:245]
	v_pk_fma_f32 v[20:21], v[20:21], v[248:249], v[244:245]
	v_pk_fma_f32 v[22:23], v[22:23], v[248:249], v[244:245]
	v_pk_fma_f32 v[24:25], v[24:25], v[248:249], v[244:245]
	v_pk_fma_f32 v[26:27], v[26:27], v[248:249], v[244:245]
	v_pk_fma_f32 v[28:29], v[28:29], v[248:249], v[244:245]
	v_pk_fma_f32 v[30:31], v[30:31], v[248:249], v[244:245]
	v_exp_f32_e32 v0, v0
	v_exp_f32_e32 v1, v1
	v_exp_f32_e32 v2, v2
	v_exp_f32_e32 v3, v3
	v_exp_f32_e32 v4, v4
	v_exp_f32_e32 v5, v5
	v_exp_f32_e32 v6, v6
	v_exp_f32_e32 v7, v7
	v_exp_f32_e32 v8, v8
	v_exp_f32_e32 v9, v9
	v_exp_f32_e32 v10, v10
	v_exp_f32_e32 v11, v11
	v_exp_f32_e32 v12, v12
	v_exp_f32_e32 v13, v13
	v_exp_f32_e32 v14, v14
	v_exp_f32_e32 v15, v15
	v_exp_f32_e32 v16, v16
	v_exp_f32_e32 v17, v17
	v_exp_f32_e32 v18, v18
	v_exp_f32_e32 v19, v19
	v_exp_f32_e32 v20, v20
	v_exp_f32_e32 v21, v21
	v_exp_f32_e32 v22, v22
	v_exp_f32_e32 v23, v23
	v_exp_f32_e32 v24, v24
	v_exp_f32_e32 v25, v25
	v_exp_f32_e32 v26, v26
	v_exp_f32_e32 v27, v27
	v_exp_f32_e32 v28, v28
	v_exp_f32_e32 v29, v29
	v_exp_f32_e32 v30, v30
	v_exp_f32_e32 v31, v31
	v_pk_add_f32 v[0:1], v[0:1], 1.0 op_sel_hi:[1,0]
	v_pk_add_f32 v[2:3], v[2:3], 1.0 op_sel_hi:[1,0]
	v_pk_add_f32 v[4:5], v[4:5], 1.0 op_sel_hi:[1,0]
	v_pk_add_f32 v[6:7], v[6:7], 1.0 op_sel_hi:[1,0]
	v_pk_add_f32 v[8:9], v[8:9], 1.0 op_sel_hi:[1,0]
	v_pk_add_f32 v[10:11], v[10:11], 1.0 op_sel_hi:[1,0]
	v_pk_add_f32 v[12:13], v[12:13], 1.0 op_sel_hi:[1,0]
	v_pk_add_f32 v[14:15], v[14:15], 1.0 op_sel_hi:[1,0]
	v_pk_add_f32 v[16:17], v[16:17], 1.0 op_sel_hi:[1,0]
	v_pk_add_f32 v[18:19], v[18:19], 1.0 op_sel_hi:[1,0]
	v_pk_add_f32 v[20:21], v[20:21], 1.0 op_sel_hi:[1,0]
	v_pk_add_f32 v[22:23], v[22:23], 1.0 op_sel_hi:[1,0]
	v_pk_add_f32 v[24:25], v[24:25], 1.0 op_sel_hi:[1,0]
; __device__ __forceinline__ unsigned f2bf(float f) { unsigned r; asm("v_cvt_pk_bf16_f32 %0, %1, %1" : "=v"(r) : "v"(f)); return r & 0xffffu; }
; __device__ __forceinline__ float sigmoid_f(float x) { return rcpf_(1.f + __expf(-x)); }
; __device__ __forceinline__ float gelu_tanh_f(float x) { const float y = 0.7978845608028654f * (x + 0.044715f * x * x * x); return x * sigmoid_f(2.f * y); }
; template <bool FINAL, int D>
; __device__ __forceinline__ void rg_dir(PREF p, int l, int h, int ch, int sidx, int rowbase  , LAS bf16_t* sXc, LAS float* stg, int lane) {
;     ...
;         for (int ti = 0; ti < 16; ++ti) { const int tk = D ? 15 - ti : ti;
;             const float zr = stg[tk * 64 + lane] + ba, zi = stg[1024 + tk * 64 + lane] + bi;
;             const float r = sigmoid_f(zr), ig = sigmoid_f(zi);
;             const float a = __builtin_amdgcn_exp2f(r * sp8);
;             const float xc = bf2f(sXc[(mt * 16 + tk) * 72 + lane]);
;             av[ti] = a; iv[ti] = __builtin_amdgcn_sqrtf(fmaxf(1.f - a * a, 0.f)) * ig * xc;
;             if (FINAL && D == 1) grv[ti] = gelu_tanh_f(grv[ti]);
;         }
; #pragma unroll
;         for (int ti = 0; ti < 16; ++ti) { const int tk = D ? 15 - ti : ti;
;             hc = av[ti] * hc + iv[ti]; Ap *= av[ti];
;             if (FINAL) { const size_t row = (size_t)(rowbase + mt * 16 + tk);
;                 if (D == 0) TMP[row * 512 + ch] = (bf16_t)f2bf(hc);
;                 else MIX[row * DM + ch] = (bf16_t)f2bf(grv[ti] * (hfv[ti] + hc)); }
	v_pk_add_f32 v[26:27], v[26:27], 1.0 op_sel_hi:[1,0]
	v_pk_add_f32 v[28:29], v[28:29], 1.0 op_sel_hi:[1,0]
	v_pk_add_f32 v[30:31], v[30:31], 1.0 op_sel_hi:[1,0]
	v_rcp_f32_e32 v0, v0
	v_rcp_f32_e32 v1, v1
	v_rcp_f32_e32 v2, v2
	v_rcp_f32_e32 v3, v3
	v_rcp_f32_e32 v4, v4
	v_rcp_f32_e32 v5, v5
	v_rcp_f32_e32 v6, v6
	v_rcp_f32_e32 v7, v7
	v_rcp_f32_e32 v8, v8
	v_rcp_f32_e32 v9, v9
	v_rcp_f32_e32 v10, v10
	v_rcp_f32_e32 v11, v11
	v_rcp_f32_e32 v12, v12
	v_rcp_f32_e32 v13, v13
	v_rcp_f32_e32 v14, v14
	v_rcp_f32_e32 v15, v15
	v_rcp_f32_e32 v16, v16
	v_rcp_f32_e32 v17, v17
	v_rcp_f32_e32 v18, v18
	v_rcp_f32_e32 v19, v19
	v_rcp_f32_e32 v20, v20
	v_rcp_f32_e32 v21, v21
	v_rcp_f32_e32 v22, v22
	v_rcp_f32_e32 v23, v23
	v_rcp_f32_e32 v24, v24
	v_rcp_f32_e32 v25, v25
	v_rcp_f32_e32 v26, v26
	v_rcp_f32_e32 v27, v27
	v_rcp_f32_e32 v28, v28
	v_rcp_f32_e32 v29, v29
	v_rcp_f32_e32 v30, v30
	v_rcp_f32_e32 v31, v31
	v_pk_mul_f32 v[0:1], v[246:247], v[0:1]
	v_pk_mul_f32 v[2:3], v[246:247], v[2:3]
	v_pk_mul_f32 v[4:5], v[246:247], v[4:5]
	v_pk_mul_f32 v[6:7], v[246:247], v[6:7]
	v_pk_mul_f32 v[8:9], v[246:247], v[8:9]
	v_pk_mul_f32 v[10:11], v[246:247], v[10:11]
	v_pk_mul_f32 v[12:13], v[246:247], v[12:13]
	v_pk_mul_f32 v[14:15], v[246:247], v[14:15]
	v_lshlrev_b32_e32 v48, 16, v48
	v_lshlrev_b32_e32 v49, 16, v49
	v_lshlrev_b32_e32 v50, 16, v50
	v_lshlrev_b32_e32 v51, 16, v51
	v_lshlrev_b32_e32 v52, 16, v52
	v_lshlrev_b32_e32 v53, 16, v53
	v_lshlrev_b32_e32 v54, 16, v54
	v_lshlrev_b32_e32 v55, 16, v55
	v_lshlrev_b32_e32 v56, 16, v56
	v_lshlrev_b32_e32 v57, 16, v57
	v_lshlrev_b32_e32 v58, 16, v58
	v_lshlrev_b32_e32 v59, 16, v59
	v_lshlrev_b32_e32 v60, 16, v60
	v_lshlrev_b32_e32 v61, 16, v61
	v_lshlrev_b32_e32 v62, 16, v62
	v_lshlrev_b32_e32 v63, 16, v63
	v_exp_f32_e32 v0, v0
	v_exp_f32_e32 v1, v1
	v_exp_f32_e32 v2, v2
	v_exp_f32_e32 v3, v3
	v_exp_f32_e32 v4, v4
	v_exp_f32_e32 v5, v5
	v_exp_f32_e32 v6, v6
	v_exp_f32_e32 v7, v7
	v_exp_f32_e32 v8, v8
	v_exp_f32_e32 v9, v9
	v_exp_f32_e32 v10, v10
	v_exp_f32_e32 v11, v11
	v_exp_f32_e32 v12, v12
	v_exp_f32_e32 v13, v13
	v_exp_f32_e32 v14, v14
	v_exp_f32_e32 v15, v15
	v_fma_f32 v32, -v0, v0, 1.0
	v_fma_f32 v33, -v1, v1, 1.0
	v_fma_f32 v34, -v2, v2, 1.0
	v_fma_f32 v35, -v3, v3, 1.0
	v_fma_f32 v36, -v4, v4, 1.0
	v_fma_f32 v37, -v5, v5, 1.0
	v_fma_f32 v38, -v6, v6, 1.0
	v_fma_f32 v39, -v7, v7, 1.0
	v_fma_f32 v40, -v8, v8, 1.0
	v_fma_f32 v41, -v9, v9, 1.0
	v_fma_f32 v42, -v10, v10, 1.0
	v_fma_f32 v43, -v11, v11, 1.0
	v_fma_f32 v44, -v12, v12, 1.0
	v_fma_f32 v45, -v13, v13, 1.0
	v_fma_f32 v46, -v14, v14, 1.0
	v_fma_f32 v47, -v15, v15, 1.0
	v_max_f32_e32 v32, 0, v32
	v_max_f32_e32 v33, 0, v33
	v_max_f32_e32 v34, 0, v34
	v_max_f32_e32 v35, 0, v35
	v_max_f32_e32 v36, 0, v36
	v_max_f32_e32 v37, 0, v37
	v_max_f32_e32 v38, 0, v38
	v_max_f32_e32 v39, 0, v39
	v_max_f32_e32 v40, 0, v40
	v_max_f32_e32 v41, 0, v41
	v_max_f32_e32 v42, 0, v42
	v_max_f32_e32 v43, 0, v43
	v_max_f32_e32 v44, 0, v44
	v_max_f32_e32 v45, 0, v45
	v_max_f32_e32 v46, 0, v46
	v_max_f32_e32 v47, 0, v47
	v_sqrt_f32_e32 v32, v32
	v_sqrt_f32_e32 v33, v33
	v_sqrt_f32_e32 v34, v34
	v_sqrt_f32_e32 v35, v35
	v_sqrt_f32_e32 v36, v36
	v_sqrt_f32_e32 v37, v37
	v_sqrt_f32_e32 v38, v38
	v_sqrt_f32_e32 v39, v39
	v_sqrt_f32_e32 v40, v40
	v_sqrt_f32_e32 v41, v41
	v_sqrt_f32_e32 v42, v42
	v_sqrt_f32_e32 v43, v43
	v_sqrt_f32_e32 v44, v44
	v_sqrt_f32_e32 v45, v45
	v_sqrt_f32_e32 v46, v46
	v_sqrt_f32_e32 v47, v47
	s_nop 0
	v_pk_mul_f32 v[16:17], v[16:17], v[32:33]
	v_pk_mul_f32 v[18:19], v[18:19], v[34:35]
	v_pk_mul_f32 v[20:21], v[20:21], v[36:37]
	v_pk_mul_f32 v[22:23], v[22:23], v[38:39]
	v_pk_mul_f32 v[24:25], v[24:25], v[40:41]
	v_pk_mul_f32 v[26:27], v[26:27], v[42:43]
	v_pk_mul_f32 v[28:29], v[28:29], v[44:45]
	v_pk_mul_f32 v[30:31], v[30:31], v[46:47]
	v_pk_mul_f32 v[16:17], v[16:17], v[48:49]
	v_pk_mul_f32 v[18:19], v[18:19], v[50:51]
	v_pk_mul_f32 v[20:21], v[20:21], v[52:53]
	v_pk_mul_f32 v[22:23], v[22:23], v[54:55]
	v_pk_mul_f32 v[24:25], v[24:25], v[56:57]
	v_pk_mul_f32 v[26:27], v[26:27], v[58:59]
	v_pk_mul_f32 v[28:29], v[28:29], v[60:61]
	v_pk_mul_f32 v[30:31], v[30:31], v[62:63]
	v_fma_f32 v32, v0, v250, v16
	v_fma_f32 v250, v1, v32, v17
	v_cvt_pk_bf16_f32 v158, v32, v250
	v_fma_f32 v32, v2, v250, v18
	v_fma_f32 v250, v3, v32, v19
	v_cvt_pk_bf16_f32 v159, v32, v250
	v_fma_f32 v32, v4, v250, v20
	v_fma_f32 v250, v5, v32, v21
	v_cvt_pk_bf16_f32 v160, v32, v250
	v_fma_f32 v32, v6, v250, v22
	v_fma_f32 v250, v7, v32, v23
	v_cvt_pk_bf16_f32 v161, v32, v250
	v_fma_f32 v32, v8, v250, v24
	v_fma_f32 v250, v9, v32, v25
	v_cvt_pk_bf16_f32 v162, v32, v250
	v_fma_f32 v32, v10, v250, v26
	v_fma_f32 v250, v11, v32, v27
	v_cvt_pk_bf16_f32 v163, v32, v250
	v_fma_f32 v32, v12, v250, v28
	v_fma_f32 v250, v13, v32, v29
	v_cvt_pk_bf16_f32 v164, v32, v250
	v_fma_f32 v32, v14, v250, v30
	v_fma_f32 v250, v15, v32, v31
	v_cvt_pk_bf16_f32 v165, v32, v250
	ds_read_b128 v[32:35], v236 offset:2304
	ds_read_b128 v[36:39], v236 offset:2368
	s_waitcnt lgkmcnt(0)
; #define LAS __attribute__((address_space(3)))
; #define WAVE_SYNC() asm volatile("s_waitcnt lgkmcnt(0)" ::: "memory")
; __device__ __forceinline__ float sigmoid_f(float x) { return rcpf_(1.f + __expf(-x)); }
; __device__ __forceinline__ f32x4 mfma16(bf16x8 a, bf16x8 b, f32x4 c) { return __builtin_amdgcn_mfma_f32_16x16x32_bf16(a, b, c, 0, 0, 0); }
; template <bool FINAL, int D>
; __device__ __forceinline__ void rg_dir(PREF p, int l, int h, int ch, int sidx, int rowbase  , LAS bf16_t* sXc, LAS float* stg, int lane) {
;     ...
;         const bf16x8 A0 = *(const LAS bf16x8*)(sXc + (mt * 16 + (lane & 15)) * 72 + (lane >> 4) * 8), A1 = *(const LAS bf16x8*)(sXc + (mt * 16 + (lane & 15)) * 72 + 32 + (lane >> 4) * 8);
;         f32x4 ar[4], ai[4];
; #pragma unroll
;         for (int nt = 0; nt < 4; ++nt) { const f32x4 z = {0.f, 0.f, 0.f, 0.f};
;             ar[nt] = mfma16(A0, Br[nt][0], z); ar[nt] = mfma16(A1, Br[nt][1], ar[nt]); ai[nt] = mfma16(A0, Bi[nt][0], z); ai[nt] = mfma16(A1, Bi[nt][1], ai[nt]); }
;         WAVE_SYNC();
; #pragma unroll
;         for (int nt = 0; nt < 4; ++nt)
; #pragma unroll
;             for (int j = 0; j < 4; ++j) { const int o = ((lane >> 4) * 4 + j) * 64 + nt * 16 + (lane & 15); stg[o] = ar[nt][j]; stg[1024 + o] = ai[nt][j]; }
;         WAVE_SYNC();
;         float av[16], iv[16];
; #pragma unroll
;         for (int ti = 0; ti < 16; ++ti) { const int tk = D ? 15 - ti : ti;
;             const float zr = stg[tk * 64 + lane] + ba, zi = stg[1024 + tk * 64 + lane] + bi;
;             const float r = sigmoid_f(zr), ig = sigmoid_f(zi);
;             const float a = __builtin_amdgcn_exp2f(r * sp8);
;             const float xc = bf2f(sXc[(mt * 16 + tk) * 72 + lane]);
;             av[ti] = a; iv[ti] = __builtin_amdgcn_sqrtf(fmaxf(1.f - a * a, 0.f)) * ig * xc;
	v_mfma_f32_16x16x32_bf16 v[0:3], v[32:35], v[80:83], 0
	v_mfma_f32_16x16x32_bf16 v[4:7], v[32:35], v[88:91], 0
	v_mfma_f32_16x16x32_bf16 v[8:11], v[32:35], v[96:99], 0
	v_mfma_f32_16x16x32_bf16 v[12:15], v[32:35], v[104:107], 0
	v_mfma_f32_16x16x32_bf16 v[16:19], v[32:35], v[112:115], 0
	v_mfma_f32_16x16x32_bf16 v[20:23], v[32:35], v[120:123], 0
	v_mfma_f32_16x16x32_bf16 v[24:27], v[32:35], v[128:131], 0
	v_mfma_f32_16x16x32_bf16 v[28:31], v[32:35], v[136:139], 0
	v_mfma_f32_16x16x32_bf16 v[0:3], v[36:39], v[84:87], v[0:3]
	v_mfma_f32_16x16x32_bf16 v[4:7], v[36:39], v[92:95], v[4:7]
	v_mfma_f32_16x16x32_bf16 v[8:11], v[36:39], v[100:103], v[8:11]
	v_mfma_f32_16x16x32_bf16 v[12:15], v[36:39], v[108:111], v[12:15]
	v_mfma_f32_16x16x32_bf16 v[16:19], v[36:39], v[116:119], v[16:19]
	v_mfma_f32_16x16x32_bf16 v[20:23], v[36:39], v[124:127], v[20:23]
	v_mfma_f32_16x16x32_bf16 v[24:27], v[36:39], v[132:135], v[24:27]
	v_mfma_f32_16x16x32_bf16 v[28:31], v[36:39], v[228:231], v[28:31]
	s_nop 3
	ds_write2_b32 v237, v0, v4 offset0:0 offset1:16
	ds_write2_b32 v237, v8, v12 offset0:32 offset1:48
	ds_write2_b32 v237, v1, v5 offset0:64 offset1:80
	ds_write2_b32 v237, v9, v13 offset0:96 offset1:112
	ds_write2_b32 v237, v2, v6 offset0:128 offset1:144
	ds_write2_b32 v237, v10, v14 offset0:160 offset1:176
	ds_write2_b32 v237, v3, v7 offset0:192 offset1:208
	ds_write2_b32 v237, v11, v15 offset0:224 offset1:240
	ds_write2_b32 v238, v16, v20 offset0:0 offset1:16
	ds_write2_b32 v238, v24, v28 offset0:32 offset1:48
	ds_write2_b32 v238, v17, v21 offset0:64 offset1:80
	ds_write2_b32 v238, v25, v29 offset0:96 offset1:112
	ds_write2_b32 v238, v18, v22 offset0:128 offset1:144
	ds_write2_b32 v238, v26, v30 offset0:160 offset1:176
	ds_write2_b32 v238, v19, v23 offset0:192 offset1:208
	ds_write2_b32 v238, v27, v31 offset0:224 offset1:240
	s_waitcnt lgkmcnt(0)
	ds_read2st64_b32 v[0:1], v239 offset0:36 offset1:37
	ds_read2st64_b32 v[2:3], v239 offset0:38 offset1:39
	ds_read2st64_b32 v[4:5], v239 offset0:40 offset1:41
	ds_read2st64_b32 v[6:7], v239 offset0:42 offset1:43
	ds_read2st64_b32 v[8:9], v239 offset0:44 offset1:45
	ds_read2st64_b32 v[10:11], v239 offset0:46 offset1:47
	ds_read2st64_b32 v[12:13], v239 offset0:48 offset1:49
	ds_read2st64_b32 v[14:15], v239 offset0:50 offset1:51
	ds_read2st64_b32 v[16:17], v239 offset0:52 offset1:53
	ds_read2st64_b32 v[18:19], v239 offset0:54 offset1:55
	ds_read2st64_b32 v[20:21], v239 offset0:56 offset1:57
	ds_read2st64_b32 v[22:23], v239 offset0:58 offset1:59
	ds_read2st64_b32 v[24:25], v239 offset0:60 offset1:61
	ds_read2st64_b32 v[26:27], v239 offset0:62 offset1:63
	ds_read2st64_b32 v[28:29], v239 offset0:64 offset1:65
	ds_read2st64_b32 v[30:31], v239 offset0:66 offset1:67
	ds_read_u16 v48, v240 offset:2304
	ds_read_u16 v49, v240 offset:2448
	ds_read_u16 v50, v240 offset:2592
	ds_read_u16 v51, v240 offset:2736
	ds_read_u16 v52, v240 offset:2880
	ds_read_u16 v53, v240 offset:3024
	ds_read_u16 v54, v240 offset:3168
	ds_read_u16 v55, v240 offset:3312
	ds_read_u16 v56, v240 offset:3456
	ds_read_u16 v57, v240 offset:3600
	ds_read_u16 v58, v240 offset:3744
	ds_read_u16 v59, v240 offset:3888
	ds_read_u16 v60, v240 offset:4032
	ds_read_u16 v61, v240 offset:4176
	ds_read_u16 v62, v240 offset:4320
	ds_read_u16 v63, v240 offset:4464
	s_waitcnt lgkmcnt(0)
	v_pk_fma_f32 v[0:1], v[0:1], v[248:249], v[242:243]
	v_pk_fma_f32 v[2:3], v[2:3], v[248:249], v[242:243]
	v_pk_fma_f32 v[4:5], v[4:5], v[248:249], v[242:243]
	v_pk_fma_f32 v[6:7], v[6:7], v[248:249], v[242:243]
	v_pk_fma_f32 v[8:9], v[8:9], v[248:249], v[242:243]
	v_pk_fma_f32 v[10:11], v[10:11], v[248:249], v[242:243]
	v_pk_fma_f32 v[12:13], v[12:13], v[248:249], v[242:243]
	v_pk_fma_f32 v[14:15], v[14:15], v[248:249], v[242:243]
	v_pk_fma_f32 v[16:17], v[16:17], v[248:249], v[244:245]
	v_pk_fma_f32 v[18:19], v[18:19], v[248:249], v[244:245]
	v_pk_fma_f32 v[20:21], v[20:21], v[248:249], v[244:245]
	v_pk_fma_f32 v[22:23], v[22:23], v[248:249], v[244:245]
	v_pk_fma_f32 v[24:25], v[24:25], v[248:249], v[244:245]
	v_pk_fma_f32 v[26:27], v[26:27], v[248:249], v[244:245]
	v_pk_fma_f32 v[28:29], v[28:29], v[248:249], v[244:245]
	v_pk_fma_f32 v[30:31], v[30:31], v[248:249], v[244:245]
	v_exp_f32_e32 v0, v0
	v_exp_f32_e32 v1, v1
	v_exp_f32_e32 v2, v2
	v_exp_f32_e32 v3, v3
	v_exp_f32_e32 v4, v4
	v_exp_f32_e32 v5, v5
	v_exp_f32_e32 v6, v6
	v_exp_f32_e32 v7, v7
	v_exp_f32_e32 v8, v8
	v_exp_f32_e32 v9, v9
	v_exp_f32_e32 v10, v10
	v_exp_f32_e32 v11, v11
	v_exp_f32_e32 v12, v12
	v_exp_f32_e32 v13, v13
	v_exp_f32_e32 v14, v14
	v_exp_f32_e32 v15, v15
	v_exp_f32_e32 v16, v16
	v_exp_f32_e32 v17, v17
	v_exp_f32_e32 v18, v18
	v_exp_f32_e32 v19, v19
	v_exp_f32_e32 v20, v20
	v_exp_f32_e32 v21, v21
	v_exp_f32_e32 v22, v22
	v_exp_f32_e32 v23, v23
	v_exp_f32_e32 v24, v24
	v_exp_f32_e32 v25, v25
	v_exp_f32_e32 v26, v26
	v_exp_f32_e32 v27, v27
	v_exp_f32_e32 v28, v28
	v_exp_f32_e32 v29, v29
	v_exp_f32_e32 v30, v30
	v_exp_f32_e32 v31, v31
	v_pk_add_f32 v[0:1], v[0:1], 1.0 op_sel_hi:[1,0]
	v_pk_add_f32 v[2:3], v[2:3], 1.0 op_sel_hi:[1,0]
	v_pk_add_f32 v[4:5], v[4:5], 1.0 op_sel_hi:[1,0]
	v_pk_add_f32 v[6:7], v[6:7], 1.0 op_sel_hi:[1,0]
	v_pk_add_f32 v[8:9], v[8:9], 1.0 op_sel_hi:[1,0]
	v_pk_add_f32 v[10:11], v[10:11], 1.0 op_sel_hi:[1,0]
	v_pk_add_f32 v[12:13], v[12:13], 1.0 op_sel_hi:[1,0]
	v_pk_add_f32 v[14:15], v[14:15], 1.0 op_sel_hi:[1,0]
	v_pk_add_f32 v[16:17], v[16:17], 1.0 op_sel_hi:[1,0]
	v_pk_add_f32 v[18:19], v[18:19], 1.0 op_sel_hi:[1,0]
	v_pk_add_f32 v[20:21], v[20:21], 1.0 op_sel_hi:[1,0]
	v_pk_add_f32 v[22:23], v[22:23], 1.0 op_sel_hi:[1,0]
	v_pk_add_f32 v[24:25], v[24:25], 1.0 op_sel_hi:[1,0]
; __device__ __forceinline__ unsigned f2bf(float f) { unsigned r; asm("v_cvt_pk_bf16_f32 %0, %1, %1" : "=v"(r) : "v"(f)); return r & 0xffffu; }
; __device__ __forceinline__ float sigmoid_f(float x) { return rcpf_(1.f + __expf(-x)); }
; __device__ __forceinline__ float gelu_tanh_f(float x) { const float y = 0.7978845608028654f * (x + 0.044715f * x * x * x); return x * sigmoid_f(2.f * y); }
; template <bool FINAL, int D>
; __device__ __forceinline__ void rg_dir(PREF p, int l, int h, int ch, int sidx, int rowbase  , LAS bf16_t* sXc, LAS float* stg, int lane) {
;     ...
;         for (int ti = 0; ti < 16; ++ti) { const int tk = D ? 15 - ti : ti;
;             const float zr = stg[tk * 64 + lane] + ba, zi = stg[1024 + tk * 64 + lane] + bi;
;             const float r = sigmoid_f(zr), ig = sigmoid_f(zi);
;             const float a = __builtin_amdgcn_exp2f(r * sp8);
;             const float xc = bf2f(sXc[(mt * 16 + tk) * 72 + lane]);
;             av[ti] = a; iv[ti] = __builtin_amdgcn_sqrtf(fmaxf(1.f - a * a, 0.f)) * ig * xc;
;             if (FINAL && D == 1) grv[ti] = gelu_tanh_f(grv[ti]);
;         }
; #pragma unroll
;         for (int ti = 0; ti < 16; ++ti) { const int tk = D ? 15 - ti : ti;
;             hc = av[ti] * hc + iv[ti]; Ap *= av[ti];
;             if (FINAL) { const size_t row = (size_t)(rowbase + mt * 16 + tk);
;                 if (D == 0) TMP[row * 512 + ch] = (bf16_t)f2bf(hc);
;                 else MIX[row * DM + ch] = (bf16_t)f2bf(grv[ti] * (hfv[ti] + hc)); }
	v_pk_add_f32 v[26:27], v[26:27], 1.0 op_sel_hi:[1,0]
	v_pk_add_f32 v[28:29], v[28:29], 1.0 op_sel_hi:[1,0]
	v_pk_add_f32 v[30:31], v[30:31], 1.0 op_sel_hi:[1,0]
	v_rcp_f32_e32 v0, v0
	v_rcp_f32_e32 v1, v1
	v_rcp_f32_e32 v2, v2
	v_rcp_f32_e32 v3, v3
	v_rcp_f32_e32 v4, v4
	v_rcp_f32_e32 v5, v5
	v_rcp_f32_e32 v6, v6
	v_rcp_f32_e32 v7, v7
	v_rcp_f32_e32 v8, v8
	v_rcp_f32_e32 v9, v9
	v_rcp_f32_e32 v10, v10
	v_rcp_f32_e32 v11, v11
	v_rcp_f32_e32 v12, v12
	v_rcp_f32_e32 v13, v13
	v_rcp_f32_e32 v14, v14
	v_rcp_f32_e32 v15, v15
	v_rcp_f32_e32 v16, v16
	v_rcp_f32_e32 v17, v17
	v_rcp_f32_e32 v18, v18
	v_rcp_f32_e32 v19, v19
	v_rcp_f32_e32 v20, v20
	v_rcp_f32_e32 v21, v21
	v_rcp_f32_e32 v22, v22
	v_rcp_f32_e32 v23, v23
	v_rcp_f32_e32 v24, v24
	v_rcp_f32_e32 v25, v25
	v_rcp_f32_e32 v26, v26
	v_rcp_f32_e32 v27, v27
	v_rcp_f32_e32 v28, v28
	v_rcp_f32_e32 v29, v29
	v_rcp_f32_e32 v30, v30
	v_rcp_f32_e32 v31, v31
	v_pk_mul_f32 v[0:1], v[246:247], v[0:1]
	v_pk_mul_f32 v[2:3], v[246:247], v[2:3]
	v_pk_mul_f32 v[4:5], v[246:247], v[4:5]
	v_pk_mul_f32 v[6:7], v[246:247], v[6:7]
	v_pk_mul_f32 v[8:9], v[246:247], v[8:9]
	v_pk_mul_f32 v[10:11], v[246:247], v[10:11]
	v_pk_mul_f32 v[12:13], v[246:247], v[12:13]
	v_pk_mul_f32 v[14:15], v[246:247], v[14:15]
	v_lshlrev_b32_e32 v48, 16, v48
	v_lshlrev_b32_e32 v49, 16, v49
	v_lshlrev_b32_e32 v50, 16, v50
	v_lshlrev_b32_e32 v51, 16, v51
	v_lshlrev_b32_e32 v52, 16, v52
	v_lshlrev_b32_e32 v53, 16, v53
	v_lshlrev_b32_e32 v54, 16, v54
	v_lshlrev_b32_e32 v55, 16, v55
	v_lshlrev_b32_e32 v56, 16, v56
	v_lshlrev_b32_e32 v57, 16, v57
	v_lshlrev_b32_e32 v58, 16, v58
	v_lshlrev_b32_e32 v59, 16, v59
	v_lshlrev_b32_e32 v60, 16, v60
	v_lshlrev_b32_e32 v61, 16, v61
	v_lshlrev_b32_e32 v62, 16, v62
	v_lshlrev_b32_e32 v63, 16, v63
	v_exp_f32_e32 v0, v0
	v_exp_f32_e32 v1, v1
	v_exp_f32_e32 v2, v2
	v_exp_f32_e32 v3, v3
	v_exp_f32_e32 v4, v4
	v_exp_f32_e32 v5, v5
	v_exp_f32_e32 v6, v6
	v_exp_f32_e32 v7, v7
	v_exp_f32_e32 v8, v8
	v_exp_f32_e32 v9, v9
	v_exp_f32_e32 v10, v10
	v_exp_f32_e32 v11, v11
	v_exp_f32_e32 v12, v12
	v_exp_f32_e32 v13, v13
	v_exp_f32_e32 v14, v14
	v_exp_f32_e32 v15, v15
	v_fma_f32 v32, -v0, v0, 1.0
	v_fma_f32 v33, -v1, v1, 1.0
	v_fma_f32 v34, -v2, v2, 1.0
	v_fma_f32 v35, -v3, v3, 1.0
	v_fma_f32 v36, -v4, v4, 1.0
	v_fma_f32 v37, -v5, v5, 1.0
	v_fma_f32 v38, -v6, v6, 1.0
	v_fma_f32 v39, -v7, v7, 1.0
	v_fma_f32 v40, -v8, v8, 1.0
	v_fma_f32 v41, -v9, v9, 1.0
	v_fma_f32 v42, -v10, v10, 1.0
	v_fma_f32 v43, -v11, v11, 1.0
	v_fma_f32 v44, -v12, v12, 1.0
	v_fma_f32 v45, -v13, v13, 1.0
	v_fma_f32 v46, -v14, v14, 1.0
	v_fma_f32 v47, -v15, v15, 1.0
	v_max_f32_e32 v32, 0, v32
	v_max_f32_e32 v33, 0, v33
	v_max_f32_e32 v34, 0, v34
	v_max_f32_e32 v35, 0, v35
	v_max_f32_e32 v36, 0, v36
	v_max_f32_e32 v37, 0, v37
	v_max_f32_e32 v38, 0, v38
	v_max_f32_e32 v39, 0, v39
	v_max_f32_e32 v40, 0, v40
	v_max_f32_e32 v41, 0, v41
	v_max_f32_e32 v42, 0, v42
	v_max_f32_e32 v43, 0, v43
	v_max_f32_e32 v44, 0, v44
	v_max_f32_e32 v45, 0, v45
	v_max_f32_e32 v46, 0, v46
	v_max_f32_e32 v47, 0, v47
	v_sqrt_f32_e32 v32, v32
	v_sqrt_f32_e32 v33, v33
	v_sqrt_f32_e32 v34, v34
	v_sqrt_f32_e32 v35, v35
	v_sqrt_f32_e32 v36, v36
	v_sqrt_f32_e32 v37, v37
	v_sqrt_f32_e32 v38, v38
	v_sqrt_f32_e32 v39, v39
	v_sqrt_f32_e32 v40, v40
	v_sqrt_f32_e32 v41, v41
	v_sqrt_f32_e32 v42, v42
	v_sqrt_f32_e32 v43, v43
	v_sqrt_f32_e32 v44, v44
	v_sqrt_f32_e32 v45, v45
	v_sqrt_f32_e32 v46, v46
	v_sqrt_f32_e32 v47, v47
	s_nop 0
	v_pk_mul_f32 v[16:17], v[16:17], v[32:33]
	v_pk_mul_f32 v[18:19], v[18:19], v[34:35]
	v_pk_mul_f32 v[20:21], v[20:21], v[36:37]
	v_pk_mul_f32 v[22:23], v[22:23], v[38:39]
	v_pk_mul_f32 v[24:25], v[24:25], v[40:41]
	v_pk_mul_f32 v[26:27], v[26:27], v[42:43]
	v_pk_mul_f32 v[28:29], v[28:29], v[44:45]
	v_pk_mul_f32 v[30:31], v[30:31], v[46:47]
	v_pk_mul_f32 v[16:17], v[16:17], v[48:49]
	v_pk_mul_f32 v[18:19], v[18:19], v[50:51]
	v_pk_mul_f32 v[20:21], v[20:21], v[52:53]
	v_pk_mul_f32 v[22:23], v[22:23], v[54:55]
	v_pk_mul_f32 v[24:25], v[24:25], v[56:57]
	v_pk_mul_f32 v[26:27], v[26:27], v[58:59]
	v_pk_mul_f32 v[28:29], v[28:29], v[60:61]
	v_pk_mul_f32 v[30:31], v[30:31], v[62:63]
	v_fma_f32 v32, v0, v250, v16
	v_fma_f32 v250, v1, v32, v17
	v_cvt_pk_bf16_f32 v166, v32, v250
	v_fma_f32 v32, v2, v250, v18
	v_fma_f32 v250, v3, v32, v19
	v_cvt_pk_bf16_f32 v167, v32, v250
	v_fma_f32 v32, v4, v250, v20
	v_fma_f32 v250, v5, v32, v21
	v_cvt_pk_bf16_f32 v168, v32, v250
	v_fma_f32 v32, v6, v250, v22
	v_fma_f32 v250, v7, v32, v23
	v_cvt_pk_bf16_f32 v169, v32, v250
	v_fma_f32 v32, v8, v250, v24
	v_fma_f32 v250, v9, v32, v25
	v_cvt_pk_bf16_f32 v170, v32, v250
	v_fma_f32 v32, v10, v250, v26
	v_fma_f32 v250, v11, v32, v27
	v_cvt_pk_bf16_f32 v171, v32, v250
	v_fma_f32 v32, v12, v250, v28
	v_fma_f32 v250, v13, v32, v29
	v_cvt_pk_bf16_f32 v172, v32, v250
	v_fma_f32 v32, v14, v250, v30
	v_fma_f32 v250, v15, v32, v31
	v_cvt_pk_bf16_f32 v173, v32, v250
	ds_read_b128 v[32:35], v236 offset:4608
	ds_read_b128 v[36:39], v236 offset:4672
	s_waitcnt lgkmcnt(0)
; #define LAS __attribute__((address_space(3)))
; #define WAVE_SYNC() asm volatile("s_waitcnt lgkmcnt(0)" ::: "memory")
; __device__ __forceinline__ float sigmoid_f(float x) { return rcpf_(1.f + __expf(-x)); }
; __device__ __forceinline__ f32x4 mfma16(bf16x8 a, bf16x8 b, f32x4 c) { return __builtin_amdgcn_mfma_f32_16x16x32_bf16(a, b, c, 0, 0, 0); }
; template <bool FINAL, int D>
; __device__ __forceinline__ void rg_dir(PREF p, int l, int h, int ch, int sidx, int rowbase  , LAS bf16_t* sXc, LAS float* stg, int lane) {
;     ...
;         const bf16x8 A0 = *(const LAS bf16x8*)(sXc + (mt * 16 + (lane & 15)) * 72 + (lane >> 4) * 8), A1 = *(const LAS bf16x8*)(sXc + (mt * 16 + (lane & 15)) * 72 + 32 + (lane >> 4) * 8);
;         f32x4 ar[4], ai[4];
; #pragma unroll
;         for (int nt = 0; nt < 4; ++nt) { const f32x4 z = {0.f, 0.f, 0.f, 0.f};
;             ar[nt] = mfma16(A0, Br[nt][0], z); ar[nt] = mfma16(A1, Br[nt][1], ar[nt]); ai[nt] = mfma16(A0, Bi[nt][0], z); ai[nt] = mfma16(A1, Bi[nt][1], ai[nt]); }
;         WAVE_SYNC();
; #pragma unroll
;         for (int nt = 0; nt < 4; ++nt)
; #pragma unroll
;             for (int j = 0; j < 4; ++j) { const int o = ((lane >> 4) * 4 + j) * 64 + nt * 16 + (lane & 15); stg[o] = ar[nt][j]; stg[1024 + o] = ai[nt][j]; }
;         WAVE_SYNC();
;         float av[16], iv[16];
; #pragma unroll
;         for (int ti = 0; ti < 16; ++ti) { const int tk = D ? 15 - ti : ti;
;             const float zr = stg[tk * 64 + lane] + ba, zi = stg[1024 + tk * 64 + lane] + bi;
;             const float r = sigmoid_f(zr), ig = sigmoid_f(zi);
;             const float a = __builtin_amdgcn_exp2f(r * sp8);
;             const float xc = bf2f(sXc[(mt * 16 + tk) * 72 + lane]);
;             av[ti] = a; iv[ti] = __builtin_amdgcn_sqrtf(fmaxf(1.f - a * a, 0.f)) * ig * xc;
	v_mfma_f32_16x16x32_bf16 v[0:3], v[32:35], v[80:83], 0
	v_mfma_f32_16x16x32_bf16 v[4:7], v[32:35], v[88:91], 0
	v_mfma_f32_16x16x32_bf16 v[8:11], v[32:35], v[96:99], 0
	v_mfma_f32_16x16x32_bf16 v[12:15], v[32:35], v[104:107], 0
	v_mfma_f32_16x16x32_bf16 v[16:19], v[32:35], v[112:115], 0
	v_mfma_f32_16x16x32_bf16 v[20:23], v[32:35], v[120:123], 0
	v_mfma_f32_16x16x32_bf16 v[24:27], v[32:35], v[128:131], 0
	v_mfma_f32_16x16x32_bf16 v[28:31], v[32:35], v[136:139], 0
	v_mfma_f32_16x16x32_bf16 v[0:3], v[36:39], v[84:87], v[0:3]
	v_mfma_f32_16x16x32_bf16 v[4:7], v[36:39], v[92:95], v[4:7]
	v_mfma_f32_16x16x32_bf16 v[8:11], v[36:39], v[100:103], v[8:11]
	v_mfma_f32_16x16x32_bf16 v[12:15], v[36:39], v[108:111], v[12:15]
	v_mfma_f32_16x16x32_bf16 v[16:19], v[36:39], v[116:119], v[16:19]
	v_mfma_f32_16x16x32_bf16 v[20:23], v[36:39], v[124:127], v[20:23]
	v_mfma_f32_16x16x32_bf16 v[24:27], v[36:39], v[132:135], v[24:27]
	v_mfma_f32_16x16x32_bf16 v[28:31], v[36:39], v[228:231], v[28:31]
	s_nop 3
	ds_write2_b32 v237, v0, v4 offset0:0 offset1:16
	ds_write2_b32 v237, v8, v12 offset0:32 offset1:48
	ds_write2_b32 v237, v1, v5 offset0:64 offset1:80
	ds_write2_b32 v237, v9, v13 offset0:96 offset1:112
	ds_write2_b32 v237, v2, v6 offset0:128 offset1:144
	ds_write2_b32 v237, v10, v14 offset0:160 offset1:176
	ds_write2_b32 v237, v3, v7 offset0:192 offset1:208
	ds_write2_b32 v237, v11, v15 offset0:224 offset1:240
	ds_write2_b32 v238, v16, v20 offset0:0 offset1:16
	ds_write2_b32 v238, v24, v28 offset0:32 offset1:48
	ds_write2_b32 v238, v17, v21 offset0:64 offset1:80
	ds_write2_b32 v238, v25, v29 offset0:96 offset1:112
	ds_write2_b32 v238, v18, v22 offset0:128 offset1:144
	ds_write2_b32 v238, v26, v30 offset0:160 offset1:176
	ds_write2_b32 v238, v19, v23 offset0:192 offset1:208
	ds_write2_b32 v238, v27, v31 offset0:224 offset1:240
	s_waitcnt lgkmcnt(0)
	ds_read2st64_b32 v[0:1], v239 offset0:36 offset1:37
	ds_read2st64_b32 v[2:3], v239 offset0:38 offset1:39
	ds_read2st64_b32 v[4:5], v239 offset0:40 offset1:41
	ds_read2st64_b32 v[6:7], v239 offset0:42 offset1:43
	ds_read2st64_b32 v[8:9], v239 offset0:44 offset1:45
	ds_read2st64_b32 v[10:11], v239 offset0:46 offset1:47
	ds_read2st64_b32 v[12:13], v239 offset0:48 offset1:49
	ds_read2st64_b32 v[14:15], v239 offset0:50 offset1:51
	ds_read2st64_b32 v[16:17], v239 offset0:52 offset1:53
	ds_read2st64_b32 v[18:19], v239 offset0:54 offset1:55
	ds_read2st64_b32 v[20:21], v239 offset0:56 offset1:57
	ds_read2st64_b32 v[22:23], v239 offset0:58 offset1:59
	ds_read2st64_b32 v[24:25], v239 offset0:60 offset1:61
	ds_read2st64_b32 v[26:27], v239 offset0:62 offset1:63
	ds_read2st64_b32 v[28:29], v239 offset0:64 offset1:65
	ds_read2st64_b32 v[30:31], v239 offset0:66 offset1:67
	ds_read_u16 v48, v240 offset:4608
	ds_read_u16 v49, v240 offset:4752
	ds_read_u16 v50, v240 offset:4896
	ds_read_u16 v51, v240 offset:5040
	ds_read_u16 v52, v240 offset:5184
	ds_read_u16 v53, v240 offset:5328
	ds_read_u16 v54, v240 offset:5472
	ds_read_u16 v55, v240 offset:5616
	ds_read_u16 v56, v240 offset:5760
	ds_read_u16 v57, v240 offset:5904
	ds_read_u16 v58, v240 offset:6048
	ds_read_u16 v59, v240 offset:6192
	ds_read_u16 v60, v240 offset:6336
	ds_read_u16 v61, v240 offset:6480
	ds_read_u16 v62, v240 offset:6624
	ds_read_u16 v63, v240 offset:6768
	s_waitcnt lgkmcnt(0)
	v_pk_fma_f32 v[0:1], v[0:1], v[248:249], v[242:243]
	v_pk_fma_f32 v[2:3], v[2:3], v[248:249], v[242:243]
	v_pk_fma_f32 v[4:5], v[4:5], v[248:249], v[242:243]
	v_pk_fma_f32 v[6:7], v[6:7], v[248:249], v[242:243]
	v_pk_fma_f32 v[8:9], v[8:9], v[248:249], v[242:243]
	v_pk_fma_f32 v[10:11], v[10:11], v[248:249], v[242:243]
	v_pk_fma_f32 v[12:13], v[12:13], v[248:249], v[242:243]
	v_pk_fma_f32 v[14:15], v[14:15], v[248:249], v[242:243]
	v_pk_fma_f32 v[16:17], v[16:17], v[248:249], v[244:245]
	v_pk_fma_f32 v[18:19], v[18:19], v[248:249], v[244:245]
	v_pk_fma_f32 v[20:21], v[20:21], v[248:249], v[244:245]
	v_pk_fma_f32 v[22:23], v[22:23], v[248:249], v[244:245]
	v_pk_fma_f32 v[24:25], v[24:25], v[248:249], v[244:245]
	v_pk_fma_f32 v[26:27], v[26:27], v[248:249], v[244:245]
	v_pk_fma_f32 v[28:29], v[28:29], v[248:249], v[244:245]
	v_pk_fma_f32 v[30:31], v[30:31], v[248:249], v[244:245]
	v_exp_f32_e32 v0, v0
	v_exp_f32_e32 v1, v1
	v_exp_f32_e32 v2, v2
	v_exp_f32_e32 v3, v3
	v_exp_f32_e32 v4, v4
	v_exp_f32_e32 v5, v5
	v_exp_f32_e32 v6, v6
	v_exp_f32_e32 v7, v7
	v_exp_f32_e32 v8, v8
	v_exp_f32_e32 v9, v9
	v_exp_f32_e32 v10, v10
	v_exp_f32_e32 v11, v11
	v_exp_f32_e32 v12, v12
	v_exp_f32_e32 v13, v13
	v_exp_f32_e32 v14, v14
	v_exp_f32_e32 v15, v15
	v_exp_f32_e32 v16, v16
	v_exp_f32_e32 v17, v17
	v_exp_f32_e32 v18, v18
	v_exp_f32_e32 v19, v19
	v_exp_f32_e32 v20, v20
	v_exp_f32_e32 v21, v21
	v_exp_f32_e32 v22, v22
	v_exp_f32_e32 v23, v23
	v_exp_f32_e32 v24, v24
	v_exp_f32_e32 v25, v25
	v_exp_f32_e32 v26, v26
	v_exp_f32_e32 v27, v27
	v_exp_f32_e32 v28, v28
	v_exp_f32_e32 v29, v29
	v_exp_f32_e32 v30, v30
	v_exp_f32_e32 v31, v31
	v_pk_add_f32 v[0:1], v[0:1], 1.0 op_sel_hi:[1,0]
	v_pk_add_f32 v[2:3], v[2:3], 1.0 op_sel_hi:[1,0]
	v_pk_add_f32 v[4:5], v[4:5], 1.0 op_sel_hi:[1,0]
	v_pk_add_f32 v[6:7], v[6:7], 1.0 op_sel_hi:[1,0]
	v_pk_add_f32 v[8:9], v[8:9], 1.0 op_sel_hi:[1,0]
	v_pk_add_f32 v[10:11], v[10:11], 1.0 op_sel_hi:[1,0]
	v_pk_add_f32 v[12:13], v[12:13], 1.0 op_sel_hi:[1,0]
	v_pk_add_f32 v[14:15], v[14:15], 1.0 op_sel_hi:[1,0]
	v_pk_add_f32 v[16:17], v[16:17], 1.0 op_sel_hi:[1,0]
	v_pk_add_f32 v[18:19], v[18:19], 1.0 op_sel_hi:[1,0]
	v_pk_add_f32 v[20:21], v[20:21], 1.0 op_sel_hi:[1,0]
	v_pk_add_f32 v[22:23], v[22:23], 1.0 op_sel_hi:[1,0]
	v_pk_add_f32 v[24:25], v[24:25], 1.0 op_sel_hi:[1,0]
; __device__ __forceinline__ unsigned f2bf(float f) { unsigned r; asm("v_cvt_pk_bf16_f32 %0, %1, %1" : "=v"(r) : "v"(f)); return r & 0xffffu; }
; __device__ __forceinline__ float sigmoid_f(float x) { return rcpf_(1.f + __expf(-x)); }
; __device__ __forceinline__ float gelu_tanh_f(float x) { const float y = 0.7978845608028654f * (x + 0.044715f * x * x * x); return x * sigmoid_f(2.f * y); }
; template <bool FINAL, int D>
; __device__ __forceinline__ void rg_dir(PREF p, int l, int h, int ch, int sidx, int rowbase  , LAS bf16_t* sXc, LAS float* stg, int lane) {
;     ...
;         for (int ti = 0; ti < 16; ++ti) { const int tk = D ? 15 - ti : ti;
;             const float zr = stg[tk * 64 + lane] + ba, zi = stg[1024 + tk * 64 + lane] + bi;
;             const float r = sigmoid_f(zr), ig = sigmoid_f(zi);
;             const float a = __builtin_amdgcn_exp2f(r * sp8);
;             const float xc = bf2f(sXc[(mt * 16 + tk) * 72 + lane]);
;             av[ti] = a; iv[ti] = __builtin_amdgcn_sqrtf(fmaxf(1.f - a * a, 0.f)) * ig * xc;
;             if (FINAL && D == 1) grv[ti] = gelu_tanh_f(grv[ti]);
;         }
; #pragma unroll
;         for (int ti = 0; ti < 16; ++ti) { const int tk = D ? 15 - ti : ti;
;             hc = av[ti] * hc + iv[ti]; Ap *= av[ti];
;             if (FINAL) { const size_t row = (size_t)(rowbase + mt * 16 + tk);
;                 if (D == 0) TMP[row * 512 + ch] = (bf16_t)f2bf(hc);
;                 else MIX[row * DM + ch] = (bf16_t)f2bf(grv[ti] * (hfv[ti] + hc)); }
	v_pk_add_f32 v[26:27], v[26:27], 1.0 op_sel_hi:[1,0]
	v_pk_add_f32 v[28:29], v[28:29], 1.0 op_sel_hi:[1,0]
	v_pk_add_f32 v[30:31], v[30:31], 1.0 op_sel_hi:[1,0]
	v_rcp_f32_e32 v0, v0
	v_rcp_f32_e32 v1, v1
	v_rcp_f32_e32 v2, v2
	v_rcp_f32_e32 v3, v3
	v_rcp_f32_e32 v4, v4
	v_rcp_f32_e32 v5, v5
	v_rcp_f32_e32 v6, v6
	v_rcp_f32_e32 v7, v7
	v_rcp_f32_e32 v8, v8
	v_rcp_f32_e32 v9, v9
	v_rcp_f32_e32 v10, v10
	v_rcp_f32_e32 v11, v11
	v_rcp_f32_e32 v12, v12
	v_rcp_f32_e32 v13, v13
	v_rcp_f32_e32 v14, v14
	v_rcp_f32_e32 v15, v15
	v_rcp_f32_e32 v16, v16
	v_rcp_f32_e32 v17, v17
	v_rcp_f32_e32 v18, v18
	v_rcp_f32_e32 v19, v19
	v_rcp_f32_e32 v20, v20
	v_rcp_f32_e32 v21, v21
	v_rcp_f32_e32 v22, v22
	v_rcp_f32_e32 v23, v23
	v_rcp_f32_e32 v24, v24
	v_rcp_f32_e32 v25, v25
	v_rcp_f32_e32 v26, v26
	v_rcp_f32_e32 v27, v27
	v_rcp_f32_e32 v28, v28
	v_rcp_f32_e32 v29, v29
	v_rcp_f32_e32 v30, v30
	v_rcp_f32_e32 v31, v31
	v_pk_mul_f32 v[0:1], v[246:247], v[0:1]
	v_pk_mul_f32 v[2:3], v[246:247], v[2:3]
	v_pk_mul_f32 v[4:5], v[246:247], v[4:5]
	v_pk_mul_f32 v[6:7], v[246:247], v[6:7]
	v_pk_mul_f32 v[8:9], v[246:247], v[8:9]
	v_pk_mul_f32 v[10:11], v[246:247], v[10:11]
	v_pk_mul_f32 v[12:13], v[246:247], v[12:13]
	v_pk_mul_f32 v[14:15], v[246:247], v[14:15]
	v_lshlrev_b32_e32 v48, 16, v48
	v_lshlrev_b32_e32 v49, 16, v49
	v_lshlrev_b32_e32 v50, 16, v50
	v_lshlrev_b32_e32 v51, 16, v51
	v_lshlrev_b32_e32 v52, 16, v52
	v_lshlrev_b32_e32 v53, 16, v53
	v_lshlrev_b32_e32 v54, 16, v54
	v_lshlrev_b32_e32 v55, 16, v55
	v_lshlrev_b32_e32 v56, 16, v56
	v_lshlrev_b32_e32 v57, 16, v57
	v_lshlrev_b32_e32 v58, 16, v58
	v_lshlrev_b32_e32 v59, 16, v59
	v_lshlrev_b32_e32 v60, 16, v60
	v_lshlrev_b32_e32 v61, 16, v61
	v_lshlrev_b32_e32 v62, 16, v62
	v_lshlrev_b32_e32 v63, 16, v63
	v_exp_f32_e32 v0, v0
	v_exp_f32_e32 v1, v1
	v_exp_f32_e32 v2, v2
	v_exp_f32_e32 v3, v3
	v_exp_f32_e32 v4, v4
	v_exp_f32_e32 v5, v5
	v_exp_f32_e32 v6, v6
	v_exp_f32_e32 v7, v7
	v_exp_f32_e32 v8, v8
	v_exp_f32_e32 v9, v9
	v_exp_f32_e32 v10, v10
	v_exp_f32_e32 v11, v11
	v_exp_f32_e32 v12, v12
	v_exp_f32_e32 v13, v13
	v_exp_f32_e32 v14, v14
	v_exp_f32_e32 v15, v15
	v_fma_f32 v32, -v0, v0, 1.0
	v_fma_f32 v33, -v1, v1, 1.0
	v_fma_f32 v34, -v2, v2, 1.0
	v_fma_f32 v35, -v3, v3, 1.0
	v_fma_f32 v36, -v4, v4, 1.0
	v_fma_f32 v37, -v5, v5, 1.0
	v_fma_f32 v38, -v6, v6, 1.0
	v_fma_f32 v39, -v7, v7, 1.0
	v_fma_f32 v40, -v8, v8, 1.0
	v_fma_f32 v41, -v9, v9, 1.0
	v_fma_f32 v42, -v10, v10, 1.0
	v_fma_f32 v43, -v11, v11, 1.0
	v_fma_f32 v44, -v12, v12, 1.0
	v_fma_f32 v45, -v13, v13, 1.0
	v_fma_f32 v46, -v14, v14, 1.0
	v_fma_f32 v47, -v15, v15, 1.0
	v_max_f32_e32 v32, 0, v32
	v_max_f32_e32 v33, 0, v33
	v_max_f32_e32 v34, 0, v34
	v_max_f32_e32 v35, 0, v35
	v_max_f32_e32 v36, 0, v36
	v_max_f32_e32 v37, 0, v37
	v_max_f32_e32 v38, 0, v38
	v_max_f32_e32 v39, 0, v39
	v_max_f32_e32 v40, 0, v40
	v_max_f32_e32 v41, 0, v41
	v_max_f32_e32 v42, 0, v42
	v_max_f32_e32 v43, 0, v43
	v_max_f32_e32 v44, 0, v44
	v_max_f32_e32 v45, 0, v45
	v_max_f32_e32 v46, 0, v46
	v_max_f32_e32 v47, 0, v47
	v_sqrt_f32_e32 v32, v32
	v_sqrt_f32_e32 v33, v33
	v_sqrt_f32_e32 v34, v34
	v_sqrt_f32_e32 v35, v35
	v_sqrt_f32_e32 v36, v36
	v_sqrt_f32_e32 v37, v37
	v_sqrt_f32_e32 v38, v38
	v_sqrt_f32_e32 v39, v39
	v_sqrt_f32_e32 v40, v40
	v_sqrt_f32_e32 v41, v41
	v_sqrt_f32_e32 v42, v42
	v_sqrt_f32_e32 v43, v43
	v_sqrt_f32_e32 v44, v44
	v_sqrt_f32_e32 v45, v45
	v_sqrt_f32_e32 v46, v46
	v_sqrt_f32_e32 v47, v47
	s_nop 0
	v_pk_mul_f32 v[16:17], v[16:17], v[32:33]
	v_pk_mul_f32 v[18:19], v[18:19], v[34:35]
	v_pk_mul_f32 v[20:21], v[20:21], v[36:37]
	v_pk_mul_f32 v[22:23], v[22:23], v[38:39]
	v_pk_mul_f32 v[24:25], v[24:25], v[40:41]
	v_pk_mul_f32 v[26:27], v[26:27], v[42:43]
	v_pk_mul_f32 v[28:29], v[28:29], v[44:45]
	v_pk_mul_f32 v[30:31], v[30:31], v[46:47]
	v_pk_mul_f32 v[16:17], v[16:17], v[48:49]
	v_pk_mul_f32 v[18:19], v[18:19], v[50:51]
	v_pk_mul_f32 v[20:21], v[20:21], v[52:53]
	v_pk_mul_f32 v[22:23], v[22:23], v[54:55]
	v_pk_mul_f32 v[24:25], v[24:25], v[56:57]
	v_pk_mul_f32 v[26:27], v[26:27], v[58:59]
	v_pk_mul_f32 v[28:29], v[28:29], v[60:61]
	v_pk_mul_f32 v[30:31], v[30:31], v[62:63]
	v_fma_f32 v32, v0, v250, v16
	v_fma_f32 v250, v1, v32, v17
	v_cvt_pk_bf16_f32 v174, v32, v250
	v_fma_f32 v32, v2, v250, v18
	v_fma_f32 v250, v3, v32, v19
	v_cvt_pk_bf16_f32 v175, v32, v250
	v_fma_f32 v32, v4, v250, v20
	v_fma_f32 v250, v5, v32, v21
	v_cvt_pk_bf16_f32 v176, v32, v250
	v_fma_f32 v32, v6, v250, v22
	v_fma_f32 v250, v7, v32, v23
	v_cvt_pk_bf16_f32 v177, v32, v250
	v_fma_f32 v32, v8, v250, v24
	v_fma_f32 v250, v9, v32, v25
	v_cvt_pk_bf16_f32 v178, v32, v250
	v_fma_f32 v32, v10, v250, v26
	v_fma_f32 v250, v11, v32, v27
	v_cvt_pk_bf16_f32 v179, v32, v250
	v_fma_f32 v32, v12, v250, v28
	v_fma_f32 v250, v13, v32, v29
	v_cvt_pk_bf16_f32 v180, v32, v250
	v_fma_f32 v32, v14, v250, v30
	v_fma_f32 v250, v15, v32, v31
	v_cvt_pk_bf16_f32 v181, v32, v250
	ds_read_b128 v[32:35], v236 offset:6912
	ds_read_b128 v[36:39], v236 offset:6976
	s_waitcnt lgkmcnt(0)
; #define LAS __attribute__((address_space(3)))
; #define WAVE_SYNC() asm volatile("s_waitcnt lgkmcnt(0)" ::: "memory")
; __device__ __forceinline__ f32x4 mfma16(bf16x8 a, bf16x8 b, f32x4 c) { return __builtin_amdgcn_mfma_f32_16x16x32_bf16(a, b, c, 0, 0, 0); }
; template <bool FINAL, int D>
; __device__ __forceinline__ void rg_dir(PREF p, int l, int h, int ch, int sidx, int rowbase  , LAS bf16_t* sXc, LAS float* stg, int lane) {
;     ...
;     for (int nt = 0; nt < 4; ++nt) { const int o0 = (nt * 16 + (lane & 15)) * 64 + (lane >> 4) * 8;
;         Br[nt][0] = *(const bf16x8*)(wr_ + o0); Br[nt][1] = *(const bf16x8*)(wr_ + o0 + 32); Bi[nt][0] = *(const bf16x8*)(wi_ + o0); Bi[nt][1] = *(const bf16x8*)(wi_ + o0 + 32); }
;     ...
;         const bf16x8 A0 = *(const LAS bf16x8*)(sXc + (mt * 16 + (lane & 15)) * 72 + (lane >> 4) * 8), A1 = *(const LAS bf16x8*)(sXc + (mt * 16 + (lane & 15)) * 72 + 32 + (lane >> 4) * 8);
;         f32x4 ar[4], ai[4];
; #pragma unroll
;         for (int nt = 0; nt < 4; ++nt) { const f32x4 z = {0.f, 0.f, 0.f, 0.f};
;             ar[nt] = mfma16(A0, Br[nt][0], z); ar[nt] = mfma16(A1, Br[nt][1], ar[nt]); ai[nt] = mfma16(A0, Bi[nt][0], z); ai[nt] = mfma16(A1, Bi[nt][1], ai[nt]); }
;         WAVE_SYNC();
; #pragma unroll
;         for (int nt = 0; nt < 4; ++nt)
; #pragma unroll
;             for (int j = 0; j < 4; ++j) { const int o = ((lane >> 4) * 4 + j) * 64 + nt * 16 + (lane & 15); stg[o] = ar[nt][j]; stg[1024 + o] = ai[nt][j]; }
;         WAVE_SYNC();
	v_mfma_f32_16x16x32_bf16 v[0:3], v[32:35], v[80:83], 0
	v_mfma_f32_16x16x32_bf16 v[4:7], v[32:35], v[88:91], 0
	v_mfma_f32_16x16x32_bf16 v[8:11], v[32:35], v[96:99], 0
	v_mfma_f32_16x16x32_bf16 v[12:15], v[32:35], v[104:107], 0
	v_mfma_f32_16x16x32_bf16 v[16:19], v[32:35], v[112:115], 0
	v_mfma_f32_16x16x32_bf16 v[20:23], v[32:35], v[120:123], 0
	v_mfma_f32_16x16x32_bf16 v[24:27], v[32:35], v[128:131], 0
	v_mfma_f32_16x16x32_bf16 v[28:31], v[32:35], v[136:139], 0
	v_mfma_f32_16x16x32_bf16 v[0:3], v[36:39], v[84:87], v[0:3]
	v_mfma_f32_16x16x32_bf16 v[4:7], v[36:39], v[92:95], v[4:7]
	v_mfma_f32_16x16x32_bf16 v[8:11], v[36:39], v[100:103], v[8:11]
	v_mfma_f32_16x16x32_bf16 v[12:15], v[36:39], v[108:111], v[12:15]
	v_mfma_f32_16x16x32_bf16 v[16:19], v[36:39], v[116:119], v[16:19]
	v_mfma_f32_16x16x32_bf16 v[20:23], v[36:39], v[124:127], v[20:23]
	v_mfma_f32_16x16x32_bf16 v[24:27], v[36:39], v[132:135], v[24:27]
	v_mfma_f32_16x16x32_bf16 v[28:31], v[36:39], v[228:231], v[28:31]
	s_nop 3
	ds_write2_b32 v237, v0, v4 offset0:0 offset1:16
	ds_write2_b32 v237, v8, v12 offset0:32 offset1:48
	ds_write2_b32 v237, v1, v5 offset0:64 offset1:80
	ds_write2_b32 v237, v9, v13 offset0:96 offset1:112
	ds_write2_b32 v237, v2, v6 offset0:128 offset1:144
	ds_write2_b32 v237, v10, v14 offset0:160 offset1:176
	ds_write2_b32 v237, v3, v7 offset0:192 offset1:208
	ds_write2_b32 v237, v11, v15 offset0:224 offset1:240
	ds_write2_b32 v238, v16, v20 offset0:0 offset1:16
	ds_write2_b32 v238, v24, v28 offset0:32 offset1:48
	ds_write2_b32 v238, v17, v21 offset0:64 offset1:80
	ds_write2_b32 v238, v25, v29 offset0:96 offset1:112
	ds_write2_b32 v238, v18, v22 offset0:128 offset1:144
	ds_write2_b32 v238, v26, v30 offset0:160 offset1:176
	ds_write2_b32 v238, v19, v23 offset0:192 offset1:208
	ds_write2_b32 v238, v27, v31 offset0:224 offset1:240
	s_waitcnt lgkmcnt(0)
	ds_read2st64_b32 v[0:1], v239 offset0:36 offset1:37
	ds_read2st64_b32 v[2:3], v239 offset0:38 offset1:39
	ds_read2st64_b32 v[4:5], v239 offset0:40 offset1:41
	ds_read2st64_b32 v[6:7], v239 offset0:42 offset1:43
	ds_read2st64_b32 v[8:9], v239 offset0:44 offset1:45
	ds_read2st64_b32 v[10:11], v239 offset0:46 offset1:47
	ds_read2st64_b32 v[12:13], v239 offset0:48 offset1:49
	ds_read2st64_b32 v[14:15], v239 offset0:50 offset1:51
	ds_read2st64_b32 v[16:17], v239 offset0:52 offset1:53
	ds_read2st64_b32 v[18:19], v239 offset0:54 offset1:55
	ds_read2st64_b32 v[20:21], v239 offset0:56 offset1:57
	ds_read2st64_b32 v[22:23], v239 offset0:58 offset1:59
	ds_read2st64_b32 v[24:25], v239 offset0:60 offset1:61
	ds_read2st64_b32 v[26:27], v239 offset0:62 offset1:63
	ds_read2st64_b32 v[28:29], v239 offset0:64 offset1:65
	ds_read2st64_b32 v[30:31], v239 offset0:66 offset1:67
	ds_read_u16 v48, v240 offset:6912
	ds_read_u16 v49, v240 offset:7056
	ds_read_u16 v50, v240 offset:7200
	ds_read_u16 v51, v240 offset:7344
	ds_read_u16 v52, v240 offset:7488
	ds_read_u16 v53, v240 offset:7632
	ds_read_u16 v54, v240 offset:7776
	ds_read_u16 v55, v240 offset:7920
	ds_read_u16 v56, v240 offset:8064
	ds_read_u16 v57, v240 offset:8208
	ds_read_u16 v58, v240 offset:8352
	ds_read_u16 v59, v240 offset:8496
	ds_read_u16 v60, v240 offset:8640
	ds_read_u16 v61, v240 offset:8784
	ds_read_u16 v62, v240 offset:8928
	ds_read_u16 v63, v240 offset:9072
	s_add_u32 s90, s92, 0x20000
	s_addc_u32 s91, s93, 0
	global_load_dwordx4 v[80:83], v241, s[90:91]
	global_load_dwordx4 v[84:87], v241, s[90:91] offset:64
	global_load_dwordx4 v[88:91], v241, s[90:91] offset:2048
	global_load_dwordx4 v[92:95], v241, s[90:91] offset:2112
	s_add_u32 s90, s92, 0x21000
	s_addc_u32 s91, s93, 0
	global_load_dwordx4 v[96:99], v241, s[90:91]
	global_load_dwordx4 v[100:103], v241, s[90:91] offset:64
	global_load_dwordx4 v[104:107], v241, s[90:91] offset:2048
	global_load_dwordx4 v[108:111], v241, s[90:91] offset:2112
	s_add_u32 s90, s92, 0x30000
	s_addc_u32 s91, s93, 0
	global_load_dwordx4 v[112:115], v241, s[90:91]
	global_load_dwordx4 v[116:119], v241, s[90:91] offset:64
	global_load_dwordx4 v[120:123], v241, s[90:91] offset:2048
	global_load_dwordx4 v[124:127], v241, s[90:91] offset:2112
	s_add_u32 s90, s92, 0x31000
	s_addc_u32 s91, s93, 0
	global_load_dwordx4 v[128:131], v241, s[90:91]
	global_load_dwordx4 v[132:135], v241, s[90:91] offset:64
	global_load_dwordx4 v[136:139], v241, s[90:91] offset:2048
	global_load_dwordx4 v[228:231], v241, s[90:91] offset:2112
	s_waitcnt lgkmcnt(0)
; __device__ __forceinline__ float sigmoid_f(float x) { return rcpf_(1.f + __expf(-x)); }
; __device__ __forceinline__ float gelu_tanh_f(float x) { const float y = 0.7978845608028654f * (x + 0.044715f * x * x * x); return x * sigmoid_f(2.f * y); }
; template <bool FINAL, int D>
; __device__ __forceinline__ void rg_dir(PREF p, int l, int h, int ch, int sidx, int rowbase  , LAS bf16_t* sXc, LAS float* stg, int lane) {
;     ...
;         for (int ti = 0; ti < 16; ++ti) { const int tk = D ? 15 - ti : ti;
;             const float zr = stg[tk * 64 + lane] + ba, zi = stg[1024 + tk * 64 + lane] + bi;
;             const float r = sigmoid_f(zr), ig = sigmoid_f(zi);
;             const float a = __builtin_amdgcn_exp2f(r * sp8);
;             const float xc = bf2f(sXc[(mt * 16 + tk) * 72 + lane]);
;             av[ti] = a; iv[ti] = __builtin_amdgcn_sqrtf(fmaxf(1.f - a * a, 0.f)) * ig * xc;
;             if (FINAL && D == 1) grv[ti] = gelu_tanh_f(grv[ti]);
;         }
; #pragma unroll
;         for (int ti = 0; ti < 16; ++ti) { const int tk = D ? 15 - ti : ti;
;             hc = av[ti] * hc + iv[ti]; Ap *= av[ti];
	v_pk_fma_f32 v[0:1], v[0:1], v[248:249], v[242:243]
	v_pk_fma_f32 v[2:3], v[2:3], v[248:249], v[242:243]
	v_pk_fma_f32 v[4:5], v[4:5], v[248:249], v[242:243]
	v_pk_fma_f32 v[6:7], v[6:7], v[248:249], v[242:243]
	v_pk_fma_f32 v[8:9], v[8:9], v[248:249], v[242:243]
	v_pk_fma_f32 v[10:11], v[10:11], v[248:249], v[242:243]
	v_pk_fma_f32 v[12:13], v[12:13], v[248:249], v[242:243]
	v_pk_fma_f32 v[14:15], v[14:15], v[248:249], v[242:243]
	v_pk_fma_f32 v[16:17], v[16:17], v[248:249], v[244:245]
	v_pk_fma_f32 v[18:19], v[18:19], v[248:249], v[244:245]
	v_pk_fma_f32 v[20:21], v[20:21], v[248:249], v[244:245]
	v_pk_fma_f32 v[22:23], v[22:23], v[248:249], v[244:245]
	v_pk_fma_f32 v[24:25], v[24:25], v[248:249], v[244:245]
	v_pk_fma_f32 v[26:27], v[26:27], v[248:249], v[244:245]
	v_pk_fma_f32 v[28:29], v[28:29], v[248:249], v[244:245]
	v_pk_fma_f32 v[30:31], v[30:31], v[248:249], v[244:245]
	v_exp_f32_e32 v0, v0
	v_exp_f32_e32 v1, v1
	v_exp_f32_e32 v2, v2
	v_exp_f32_e32 v3, v3
	v_exp_f32_e32 v4, v4
	v_exp_f32_e32 v5, v5
	v_exp_f32_e32 v6, v6
	v_exp_f32_e32 v7, v7
	v_exp_f32_e32 v8, v8
	v_exp_f32_e32 v9, v9
	v_exp_f32_e32 v10, v10
	v_exp_f32_e32 v11, v11
	v_exp_f32_e32 v12, v12
	v_exp_f32_e32 v13, v13
	v_exp_f32_e32 v14, v14
	v_exp_f32_e32 v15, v15
	v_exp_f32_e32 v16, v16
	v_exp_f32_e32 v17, v17
	v_exp_f32_e32 v18, v18
	v_exp_f32_e32 v19, v19
	v_exp_f32_e32 v20, v20
	v_exp_f32_e32 v21, v21
	v_exp_f32_e32 v22, v22
	v_exp_f32_e32 v23, v23
	v_exp_f32_e32 v24, v24
	v_exp_f32_e32 v25, v25
	v_exp_f32_e32 v26, v26
	v_exp_f32_e32 v27, v27
	v_exp_f32_e32 v28, v28
	v_exp_f32_e32 v29, v29
	v_exp_f32_e32 v30, v30
	v_exp_f32_e32 v31, v31
	v_pk_add_f32 v[0:1], v[0:1], 1.0 op_sel_hi:[1,0]
	v_pk_add_f32 v[2:3], v[2:3], 1.0 op_sel_hi:[1,0]
	v_pk_add_f32 v[4:5], v[4:5], 1.0 op_sel_hi:[1,0]
	v_pk_add_f32 v[6:7], v[6:7], 1.0 op_sel_hi:[1,0]
	v_pk_add_f32 v[8:9], v[8:9], 1.0 op_sel_hi:[1,0]
	v_pk_add_f32 v[10:11], v[10:11], 1.0 op_sel_hi:[1,0]
	v_pk_add_f32 v[12:13], v[12:13], 1.0 op_sel_hi:[1,0]
	v_pk_add_f32 v[14:15], v[14:15], 1.0 op_sel_hi:[1,0]
	v_pk_add_f32 v[16:17], v[16:17], 1.0 op_sel_hi:[1,0]
	v_pk_add_f32 v[18:19], v[18:19], 1.0 op_sel_hi:[1,0]
	v_pk_add_f32 v[20:21], v[20:21], 1.0 op_sel_hi:[1,0]
	v_pk_add_f32 v[22:23], v[22:23], 1.0 op_sel_hi:[1,0]
	v_pk_add_f32 v[24:25], v[24:25], 1.0 op_sel_hi:[1,0]
	v_pk_add_f32 v[26:27], v[26:27], 1.0 op_sel_hi:[1,0]
	v_pk_add_f32 v[28:29], v[28:29], 1.0 op_sel_hi:[1,0]
	v_pk_add_f32 v[30:31], v[30:31], 1.0 op_sel_hi:[1,0]
	v_rcp_f32_e32 v0, v0
	v_rcp_f32_e32 v1, v1
	v_rcp_f32_e32 v2, v2
	v_rcp_f32_e32 v3, v3
	v_rcp_f32_e32 v4, v4
	v_rcp_f32_e32 v5, v5
	v_rcp_f32_e32 v6, v6
	v_rcp_f32_e32 v7, v7
	v_rcp_f32_e32 v8, v8
	v_rcp_f32_e32 v9, v9
	v_rcp_f32_e32 v10, v10
	v_rcp_f32_e32 v11, v11
	v_rcp_f32_e32 v12, v12
	v_rcp_f32_e32 v13, v13
	v_rcp_f32_e32 v14, v14
	v_rcp_f32_e32 v15, v15
	v_rcp_f32_e32 v16, v16
	v_rcp_f32_e32 v17, v17
	v_rcp_f32_e32 v18, v18
	v_rcp_f32_e32 v19, v19
	v_rcp_f32_e32 v20, v20
	v_rcp_f32_e32 v21, v21
	v_rcp_f32_e32 v22, v22
	v_rcp_f32_e32 v23, v23
	v_rcp_f32_e32 v24, v24
	v_rcp_f32_e32 v25, v25
	v_rcp_f32_e32 v26, v26
	v_rcp_f32_e32 v27, v27
	v_rcp_f32_e32 v28, v28
	v_rcp_f32_e32 v29, v29
	v_rcp_f32_e32 v30, v30
	v_rcp_f32_e32 v31, v31
	v_pk_mul_f32 v[0:1], v[246:247], v[0:1]
	v_pk_mul_f32 v[2:3], v[246:247], v[2:3]
	v_pk_mul_f32 v[4:5], v[246:247], v[4:5]
	v_pk_mul_f32 v[6:7], v[246:247], v[6:7]
	v_pk_mul_f32 v[8:9], v[246:247], v[8:9]
	v_pk_mul_f32 v[10:11], v[246:247], v[10:11]
	v_pk_mul_f32 v[12:13], v[246:247], v[12:13]
	v_pk_mul_f32 v[14:15], v[246:247], v[14:15]
	v_lshlrev_b32_e32 v48, 16, v48
	v_lshlrev_b32_e32 v49, 16, v49
	v_lshlrev_b32_e32 v50, 16, v50
	v_lshlrev_b32_e32 v51, 16, v51
	v_lshlrev_b32_e32 v52, 16, v52
	v_lshlrev_b32_e32 v53, 16, v53
	v_lshlrev_b32_e32 v54, 16, v54
	v_lshlrev_b32_e32 v55, 16, v55
	v_lshlrev_b32_e32 v56, 16, v56
	v_lshlrev_b32_e32 v57, 16, v57
	v_lshlrev_b32_e32 v58, 16, v58
	v_lshlrev_b32_e32 v59, 16, v59
	v_lshlrev_b32_e32 v60, 16, v60
	v_lshlrev_b32_e32 v61, 16, v61
	v_lshlrev_b32_e32 v62, 16, v62
	v_lshlrev_b32_e32 v63, 16, v63
	v_exp_f32_e32 v0, v0
	v_exp_f32_e32 v1, v1
	v_exp_f32_e32 v2, v2
	v_exp_f32_e32 v3, v3
	v_exp_f32_e32 v4, v4
	v_exp_f32_e32 v5, v5
	v_exp_f32_e32 v6, v6
	v_exp_f32_e32 v7, v7
	v_exp_f32_e32 v8, v8
	v_exp_f32_e32 v9, v9
	v_exp_f32_e32 v10, v10
	v_exp_f32_e32 v11, v11
	v_exp_f32_e32 v12, v12
	v_exp_f32_e32 v13, v13
	v_exp_f32_e32 v14, v14
	v_exp_f32_e32 v15, v15
	v_fma_f32 v32, -v0, v0, 1.0
	v_fma_f32 v33, -v1, v1, 1.0
	v_fma_f32 v34, -v2, v2, 1.0
	v_fma_f32 v35, -v3, v3, 1.0
	v_fma_f32 v36, -v4, v4, 1.0
	v_fma_f32 v37, -v5, v5, 1.0
	v_fma_f32 v38, -v6, v6, 1.0
	v_fma_f32 v39, -v7, v7, 1.0
	v_fma_f32 v40, -v8, v8, 1.0
	v_fma_f32 v41, -v9, v9, 1.0
	v_fma_f32 v42, -v10, v10, 1.0
	v_fma_f32 v43, -v11, v11, 1.0
	v_fma_f32 v44, -v12, v12, 1.0
	v_fma_f32 v45, -v13, v13, 1.0
	v_fma_f32 v46, -v14, v14, 1.0
	v_fma_f32 v47, -v15, v15, 1.0
	v_max_f32_e32 v32, 0, v32
	v_max_f32_e32 v33, 0, v33
	v_max_f32_e32 v34, 0, v34
	v_max_f32_e32 v35, 0, v35
	v_max_f32_e32 v36, 0, v36
	v_max_f32_e32 v37, 0, v37
	v_max_f32_e32 v38, 0, v38
	v_max_f32_e32 v39, 0, v39
	v_max_f32_e32 v40, 0, v40
	v_max_f32_e32 v41, 0, v41
	v_max_f32_e32 v42, 0, v42
	v_max_f32_e32 v43, 0, v43
	v_max_f32_e32 v44, 0, v44
	v_max_f32_e32 v45, 0, v45
	v_max_f32_e32 v46, 0, v46
	v_max_f32_e32 v47, 0, v47
	v_sqrt_f32_e32 v32, v32
	v_sqrt_f32_e32 v33, v33
	v_sqrt_f32_e32 v34, v34
	v_sqrt_f32_e32 v35, v35
	v_sqrt_f32_e32 v36, v36
	v_sqrt_f32_e32 v37, v37
	v_sqrt_f32_e32 v38, v38
	v_sqrt_f32_e32 v39, v39
	v_sqrt_f32_e32 v40, v40
	v_sqrt_f32_e32 v41, v41
	v_sqrt_f32_e32 v42, v42
; template <bool FINAL, int D>
; __device__ __forceinline__ void rg_dir(PREF p, int l, int h, int ch, int sidx, int rowbase  , LAS bf16_t* sXc, LAS float* stg, int lane) {
;     ...
;     const float ba = p.rg_ba[(l * 2 + D) * 512 + ch], bi = p.rg_bi[(l * 2 + D) * 512 + ch], lam = p.rg_lam[(l * 2 + D) * 512 + ch];
;     const float e_ = __expf(-lam), u_ = 1.f + e_;
;     const float l1p = (u_ == 1.f) ? e_ : __logf(u_) * e_ * rcpf_(u_ - 1.f);
;     const float sp8 = -8.f * 1.4426950408889634f * l1p;
;     float hc = FINAL ? RGC[sidx] : 0.f, Ap = 1.f;
;     bf16x8 Br[4][2], Bi[4][2];
; #pragma unroll
;     for (int nt = 0; nt < 4; ++nt) { const int o0 = (nt * 16 + (lane & 15)) * 64 + (lane >> 4) * 8;
;         Br[nt][0] = *(const bf16x8*)(wr_ + o0); Br[nt][1] = *(const bf16x8*)(wr_ + o0 + 32); Bi[nt][0] = *(const bf16x8*)(wi_ + o0); Bi[nt][1] = *(const bf16x8*)(wi_ + o0 + 32); }
;     if (FINAL && D == 1) asm volatile("s_waitcnt vmcnt(0)" ::: "memory");
; #pragma unroll 1
;     for (int mi = 0; mi < 4; ++mi) { const int mt = D ? 3 - mi : mi;
;         float grv[16], hfv[16];
;         if (FINAL && D == 1) {
; #pragma unroll
;             for (int ti = 0; ti < 16; ++ti) { const size_t row = (size_t)(rowbase + mt * 16 + 15 - ti); grv[ti] = __builtin_bit_cast(float, (unsigned)P[row * PW + 512 + ch]); hfv[ti] = __builtin_bit_cast(float, (unsigned)TMP[row * 512 + ch]); }
;             __builtin_amdgcn_sched_barrier(0);
; #pragma unroll
;             for (int ti = 0; ti < 16; ++ti) { grv[ti] = bf2f(__builtin_bit_cast(unsigned, grv[ti])); hfv[ti] = bf2f(__builtin_bit_cast(unsigned, hfv[ti])); }
;         }
;         const bf16x8 A0 = *(const LAS bf16x8*)(sXc + (mt * 16 + (lane & 15)) * 72 + (lane >> 4) * 8), A1 = *(const LAS bf16x8*)(sXc + (mt * 16 + (lane & 15)) * 72 + 32 + (lane >> 4) * 8);
;         f32x4 ar[4], ai[4];
; #pragma unroll
;         for (int nt = 0; nt < 4; ++nt) { const f32x4 z = {0.f, 0.f, 0.f, 0.f};
;             ar[nt] = mfma16(A0, Br[nt][0], z); ar[nt] = mfma16(A1, Br[nt][1], ar[nt]); ai[nt] = mfma16(A0, Bi[nt][0], z); ai[nt] = mfma16(A1, Bi[nt][1], ai[nt]); }
;         WAVE_SYNC();
; #pragma unroll
;         for (int nt = 0; nt < 4; ++nt)
; #pragma unroll
;             for (int j = 0; j < 4; ++j) { const int o = ((lane >> 4) * 4 + j) * 64 + nt * 16 + (lane & 15); stg[o] = ar[nt][j]; stg[1024 + o] = ai[nt][j]; }
;         WAVE_SYNC();
	v_sqrt_f32_e32 v43, v43
	v_sqrt_f32_e32 v44, v44
	v_sqrt_f32_e32 v45, v45
	v_sqrt_f32_e32 v46, v46
	v_sqrt_f32_e32 v47, v47
	s_nop 0
	v_pk_mul_f32 v[16:17], v[16:17], v[32:33]
	v_pk_mul_f32 v[18:19], v[18:19], v[34:35]
	v_pk_mul_f32 v[20:21], v[20:21], v[36:37]
	v_pk_mul_f32 v[22:23], v[22:23], v[38:39]
	v_pk_mul_f32 v[24:25], v[24:25], v[40:41]
	v_pk_mul_f32 v[26:27], v[26:27], v[42:43]
	v_pk_mul_f32 v[28:29], v[28:29], v[44:45]
	v_pk_mul_f32 v[30:31], v[30:31], v[46:47]
	v_pk_mul_f32 v[16:17], v[16:17], v[48:49]
	v_pk_mul_f32 v[18:19], v[18:19], v[50:51]
	v_pk_mul_f32 v[20:21], v[20:21], v[52:53]
	v_pk_mul_f32 v[22:23], v[22:23], v[54:55]
	v_pk_mul_f32 v[24:25], v[24:25], v[56:57]
	v_pk_mul_f32 v[26:27], v[26:27], v[58:59]
	v_pk_mul_f32 v[28:29], v[28:29], v[60:61]
	v_pk_mul_f32 v[30:31], v[30:31], v[62:63]
	global_load_dword v45, v235, s[76:77] offset:2048
	global_load_dword v46, v235, s[78:79] offset:2048
	global_load_dword v47, v235, s[80:81] offset:2048
	global_load_dword v251, v235, s[96:97] offset:2048
	v_fma_f32 v32, v0, v250, v16
	v_fma_f32 v250, v1, v32, v17
	v_cvt_pk_bf16_f32 v182, v32, v250
	v_fma_f32 v32, v2, v250, v18
	v_fma_f32 v250, v3, v32, v19
	v_cvt_pk_bf16_f32 v183, v32, v250
	v_fma_f32 v32, v4, v250, v20
	v_fma_f32 v250, v5, v32, v21
	v_cvt_pk_bf16_f32 v184, v32, v250
	v_fma_f32 v32, v6, v250, v22
	v_fma_f32 v250, v7, v32, v23
	v_cvt_pk_bf16_f32 v185, v32, v250
	v_fma_f32 v32, v8, v250, v24
	v_fma_f32 v250, v9, v32, v25
	v_cvt_pk_bf16_f32 v186, v32, v250
	v_fma_f32 v32, v10, v250, v26
	v_fma_f32 v250, v11, v32, v27
	v_cvt_pk_bf16_f32 v187, v32, v250
	v_fma_f32 v32, v12, v250, v28
	v_fma_f32 v250, v13, v32, v29
	v_cvt_pk_bf16_f32 v188, v32, v250
	v_fma_f32 v32, v14, v250, v30
	v_fma_f32 v250, v15, v32, v31
	v_cvt_pk_bf16_f32 v189, v32, v250
	s_waitcnt vmcnt(0)
	s_mov_b32 s8, 0x800000
	s_mov_b32 s9, 0x3f317217
	s_mov_b32 s14, 0x7f800000
	v_mul_f32_e32 v32, 0xbfb8aa3b, v45
	v_exp_f32_e32 v32, v32
	s_nop 0
	v_add_f32_e32 v33, 1.0, v32
	v_cmp_gt_f32_e32 vcc, s8, v33
	s_nop 1
	v_cndmask_b32_e64 v34, 0, 32, vcc
	v_ldexp_f32 v34, v33, v34
	v_log_f32_e32 v34, v34
	v_cndmask_b32_e32 v36, 0, v226, vcc
	v_cmp_eq_f32_e32 vcc, 1.0, v33
	v_mul_f32_e32 v35, 0x3f317217, v34
	v_fma_f32 v35, v34, s9, -v35
	v_fmac_f32_e32 v35, 0x3377d1cf, v34
	v_fmac_f32_e32 v35, 0x3f317217, v34
	v_cmp_lt_f32_e64 s[10:11], |v34|, s14
	s_nop 1
	v_cndmask_b32_e64 v34, v34, v35, s[10:11]
	v_add_f32_e32 v35, -1.0, v33
	v_rcp_f32_e32 v35, v35
	v_sub_f32_e32 v34, v34, v36
	v_mul_f32_e32 v34, v32, v34
	v_mul_f32_e32 v34, v34, v35
	v_cndmask_b32_e32 v32, v34, v32, vcc
	v_mul_f32_e32 v246, 0xc138aa3b, v32
	v_mov_b32_e32 v247, v246
	v_mul_f32_e32 v242, 0xbfb8aa3b, v46
	v_mul_f32_e32 v244, 0xbfb8aa3b, v47
	v_mov_b32_e32 v243, v242
	v_mov_b32_e32 v245, v244
	v_mov_b32_e32 v250, v251
	ds_read_b128 v[32:35], v236 offset:6912
	ds_read_b128 v[36:39], v236 offset:6976
	s_waitcnt lgkmcnt(0)
	v_mfma_f32_16x16x32_bf16 v[0:3], v[32:35], v[80:83], 0
	v_mfma_f32_16x16x32_bf16 v[4:7], v[32:35], v[88:91], 0
	v_mfma_f32_16x16x32_bf16 v[8:11], v[32:35], v[96:99], 0
	v_mfma_f32_16x16x32_bf16 v[12:15], v[32:35], v[104:107], 0
	v_mfma_f32_16x16x32_bf16 v[16:19], v[32:35], v[112:115], 0
	v_mfma_f32_16x16x32_bf16 v[20:23], v[32:35], v[120:123], 0
	v_mfma_f32_16x16x32_bf16 v[24:27], v[32:35], v[128:131], 0
	v_mfma_f32_16x16x32_bf16 v[28:31], v[32:35], v[136:139], 0
	v_mfma_f32_16x16x32_bf16 v[0:3], v[36:39], v[84:87], v[0:3]
	v_mfma_f32_16x16x32_bf16 v[4:7], v[36:39], v[92:95], v[4:7]
	v_mfma_f32_16x16x32_bf16 v[8:11], v[36:39], v[100:103], v[8:11]
	v_mfma_f32_16x16x32_bf16 v[12:15], v[36:39], v[108:111], v[12:15]
	v_mfma_f32_16x16x32_bf16 v[16:19], v[36:39], v[116:119], v[16:19]
	v_mfma_f32_16x16x32_bf16 v[20:23], v[36:39], v[124:127], v[20:23]
	v_mfma_f32_16x16x32_bf16 v[24:27], v[36:39], v[132:135], v[24:27]
	v_mfma_f32_16x16x32_bf16 v[28:31], v[36:39], v[228:231], v[28:31]
	s_nop 3
	ds_write2_b32 v237, v0, v4 offset0:0 offset1:16
	ds_write2_b32 v237, v8, v12 offset0:32 offset1:48
	ds_write2_b32 v237, v1, v5 offset0:64 offset1:80
	ds_write2_b32 v237, v9, v13 offset0:96 offset1:112
	ds_write2_b32 v237, v2, v6 offset0:128 offset1:144
	ds_write2_b32 v237, v10, v14 offset0:160 offset1:176
	ds_write2_b32 v237, v3, v7 offset0:192 offset1:208
	ds_write2_b32 v237, v11, v15 offset0:224 offset1:240
	ds_write2_b32 v238, v16, v20 offset0:0 offset1:16
	ds_write2_b32 v238, v24, v28 offset0:32 offset1:48
	ds_write2_b32 v238, v17, v21 offset0:64 offset1:80
	ds_write2_b32 v238, v25, v29 offset0:96 offset1:112
	ds_write2_b32 v238, v18, v22 offset0:128 offset1:144
	ds_write2_b32 v238, v26, v30 offset0:160 offset1:176
	ds_write2_b32 v238, v19, v23 offset0:192 offset1:208
	ds_write2_b32 v238, v27, v31 offset0:224 offset1:240
	s_waitcnt lgkmcnt(0)
; #define LAS __attribute__((address_space(3)))
; #define WAVE_SYNC() asm volatile("s_waitcnt lgkmcnt(0)" ::: "memory")
; __device__ __forceinline__ float rcpf_(float x) { return __builtin_amdgcn_rcpf(x); }
; __device__ __forceinline__ float sigmoid_f(float x) { return rcpf_(1.f + __expf(-x)); }
; __device__ __forceinline__ float silu_f(float x) { return x * sigmoid_f(x); }
; template <bool FINAL, int D>
; __device__ __forceinline__ void rg_dir(PREF p, int l, int h, int ch, int sidx, int rowbase  , LAS bf16_t* sXc, LAS float* stg, int lane) {
;     ...
;             for (int ti = 0; ti < 16; ++ti) { const size_t row = (size_t)(rowbase + mt * 16 + 15 - ti); grv[ti] = __builtin_bit_cast(float, (unsigned)P[row * PW + 512 + ch]); hfv[ti] = __builtin_bit_cast(float, (unsigned)TMP[row * 512 + ch]); }
;             __builtin_amdgcn_sched_barrier(0);
; #pragma unroll
;             for (int ti = 0; ti < 16; ++ti) { grv[ti] = bf2f(__builtin_bit_cast(unsigned, grv[ti])); hfv[ti] = bf2f(__builtin_bit_cast(unsigned, hfv[ti])); }
;         }
;         const bf16x8 A0 = *(const LAS bf16x8*)(sXc + (mt * 16 + (lane & 15)) * 72 + (lane >> 4) * 8), A1 = *(const LAS bf16x8*)(sXc + (mt * 16 + (lane & 15)) * 72 + 32 + (lane >> 4) * 8);
;         f32x4 ar[4], ai[4];
; #pragma unroll
;         for (int nt = 0; nt < 4; ++nt) { const f32x4 z = {0.f, 0.f, 0.f, 0.f};
;             ar[nt] = mfma16(A0, Br[nt][0], z); ar[nt] = mfma16(A1, Br[nt][1], ar[nt]); ai[nt] = mfma16(A0, Bi[nt][0], z); ai[nt] = mfma16(A1, Bi[nt][1], ai[nt]); }
;         WAVE_SYNC();
; #pragma unroll
;         for (int nt = 0; nt < 4; ++nt)
; #pragma unroll
;             for (int j = 0; j < 4; ++j) { const int o = ((lane >> 4) * 4 + j) * 64 + nt * 16 + (lane & 15); stg[o] = ar[nt][j]; stg[1024 + o] = ai[nt][j]; }
;         WAVE_SYNC();
;         float av[16], iv[16];
; #pragma unroll
;         for (int ti = 0; ti < 16; ++ti) { const int tk = D ? 15 - ti : ti;
;             const float zr = stg[tk * 64 + lane] + ba, zi = stg[1024 + tk * 64 + lane] + bi;
;             const float r = sigmoid_f(zr), ig = sigmoid_f(zi);
;             const float a = __builtin_amdgcn_exp2f(r * sp8);
;             const float xc = bf2f(sXc[(mt * 16 + tk) * 72 + lane]);
;             av[ti] = a; iv[ti] = __builtin_amdgcn_sqrtf(fmaxf(1.f - a * a, 0.f)) * ig * xc;
;             if (FINAL && D == 1) grv[ti] = gelu_tanh_f(grv[ti]);
	ds_read2st64_b32 v[0:1], v239 offset0:36 offset1:37
	ds_read2st64_b32 v[2:3], v239 offset0:38 offset1:39
	ds_read2st64_b32 v[4:5], v239 offset0:40 offset1:41
	ds_read2st64_b32 v[6:7], v239 offset0:42 offset1:43
	ds_read2st64_b32 v[8:9], v239 offset0:44 offset1:45
	ds_read2st64_b32 v[10:11], v239 offset0:46 offset1:47
	ds_read2st64_b32 v[12:13], v239 offset0:48 offset1:49
	ds_read2st64_b32 v[14:15], v239 offset0:50 offset1:51
	ds_read2st64_b32 v[16:17], v239 offset0:52 offset1:53
	ds_read2st64_b32 v[18:19], v239 offset0:54 offset1:55
	ds_read2st64_b32 v[20:21], v239 offset0:56 offset1:57
	ds_read2st64_b32 v[22:23], v239 offset0:58 offset1:59
	ds_read2st64_b32 v[24:25], v239 offset0:60 offset1:61
	ds_read2st64_b32 v[26:27], v239 offset0:62 offset1:63
	ds_read2st64_b32 v[28:29], v239 offset0:64 offset1:65
	ds_read2st64_b32 v[30:31], v239 offset0:66 offset1:67
	ds_read_u16 v48, v240 offset:6912
	ds_read_u16 v49, v240 offset:7056
	ds_read_u16 v50, v240 offset:7200
	ds_read_u16 v51, v240 offset:7344
	ds_read_u16 v52, v240 offset:7488
	ds_read_u16 v53, v240 offset:7632
	ds_read_u16 v54, v240 offset:7776
	ds_read_u16 v55, v240 offset:7920
	ds_read_u16 v56, v240 offset:8064
	ds_read_u16 v57, v240 offset:8208
	ds_read_u16 v58, v240 offset:8352
	ds_read_u16 v59, v240 offset:8496
	ds_read_u16 v60, v240 offset:8640
	ds_read_u16 v61, v240 offset:8784
	ds_read_u16 v62, v240 offset:8928
	ds_read_u16 v63, v240 offset:9072
	v_lshlrev_b32_e32 v206, 16, v190
	v_lshlrev_b32_e32 v207, 16, v191
	v_lshlrev_b32_e32 v208, 16, v192
	v_lshlrev_b32_e32 v209, 16, v193
	v_lshlrev_b32_e32 v210, 16, v194
	v_lshlrev_b32_e32 v211, 16, v195
	v_lshlrev_b32_e32 v212, 16, v196
	v_lshlrev_b32_e32 v213, 16, v197
	v_lshlrev_b32_e32 v214, 16, v198
	v_lshlrev_b32_e32 v215, 16, v199
	v_lshlrev_b32_e32 v216, 16, v200
	v_lshlrev_b32_e32 v217, 16, v201
	v_lshlrev_b32_e32 v218, 16, v202
	v_lshlrev_b32_e32 v219, 16, v203
	v_lshlrev_b32_e32 v222, 16, v204
	v_lshlrev_b32_e32 v223, 16, v205
	v_pk_mul_f32 v[32:33], v[140:141], v[206:207]
	v_pk_mul_f32 v[34:35], v[140:141], v[208:209]
	v_pk_mul_f32 v[36:37], v[140:141], v[210:211]
	v_pk_mul_f32 v[38:39], v[140:141], v[212:213]
	v_pk_mul_f32 v[40:41], v[140:141], v[214:215]
	v_pk_mul_f32 v[42:43], v[140:141], v[216:217]
	v_pk_mul_f32 v[44:45], v[140:141], v[218:219]
	v_pk_mul_f32 v[46:47], v[140:141], v[222:223]
	v_pk_mul_f32 v[32:33], v[32:33], v[206:207]
	v_pk_mul_f32 v[34:35], v[34:35], v[208:209]
	v_pk_mul_f32 v[36:37], v[36:37], v[210:211]
	v_pk_mul_f32 v[38:39], v[38:39], v[212:213]
	v_pk_mul_f32 v[40:41], v[40:41], v[214:215]
	v_pk_mul_f32 v[42:43], v[42:43], v[216:217]
	v_pk_mul_f32 v[44:45], v[44:45], v[218:219]
	v_pk_mul_f32 v[46:47], v[46:47], v[222:223]
	v_fma_f32 v32, v32, v206, v206
	v_fma_f32 v33, v33, v207, v207
	v_fma_f32 v34, v34, v208, v208
	v_fma_f32 v35, v35, v209, v209
	v_fma_f32 v36, v36, v210, v210
	v_fma_f32 v37, v37, v211, v211
	v_fma_f32 v38, v38, v212, v212
	v_fma_f32 v39, v39, v213, v213
	v_fma_f32 v40, v40, v214, v214
	v_fma_f32 v41, v41, v215, v215
	v_fma_f32 v42, v42, v216, v216
	v_fma_f32 v43, v43, v217, v217
	v_fma_f32 v44, v44, v218, v218
	v_fma_f32 v45, v45, v219, v219
	v_fma_f32 v46, v46, v222, v222
	v_fma_f32 v47, v47, v223, v223
	s_mov_b32 s98, 0xc0135761
	v_pk_mul_f32 v[32:33], v[32:33], s[98:99] op_sel_hi:[1,0]
	v_pk_mul_f32 v[34:35], v[34:35], s[98:99] op_sel_hi:[1,0]
	v_pk_mul_f32 v[36:37], v[36:37], s[98:99] op_sel_hi:[1,0]
	v_pk_mul_f32 v[38:39], v[38:39], s[98:99] op_sel_hi:[1,0]
	v_pk_mul_f32 v[40:41], v[40:41], s[98:99] op_sel_hi:[1,0]
	v_pk_mul_f32 v[42:43], v[42:43], s[98:99] op_sel_hi:[1,0]
	v_pk_mul_f32 v[44:45], v[44:45], s[98:99] op_sel_hi:[1,0]
	v_pk_mul_f32 v[46:47], v[46:47], s[98:99] op_sel_hi:[1,0]
	v_exp_f32_e32 v32, v32
	v_exp_f32_e32 v33, v33
	v_exp_f32_e32 v34, v34
	v_exp_f32_e32 v35, v35
	v_exp_f32_e32 v36, v36
	v_exp_f32_e32 v37, v37
	v_exp_f32_e32 v38, v38
	v_exp_f32_e32 v39, v39
	v_exp_f32_e32 v40, v40
	v_exp_f32_e32 v41, v41
	v_exp_f32_e32 v42, v42
	v_exp_f32_e32 v43, v43
	v_exp_f32_e32 v44, v44
	v_exp_f32_e32 v45, v45
	v_exp_f32_e32 v46, v46
	v_exp_f32_e32 v47, v47
	v_pk_add_f32 v[32:33], v[32:33], 1.0 op_sel_hi:[1,0]
	v_pk_add_f32 v[34:35], v[34:35], 1.0 op_sel_hi:[1,0]
	v_pk_add_f32 v[36:37], v[36:37], 1.0 op_sel_hi:[1,0]
	v_pk_add_f32 v[38:39], v[38:39], 1.0 op_sel_hi:[1,0]
	v_pk_add_f32 v[40:41], v[40:41], 1.0 op_sel_hi:[1,0]
	v_pk_add_f32 v[42:43], v[42:43], 1.0 op_sel_hi:[1,0]
	v_pk_add_f32 v[44:45], v[44:45], 1.0 op_sel_hi:[1,0]
	v_pk_add_f32 v[46:47], v[46:47], 1.0 op_sel_hi:[1,0]
	v_rcp_f32_e32 v32, v32
	v_rcp_f32_e32 v33, v33
	v_rcp_f32_e32 v34, v34
	v_rcp_f32_e32 v35, v35
	v_rcp_f32_e32 v36, v36
	v_rcp_f32_e32 v37, v37
	v_rcp_f32_e32 v38, v38
	v_rcp_f32_e32 v39, v39
	v_rcp_f32_e32 v40, v40
	v_rcp_f32_e32 v41, v41
	v_rcp_f32_e32 v42, v42
	v_rcp_f32_e32 v43, v43
	v_rcp_f32_e32 v44, v44
	v_rcp_f32_e32 v45, v45
	v_rcp_f32_e32 v46, v46
	v_rcp_f32_e32 v47, v47
	s_nop 0
	v_pk_mul_f32 v[206:207], v[32:33], v[206:207]
	v_pk_mul_f32 v[208:209], v[34:35], v[208:209]
	v_pk_mul_f32 v[210:211], v[36:37], v[210:211]
	v_pk_mul_f32 v[212:213], v[38:39], v[212:213]
	v_pk_mul_f32 v[214:215], v[40:41], v[214:215]
	v_pk_mul_f32 v[216:217], v[42:43], v[216:217]
	v_pk_mul_f32 v[218:219], v[44:45], v[218:219]
	v_pk_mul_f32 v[222:223], v[46:47], v[222:223]
	s_add_i32 s39, s15, 32
	s_mul_hi_u32 s83, s39, 0x1600
	s_mul_i32 s82, s39, 0x1600
	s_add_u32 s82, s82, s0
	s_addc_u32 s83, s83, s1
	s_add_u32 s82, s82, 0xbc00400
	s_addc_u32 s83, s83, 0
	global_load_ushort v190, v234, s[82:83]
	s_add_u32 s82, s82, 0x1600
	s_addc_u32 s83, s83, 0
	global_load_ushort v191, v234, s[82:83]
	s_add_u32 s82, s82, 0x1600
	s_addc_u32 s83, s83, 0
	global_load_ushort v192, v234, s[82:83]
	s_add_u32 s82, s82, 0x1600
	s_addc_u32 s83, s83, 0
	global_load_ushort v193, v234, s[82:83]
	s_add_u32 s82, s82, 0x1600
	s_addc_u32 s83, s83, 0
	global_load_ushort v194, v234, s[82:83]
	s_add_u32 s82, s82, 0x1600
	s_addc_u32 s83, s83, 0
	global_load_ushort v195, v234, s[82:83]
	s_add_u32 s82, s82, 0x1600
	s_addc_u32 s83, s83, 0
	global_load_ushort v196, v234, s[82:83]
	s_add_u32 s82, s82, 0x1600
	s_addc_u32 s83, s83, 0
	global_load_ushort v197, v234, s[82:83]
	s_add_u32 s82, s82, 0x1600
	s_addc_u32 s83, s83, 0
	global_load_ushort v198, v234, s[82:83]
	s_add_u32 s82, s82, 0x1600
	s_addc_u32 s83, s83, 0
	global_load_ushort v199, v234, s[82:83]
	s_add_u32 s82, s82, 0x1600
	s_addc_u32 s83, s83, 0
	global_load_ushort v200, v234, s[82:83]
	s_add_u32 s82, s82, 0x1600
	s_addc_u32 s83, s83, 0
	global_load_ushort v201, v234, s[82:83]
	s_add_u32 s82, s82, 0x1600
	s_addc_u32 s83, s83, 0
	global_load_ushort v202, v234, s[82:83]
	s_add_u32 s82, s82, 0x1600
	s_addc_u32 s83, s83, 0
	global_load_ushort v203, v234, s[82:83]
	s_add_u32 s82, s82, 0x1600
	s_addc_u32 s83, s83, 0
	global_load_ushort v204, v234, s[82:83]
	s_add_u32 s82, s82, 0x1600
	s_addc_u32 s83, s83, 0
	global_load_ushort v205, v234, s[82:83]
	s_waitcnt lgkmcnt(0)
; __device__ __forceinline__ float sigmoid_f(float x) { return rcpf_(1.f + __expf(-x)); }
; template <bool FINAL, int D>
; __device__ __forceinline__ void rg_dir(PREF p, int l, int h, int ch, int sidx, int rowbase  , LAS bf16_t* sXc, LAS float* stg, int lane) {
;     ...
;         for (int ti = 0; ti < 16; ++ti) { const int tk = D ? 15 - ti : ti;
;             const float zr = stg[tk * 64 + lane] + ba, zi = stg[1024 + tk * 64 + lane] + bi;
;             const float r = sigmoid_f(zr), ig = sigmoid_f(zi);
;             const float a = __builtin_amdgcn_exp2f(r * sp8);
;             const float xc = bf2f(sXc[(mt * 16 + tk) * 72 + lane]);
;             av[ti] = a; iv[ti] = __builtin_amdgcn_sqrtf(fmaxf(1.f - a * a, 0.f)) * ig * xc;
	v_pk_fma_f32 v[0:1], v[0:1], v[248:249], v[242:243]
	v_pk_fma_f32 v[2:3], v[2:3], v[248:249], v[242:243]
	v_pk_fma_f32 v[4:5], v[4:5], v[248:249], v[242:243]
	v_pk_fma_f32 v[6:7], v[6:7], v[248:249], v[242:243]
	v_pk_fma_f32 v[8:9], v[8:9], v[248:249], v[242:243]
	v_pk_fma_f32 v[10:11], v[10:11], v[248:249], v[242:243]
	v_pk_fma_f32 v[12:13], v[12:13], v[248:249], v[242:243]
	v_pk_fma_f32 v[14:15], v[14:15], v[248:249], v[242:243]
	v_pk_fma_f32 v[16:17], v[16:17], v[248:249], v[244:245]
	v_pk_fma_f32 v[18:19], v[18:19], v[248:249], v[244:245]
	v_pk_fma_f32 v[20:21], v[20:21], v[248:249], v[244:245]
	v_pk_fma_f32 v[22:23], v[22:23], v[248:249], v[244:245]
	v_pk_fma_f32 v[24:25], v[24:25], v[248:249], v[244:245]
	v_pk_fma_f32 v[26:27], v[26:27], v[248:249], v[244:245]
	v_pk_fma_f32 v[28:29], v[28:29], v[248:249], v[244:245]
	v_pk_fma_f32 v[30:31], v[30:31], v[248:249], v[244:245]
	v_exp_f32_e32 v0, v0
	v_exp_f32_e32 v1, v1
	v_exp_f32_e32 v2, v2
	v_exp_f32_e32 v3, v3
	v_exp_f32_e32 v4, v4
	v_exp_f32_e32 v5, v5
	v_exp_f32_e32 v6, v6
	v_exp_f32_e32 v7, v7
	v_exp_f32_e32 v8, v8
	v_exp_f32_e32 v9, v9
	v_exp_f32_e32 v10, v10
	v_exp_f32_e32 v11, v11
	v_exp_f32_e32 v12, v12
	v_exp_f32_e32 v13, v13
	v_exp_f32_e32 v14, v14
	v_exp_f32_e32 v15, v15
	v_exp_f32_e32 v16, v16
	v_exp_f32_e32 v17, v17
	v_exp_f32_e32 v18, v18
	v_exp_f32_e32 v19, v19
	v_exp_f32_e32 v20, v20
	v_exp_f32_e32 v21, v21
	v_exp_f32_e32 v22, v22
	v_exp_f32_e32 v23, v23
	v_exp_f32_e32 v24, v24
	v_exp_f32_e32 v25, v25
	v_exp_f32_e32 v26, v26
	v_exp_f32_e32 v27, v27
	v_exp_f32_e32 v28, v28
	v_exp_f32_e32 v29, v29
	v_exp_f32_e32 v30, v30
	v_exp_f32_e32 v31, v31
	v_pk_add_f32 v[0:1], v[0:1], 1.0 op_sel_hi:[1,0]
	v_pk_add_f32 v[2:3], v[2:3], 1.0 op_sel_hi:[1,0]
	v_pk_add_f32 v[4:5], v[4:5], 1.0 op_sel_hi:[1,0]
	v_pk_add_f32 v[6:7], v[6:7], 1.0 op_sel_hi:[1,0]
	v_pk_add_f32 v[8:9], v[8:9], 1.0 op_sel_hi:[1,0]
	v_pk_add_f32 v[10:11], v[10:11], 1.0 op_sel_hi:[1,0]
	v_pk_add_f32 v[12:13], v[12:13], 1.0 op_sel_hi:[1,0]
	v_pk_add_f32 v[14:15], v[14:15], 1.0 op_sel_hi:[1,0]
	v_pk_add_f32 v[16:17], v[16:17], 1.0 op_sel_hi:[1,0]
	v_pk_add_f32 v[18:19], v[18:19], 1.0 op_sel_hi:[1,0]
	v_pk_add_f32 v[20:21], v[20:21], 1.0 op_sel_hi:[1,0]
	v_pk_add_f32 v[22:23], v[22:23], 1.0 op_sel_hi:[1,0]
	v_pk_add_f32 v[24:25], v[24:25], 1.0 op_sel_hi:[1,0]
	v_pk_add_f32 v[26:27], v[26:27], 1.0 op_sel_hi:[1,0]
	v_pk_add_f32 v[28:29], v[28:29], 1.0 op_sel_hi:[1,0]
	v_pk_add_f32 v[30:31], v[30:31], 1.0 op_sel_hi:[1,0]
	v_rcp_f32_e32 v0, v0
	v_rcp_f32_e32 v1, v1
	v_rcp_f32_e32 v2, v2
	v_rcp_f32_e32 v3, v3
	v_rcp_f32_e32 v4, v4
	v_rcp_f32_e32 v5, v5
	v_rcp_f32_e32 v6, v6
	v_rcp_f32_e32 v7, v7
	v_rcp_f32_e32 v8, v8
	v_rcp_f32_e32 v9, v9
	v_rcp_f32_e32 v10, v10
	v_rcp_f32_e32 v11, v11
	v_rcp_f32_e32 v12, v12
	v_rcp_f32_e32 v13, v13
	v_rcp_f32_e32 v14, v14
	v_rcp_f32_e32 v15, v15
	v_rcp_f32_e32 v16, v16
	v_rcp_f32_e32 v17, v17
	v_rcp_f32_e32 v18, v18
	v_rcp_f32_e32 v19, v19
	v_rcp_f32_e32 v20, v20
	v_rcp_f32_e32 v21, v21
	v_rcp_f32_e32 v22, v22
	v_rcp_f32_e32 v23, v23
	v_rcp_f32_e32 v24, v24
	v_rcp_f32_e32 v25, v25
	v_rcp_f32_e32 v26, v26
	v_rcp_f32_e32 v27, v27
	v_rcp_f32_e32 v28, v28
	v_rcp_f32_e32 v29, v29
	v_rcp_f32_e32 v30, v30
	v_rcp_f32_e32 v31, v31
	v_pk_mul_f32 v[0:1], v[246:247], v[0:1]
	v_pk_mul_f32 v[2:3], v[246:247], v[2:3]
	v_pk_mul_f32 v[4:5], v[246:247], v[4:5]
	v_pk_mul_f32 v[6:7], v[246:247], v[6:7]
	v_pk_mul_f32 v[8:9], v[246:247], v[8:9]
	v_pk_mul_f32 v[10:11], v[246:247], v[10:11]
	v_pk_mul_f32 v[12:13], v[246:247], v[12:13]
	v_pk_mul_f32 v[14:15], v[246:247], v[14:15]
	v_lshlrev_b32_e32 v48, 16, v48
	v_lshlrev_b32_e32 v49, 16, v49
	v_lshlrev_b32_e32 v50, 16, v50
	v_lshlrev_b32_e32 v51, 16, v51
	v_lshlrev_b32_e32 v52, 16, v52
	v_lshlrev_b32_e32 v53, 16, v53
	v_lshlrev_b32_e32 v54, 16, v54
	v_lshlrev_b32_e32 v55, 16, v55
	v_lshlrev_b32_e32 v56, 16, v56
	v_lshlrev_b32_e32 v57, 16, v57
	v_lshlrev_b32_e32 v58, 16, v58
	v_lshlrev_b32_e32 v59, 16, v59
	v_lshlrev_b32_e32 v60, 16, v60
	v_lshlrev_b32_e32 v61, 16, v61
	v_lshlrev_b32_e32 v62, 16, v62
	v_lshlrev_b32_e32 v63, 16, v63
	v_exp_f32_e32 v0, v0
	v_exp_f32_e32 v1, v1
	v_exp_f32_e32 v2, v2
	v_exp_f32_e32 v3, v3
	v_exp_f32_e32 v4, v4
	v_exp_f32_e32 v5, v5
	v_exp_f32_e32 v6, v6
	v_exp_f32_e32 v7, v7
	v_exp_f32_e32 v8, v8
	v_exp_f32_e32 v9, v9
	v_exp_f32_e32 v10, v10
	v_exp_f32_e32 v11, v11
	v_exp_f32_e32 v12, v12
	v_exp_f32_e32 v13, v13
	v_exp_f32_e32 v14, v14
	v_exp_f32_e32 v15, v15
	v_fma_f32 v32, -v0, v0, 1.0
	v_fma_f32 v33, -v1, v1, 1.0
	v_fma_f32 v34, -v2, v2, 1.0
	v_fma_f32 v35, -v3, v3, 1.0
	v_fma_f32 v36, -v4, v4, 1.0
	v_fma_f32 v37, -v5, v5, 1.0
	v_fma_f32 v38, -v6, v6, 1.0
	v_fma_f32 v39, -v7, v7, 1.0
	v_fma_f32 v40, -v8, v8, 1.0
	v_fma_f32 v41, -v9, v9, 1.0
	v_fma_f32 v42, -v10, v10, 1.0
	v_fma_f32 v43, -v11, v11, 1.0
	v_fma_f32 v44, -v12, v12, 1.0
	v_fma_f32 v45, -v13, v13, 1.0
	v_fma_f32 v46, -v14, v14, 1.0
	v_fma_f32 v47, -v15, v15, 1.0
	v_max_f32_e32 v32, 0, v32
	v_max_f32_e32 v33, 0, v33
	v_max_f32_e32 v34, 0, v34
	v_max_f32_e32 v35, 0, v35
	v_max_f32_e32 v36, 0, v36
	v_max_f32_e32 v37, 0, v37
	v_max_f32_e32 v38, 0, v38
	v_max_f32_e32 v39, 0, v39
	v_max_f32_e32 v40, 0, v40
	v_max_f32_e32 v41, 0, v41
	v_max_f32_e32 v42, 0, v42
	v_max_f32_e32 v43, 0, v43
	v_max_f32_e32 v44, 0, v44
	v_max_f32_e32 v45, 0, v45
	v_max_f32_e32 v46, 0, v46
	v_max_f32_e32 v47, 0, v47
	v_sqrt_f32_e32 v32, v32
	v_sqrt_f32_e32 v33, v33
	v_sqrt_f32_e32 v34, v34
	v_sqrt_f32_e32 v35, v35
	v_sqrt_f32_e32 v36, v36
	v_sqrt_f32_e32 v37, v37
	v_sqrt_f32_e32 v38, v38
	v_sqrt_f32_e32 v39, v39
	v_sqrt_f32_e32 v40, v40
	v_sqrt_f32_e32 v41, v41
	v_sqrt_f32_e32 v42, v42
; __device__ __forceinline__ unsigned f2bf(float f) { unsigned r; asm("v_cvt_pk_bf16_f32 %0, %1, %1" : "=v"(r) : "v"(f)); return r & 0xffffu; }
; __device__ __forceinline__ float sigmoid_f(float x) { return rcpf_(1.f + __expf(-x)); }
; __device__ __forceinline__ float gelu_tanh_f(float x) { const float y = 0.7978845608028654f * (x + 0.044715f * x * x * x); return x * sigmoid_f(2.f * y); }
; template <bool FINAL, int D>
; __device__ __forceinline__ void rg_dir(PREF p, int l, int h, int ch, int sidx, int rowbase  , LAS bf16_t* sXc, LAS float* stg, int lane) {
;     ...
;         for (int ti = 0; ti < 16; ++ti) { const int tk = D ? 15 - ti : ti;
;             const float zr = stg[tk * 64 + lane] + ba, zi = stg[1024 + tk * 64 + lane] + bi;
;             const float r = sigmoid_f(zr), ig = sigmoid_f(zi);
;             const float a = __builtin_amdgcn_exp2f(r * sp8);
;             const float xc = bf2f(sXc[(mt * 16 + tk) * 72 + lane]);
;             av[ti] = a; iv[ti] = __builtin_amdgcn_sqrtf(fmaxf(1.f - a * a, 0.f)) * ig * xc;
;             if (FINAL && D == 1) grv[ti] = gelu_tanh_f(grv[ti]);
;         }
; #pragma unroll
;         for (int ti = 0; ti < 16; ++ti) { const int tk = D ? 15 - ti : ti;
;             hc = av[ti] * hc + iv[ti]; Ap *= av[ti];
;             if (FINAL) { const size_t row = (size_t)(rowbase + mt * 16 + tk);
;                 if (D == 0) TMP[row * 512 + ch] = (bf16_t)f2bf(hc);
;                 else MIX[row * DM + ch] = (bf16_t)f2bf(grv[ti] * (hfv[ti] + hc)); }
	v_sqrt_f32_e32 v43, v43
	v_sqrt_f32_e32 v44, v44
	v_sqrt_f32_e32 v45, v45
	v_sqrt_f32_e32 v46, v46
	v_sqrt_f32_e32 v47, v47
	s_nop 0
	v_pk_mul_f32 v[16:17], v[16:17], v[32:33]
	v_pk_mul_f32 v[18:19], v[18:19], v[34:35]
	v_pk_mul_f32 v[20:21], v[20:21], v[36:37]
	v_pk_mul_f32 v[22:23], v[22:23], v[38:39]
	v_pk_mul_f32 v[24:25], v[24:25], v[40:41]
	v_pk_mul_f32 v[26:27], v[26:27], v[42:43]
	v_pk_mul_f32 v[28:29], v[28:29], v[44:45]
	v_pk_mul_f32 v[30:31], v[30:31], v[46:47]
	v_pk_mul_f32 v[16:17], v[16:17], v[48:49]
	v_pk_mul_f32 v[18:19], v[18:19], v[50:51]
	v_pk_mul_f32 v[20:21], v[20:21], v[52:53]
	v_pk_mul_f32 v[22:23], v[22:23], v[54:55]
	v_pk_mul_f32 v[24:25], v[24:25], v[56:57]
	v_pk_mul_f32 v[26:27], v[26:27], v[58:59]
	v_pk_mul_f32 v[28:29], v[28:29], v[60:61]
	v_pk_mul_f32 v[30:31], v[30:31], v[62:63]
	s_add_i32 s39, s15, 63
	s_lshl_b32 s39, s39, 11
	s_add_u32 s90, s0, 0x7b00000
	s_addc_u32 s91, s1, 0
	s_add_u32 s90, s90, s39
	s_addc_u32 s91, s91, 0
	v_lshlrev_b32_e32 v48, 16, v182
	v_and_b32_e32 v49, 0xffff0000, v182
	v_lshlrev_b32_e32 v50, 16, v183
	v_and_b32_e32 v51, 0xffff0000, v183
	v_lshlrev_b32_e32 v52, 16, v184
	v_and_b32_e32 v53, 0xffff0000, v184
	v_lshlrev_b32_e32 v54, 16, v185
	v_and_b32_e32 v55, 0xffff0000, v185
	v_lshlrev_b32_e32 v56, 16, v186
	v_and_b32_e32 v57, 0xffff0000, v186
	v_lshlrev_b32_e32 v58, 16, v187
	v_and_b32_e32 v59, 0xffff0000, v187
	v_lshlrev_b32_e32 v60, 16, v188
	v_and_b32_e32 v61, 0xffff0000, v188
	v_lshlrev_b32_e32 v62, 16, v189
	v_and_b32_e32 v63, 0xffff0000, v189
	v_fma_f32 v47, v15, v250, v31
	v_fma_f32 v46, v14, v47, v30
	v_fma_f32 v45, v13, v46, v29
	v_fma_f32 v44, v12, v45, v28
	v_fma_f32 v43, v11, v44, v27
	v_fma_f32 v42, v10, v43, v26
	v_fma_f32 v41, v9, v42, v25
	v_fma_f32 v40, v8, v41, v24
	v_fma_f32 v39, v7, v40, v23
	v_fma_f32 v38, v6, v39, v22
	v_fma_f32 v37, v5, v38, v21
	v_fma_f32 v36, v4, v37, v20
	v_fma_f32 v35, v3, v36, v19
	v_fma_f32 v34, v2, v35, v18
	v_fma_f32 v33, v1, v34, v17
	v_fma_f32 v32, v0, v33, v16
	v_mov_b32_e32 v250, v32
	v_pk_add_f32 v[48:49], v[48:49], v[32:33]
	v_pk_add_f32 v[50:51], v[50:51], v[34:35]
	v_pk_add_f32 v[52:53], v[52:53], v[36:37]
	v_pk_add_f32 v[54:55], v[54:55], v[38:39]
	v_pk_add_f32 v[56:57], v[56:57], v[40:41]
	v_pk_add_f32 v[58:59], v[58:59], v[42:43]
	v_pk_add_f32 v[60:61], v[60:61], v[44:45]
	v_pk_add_f32 v[62:63], v[62:63], v[46:47]
	v_pk_mul_f32 v[48:49], v[206:207], v[48:49]
	v_pk_mul_f32 v[50:51], v[208:209], v[50:51]
	v_pk_mul_f32 v[52:53], v[210:211], v[52:53]
	v_pk_mul_f32 v[54:55], v[212:213], v[54:55]
	v_pk_mul_f32 v[56:57], v[214:215], v[56:57]
	v_pk_mul_f32 v[58:59], v[216:217], v[58:59]
	v_pk_mul_f32 v[60:61], v[218:219], v[60:61]
	v_pk_mul_f32 v[62:63], v[222:223], v[62:63]
	v_cvt_pk_bf16_f32 v48, v48, v48
	v_cvt_pk_bf16_f32 v49, v49, v49
	v_cvt_pk_bf16_f32 v50, v50, v50
	v_cvt_pk_bf16_f32 v51, v51, v51
	v_cvt_pk_bf16_f32 v52, v52, v52
	v_cvt_pk_bf16_f32 v53, v53, v53
	v_cvt_pk_bf16_f32 v54, v54, v54
	v_cvt_pk_bf16_f32 v55, v55, v55
	v_cvt_pk_bf16_f32 v56, v56, v56
	v_cvt_pk_bf16_f32 v57, v57, v57
	v_cvt_pk_bf16_f32 v58, v58, v58
	v_cvt_pk_bf16_f32 v59, v59, v59
	v_cvt_pk_bf16_f32 v60, v60, v60
	v_cvt_pk_bf16_f32 v61, v61, v61
	v_cvt_pk_bf16_f32 v62, v62, v62
	v_cvt_pk_bf16_f32 v63, v63, v63
	global_store_short v234, v63, s[90:91]
	s_sub_u32 s90, s90, 0x800
	s_subb_u32 s91, s91, 0
	global_store_short v234, v62, s[90:91]
	s_sub_u32 s90, s90, 0x800
	s_subb_u32 s91, s91, 0
	global_store_short v234, v61, s[90:91]
	s_sub_u32 s90, s90, 0x800
	s_subb_u32 s91, s91, 0
	global_store_short v234, v60, s[90:91]
	s_sub_u32 s90, s90, 0x800
	s_subb_u32 s91, s91, 0
	global_store_short v234, v59, s[90:91]
	s_sub_u32 s90, s90, 0x800
	s_subb_u32 s91, s91, 0
	global_store_short v234, v58, s[90:91]
	s_sub_u32 s90, s90, 0x800
	s_subb_u32 s91, s91, 0
	global_store_short v234, v57, s[90:91]
	s_sub_u32 s90, s90, 0x800
	s_subb_u32 s91, s91, 0
	global_store_short v234, v56, s[90:91]
	s_sub_u32 s90, s90, 0x800
	s_subb_u32 s91, s91, 0
	global_store_short v234, v55, s[90:91]
	s_sub_u32 s90, s90, 0x800
	s_subb_u32 s91, s91, 0
	global_store_short v234, v54, s[90:91]
	s_sub_u32 s90, s90, 0x800
	s_subb_u32 s91, s91, 0
	global_store_short v234, v53, s[90:91]
	s_sub_u32 s90, s90, 0x800
	s_subb_u32 s91, s91, 0
	global_store_short v234, v52, s[90:91]
	s_sub_u32 s90, s90, 0x800
	s_subb_u32 s91, s91, 0
	global_store_short v234, v51, s[90:91]
	s_sub_u32 s90, s90, 0x800
	s_subb_u32 s91, s91, 0
	global_store_short v234, v50, s[90:91]
	s_sub_u32 s90, s90, 0x800
	s_subb_u32 s91, s91, 0
	global_store_short v234, v49, s[90:91]
	s_sub_u32 s90, s90, 0x800
	s_subb_u32 s91, s91, 0
	global_store_short v234, v48, s[90:91]
	ds_read_b128 v[32:35], v236 offset:4608
	ds_read_b128 v[36:39], v236 offset:4672
	s_waitcnt lgkmcnt(0)
; #define LAS __attribute__((address_space(3)))
; #define WAVE_SYNC() asm volatile("s_waitcnt lgkmcnt(0)" ::: "memory")
; __device__ __forceinline__ float sigmoid_f(float x) { return rcpf_(1.f + __expf(-x)); }
; __device__ __forceinline__ float gelu_tanh_f(float x) { const float y = 0.7978845608028654f * (x + 0.044715f * x * x * x); return x * sigmoid_f(2.f * y); }
; template <bool FINAL, int D>
; __device__ __forceinline__ void rg_dir(PREF p, int l, int h, int ch, int sidx, int rowbase  , LAS bf16_t* sXc, LAS float* stg, int lane) {
;     ...
;             for (int ti = 0; ti < 16; ++ti) { const size_t row = (size_t)(rowbase + mt * 16 + 15 - ti); grv[ti] = __builtin_bit_cast(float, (unsigned)P[row * PW + 512 + ch]); hfv[ti] = __builtin_bit_cast(float, (unsigned)TMP[row * 512 + ch]); }
;             __builtin_amdgcn_sched_barrier(0);
; #pragma unroll
;             for (int ti = 0; ti < 16; ++ti) { grv[ti] = bf2f(__builtin_bit_cast(unsigned, grv[ti])); hfv[ti] = bf2f(__builtin_bit_cast(unsigned, hfv[ti])); }
;         }
;         const bf16x8 A0 = *(const LAS bf16x8*)(sXc + (mt * 16 + (lane & 15)) * 72 + (lane >> 4) * 8), A1 = *(const LAS bf16x8*)(sXc + (mt * 16 + (lane & 15)) * 72 + 32 + (lane >> 4) * 8);
;         f32x4 ar[4], ai[4];
; #pragma unroll
;         for (int nt = 0; nt < 4; ++nt) { const f32x4 z = {0.f, 0.f, 0.f, 0.f};
;             ar[nt] = mfma16(A0, Br[nt][0], z); ar[nt] = mfma16(A1, Br[nt][1], ar[nt]); ai[nt] = mfma16(A0, Bi[nt][0], z); ai[nt] = mfma16(A1, Bi[nt][1], ai[nt]); }
;         WAVE_SYNC();
; #pragma unroll
;         for (int nt = 0; nt < 4; ++nt)
; #pragma unroll
;             for (int j = 0; j < 4; ++j) { const int o = ((lane >> 4) * 4 + j) * 64 + nt * 16 + (lane & 15); stg[o] = ar[nt][j]; stg[1024 + o] = ai[nt][j]; }
;         WAVE_SYNC();
;         float av[16], iv[16];
; #pragma unroll
;         for (int ti = 0; ti < 16; ++ti) { const int tk = D ? 15 - ti : ti;
;             const float zr = stg[tk * 64 + lane] + ba, zi = stg[1024 + tk * 64 + lane] + bi;
;             const float r = sigmoid_f(zr), ig = sigmoid_f(zi);
;             const float a = __builtin_amdgcn_exp2f(r * sp8);
;             const float xc = bf2f(sXc[(mt * 16 + tk) * 72 + lane]);
;             av[ti] = a; iv[ti] = __builtin_amdgcn_sqrtf(fmaxf(1.f - a * a, 0.f)) * ig * xc;
;             if (FINAL && D == 1) grv[ti] = gelu_tanh_f(grv[ti]);
	v_mfma_f32_16x16x32_bf16 v[0:3], v[32:35], v[80:83], 0
	v_mfma_f32_16x16x32_bf16 v[4:7], v[32:35], v[88:91], 0
	v_mfma_f32_16x16x32_bf16 v[8:11], v[32:35], v[96:99], 0
	v_mfma_f32_16x16x32_bf16 v[12:15], v[32:35], v[104:107], 0
	v_mfma_f32_16x16x32_bf16 v[16:19], v[32:35], v[112:115], 0
	v_mfma_f32_16x16x32_bf16 v[20:23], v[32:35], v[120:123], 0
	v_mfma_f32_16x16x32_bf16 v[24:27], v[32:35], v[128:131], 0
	v_mfma_f32_16x16x32_bf16 v[28:31], v[32:35], v[136:139], 0
	v_mfma_f32_16x16x32_bf16 v[0:3], v[36:39], v[84:87], v[0:3]
	v_mfma_f32_16x16x32_bf16 v[4:7], v[36:39], v[92:95], v[4:7]
	v_mfma_f32_16x16x32_bf16 v[8:11], v[36:39], v[100:103], v[8:11]
	v_mfma_f32_16x16x32_bf16 v[12:15], v[36:39], v[108:111], v[12:15]
	v_mfma_f32_16x16x32_bf16 v[16:19], v[36:39], v[116:119], v[16:19]
	v_mfma_f32_16x16x32_bf16 v[20:23], v[36:39], v[124:127], v[20:23]
	v_mfma_f32_16x16x32_bf16 v[24:27], v[36:39], v[132:135], v[24:27]
	v_mfma_f32_16x16x32_bf16 v[28:31], v[36:39], v[228:231], v[28:31]
	s_nop 3
	ds_write2_b32 v237, v0, v4 offset0:0 offset1:16
	ds_write2_b32 v237, v8, v12 offset0:32 offset1:48
	ds_write2_b32 v237, v1, v5 offset0:64 offset1:80
	ds_write2_b32 v237, v9, v13 offset0:96 offset1:112
	ds_write2_b32 v237, v2, v6 offset0:128 offset1:144
	ds_write2_b32 v237, v10, v14 offset0:160 offset1:176
	ds_write2_b32 v237, v3, v7 offset0:192 offset1:208
	ds_write2_b32 v237, v11, v15 offset0:224 offset1:240
	ds_write2_b32 v238, v16, v20 offset0:0 offset1:16
	ds_write2_b32 v238, v24, v28 offset0:32 offset1:48
	ds_write2_b32 v238, v17, v21 offset0:64 offset1:80
	ds_write2_b32 v238, v25, v29 offset0:96 offset1:112
	ds_write2_b32 v238, v18, v22 offset0:128 offset1:144
	ds_write2_b32 v238, v26, v30 offset0:160 offset1:176
	ds_write2_b32 v238, v19, v23 offset0:192 offset1:208
	ds_write2_b32 v238, v27, v31 offset0:224 offset1:240
	s_waitcnt lgkmcnt(0)
	ds_read2st64_b32 v[0:1], v239 offset0:36 offset1:37
	ds_read2st64_b32 v[2:3], v239 offset0:38 offset1:39
	ds_read2st64_b32 v[4:5], v239 offset0:40 offset1:41
	ds_read2st64_b32 v[6:7], v239 offset0:42 offset1:43
	ds_read2st64_b32 v[8:9], v239 offset0:44 offset1:45
	ds_read2st64_b32 v[10:11], v239 offset0:46 offset1:47
	ds_read2st64_b32 v[12:13], v239 offset0:48 offset1:49
	ds_read2st64_b32 v[14:15], v239 offset0:50 offset1:51
	ds_read2st64_b32 v[16:17], v239 offset0:52 offset1:53
	ds_read2st64_b32 v[18:19], v239 offset0:54 offset1:55
	ds_read2st64_b32 v[20:21], v239 offset0:56 offset1:57
	ds_read2st64_b32 v[22:23], v239 offset0:58 offset1:59
	ds_read2st64_b32 v[24:25], v239 offset0:60 offset1:61
	ds_read2st64_b32 v[26:27], v239 offset0:62 offset1:63
	ds_read2st64_b32 v[28:29], v239 offset0:64 offset1:65
	ds_read2st64_b32 v[30:31], v239 offset0:66 offset1:67
	ds_read_u16 v48, v240 offset:4608
	ds_read_u16 v49, v240 offset:4752
	ds_read_u16 v50, v240 offset:4896
	ds_read_u16 v51, v240 offset:5040
	ds_read_u16 v52, v240 offset:5184
	ds_read_u16 v53, v240 offset:5328
	ds_read_u16 v54, v240 offset:5472
	ds_read_u16 v55, v240 offset:5616
	ds_read_u16 v56, v240 offset:5760
	ds_read_u16 v57, v240 offset:5904
	ds_read_u16 v58, v240 offset:6048
	ds_read_u16 v59, v240 offset:6192
	ds_read_u16 v60, v240 offset:6336
	ds_read_u16 v61, v240 offset:6480
	ds_read_u16 v62, v240 offset:6624
	ds_read_u16 v63, v240 offset:6768
	s_waitcnt vmcnt(16)
	v_lshlrev_b32_e32 v206, 16, v190
	v_lshlrev_b32_e32 v207, 16, v191
	v_lshlrev_b32_e32 v208, 16, v192
	v_lshlrev_b32_e32 v209, 16, v193
	v_lshlrev_b32_e32 v210, 16, v194
	v_lshlrev_b32_e32 v211, 16, v195
	v_lshlrev_b32_e32 v212, 16, v196
	v_lshlrev_b32_e32 v213, 16, v197
	v_lshlrev_b32_e32 v214, 16, v198
	v_lshlrev_b32_e32 v215, 16, v199
	v_lshlrev_b32_e32 v216, 16, v200
	v_lshlrev_b32_e32 v217, 16, v201
	v_lshlrev_b32_e32 v218, 16, v202
	v_lshlrev_b32_e32 v219, 16, v203
	v_lshlrev_b32_e32 v222, 16, v204
	v_lshlrev_b32_e32 v223, 16, v205
	v_pk_mul_f32 v[32:33], v[140:141], v[206:207]
	v_pk_mul_f32 v[34:35], v[140:141], v[208:209]
	v_pk_mul_f32 v[36:37], v[140:141], v[210:211]
	v_pk_mul_f32 v[38:39], v[140:141], v[212:213]
	v_pk_mul_f32 v[40:41], v[140:141], v[214:215]
	v_pk_mul_f32 v[42:43], v[140:141], v[216:217]
	v_pk_mul_f32 v[44:45], v[140:141], v[218:219]
	v_pk_mul_f32 v[46:47], v[140:141], v[222:223]
	v_pk_mul_f32 v[32:33], v[32:33], v[206:207]
	v_pk_mul_f32 v[34:35], v[34:35], v[208:209]
	v_pk_mul_f32 v[36:37], v[36:37], v[210:211]
	v_pk_mul_f32 v[38:39], v[38:39], v[212:213]
	v_pk_mul_f32 v[40:41], v[40:41], v[214:215]
	v_pk_mul_f32 v[42:43], v[42:43], v[216:217]
	v_pk_mul_f32 v[44:45], v[44:45], v[218:219]
	v_pk_mul_f32 v[46:47], v[46:47], v[222:223]
	v_fma_f32 v32, v32, v206, v206
	v_fma_f32 v33, v33, v207, v207
	v_fma_f32 v34, v34, v208, v208
	v_fma_f32 v35, v35, v209, v209
	v_fma_f32 v36, v36, v210, v210
	v_fma_f32 v37, v37, v211, v211
	v_fma_f32 v38, v38, v212, v212
	v_fma_f32 v39, v39, v213, v213
	v_fma_f32 v40, v40, v214, v214
	v_fma_f32 v41, v41, v215, v215
	v_fma_f32 v42, v42, v216, v216
	v_fma_f32 v43, v43, v217, v217
	v_fma_f32 v44, v44, v218, v218
	v_fma_f32 v45, v45, v219, v219
	v_fma_f32 v46, v46, v222, v222
	v_fma_f32 v47, v47, v223, v223
	s_mov_b32 s98, 0xc0135761
	v_pk_mul_f32 v[32:33], v[32:33], s[98:99] op_sel_hi:[1,0]
	v_pk_mul_f32 v[34:35], v[34:35], s[98:99] op_sel_hi:[1,0]
	v_pk_mul_f32 v[36:37], v[36:37], s[98:99] op_sel_hi:[1,0]
	v_pk_mul_f32 v[38:39], v[38:39], s[98:99] op_sel_hi:[1,0]
	v_pk_mul_f32 v[40:41], v[40:41], s[98:99] op_sel_hi:[1,0]
	v_pk_mul_f32 v[42:43], v[42:43], s[98:99] op_sel_hi:[1,0]
	v_pk_mul_f32 v[44:45], v[44:45], s[98:99] op_sel_hi:[1,0]
	v_pk_mul_f32 v[46:47], v[46:47], s[98:99] op_sel_hi:[1,0]
	v_exp_f32_e32 v32, v32
	v_exp_f32_e32 v33, v33
; #define LAS __attribute__((address_space(3)))
; #define WAVE_SYNC() asm volatile("s_waitcnt lgkmcnt(0)" ::: "memory")
; __device__ __forceinline__ float sigmoid_f(float x) { return rcpf_(1.f + __expf(-x)); }
; __device__ __forceinline__ float gelu_tanh_f(float x) { const float y = 0.7978845608028654f * (x + 0.044715f * x * x * x); return x * sigmoid_f(2.f * y); }
; template <bool FINAL, int D>
; __device__ __forceinline__ void rg_dir(PREF p, int l, int h, int ch, int sidx, int rowbase  , LAS bf16_t* sXc, LAS float* stg, int lane) {
;     ...
;             for (int ti = 0; ti < 16; ++ti) { const size_t row = (size_t)(rowbase + mt * 16 + 15 - ti); grv[ti] = __builtin_bit_cast(float, (unsigned)P[row * PW + 512 + ch]); hfv[ti] = __builtin_bit_cast(float, (unsigned)TMP[row * 512 + ch]); }
;             __builtin_amdgcn_sched_barrier(0);
; #pragma unroll
;             for (int ti = 0; ti < 16; ++ti) { grv[ti] = bf2f(__builtin_bit_cast(unsigned, grv[ti])); hfv[ti] = bf2f(__builtin_bit_cast(unsigned, hfv[ti])); }
;         }
;         const bf16x8 A0 = *(const LAS bf16x8*)(sXc + (mt * 16 + (lane & 15)) * 72 + (lane >> 4) * 8), A1 = *(const LAS bf16x8*)(sXc + (mt * 16 + (lane & 15)) * 72 + 32 + (lane >> 4) * 8);
;         f32x4 ar[4], ai[4];
; #pragma unroll
;         for (int nt = 0; nt < 4; ++nt) { const f32x4 z = {0.f, 0.f, 0.f, 0.f};
;             ar[nt] = mfma16(A0, Br[nt][0], z); ar[nt] = mfma16(A1, Br[nt][1], ar[nt]); ai[nt] = mfma16(A0, Bi[nt][0], z); ai[nt] = mfma16(A1, Bi[nt][1], ai[nt]); }
;         WAVE_SYNC();
; #pragma unroll
;         for (int nt = 0; nt < 4; ++nt)
; #pragma unroll
;             for (int j = 0; j < 4; ++j) { const int o = ((lane >> 4) * 4 + j) * 64 + nt * 16 + (lane & 15); stg[o] = ar[nt][j]; stg[1024 + o] = ai[nt][j]; }
;         WAVE_SYNC();
;         float av[16], iv[16];
; #pragma unroll
;         for (int ti = 0; ti < 16; ++ti) { const int tk = D ? 15 - ti : ti;
;             const float zr = stg[tk * 64 + lane] + ba, zi = stg[1024 + tk * 64 + lane] + bi;
;             const float r = sigmoid_f(zr), ig = sigmoid_f(zi);
;             const float a = __builtin_amdgcn_exp2f(r * sp8);
;             const float xc = bf2f(sXc[(mt * 16 + tk) * 72 + lane]);
;             av[ti] = a; iv[ti] = __builtin_amdgcn_sqrtf(fmaxf(1.f - a * a, 0.f)) * ig * xc;
;             if (FINAL && D == 1) grv[ti] = gelu_tanh_f(grv[ti]);
	v_exp_f32_e32 v34, v34
	v_exp_f32_e32 v35, v35
	v_exp_f32_e32 v36, v36
	v_exp_f32_e32 v37, v37
	v_exp_f32_e32 v38, v38
	v_exp_f32_e32 v39, v39
	v_exp_f32_e32 v40, v40
	v_exp_f32_e32 v41, v41
	v_exp_f32_e32 v42, v42
	v_exp_f32_e32 v43, v43
	v_exp_f32_e32 v44, v44
	v_exp_f32_e32 v45, v45
	v_exp_f32_e32 v46, v46
	v_exp_f32_e32 v47, v47
	v_pk_add_f32 v[32:33], v[32:33], 1.0 op_sel_hi:[1,0]
	v_pk_add_f32 v[34:35], v[34:35], 1.0 op_sel_hi:[1,0]
	v_pk_add_f32 v[36:37], v[36:37], 1.0 op_sel_hi:[1,0]
	v_pk_add_f32 v[38:39], v[38:39], 1.0 op_sel_hi:[1,0]
	v_pk_add_f32 v[40:41], v[40:41], 1.0 op_sel_hi:[1,0]
	v_pk_add_f32 v[42:43], v[42:43], 1.0 op_sel_hi:[1,0]
	v_pk_add_f32 v[44:45], v[44:45], 1.0 op_sel_hi:[1,0]
	v_pk_add_f32 v[46:47], v[46:47], 1.0 op_sel_hi:[1,0]
	v_rcp_f32_e32 v32, v32
	v_rcp_f32_e32 v33, v33
	v_rcp_f32_e32 v34, v34
	v_rcp_f32_e32 v35, v35
	v_rcp_f32_e32 v36, v36
	v_rcp_f32_e32 v37, v37
	v_rcp_f32_e32 v38, v38
	v_rcp_f32_e32 v39, v39
	v_rcp_f32_e32 v40, v40
	v_rcp_f32_e32 v41, v41
	v_rcp_f32_e32 v42, v42
	v_rcp_f32_e32 v43, v43
	v_rcp_f32_e32 v44, v44
	v_rcp_f32_e32 v45, v45
	v_rcp_f32_e32 v46, v46
	v_rcp_f32_e32 v47, v47
	s_nop 0
	v_pk_mul_f32 v[206:207], v[32:33], v[206:207]
	v_pk_mul_f32 v[208:209], v[34:35], v[208:209]
	v_pk_mul_f32 v[210:211], v[36:37], v[210:211]
	v_pk_mul_f32 v[212:213], v[38:39], v[212:213]
	v_pk_mul_f32 v[214:215], v[40:41], v[214:215]
	v_pk_mul_f32 v[216:217], v[42:43], v[216:217]
	v_pk_mul_f32 v[218:219], v[44:45], v[218:219]
	v_pk_mul_f32 v[222:223], v[46:47], v[222:223]
	s_add_i32 s39, s15, 16
	s_mul_hi_u32 s83, s39, 0x1600
	s_mul_i32 s82, s39, 0x1600
	s_add_u32 s82, s82, s0
	s_addc_u32 s83, s83, s1
	s_add_u32 s82, s82, 0xbc00400
	s_addc_u32 s83, s83, 0
	global_load_ushort v190, v234, s[82:83]
	s_add_u32 s82, s82, 0x1600
	s_addc_u32 s83, s83, 0
	global_load_ushort v191, v234, s[82:83]
	s_add_u32 s82, s82, 0x1600
	s_addc_u32 s83, s83, 0
	global_load_ushort v192, v234, s[82:83]
	s_add_u32 s82, s82, 0x1600
	s_addc_u32 s83, s83, 0
	global_load_ushort v193, v234, s[82:83]
	s_add_u32 s82, s82, 0x1600
	s_addc_u32 s83, s83, 0
	global_load_ushort v194, v234, s[82:83]
	s_add_u32 s82, s82, 0x1600
	s_addc_u32 s83, s83, 0
	global_load_ushort v195, v234, s[82:83]
	s_add_u32 s82, s82, 0x1600
	s_addc_u32 s83, s83, 0
	global_load_ushort v196, v234, s[82:83]
	s_add_u32 s82, s82, 0x1600
	s_addc_u32 s83, s83, 0
	global_load_ushort v197, v234, s[82:83]
	s_add_u32 s82, s82, 0x1600
	s_addc_u32 s83, s83, 0
	global_load_ushort v198, v234, s[82:83]
	s_add_u32 s82, s82, 0x1600
	s_addc_u32 s83, s83, 0
	global_load_ushort v199, v234, s[82:83]
	s_add_u32 s82, s82, 0x1600
	s_addc_u32 s83, s83, 0
	global_load_ushort v200, v234, s[82:83]
	s_add_u32 s82, s82, 0x1600
	s_addc_u32 s83, s83, 0
	global_load_ushort v201, v234, s[82:83]
	s_add_u32 s82, s82, 0x1600
	s_addc_u32 s83, s83, 0
	global_load_ushort v202, v234, s[82:83]
	s_add_u32 s82, s82, 0x1600
	s_addc_u32 s83, s83, 0
	global_load_ushort v203, v234, s[82:83]
	s_add_u32 s82, s82, 0x1600
	s_addc_u32 s83, s83, 0
	global_load_ushort v204, v234, s[82:83]
	s_add_u32 s82, s82, 0x1600
	s_addc_u32 s83, s83, 0
	global_load_ushort v205, v234, s[82:83]
	s_waitcnt lgkmcnt(0)
	v_pk_fma_f32 v[0:1], v[0:1], v[248:249], v[242:243]
	v_pk_fma_f32 v[2:3], v[2:3], v[248:249], v[242:243]
	v_pk_fma_f32 v[4:5], v[4:5], v[248:249], v[242:243]
	v_pk_fma_f32 v[6:7], v[6:7], v[248:249], v[242:243]
	v_pk_fma_f32 v[8:9], v[8:9], v[248:249], v[242:243]
	v_pk_fma_f32 v[10:11], v[10:11], v[248:249], v[242:243]
	v_pk_fma_f32 v[12:13], v[12:13], v[248:249], v[242:243]
	v_pk_fma_f32 v[14:15], v[14:15], v[248:249], v[242:243]
	v_pk_fma_f32 v[16:17], v[16:17], v[248:249], v[244:245]
	v_pk_fma_f32 v[18:19], v[18:19], v[248:249], v[244:245]
	v_pk_fma_f32 v[20:21], v[20:21], v[248:249], v[244:245]
	v_pk_fma_f32 v[22:23], v[22:23], v[248:249], v[244:245]
	v_pk_fma_f32 v[24:25], v[24:25], v[248:249], v[244:245]
	v_pk_fma_f32 v[26:27], v[26:27], v[248:249], v[244:245]
	v_pk_fma_f32 v[28:29], v[28:29], v[248:249], v[244:245]
	v_pk_fma_f32 v[30:31], v[30:31], v[248:249], v[244:245]
	v_exp_f32_e32 v0, v0
	v_exp_f32_e32 v1, v1
	v_exp_f32_e32 v2, v2
	v_exp_f32_e32 v3, v3
	v_exp_f32_e32 v4, v4
	v_exp_f32_e32 v5, v5
	v_exp_f32_e32 v6, v6
	v_exp_f32_e32 v7, v7
	v_exp_f32_e32 v8, v8
	v_exp_f32_e32 v9, v9
	v_exp_f32_e32 v10, v10
	v_exp_f32_e32 v11, v11
	v_exp_f32_e32 v12, v12
	v_exp_f32_e32 v13, v13
	v_exp_f32_e32 v14, v14
	v_exp_f32_e32 v15, v15
	v_exp_f32_e32 v16, v16
	v_exp_f32_e32 v17, v17
	v_exp_f32_e32 v18, v18
	v_exp_f32_e32 v19, v19
	v_exp_f32_e32 v20, v20
	v_exp_f32_e32 v21, v21
	v_exp_f32_e32 v22, v22
	v_exp_f32_e32 v23, v23
	v_exp_f32_e32 v24, v24
	v_exp_f32_e32 v25, v25
	v_exp_f32_e32 v26, v26
	v_exp_f32_e32 v27, v27
	v_exp_f32_e32 v28, v28
	v_exp_f32_e32 v29, v29
	v_exp_f32_e32 v30, v30
	v_exp_f32_e32 v31, v31
	v_pk_add_f32 v[0:1], v[0:1], 1.0 op_sel_hi:[1,0]
	v_pk_add_f32 v[2:3], v[2:3], 1.0 op_sel_hi:[1,0]
	v_pk_add_f32 v[4:5], v[4:5], 1.0 op_sel_hi:[1,0]
	v_pk_add_f32 v[6:7], v[6:7], 1.0 op_sel_hi:[1,0]
	v_pk_add_f32 v[8:9], v[8:9], 1.0 op_sel_hi:[1,0]
	v_pk_add_f32 v[10:11], v[10:11], 1.0 op_sel_hi:[1,0]
	v_pk_add_f32 v[12:13], v[12:13], 1.0 op_sel_hi:[1,0]
	v_pk_add_f32 v[14:15], v[14:15], 1.0 op_sel_hi:[1,0]
	v_pk_add_f32 v[16:17], v[16:17], 1.0 op_sel_hi:[1,0]
	v_pk_add_f32 v[18:19], v[18:19], 1.0 op_sel_hi:[1,0]
	v_pk_add_f32 v[20:21], v[20:21], 1.0 op_sel_hi:[1,0]
	v_pk_add_f32 v[22:23], v[22:23], 1.0 op_sel_hi:[1,0]
	v_pk_add_f32 v[24:25], v[24:25], 1.0 op_sel_hi:[1,0]
	v_pk_add_f32 v[26:27], v[26:27], 1.0 op_sel_hi:[1,0]
	v_pk_add_f32 v[28:29], v[28:29], 1.0 op_sel_hi:[1,0]
	v_pk_add_f32 v[30:31], v[30:31], 1.0 op_sel_hi:[1,0]
; __device__ __forceinline__ unsigned f2bf(float f) { unsigned r; asm("v_cvt_pk_bf16_f32 %0, %1, %1" : "=v"(r) : "v"(f)); return r & 0xffffu; }
; __device__ __forceinline__ float sigmoid_f(float x) { return rcpf_(1.f + __expf(-x)); }
; __device__ __forceinline__ float gelu_tanh_f(float x) { const float y = 0.7978845608028654f * (x + 0.044715f * x * x * x); return x * sigmoid_f(2.f * y); }
; template <bool FINAL, int D>
; __device__ __forceinline__ void rg_dir(PREF p, int l, int h, int ch, int sidx, int rowbase  , LAS bf16_t* sXc, LAS float* stg, int lane) {
;     ...
;         for (int ti = 0; ti < 16; ++ti) { const int tk = D ? 15 - ti : ti;
;             const float zr = stg[tk * 64 + lane] + ba, zi = stg[1024 + tk * 64 + lane] + bi;
;             const float r = sigmoid_f(zr), ig = sigmoid_f(zi);
;             const float a = __builtin_amdgcn_exp2f(r * sp8);
;             const float xc = bf2f(sXc[(mt * 16 + tk) * 72 + lane]);
;             av[ti] = a; iv[ti] = __builtin_amdgcn_sqrtf(fmaxf(1.f - a * a, 0.f)) * ig * xc;
;             if (FINAL && D == 1) grv[ti] = gelu_tanh_f(grv[ti]);
;         }
; #pragma unroll
;         for (int ti = 0; ti < 16; ++ti) { const int tk = D ? 15 - ti : ti;
;             hc = av[ti] * hc + iv[ti]; Ap *= av[ti];
;             if (FINAL) { const size_t row = (size_t)(rowbase + mt * 16 + tk);
;                 if (D == 0) TMP[row * 512 + ch] = (bf16_t)f2bf(hc);
;                 else MIX[row * DM + ch] = (bf16_t)f2bf(grv[ti] * (hfv[ti] + hc)); }
	v_rcp_f32_e32 v0, v0
	v_rcp_f32_e32 v1, v1
	v_rcp_f32_e32 v2, v2
	v_rcp_f32_e32 v3, v3
	v_rcp_f32_e32 v4, v4
	v_rcp_f32_e32 v5, v5
	v_rcp_f32_e32 v6, v6
	v_rcp_f32_e32 v7, v7
	v_rcp_f32_e32 v8, v8
	v_rcp_f32_e32 v9, v9
	v_rcp_f32_e32 v10, v10
	v_rcp_f32_e32 v11, v11
	v_rcp_f32_e32 v12, v12
	v_rcp_f32_e32 v13, v13
	v_rcp_f32_e32 v14, v14
	v_rcp_f32_e32 v15, v15
	v_rcp_f32_e32 v16, v16
	v_rcp_f32_e32 v17, v17
	v_rcp_f32_e32 v18, v18
	v_rcp_f32_e32 v19, v19
	v_rcp_f32_e32 v20, v20
	v_rcp_f32_e32 v21, v21
	v_rcp_f32_e32 v22, v22
	v_rcp_f32_e32 v23, v23
	v_rcp_f32_e32 v24, v24
	v_rcp_f32_e32 v25, v25
	v_rcp_f32_e32 v26, v26
	v_rcp_f32_e32 v27, v27
	v_rcp_f32_e32 v28, v28
	v_rcp_f32_e32 v29, v29
	v_rcp_f32_e32 v30, v30
	v_rcp_f32_e32 v31, v31
	v_pk_mul_f32 v[0:1], v[246:247], v[0:1]
	v_pk_mul_f32 v[2:3], v[246:247], v[2:3]
	v_pk_mul_f32 v[4:5], v[246:247], v[4:5]
	v_pk_mul_f32 v[6:7], v[246:247], v[6:7]
	v_pk_mul_f32 v[8:9], v[246:247], v[8:9]
	v_pk_mul_f32 v[10:11], v[246:247], v[10:11]
	v_pk_mul_f32 v[12:13], v[246:247], v[12:13]
	v_pk_mul_f32 v[14:15], v[246:247], v[14:15]
	v_lshlrev_b32_e32 v48, 16, v48
	v_lshlrev_b32_e32 v49, 16, v49
	v_lshlrev_b32_e32 v50, 16, v50
	v_lshlrev_b32_e32 v51, 16, v51
	v_lshlrev_b32_e32 v52, 16, v52
	v_lshlrev_b32_e32 v53, 16, v53
	v_lshlrev_b32_e32 v54, 16, v54
	v_lshlrev_b32_e32 v55, 16, v55
	v_lshlrev_b32_e32 v56, 16, v56
	v_lshlrev_b32_e32 v57, 16, v57
	v_lshlrev_b32_e32 v58, 16, v58
	v_lshlrev_b32_e32 v59, 16, v59
	v_lshlrev_b32_e32 v60, 16, v60
	v_lshlrev_b32_e32 v61, 16, v61
	v_lshlrev_b32_e32 v62, 16, v62
	v_lshlrev_b32_e32 v63, 16, v63
	v_exp_f32_e32 v0, v0
	v_exp_f32_e32 v1, v1
	v_exp_f32_e32 v2, v2
	v_exp_f32_e32 v3, v3
	v_exp_f32_e32 v4, v4
	v_exp_f32_e32 v5, v5
	v_exp_f32_e32 v6, v6
	v_exp_f32_e32 v7, v7
	v_exp_f32_e32 v8, v8
	v_exp_f32_e32 v9, v9
	v_exp_f32_e32 v10, v10
	v_exp_f32_e32 v11, v11
	v_exp_f32_e32 v12, v12
	v_exp_f32_e32 v13, v13
	v_exp_f32_e32 v14, v14
	v_exp_f32_e32 v15, v15
	v_fma_f32 v32, -v0, v0, 1.0
	v_fma_f32 v33, -v1, v1, 1.0
	v_fma_f32 v34, -v2, v2, 1.0
	v_fma_f32 v35, -v3, v3, 1.0
	v_fma_f32 v36, -v4, v4, 1.0
	v_fma_f32 v37, -v5, v5, 1.0
	v_fma_f32 v38, -v6, v6, 1.0
	v_fma_f32 v39, -v7, v7, 1.0
	v_fma_f32 v40, -v8, v8, 1.0
	v_fma_f32 v41, -v9, v9, 1.0
	v_fma_f32 v42, -v10, v10, 1.0
	v_fma_f32 v43, -v11, v11, 1.0
	v_fma_f32 v44, -v12, v12, 1.0
	v_fma_f32 v45, -v13, v13, 1.0
	v_fma_f32 v46, -v14, v14, 1.0
	v_fma_f32 v47, -v15, v15, 1.0
	v_max_f32_e32 v32, 0, v32
	v_max_f32_e32 v33, 0, v33
	v_max_f32_e32 v34, 0, v34
	v_max_f32_e32 v35, 0, v35
	v_max_f32_e32 v36, 0, v36
	v_max_f32_e32 v37, 0, v37
	v_max_f32_e32 v38, 0, v38
	v_max_f32_e32 v39, 0, v39
	v_max_f32_e32 v40, 0, v40
	v_max_f32_e32 v41, 0, v41
	v_max_f32_e32 v42, 0, v42
	v_max_f32_e32 v43, 0, v43
	v_max_f32_e32 v44, 0, v44
	v_max_f32_e32 v45, 0, v45
	v_max_f32_e32 v46, 0, v46
	v_max_f32_e32 v47, 0, v47
	v_sqrt_f32_e32 v32, v32
	v_sqrt_f32_e32 v33, v33
	v_sqrt_f32_e32 v34, v34
	v_sqrt_f32_e32 v35, v35
	v_sqrt_f32_e32 v36, v36
	v_sqrt_f32_e32 v37, v37
	v_sqrt_f32_e32 v38, v38
	v_sqrt_f32_e32 v39, v39
	v_sqrt_f32_e32 v40, v40
	v_sqrt_f32_e32 v41, v41
	v_sqrt_f32_e32 v42, v42
	v_sqrt_f32_e32 v43, v43
	v_sqrt_f32_e32 v44, v44
	v_sqrt_f32_e32 v45, v45
	v_sqrt_f32_e32 v46, v46
	v_sqrt_f32_e32 v47, v47
	s_nop 0
	v_pk_mul_f32 v[16:17], v[16:17], v[32:33]
	v_pk_mul_f32 v[18:19], v[18:19], v[34:35]
	v_pk_mul_f32 v[20:21], v[20:21], v[36:37]
	v_pk_mul_f32 v[22:23], v[22:23], v[38:39]
	v_pk_mul_f32 v[24:25], v[24:25], v[40:41]
	v_pk_mul_f32 v[26:27], v[26:27], v[42:43]
	v_pk_mul_f32 v[28:29], v[28:29], v[44:45]
	v_pk_mul_f32 v[30:31], v[30:31], v[46:47]
	v_pk_mul_f32 v[16:17], v[16:17], v[48:49]
	v_pk_mul_f32 v[18:19], v[18:19], v[50:51]
	v_pk_mul_f32 v[20:21], v[20:21], v[52:53]
	v_pk_mul_f32 v[22:23], v[22:23], v[54:55]
	v_pk_mul_f32 v[24:25], v[24:25], v[56:57]
	v_pk_mul_f32 v[26:27], v[26:27], v[58:59]
	v_pk_mul_f32 v[28:29], v[28:29], v[60:61]
	v_pk_mul_f32 v[30:31], v[30:31], v[62:63]
	s_add_i32 s39, s15, 47
	s_lshl_b32 s39, s39, 11
	s_add_u32 s90, s0, 0x7b00000
	s_addc_u32 s91, s1, 0
	s_add_u32 s90, s90, s39
	s_addc_u32 s91, s91, 0
	v_lshlrev_b32_e32 v48, 16, v174
	v_and_b32_e32 v49, 0xffff0000, v174
	v_lshlrev_b32_e32 v50, 16, v175
	v_and_b32_e32 v51, 0xffff0000, v175
	v_lshlrev_b32_e32 v52, 16, v176
	v_and_b32_e32 v53, 0xffff0000, v176
	v_lshlrev_b32_e32 v54, 16, v177
	v_and_b32_e32 v55, 0xffff0000, v177
	v_lshlrev_b32_e32 v56, 16, v178
	v_and_b32_e32 v57, 0xffff0000, v178
	v_lshlrev_b32_e32 v58, 16, v179
	v_and_b32_e32 v59, 0xffff0000, v179
	v_lshlrev_b32_e32 v60, 16, v180
	v_and_b32_e32 v61, 0xffff0000, v180
	v_lshlrev_b32_e32 v62, 16, v181
	v_and_b32_e32 v63, 0xffff0000, v181
	v_fma_f32 v47, v15, v250, v31
	v_fma_f32 v46, v14, v47, v30
	v_fma_f32 v45, v13, v46, v29
	v_fma_f32 v44, v12, v45, v28
	v_fma_f32 v43, v11, v44, v27
	v_fma_f32 v42, v10, v43, v26
	v_fma_f32 v41, v9, v42, v25
	v_fma_f32 v40, v8, v41, v24
	v_fma_f32 v39, v7, v40, v23
	v_fma_f32 v38, v6, v39, v22
	v_fma_f32 v37, v5, v38, v21
	v_fma_f32 v36, v4, v37, v20
	v_fma_f32 v35, v3, v36, v19
	v_fma_f32 v34, v2, v35, v18
	v_fma_f32 v33, v1, v34, v17
	v_fma_f32 v32, v0, v33, v16
	v_mov_b32_e32 v250, v32
	v_pk_add_f32 v[48:49], v[48:49], v[32:33]
	v_pk_add_f32 v[50:51], v[50:51], v[34:35]
	v_pk_add_f32 v[52:53], v[52:53], v[36:37]
	v_pk_add_f32 v[54:55], v[54:55], v[38:39]
	v_pk_add_f32 v[56:57], v[56:57], v[40:41]
	v_pk_add_f32 v[58:59], v[58:59], v[42:43]
	v_pk_add_f32 v[60:61], v[60:61], v[44:45]
	v_pk_add_f32 v[62:63], v[62:63], v[46:47]
	v_pk_mul_f32 v[48:49], v[206:207], v[48:49]
	v_pk_mul_f32 v[50:51], v[208:209], v[50:51]
	v_pk_mul_f32 v[52:53], v[210:211], v[52:53]
; #define LAS __attribute__((address_space(3)))
; #define WAVE_SYNC() asm volatile("s_waitcnt lgkmcnt(0)" ::: "memory")
; __device__ __forceinline__ unsigned f2bf(float f) { unsigned r; asm("v_cvt_pk_bf16_f32 %0, %1, %1" : "=v"(r) : "v"(f)); return r & 0xffffu; }
; __device__ __forceinline__ float sigmoid_f(float x) { return rcpf_(1.f + __expf(-x)); }
; template <bool FINAL, int D>
; __device__ __forceinline__ void rg_dir(PREF p, int l, int h, int ch, int sidx, int rowbase  , LAS bf16_t* sXc, LAS float* stg, int lane) {
;     ...
;         const bf16x8 A0 = *(const LAS bf16x8*)(sXc + (mt * 16 + (lane & 15)) * 72 + (lane >> 4) * 8), A1 = *(const LAS bf16x8*)(sXc + (mt * 16 + (lane & 15)) * 72 + 32 + (lane >> 4) * 8);
;         f32x4 ar[4], ai[4];
; #pragma unroll
;         for (int nt = 0; nt < 4; ++nt) { const f32x4 z = {0.f, 0.f, 0.f, 0.f};
;             ar[nt] = mfma16(A0, Br[nt][0], z); ar[nt] = mfma16(A1, Br[nt][1], ar[nt]); ai[nt] = mfma16(A0, Bi[nt][0], z); ai[nt] = mfma16(A1, Bi[nt][1], ai[nt]); }
;         WAVE_SYNC();
; #pragma unroll
;         for (int nt = 0; nt < 4; ++nt)
; #pragma unroll
;             for (int j = 0; j < 4; ++j) { const int o = ((lane >> 4) * 4 + j) * 64 + nt * 16 + (lane & 15); stg[o] = ar[nt][j]; stg[1024 + o] = ai[nt][j]; }
;         WAVE_SYNC();
;         float av[16], iv[16];
; #pragma unroll
;         for (int ti = 0; ti < 16; ++ti) { const int tk = D ? 15 - ti : ti;
;             const float zr = stg[tk * 64 + lane] + ba, zi = stg[1024 + tk * 64 + lane] + bi;
;             const float r = sigmoid_f(zr), ig = sigmoid_f(zi);
;             const float a = __builtin_amdgcn_exp2f(r * sp8);
;             const float xc = bf2f(sXc[(mt * 16 + tk) * 72 + lane]);
;             av[ti] = a; iv[ti] = __builtin_amdgcn_sqrtf(fmaxf(1.f - a * a, 0.f)) * ig * xc;
;             if (FINAL && D == 1) grv[ti] = gelu_tanh_f(grv[ti]);
;         }
; #pragma unroll
;         for (int ti = 0; ti < 16; ++ti) { const int tk = D ? 15 - ti : ti;
;             hc = av[ti] * hc + iv[ti]; Ap *= av[ti];
;             if (FINAL) { const size_t row = (size_t)(rowbase + mt * 16 + tk);
;                 if (D == 0) TMP[row * 512 + ch] = (bf16_t)f2bf(hc);
;                 else MIX[row * DM + ch] = (bf16_t)f2bf(grv[ti] * (hfv[ti] + hc)); }
	v_pk_mul_f32 v[54:55], v[212:213], v[54:55]
	v_pk_mul_f32 v[56:57], v[214:215], v[56:57]
	v_pk_mul_f32 v[58:59], v[216:217], v[58:59]
	v_pk_mul_f32 v[60:61], v[218:219], v[60:61]
	v_pk_mul_f32 v[62:63], v[222:223], v[62:63]
	v_cvt_pk_bf16_f32 v48, v48, v48
	v_cvt_pk_bf16_f32 v49, v49, v49
	v_cvt_pk_bf16_f32 v50, v50, v50
	v_cvt_pk_bf16_f32 v51, v51, v51
	v_cvt_pk_bf16_f32 v52, v52, v52
	v_cvt_pk_bf16_f32 v53, v53, v53
	v_cvt_pk_bf16_f32 v54, v54, v54
	v_cvt_pk_bf16_f32 v55, v55, v55
	v_cvt_pk_bf16_f32 v56, v56, v56
	v_cvt_pk_bf16_f32 v57, v57, v57
	v_cvt_pk_bf16_f32 v58, v58, v58
	v_cvt_pk_bf16_f32 v59, v59, v59
	v_cvt_pk_bf16_f32 v60, v60, v60
	v_cvt_pk_bf16_f32 v61, v61, v61
	v_cvt_pk_bf16_f32 v62, v62, v62
	v_cvt_pk_bf16_f32 v63, v63, v63
	global_store_short v234, v63, s[90:91]
	s_sub_u32 s90, s90, 0x800
	s_subb_u32 s91, s91, 0
	global_store_short v234, v62, s[90:91]
	s_sub_u32 s90, s90, 0x800
	s_subb_u32 s91, s91, 0
	global_store_short v234, v61, s[90:91]
	s_sub_u32 s90, s90, 0x800
	s_subb_u32 s91, s91, 0
	global_store_short v234, v60, s[90:91]
	s_sub_u32 s90, s90, 0x800
	s_subb_u32 s91, s91, 0
	global_store_short v234, v59, s[90:91]
	s_sub_u32 s90, s90, 0x800
	s_subb_u32 s91, s91, 0
	global_store_short v234, v58, s[90:91]
	s_sub_u32 s90, s90, 0x800
	s_subb_u32 s91, s91, 0
	global_store_short v234, v57, s[90:91]
	s_sub_u32 s90, s90, 0x800
	s_subb_u32 s91, s91, 0
	global_store_short v234, v56, s[90:91]
	s_sub_u32 s90, s90, 0x800
	s_subb_u32 s91, s91, 0
	global_store_short v234, v55, s[90:91]
	s_sub_u32 s90, s90, 0x800
	s_subb_u32 s91, s91, 0
	global_store_short v234, v54, s[90:91]
	s_sub_u32 s90, s90, 0x800
	s_subb_u32 s91, s91, 0
	global_store_short v234, v53, s[90:91]
	s_sub_u32 s90, s90, 0x800
	s_subb_u32 s91, s91, 0
	global_store_short v234, v52, s[90:91]
	s_sub_u32 s90, s90, 0x800
	s_subb_u32 s91, s91, 0
	global_store_short v234, v51, s[90:91]
	s_sub_u32 s90, s90, 0x800
	s_subb_u32 s91, s91, 0
	global_store_short v234, v50, s[90:91]
	s_sub_u32 s90, s90, 0x800
	s_subb_u32 s91, s91, 0
	global_store_short v234, v49, s[90:91]
	s_sub_u32 s90, s90, 0x800
	s_subb_u32 s91, s91, 0
	global_store_short v234, v48, s[90:91]
	ds_read_b128 v[32:35], v236 offset:2304
	ds_read_b128 v[36:39], v236 offset:2368
	s_waitcnt lgkmcnt(0)
	v_mfma_f32_16x16x32_bf16 v[0:3], v[32:35], v[80:83], 0
	v_mfma_f32_16x16x32_bf16 v[4:7], v[32:35], v[88:91], 0
	v_mfma_f32_16x16x32_bf16 v[8:11], v[32:35], v[96:99], 0
	v_mfma_f32_16x16x32_bf16 v[12:15], v[32:35], v[104:107], 0
	v_mfma_f32_16x16x32_bf16 v[16:19], v[32:35], v[112:115], 0
	v_mfma_f32_16x16x32_bf16 v[20:23], v[32:35], v[120:123], 0
	v_mfma_f32_16x16x32_bf16 v[24:27], v[32:35], v[128:131], 0
	v_mfma_f32_16x16x32_bf16 v[28:31], v[32:35], v[136:139], 0
	v_mfma_f32_16x16x32_bf16 v[0:3], v[36:39], v[84:87], v[0:3]
	v_mfma_f32_16x16x32_bf16 v[4:7], v[36:39], v[92:95], v[4:7]
	v_mfma_f32_16x16x32_bf16 v[8:11], v[36:39], v[100:103], v[8:11]
	v_mfma_f32_16x16x32_bf16 v[12:15], v[36:39], v[108:111], v[12:15]
	v_mfma_f32_16x16x32_bf16 v[16:19], v[36:39], v[116:119], v[16:19]
	v_mfma_f32_16x16x32_bf16 v[20:23], v[36:39], v[124:127], v[20:23]
	v_mfma_f32_16x16x32_bf16 v[24:27], v[36:39], v[132:135], v[24:27]
	v_mfma_f32_16x16x32_bf16 v[28:31], v[36:39], v[228:231], v[28:31]
	s_nop 3
	ds_write2_b32 v237, v0, v4 offset0:0 offset1:16
	ds_write2_b32 v237, v8, v12 offset0:32 offset1:48
	ds_write2_b32 v237, v1, v5 offset0:64 offset1:80
	ds_write2_b32 v237, v9, v13 offset0:96 offset1:112
	ds_write2_b32 v237, v2, v6 offset0:128 offset1:144
	ds_write2_b32 v237, v10, v14 offset0:160 offset1:176
	ds_write2_b32 v237, v3, v7 offset0:192 offset1:208
	ds_write2_b32 v237, v11, v15 offset0:224 offset1:240
	ds_write2_b32 v238, v16, v20 offset0:0 offset1:16
	ds_write2_b32 v238, v24, v28 offset0:32 offset1:48
	ds_write2_b32 v238, v17, v21 offset0:64 offset1:80
	ds_write2_b32 v238, v25, v29 offset0:96 offset1:112
	ds_write2_b32 v238, v18, v22 offset0:128 offset1:144
	ds_write2_b32 v238, v26, v30 offset0:160 offset1:176
	ds_write2_b32 v238, v19, v23 offset0:192 offset1:208
	ds_write2_b32 v238, v27, v31 offset0:224 offset1:240
	s_waitcnt lgkmcnt(0)
	ds_read2st64_b32 v[0:1], v239 offset0:36 offset1:37
	ds_read2st64_b32 v[2:3], v239 offset0:38 offset1:39
	ds_read2st64_b32 v[4:5], v239 offset0:40 offset1:41
	ds_read2st64_b32 v[6:7], v239 offset0:42 offset1:43
	ds_read2st64_b32 v[8:9], v239 offset0:44 offset1:45
	ds_read2st64_b32 v[10:11], v239 offset0:46 offset1:47
	ds_read2st64_b32 v[12:13], v239 offset0:48 offset1:49
	ds_read2st64_b32 v[14:15], v239 offset0:50 offset1:51
	ds_read2st64_b32 v[16:17], v239 offset0:52 offset1:53
	ds_read2st64_b32 v[18:19], v239 offset0:54 offset1:55
	ds_read2st64_b32 v[20:21], v239 offset0:56 offset1:57
	ds_read2st64_b32 v[22:23], v239 offset0:58 offset1:59
	ds_read2st64_b32 v[24:25], v239 offset0:60 offset1:61
	ds_read2st64_b32 v[26:27], v239 offset0:62 offset1:63
	ds_read2st64_b32 v[28:29], v239 offset0:64 offset1:65
	ds_read2st64_b32 v[30:31], v239 offset0:66 offset1:67
	ds_read_u16 v48, v240 offset:2304
	ds_read_u16 v49, v240 offset:2448
	ds_read_u16 v50, v240 offset:2592
	ds_read_u16 v51, v240 offset:2736
	ds_read_u16 v52, v240 offset:2880
	ds_read_u16 v53, v240 offset:3024
	ds_read_u16 v54, v240 offset:3168
	ds_read_u16 v55, v240 offset:3312
	ds_read_u16 v56, v240 offset:3456
	ds_read_u16 v57, v240 offset:3600
	ds_read_u16 v58, v240 offset:3744
	ds_read_u16 v59, v240 offset:3888
	ds_read_u16 v60, v240 offset:4032
	ds_read_u16 v61, v240 offset:4176
	ds_read_u16 v62, v240 offset:4320
	ds_read_u16 v63, v240 offset:4464
	s_waitcnt vmcnt(16)
; #define LAS __attribute__((address_space(3)))
; #define WAVE_SYNC() asm volatile("s_waitcnt lgkmcnt(0)" ::: "memory")
; __device__ __forceinline__ float sigmoid_f(float x) { return rcpf_(1.f + __expf(-x)); }
; __device__ __forceinline__ float gelu_tanh_f(float x) { const float y = 0.7978845608028654f * (x + 0.044715f * x * x * x); return x * sigmoid_f(2.f * y); }
; template <bool FINAL, int D>
; __device__ __forceinline__ void rg_dir(PREF p, int l, int h, int ch, int sidx, int rowbase  , LAS bf16_t* sXc, LAS float* stg, int lane) {
;     ...
;             for (int ti = 0; ti < 16; ++ti) { const size_t row = (size_t)(rowbase + mt * 16 + 15 - ti); grv[ti] = __builtin_bit_cast(float, (unsigned)P[row * PW + 512 + ch]); hfv[ti] = __builtin_bit_cast(float, (unsigned)TMP[row * 512 + ch]); }
;             __builtin_amdgcn_sched_barrier(0);
; #pragma unroll
;             for (int ti = 0; ti < 16; ++ti) { grv[ti] = bf2f(__builtin_bit_cast(unsigned, grv[ti])); hfv[ti] = bf2f(__builtin_bit_cast(unsigned, hfv[ti])); }
;         }
;         const bf16x8 A0 = *(const LAS bf16x8*)(sXc + (mt * 16 + (lane & 15)) * 72 + (lane >> 4) * 8), A1 = *(const LAS bf16x8*)(sXc + (mt * 16 + (lane & 15)) * 72 + 32 + (lane >> 4) * 8);
;         f32x4 ar[4], ai[4];
; #pragma unroll
;         for (int nt = 0; nt < 4; ++nt) { const f32x4 z = {0.f, 0.f, 0.f, 0.f};
;             ar[nt] = mfma16(A0, Br[nt][0], z); ar[nt] = mfma16(A1, Br[nt][1], ar[nt]); ai[nt] = mfma16(A0, Bi[nt][0], z); ai[nt] = mfma16(A1, Bi[nt][1], ai[nt]); }
;         WAVE_SYNC();
; #pragma unroll
;         for (int nt = 0; nt < 4; ++nt)
; #pragma unroll
;             for (int j = 0; j < 4; ++j) { const int o = ((lane >> 4) * 4 + j) * 64 + nt * 16 + (lane & 15); stg[o] = ar[nt][j]; stg[1024 + o] = ai[nt][j]; }
;         WAVE_SYNC();
;         float av[16], iv[16];
; #pragma unroll
;         for (int ti = 0; ti < 16; ++ti) { const int tk = D ? 15 - ti : ti;
;             const float zr = stg[tk * 64 + lane] + ba, zi = stg[1024 + tk * 64 + lane] + bi;
;             const float r = sigmoid_f(zr), ig = sigmoid_f(zi);
;             const float a = __builtin_amdgcn_exp2f(r * sp8);
;             const float xc = bf2f(sXc[(mt * 16 + tk) * 72 + lane]);
;             av[ti] = a; iv[ti] = __builtin_amdgcn_sqrtf(fmaxf(1.f - a * a, 0.f)) * ig * xc;
;             if (FINAL && D == 1) grv[ti] = gelu_tanh_f(grv[ti]);
	v_lshlrev_b32_e32 v206, 16, v190
	v_lshlrev_b32_e32 v207, 16, v191
	v_lshlrev_b32_e32 v208, 16, v192
	v_lshlrev_b32_e32 v209, 16, v193
	v_lshlrev_b32_e32 v210, 16, v194
	v_lshlrev_b32_e32 v211, 16, v195
	v_lshlrev_b32_e32 v212, 16, v196
	v_lshlrev_b32_e32 v213, 16, v197
	v_lshlrev_b32_e32 v214, 16, v198
	v_lshlrev_b32_e32 v215, 16, v199
	v_lshlrev_b32_e32 v216, 16, v200
	v_lshlrev_b32_e32 v217, 16, v201
	v_lshlrev_b32_e32 v218, 16, v202
	v_lshlrev_b32_e32 v219, 16, v203
	v_lshlrev_b32_e32 v222, 16, v204
	v_lshlrev_b32_e32 v223, 16, v205
	v_pk_mul_f32 v[32:33], v[140:141], v[206:207]
	v_pk_mul_f32 v[34:35], v[140:141], v[208:209]
	v_pk_mul_f32 v[36:37], v[140:141], v[210:211]
	v_pk_mul_f32 v[38:39], v[140:141], v[212:213]
	v_pk_mul_f32 v[40:41], v[140:141], v[214:215]
	v_pk_mul_f32 v[42:43], v[140:141], v[216:217]
	v_pk_mul_f32 v[44:45], v[140:141], v[218:219]
	v_pk_mul_f32 v[46:47], v[140:141], v[222:223]
	v_pk_mul_f32 v[32:33], v[32:33], v[206:207]
	v_pk_mul_f32 v[34:35], v[34:35], v[208:209]
	v_pk_mul_f32 v[36:37], v[36:37], v[210:211]
	v_pk_mul_f32 v[38:39], v[38:39], v[212:213]
	v_pk_mul_f32 v[40:41], v[40:41], v[214:215]
	v_pk_mul_f32 v[42:43], v[42:43], v[216:217]
	v_pk_mul_f32 v[44:45], v[44:45], v[218:219]
	v_pk_mul_f32 v[46:47], v[46:47], v[222:223]
	v_fma_f32 v32, v32, v206, v206
	v_fma_f32 v33, v33, v207, v207
	v_fma_f32 v34, v34, v208, v208
	v_fma_f32 v35, v35, v209, v209
	v_fma_f32 v36, v36, v210, v210
	v_fma_f32 v37, v37, v211, v211
	v_fma_f32 v38, v38, v212, v212
	v_fma_f32 v39, v39, v213, v213
	v_fma_f32 v40, v40, v214, v214
	v_fma_f32 v41, v41, v215, v215
	v_fma_f32 v42, v42, v216, v216
	v_fma_f32 v43, v43, v217, v217
	v_fma_f32 v44, v44, v218, v218
	v_fma_f32 v45, v45, v219, v219
	v_fma_f32 v46, v46, v222, v222
	v_fma_f32 v47, v47, v223, v223
	s_mov_b32 s98, 0xc0135761
	v_pk_mul_f32 v[32:33], v[32:33], s[98:99] op_sel_hi:[1,0]
	v_pk_mul_f32 v[34:35], v[34:35], s[98:99] op_sel_hi:[1,0]
	v_pk_mul_f32 v[36:37], v[36:37], s[98:99] op_sel_hi:[1,0]
	v_pk_mul_f32 v[38:39], v[38:39], s[98:99] op_sel_hi:[1,0]
	v_pk_mul_f32 v[40:41], v[40:41], s[98:99] op_sel_hi:[1,0]
	v_pk_mul_f32 v[42:43], v[42:43], s[98:99] op_sel_hi:[1,0]
	v_pk_mul_f32 v[44:45], v[44:45], s[98:99] op_sel_hi:[1,0]
	v_pk_mul_f32 v[46:47], v[46:47], s[98:99] op_sel_hi:[1,0]
	v_exp_f32_e32 v32, v32
	v_exp_f32_e32 v33, v33
	v_exp_f32_e32 v34, v34
	v_exp_f32_e32 v35, v35
	v_exp_f32_e32 v36, v36
	v_exp_f32_e32 v37, v37
	v_exp_f32_e32 v38, v38
	v_exp_f32_e32 v39, v39
	v_exp_f32_e32 v40, v40
	v_exp_f32_e32 v41, v41
	v_exp_f32_e32 v42, v42
	v_exp_f32_e32 v43, v43
	v_exp_f32_e32 v44, v44
	v_exp_f32_e32 v45, v45
	v_exp_f32_e32 v46, v46
	v_exp_f32_e32 v47, v47
	v_pk_add_f32 v[32:33], v[32:33], 1.0 op_sel_hi:[1,0]
	v_pk_add_f32 v[34:35], v[34:35], 1.0 op_sel_hi:[1,0]
	v_pk_add_f32 v[36:37], v[36:37], 1.0 op_sel_hi:[1,0]
	v_pk_add_f32 v[38:39], v[38:39], 1.0 op_sel_hi:[1,0]
	v_pk_add_f32 v[40:41], v[40:41], 1.0 op_sel_hi:[1,0]
	v_pk_add_f32 v[42:43], v[42:43], 1.0 op_sel_hi:[1,0]
	v_pk_add_f32 v[44:45], v[44:45], 1.0 op_sel_hi:[1,0]
	v_pk_add_f32 v[46:47], v[46:47], 1.0 op_sel_hi:[1,0]
	v_rcp_f32_e32 v32, v32
	v_rcp_f32_e32 v33, v33
	v_rcp_f32_e32 v34, v34
	v_rcp_f32_e32 v35, v35
	v_rcp_f32_e32 v36, v36
	v_rcp_f32_e32 v37, v37
	v_rcp_f32_e32 v38, v38
	v_rcp_f32_e32 v39, v39
	v_rcp_f32_e32 v40, v40
	v_rcp_f32_e32 v41, v41
	v_rcp_f32_e32 v42, v42
	v_rcp_f32_e32 v43, v43
	v_rcp_f32_e32 v44, v44
	v_rcp_f32_e32 v45, v45
	v_rcp_f32_e32 v46, v46
	v_rcp_f32_e32 v47, v47
	s_nop 0
	v_pk_mul_f32 v[206:207], v[32:33], v[206:207]
	v_pk_mul_f32 v[208:209], v[34:35], v[208:209]
	v_pk_mul_f32 v[210:211], v[36:37], v[210:211]
	v_pk_mul_f32 v[212:213], v[38:39], v[212:213]
	v_pk_mul_f32 v[214:215], v[40:41], v[214:215]
	v_pk_mul_f32 v[216:217], v[42:43], v[216:217]
	v_pk_mul_f32 v[218:219], v[44:45], v[218:219]
	v_pk_mul_f32 v[222:223], v[46:47], v[222:223]
	s_add_i32 s39, s15, 0
	s_mul_hi_u32 s83, s39, 0x1600
	s_mul_i32 s82, s39, 0x1600
	s_add_u32 s82, s82, s0
	s_addc_u32 s83, s83, s1
	s_add_u32 s82, s82, 0xbc00400
	s_addc_u32 s83, s83, 0
	global_load_ushort v190, v234, s[82:83]
	s_add_u32 s82, s82, 0x1600
	s_addc_u32 s83, s83, 0
	global_load_ushort v191, v234, s[82:83]
	s_add_u32 s82, s82, 0x1600
	s_addc_u32 s83, s83, 0
	global_load_ushort v192, v234, s[82:83]
	s_add_u32 s82, s82, 0x1600
	s_addc_u32 s83, s83, 0
	global_load_ushort v193, v234, s[82:83]
	s_add_u32 s82, s82, 0x1600
	s_addc_u32 s83, s83, 0
	global_load_ushort v194, v234, s[82:83]
	s_add_u32 s82, s82, 0x1600
	s_addc_u32 s83, s83, 0
	global_load_ushort v195, v234, s[82:83]
	s_add_u32 s82, s82, 0x1600
	s_addc_u32 s83, s83, 0
	global_load_ushort v196, v234, s[82:83]
	s_add_u32 s82, s82, 0x1600
	s_addc_u32 s83, s83, 0
	global_load_ushort v197, v234, s[82:83]
	s_add_u32 s82, s82, 0x1600
	s_addc_u32 s83, s83, 0
	global_load_ushort v198, v234, s[82:83]
	s_add_u32 s82, s82, 0x1600
	s_addc_u32 s83, s83, 0
	global_load_ushort v199, v234, s[82:83]
	s_add_u32 s82, s82, 0x1600
	s_addc_u32 s83, s83, 0
	global_load_ushort v200, v234, s[82:83]
	s_add_u32 s82, s82, 0x1600
	s_addc_u32 s83, s83, 0
	global_load_ushort v201, v234, s[82:83]
	s_add_u32 s82, s82, 0x1600
	s_addc_u32 s83, s83, 0
	global_load_ushort v202, v234, s[82:83]
	s_add_u32 s82, s82, 0x1600
	s_addc_u32 s83, s83, 0
	global_load_ushort v203, v234, s[82:83]
	s_add_u32 s82, s82, 0x1600
	s_addc_u32 s83, s83, 0
	global_load_ushort v204, v234, s[82:83]
	s_add_u32 s82, s82, 0x1600
	s_addc_u32 s83, s83, 0
	global_load_ushort v205, v234, s[82:83]
	s_waitcnt lgkmcnt(0)
; __device__ __forceinline__ float sigmoid_f(float x) { return rcpf_(1.f + __expf(-x)); }
; __device__ __forceinline__ float gelu_tanh_f(float x) { const float y = 0.7978845608028654f * (x + 0.044715f * x * x * x); return x * sigmoid_f(2.f * y); }
; template <bool FINAL, int D>
; __device__ __forceinline__ void rg_dir(PREF p, int l, int h, int ch, int sidx, int rowbase  , LAS bf16_t* sXc, LAS float* stg, int lane) {
;     ...
;         float av[16], iv[16];
; #pragma unroll
;         for (int ti = 0; ti < 16; ++ti) { const int tk = D ? 15 - ti : ti;
;             const float zr = stg[tk * 64 + lane] + ba, zi = stg[1024 + tk * 64 + lane] + bi;
;             const float r = sigmoid_f(zr), ig = sigmoid_f(zi);
;             const float a = __builtin_amdgcn_exp2f(r * sp8);
;             const float xc = bf2f(sXc[(mt * 16 + tk) * 72 + lane]);
;             av[ti] = a; iv[ti] = __builtin_amdgcn_sqrtf(fmaxf(1.f - a * a, 0.f)) * ig * xc;
;             if (FINAL && D == 1) grv[ti] = gelu_tanh_f(grv[ti]);
	v_pk_fma_f32 v[0:1], v[0:1], v[248:249], v[242:243]
	v_pk_fma_f32 v[2:3], v[2:3], v[248:249], v[242:243]
	v_pk_fma_f32 v[4:5], v[4:5], v[248:249], v[242:243]
	v_pk_fma_f32 v[6:7], v[6:7], v[248:249], v[242:243]
	v_pk_fma_f32 v[8:9], v[8:9], v[248:249], v[242:243]
	v_pk_fma_f32 v[10:11], v[10:11], v[248:249], v[242:243]
	v_pk_fma_f32 v[12:13], v[12:13], v[248:249], v[242:243]
	v_pk_fma_f32 v[14:15], v[14:15], v[248:249], v[242:243]
	v_pk_fma_f32 v[16:17], v[16:17], v[248:249], v[244:245]
	v_pk_fma_f32 v[18:19], v[18:19], v[248:249], v[244:245]
	v_pk_fma_f32 v[20:21], v[20:21], v[248:249], v[244:245]
	v_pk_fma_f32 v[22:23], v[22:23], v[248:249], v[244:245]
	v_pk_fma_f32 v[24:25], v[24:25], v[248:249], v[244:245]
	v_pk_fma_f32 v[26:27], v[26:27], v[248:249], v[244:245]
	v_pk_fma_f32 v[28:29], v[28:29], v[248:249], v[244:245]
	v_pk_fma_f32 v[30:31], v[30:31], v[248:249], v[244:245]
	v_exp_f32_e32 v0, v0
	v_exp_f32_e32 v1, v1
	v_exp_f32_e32 v2, v2
	v_exp_f32_e32 v3, v3
	v_exp_f32_e32 v4, v4
	v_exp_f32_e32 v5, v5
	v_exp_f32_e32 v6, v6
	v_exp_f32_e32 v7, v7
	v_exp_f32_e32 v8, v8
	v_exp_f32_e32 v9, v9
	v_exp_f32_e32 v10, v10
	v_exp_f32_e32 v11, v11
	v_exp_f32_e32 v12, v12
	v_exp_f32_e32 v13, v13
	v_exp_f32_e32 v14, v14
	v_exp_f32_e32 v15, v15
	v_exp_f32_e32 v16, v16
	v_exp_f32_e32 v17, v17
	v_exp_f32_e32 v18, v18
	v_exp_f32_e32 v19, v19
	v_exp_f32_e32 v20, v20
	v_exp_f32_e32 v21, v21
	v_exp_f32_e32 v22, v22
	v_exp_f32_e32 v23, v23
	v_exp_f32_e32 v24, v24
	v_exp_f32_e32 v25, v25
	v_exp_f32_e32 v26, v26
	v_exp_f32_e32 v27, v27
	v_exp_f32_e32 v28, v28
	v_exp_f32_e32 v29, v29
	v_exp_f32_e32 v30, v30
	v_exp_f32_e32 v31, v31
	v_pk_add_f32 v[0:1], v[0:1], 1.0 op_sel_hi:[1,0]
	v_pk_add_f32 v[2:3], v[2:3], 1.0 op_sel_hi:[1,0]
	v_pk_add_f32 v[4:5], v[4:5], 1.0 op_sel_hi:[1,0]
	v_pk_add_f32 v[6:7], v[6:7], 1.0 op_sel_hi:[1,0]
	v_pk_add_f32 v[8:9], v[8:9], 1.0 op_sel_hi:[1,0]
	v_pk_add_f32 v[10:11], v[10:11], 1.0 op_sel_hi:[1,0]
	v_pk_add_f32 v[12:13], v[12:13], 1.0 op_sel_hi:[1,0]
	v_pk_add_f32 v[14:15], v[14:15], 1.0 op_sel_hi:[1,0]
	v_pk_add_f32 v[16:17], v[16:17], 1.0 op_sel_hi:[1,0]
	v_pk_add_f32 v[18:19], v[18:19], 1.0 op_sel_hi:[1,0]
	v_pk_add_f32 v[20:21], v[20:21], 1.0 op_sel_hi:[1,0]
	v_pk_add_f32 v[22:23], v[22:23], 1.0 op_sel_hi:[1,0]
	v_pk_add_f32 v[24:25], v[24:25], 1.0 op_sel_hi:[1,0]
	v_pk_add_f32 v[26:27], v[26:27], 1.0 op_sel_hi:[1,0]
	v_pk_add_f32 v[28:29], v[28:29], 1.0 op_sel_hi:[1,0]
	v_pk_add_f32 v[30:31], v[30:31], 1.0 op_sel_hi:[1,0]
	v_rcp_f32_e32 v0, v0
	v_rcp_f32_e32 v1, v1
	v_rcp_f32_e32 v2, v2
	v_rcp_f32_e32 v3, v3
	v_rcp_f32_e32 v4, v4
	v_rcp_f32_e32 v5, v5
	v_rcp_f32_e32 v6, v6
	v_rcp_f32_e32 v7, v7
	v_rcp_f32_e32 v8, v8
	v_rcp_f32_e32 v9, v9
	v_rcp_f32_e32 v10, v10
	v_rcp_f32_e32 v11, v11
	v_rcp_f32_e32 v12, v12
	v_rcp_f32_e32 v13, v13
	v_rcp_f32_e32 v14, v14
	v_rcp_f32_e32 v15, v15
	v_rcp_f32_e32 v16, v16
	v_rcp_f32_e32 v17, v17
	v_rcp_f32_e32 v18, v18
	v_rcp_f32_e32 v19, v19
	v_rcp_f32_e32 v20, v20
	v_rcp_f32_e32 v21, v21
	v_rcp_f32_e32 v22, v22
	v_rcp_f32_e32 v23, v23
	v_rcp_f32_e32 v24, v24
	v_rcp_f32_e32 v25, v25
	v_rcp_f32_e32 v26, v26
	v_rcp_f32_e32 v27, v27
	v_rcp_f32_e32 v28, v28
	v_rcp_f32_e32 v29, v29
	v_rcp_f32_e32 v30, v30
	v_rcp_f32_e32 v31, v31
	v_pk_mul_f32 v[0:1], v[246:247], v[0:1]
	v_pk_mul_f32 v[2:3], v[246:247], v[2:3]
	v_pk_mul_f32 v[4:5], v[246:247], v[4:5]
	v_pk_mul_f32 v[6:7], v[246:247], v[6:7]
	v_pk_mul_f32 v[8:9], v[246:247], v[8:9]
	v_pk_mul_f32 v[10:11], v[246:247], v[10:11]
	v_pk_mul_f32 v[12:13], v[246:247], v[12:13]
	v_pk_mul_f32 v[14:15], v[246:247], v[14:15]
	v_lshlrev_b32_e32 v48, 16, v48
	v_lshlrev_b32_e32 v49, 16, v49
	v_lshlrev_b32_e32 v50, 16, v50
	v_lshlrev_b32_e32 v51, 16, v51
	v_lshlrev_b32_e32 v52, 16, v52
	v_lshlrev_b32_e32 v53, 16, v53
	v_lshlrev_b32_e32 v54, 16, v54
	v_lshlrev_b32_e32 v55, 16, v55
	v_lshlrev_b32_e32 v56, 16, v56
	v_lshlrev_b32_e32 v57, 16, v57
	v_lshlrev_b32_e32 v58, 16, v58
	v_lshlrev_b32_e32 v59, 16, v59
	v_lshlrev_b32_e32 v60, 16, v60
	v_lshlrev_b32_e32 v61, 16, v61
	v_lshlrev_b32_e32 v62, 16, v62
	v_lshlrev_b32_e32 v63, 16, v63
	v_exp_f32_e32 v0, v0
	v_exp_f32_e32 v1, v1
	v_exp_f32_e32 v2, v2
	v_exp_f32_e32 v3, v3
	v_exp_f32_e32 v4, v4
	v_exp_f32_e32 v5, v5
	v_exp_f32_e32 v6, v6
	v_exp_f32_e32 v7, v7
	v_exp_f32_e32 v8, v8
	v_exp_f32_e32 v9, v9
	v_exp_f32_e32 v10, v10
	v_exp_f32_e32 v11, v11
	v_exp_f32_e32 v12, v12
	v_exp_f32_e32 v13, v13
	v_exp_f32_e32 v14, v14
	v_exp_f32_e32 v15, v15
	v_fma_f32 v32, -v0, v0, 1.0
	v_fma_f32 v33, -v1, v1, 1.0
	v_fma_f32 v34, -v2, v2, 1.0
	v_fma_f32 v35, -v3, v3, 1.0
	v_fma_f32 v36, -v4, v4, 1.0
	v_fma_f32 v37, -v5, v5, 1.0
	v_fma_f32 v38, -v6, v6, 1.0
	v_fma_f32 v39, -v7, v7, 1.0
	v_fma_f32 v40, -v8, v8, 1.0
	v_fma_f32 v41, -v9, v9, 1.0
	v_fma_f32 v42, -v10, v10, 1.0
	v_fma_f32 v43, -v11, v11, 1.0
	v_fma_f32 v44, -v12, v12, 1.0
	v_fma_f32 v45, -v13, v13, 1.0
	v_fma_f32 v46, -v14, v14, 1.0
	v_fma_f32 v47, -v15, v15, 1.0
	v_max_f32_e32 v32, 0, v32
	v_max_f32_e32 v33, 0, v33
	v_max_f32_e32 v34, 0, v34
	v_max_f32_e32 v35, 0, v35
	v_max_f32_e32 v36, 0, v36
	v_max_f32_e32 v37, 0, v37
	v_max_f32_e32 v38, 0, v38
	v_max_f32_e32 v39, 0, v39
	v_max_f32_e32 v40, 0, v40
	v_max_f32_e32 v41, 0, v41
	v_max_f32_e32 v42, 0, v42
	v_max_f32_e32 v43, 0, v43
	v_max_f32_e32 v44, 0, v44
	v_max_f32_e32 v45, 0, v45
	v_max_f32_e32 v46, 0, v46
	v_max_f32_e32 v47, 0, v47
	v_sqrt_f32_e32 v32, v32
	v_sqrt_f32_e32 v33, v33
	v_sqrt_f32_e32 v34, v34
	v_sqrt_f32_e32 v35, v35
	v_sqrt_f32_e32 v36, v36
	v_sqrt_f32_e32 v37, v37
	v_sqrt_f32_e32 v38, v38
	v_sqrt_f32_e32 v39, v39
	v_sqrt_f32_e32 v40, v40
	v_sqrt_f32_e32 v41, v41
	v_sqrt_f32_e32 v42, v42
; __device__ __forceinline__ unsigned f2bf(float f) { unsigned r; asm("v_cvt_pk_bf16_f32 %0, %1, %1" : "=v"(r) : "v"(f)); return r & 0xffffu; }
; __device__ __forceinline__ float gelu_tanh_f(float x) { const float y = 0.7978845608028654f * (x + 0.044715f * x * x * x); return x * sigmoid_f(2.f * y); }
; template <bool FINAL, int D>
; __device__ __forceinline__ void rg_dir(PREF p, int l, int h, int ch, int sidx, int rowbase  , LAS bf16_t* sXc, LAS float* stg, int lane) {
;     ...
;             av[ti] = a; iv[ti] = __builtin_amdgcn_sqrtf(fmaxf(1.f - a * a, 0.f)) * ig * xc;
;             if (FINAL && D == 1) grv[ti] = gelu_tanh_f(grv[ti]);
;         }
; #pragma unroll
;         for (int ti = 0; ti < 16; ++ti) { const int tk = D ? 15 - ti : ti;
;             hc = av[ti] * hc + iv[ti]; Ap *= av[ti];
;             if (FINAL) { const size_t row = (size_t)(rowbase + mt * 16 + tk);
;                 if (D == 0) TMP[row * 512 + ch] = (bf16_t)f2bf(hc);
;                 else MIX[row * DM + ch] = (bf16_t)f2bf(grv[ti] * (hfv[ti] + hc)); }
	v_sqrt_f32_e32 v43, v43
	v_sqrt_f32_e32 v44, v44
	v_sqrt_f32_e32 v45, v45
	v_sqrt_f32_e32 v46, v46
	v_sqrt_f32_e32 v47, v47
	s_nop 0
	v_pk_mul_f32 v[16:17], v[16:17], v[32:33]
	v_pk_mul_f32 v[18:19], v[18:19], v[34:35]
	v_pk_mul_f32 v[20:21], v[20:21], v[36:37]
	v_pk_mul_f32 v[22:23], v[22:23], v[38:39]
	v_pk_mul_f32 v[24:25], v[24:25], v[40:41]
	v_pk_mul_f32 v[26:27], v[26:27], v[42:43]
	v_pk_mul_f32 v[28:29], v[28:29], v[44:45]
	v_pk_mul_f32 v[30:31], v[30:31], v[46:47]
	v_pk_mul_f32 v[16:17], v[16:17], v[48:49]
	v_pk_mul_f32 v[18:19], v[18:19], v[50:51]
	v_pk_mul_f32 v[20:21], v[20:21], v[52:53]
	v_pk_mul_f32 v[22:23], v[22:23], v[54:55]
	v_pk_mul_f32 v[24:25], v[24:25], v[56:57]
	v_pk_mul_f32 v[26:27], v[26:27], v[58:59]
	v_pk_mul_f32 v[28:29], v[28:29], v[60:61]
	v_pk_mul_f32 v[30:31], v[30:31], v[62:63]
	s_add_i32 s39, s15, 31
	s_lshl_b32 s39, s39, 11
	s_add_u32 s90, s0, 0x7b00000
	s_addc_u32 s91, s1, 0
	s_add_u32 s90, s90, s39
	s_addc_u32 s91, s91, 0
	v_lshlrev_b32_e32 v48, 16, v166
	v_and_b32_e32 v49, 0xffff0000, v166
	v_lshlrev_b32_e32 v50, 16, v167
	v_and_b32_e32 v51, 0xffff0000, v167
	v_lshlrev_b32_e32 v52, 16, v168
	v_and_b32_e32 v53, 0xffff0000, v168
	v_lshlrev_b32_e32 v54, 16, v169
	v_and_b32_e32 v55, 0xffff0000, v169
	v_lshlrev_b32_e32 v56, 16, v170
	v_and_b32_e32 v57, 0xffff0000, v170
	v_lshlrev_b32_e32 v58, 16, v171
	v_and_b32_e32 v59, 0xffff0000, v171
	v_lshlrev_b32_e32 v60, 16, v172
	v_and_b32_e32 v61, 0xffff0000, v172
	v_lshlrev_b32_e32 v62, 16, v173
	v_and_b32_e32 v63, 0xffff0000, v173
	v_fma_f32 v47, v15, v250, v31
	v_fma_f32 v46, v14, v47, v30
	v_fma_f32 v45, v13, v46, v29
	v_fma_f32 v44, v12, v45, v28
	v_fma_f32 v43, v11, v44, v27
	v_fma_f32 v42, v10, v43, v26
	v_fma_f32 v41, v9, v42, v25
	v_fma_f32 v40, v8, v41, v24
	v_fma_f32 v39, v7, v40, v23
	v_fma_f32 v38, v6, v39, v22
	v_fma_f32 v37, v5, v38, v21
	v_fma_f32 v36, v4, v37, v20
	v_fma_f32 v35, v3, v36, v19
	v_fma_f32 v34, v2, v35, v18
	v_fma_f32 v33, v1, v34, v17
	v_fma_f32 v32, v0, v33, v16
	v_mov_b32_e32 v250, v32
	v_pk_add_f32 v[48:49], v[48:49], v[32:33]
	v_pk_add_f32 v[50:51], v[50:51], v[34:35]
	v_pk_add_f32 v[52:53], v[52:53], v[36:37]
	v_pk_add_f32 v[54:55], v[54:55], v[38:39]
	v_pk_add_f32 v[56:57], v[56:57], v[40:41]
	v_pk_add_f32 v[58:59], v[58:59], v[42:43]
	v_pk_add_f32 v[60:61], v[60:61], v[44:45]
	v_pk_add_f32 v[62:63], v[62:63], v[46:47]
	v_pk_mul_f32 v[48:49], v[206:207], v[48:49]
	v_pk_mul_f32 v[50:51], v[208:209], v[50:51]
	v_pk_mul_f32 v[52:53], v[210:211], v[52:53]
	v_pk_mul_f32 v[54:55], v[212:213], v[54:55]
	v_pk_mul_f32 v[56:57], v[214:215], v[56:57]
	v_pk_mul_f32 v[58:59], v[216:217], v[58:59]
	v_pk_mul_f32 v[60:61], v[218:219], v[60:61]
	v_pk_mul_f32 v[62:63], v[222:223], v[62:63]
	v_cvt_pk_bf16_f32 v48, v48, v48
	v_cvt_pk_bf16_f32 v49, v49, v49
	v_cvt_pk_bf16_f32 v50, v50, v50
	v_cvt_pk_bf16_f32 v51, v51, v51
	v_cvt_pk_bf16_f32 v52, v52, v52
	v_cvt_pk_bf16_f32 v53, v53, v53
	v_cvt_pk_bf16_f32 v54, v54, v54
	v_cvt_pk_bf16_f32 v55, v55, v55
	v_cvt_pk_bf16_f32 v56, v56, v56
	v_cvt_pk_bf16_f32 v57, v57, v57
	v_cvt_pk_bf16_f32 v58, v58, v58
	v_cvt_pk_bf16_f32 v59, v59, v59
	v_cvt_pk_bf16_f32 v60, v60, v60
	v_cvt_pk_bf16_f32 v61, v61, v61
	v_cvt_pk_bf16_f32 v62, v62, v62
	v_cvt_pk_bf16_f32 v63, v63, v63
	global_store_short v234, v63, s[90:91]
	s_sub_u32 s90, s90, 0x800
	s_subb_u32 s91, s91, 0
	global_store_short v234, v62, s[90:91]
	s_sub_u32 s90, s90, 0x800
	s_subb_u32 s91, s91, 0
	global_store_short v234, v61, s[90:91]
	s_sub_u32 s90, s90, 0x800
	s_subb_u32 s91, s91, 0
	global_store_short v234, v60, s[90:91]
	s_sub_u32 s90, s90, 0x800
	s_subb_u32 s91, s91, 0
	global_store_short v234, v59, s[90:91]
	s_sub_u32 s90, s90, 0x800
	s_subb_u32 s91, s91, 0
	global_store_short v234, v58, s[90:91]
	s_sub_u32 s90, s90, 0x800
	s_subb_u32 s91, s91, 0
	global_store_short v234, v57, s[90:91]
	s_sub_u32 s90, s90, 0x800
	s_subb_u32 s91, s91, 0
	global_store_short v234, v56, s[90:91]
	s_sub_u32 s90, s90, 0x800
	s_subb_u32 s91, s91, 0
	global_store_short v234, v55, s[90:91]
	s_sub_u32 s90, s90, 0x800
	s_subb_u32 s91, s91, 0
	global_store_short v234, v54, s[90:91]
	s_sub_u32 s90, s90, 0x800
	s_subb_u32 s91, s91, 0
	global_store_short v234, v53, s[90:91]
	s_sub_u32 s90, s90, 0x800
	s_subb_u32 s91, s91, 0
	global_store_short v234, v52, s[90:91]
	s_sub_u32 s90, s90, 0x800
	s_subb_u32 s91, s91, 0
	global_store_short v234, v51, s[90:91]
	s_sub_u32 s90, s90, 0x800
	s_subb_u32 s91, s91, 0
	global_store_short v234, v50, s[90:91]
	s_sub_u32 s90, s90, 0x800
	s_subb_u32 s91, s91, 0
	global_store_short v234, v49, s[90:91]
	s_sub_u32 s90, s90, 0x800
	s_subb_u32 s91, s91, 0
	global_store_short v234, v48, s[90:91]
	ds_read_b128 v[32:35], v236 offset:0
	ds_read_b128 v[36:39], v236 offset:64
	s_waitcnt lgkmcnt(0)
; #define LAS __attribute__((address_space(3)))
; #define WAVE_SYNC() asm volatile("s_waitcnt lgkmcnt(0)" ::: "memory")
; __device__ __forceinline__ float sigmoid_f(float x) { return rcpf_(1.f + __expf(-x)); }
; __device__ __forceinline__ float gelu_tanh_f(float x) { const float y = 0.7978845608028654f * (x + 0.044715f * x * x * x); return x * sigmoid_f(2.f * y); }
; __device__ __forceinline__ f32x4 mfma16(bf16x8 a, bf16x8 b, f32x4 c) { return __builtin_amdgcn_mfma_f32_16x16x32_bf16(a, b, c, 0, 0, 0); }
; template <bool FINAL, int D>
; __device__ __forceinline__ void rg_dir(PREF p, int l, int h, int ch, int sidx, int rowbase  , LAS bf16_t* sXc, LAS float* stg, int lane) {
;     ...
;         const bf16x8 A0 = *(const LAS bf16x8*)(sXc + (mt * 16 + (lane & 15)) * 72 + (lane >> 4) * 8), A1 = *(const LAS bf16x8*)(sXc + (mt * 16 + (lane & 15)) * 72 + 32 + (lane >> 4) * 8);
;         f32x4 ar[4], ai[4];
; #pragma unroll
;         for (int nt = 0; nt < 4; ++nt) { const f32x4 z = {0.f, 0.f, 0.f, 0.f};
;             ar[nt] = mfma16(A0, Br[nt][0], z); ar[nt] = mfma16(A1, Br[nt][1], ar[nt]); ai[nt] = mfma16(A0, Bi[nt][0], z); ai[nt] = mfma16(A1, Bi[nt][1], ai[nt]); }
;         WAVE_SYNC();
; #pragma unroll
;         for (int nt = 0; nt < 4; ++nt)
; #pragma unroll
;             for (int j = 0; j < 4; ++j) { const int o = ((lane >> 4) * 4 + j) * 64 + nt * 16 + (lane & 15); stg[o] = ar[nt][j]; stg[1024 + o] = ai[nt][j]; }
;         WAVE_SYNC();
;         float av[16], iv[16];
; #pragma unroll
;         for (int ti = 0; ti < 16; ++ti) { const int tk = D ? 15 - ti : ti;
;             const float zr = stg[tk * 64 + lane] + ba, zi = stg[1024 + tk * 64 + lane] + bi;
;             const float r = sigmoid_f(zr), ig = sigmoid_f(zi);
;             const float a = __builtin_amdgcn_exp2f(r * sp8);
;             const float xc = bf2f(sXc[(mt * 16 + tk) * 72 + lane]);
;             av[ti] = a; iv[ti] = __builtin_amdgcn_sqrtf(fmaxf(1.f - a * a, 0.f)) * ig * xc;
;             if (FINAL && D == 1) grv[ti] = gelu_tanh_f(grv[ti]);
	v_mfma_f32_16x16x32_bf16 v[0:3], v[32:35], v[80:83], 0
	v_mfma_f32_16x16x32_bf16 v[4:7], v[32:35], v[88:91], 0
	v_mfma_f32_16x16x32_bf16 v[8:11], v[32:35], v[96:99], 0
	v_mfma_f32_16x16x32_bf16 v[12:15], v[32:35], v[104:107], 0
	v_mfma_f32_16x16x32_bf16 v[16:19], v[32:35], v[112:115], 0
	v_mfma_f32_16x16x32_bf16 v[20:23], v[32:35], v[120:123], 0
	v_mfma_f32_16x16x32_bf16 v[24:27], v[32:35], v[128:131], 0
	v_mfma_f32_16x16x32_bf16 v[28:31], v[32:35], v[136:139], 0
	v_mfma_f32_16x16x32_bf16 v[0:3], v[36:39], v[84:87], v[0:3]
	v_mfma_f32_16x16x32_bf16 v[4:7], v[36:39], v[92:95], v[4:7]
	v_mfma_f32_16x16x32_bf16 v[8:11], v[36:39], v[100:103], v[8:11]
	v_mfma_f32_16x16x32_bf16 v[12:15], v[36:39], v[108:111], v[12:15]
	v_mfma_f32_16x16x32_bf16 v[16:19], v[36:39], v[116:119], v[16:19]
	v_mfma_f32_16x16x32_bf16 v[20:23], v[36:39], v[124:127], v[20:23]
	v_mfma_f32_16x16x32_bf16 v[24:27], v[36:39], v[132:135], v[24:27]
	v_mfma_f32_16x16x32_bf16 v[28:31], v[36:39], v[228:231], v[28:31]
	s_nop 3
	ds_write2_b32 v237, v0, v4 offset0:0 offset1:16
	ds_write2_b32 v237, v8, v12 offset0:32 offset1:48
	ds_write2_b32 v237, v1, v5 offset0:64 offset1:80
	ds_write2_b32 v237, v9, v13 offset0:96 offset1:112
	ds_write2_b32 v237, v2, v6 offset0:128 offset1:144
	ds_write2_b32 v237, v10, v14 offset0:160 offset1:176
	ds_write2_b32 v237, v3, v7 offset0:192 offset1:208
	ds_write2_b32 v237, v11, v15 offset0:224 offset1:240
	ds_write2_b32 v238, v16, v20 offset0:0 offset1:16
	ds_write2_b32 v238, v24, v28 offset0:32 offset1:48
	ds_write2_b32 v238, v17, v21 offset0:64 offset1:80
	ds_write2_b32 v238, v25, v29 offset0:96 offset1:112
	ds_write2_b32 v238, v18, v22 offset0:128 offset1:144
	ds_write2_b32 v238, v26, v30 offset0:160 offset1:176
	ds_write2_b32 v238, v19, v23 offset0:192 offset1:208
	ds_write2_b32 v238, v27, v31 offset0:224 offset1:240
	s_waitcnt lgkmcnt(0)
	ds_read2st64_b32 v[0:1], v239 offset0:36 offset1:37
	ds_read2st64_b32 v[2:3], v239 offset0:38 offset1:39
	ds_read2st64_b32 v[4:5], v239 offset0:40 offset1:41
	ds_read2st64_b32 v[6:7], v239 offset0:42 offset1:43
	ds_read2st64_b32 v[8:9], v239 offset0:44 offset1:45
	ds_read2st64_b32 v[10:11], v239 offset0:46 offset1:47
	ds_read2st64_b32 v[12:13], v239 offset0:48 offset1:49
	ds_read2st64_b32 v[14:15], v239 offset0:50 offset1:51
	ds_read2st64_b32 v[16:17], v239 offset0:52 offset1:53
	ds_read2st64_b32 v[18:19], v239 offset0:54 offset1:55
	ds_read2st64_b32 v[20:21], v239 offset0:56 offset1:57
	ds_read2st64_b32 v[22:23], v239 offset0:58 offset1:59
	ds_read2st64_b32 v[24:25], v239 offset0:60 offset1:61
	ds_read2st64_b32 v[26:27], v239 offset0:62 offset1:63
	ds_read2st64_b32 v[28:29], v239 offset0:64 offset1:65
	ds_read2st64_b32 v[30:31], v239 offset0:66 offset1:67
	ds_read_u16 v48, v240 offset:0
	ds_read_u16 v49, v240 offset:144
	ds_read_u16 v50, v240 offset:288
	ds_read_u16 v51, v240 offset:432
	ds_read_u16 v52, v240 offset:576
	ds_read_u16 v53, v240 offset:720
	ds_read_u16 v54, v240 offset:864
	ds_read_u16 v55, v240 offset:1008
	ds_read_u16 v56, v240 offset:1152
	ds_read_u16 v57, v240 offset:1296
	ds_read_u16 v58, v240 offset:1440
	ds_read_u16 v59, v240 offset:1584
	ds_read_u16 v60, v240 offset:1728
	ds_read_u16 v61, v240 offset:1872
	ds_read_u16 v62, v240 offset:2016
	ds_read_u16 v63, v240 offset:2160
	s_waitcnt vmcnt(16)
	v_lshlrev_b32_e32 v206, 16, v190
	v_lshlrev_b32_e32 v207, 16, v191
	v_lshlrev_b32_e32 v208, 16, v192
	v_lshlrev_b32_e32 v209, 16, v193
	v_lshlrev_b32_e32 v210, 16, v194
	v_lshlrev_b32_e32 v211, 16, v195
	v_lshlrev_b32_e32 v212, 16, v196
	v_lshlrev_b32_e32 v213, 16, v197
	v_lshlrev_b32_e32 v214, 16, v198
	v_lshlrev_b32_e32 v215, 16, v199
	v_lshlrev_b32_e32 v216, 16, v200
	v_lshlrev_b32_e32 v217, 16, v201
	v_lshlrev_b32_e32 v218, 16, v202
	v_lshlrev_b32_e32 v219, 16, v203
	v_lshlrev_b32_e32 v222, 16, v204
	v_lshlrev_b32_e32 v223, 16, v205
	v_pk_mul_f32 v[32:33], v[140:141], v[206:207]
	v_pk_mul_f32 v[34:35], v[140:141], v[208:209]
	v_pk_mul_f32 v[36:37], v[140:141], v[210:211]
	v_pk_mul_f32 v[38:39], v[140:141], v[212:213]
	v_pk_mul_f32 v[40:41], v[140:141], v[214:215]
	v_pk_mul_f32 v[42:43], v[140:141], v[216:217]
	v_pk_mul_f32 v[44:45], v[140:141], v[218:219]
	v_pk_mul_f32 v[46:47], v[140:141], v[222:223]
	v_pk_mul_f32 v[32:33], v[32:33], v[206:207]
	v_pk_mul_f32 v[34:35], v[34:35], v[208:209]
	v_pk_mul_f32 v[36:37], v[36:37], v[210:211]
	v_pk_mul_f32 v[38:39], v[38:39], v[212:213]
	v_pk_mul_f32 v[40:41], v[40:41], v[214:215]
	v_pk_mul_f32 v[42:43], v[42:43], v[216:217]
	v_pk_mul_f32 v[44:45], v[44:45], v[218:219]
	v_pk_mul_f32 v[46:47], v[46:47], v[222:223]
	v_fma_f32 v32, v32, v206, v206
	v_fma_f32 v33, v33, v207, v207
	v_fma_f32 v34, v34, v208, v208
	v_fma_f32 v35, v35, v209, v209
	v_fma_f32 v36, v36, v210, v210
	v_fma_f32 v37, v37, v211, v211
	v_fma_f32 v38, v38, v212, v212
	v_fma_f32 v39, v39, v213, v213
	v_fma_f32 v40, v40, v214, v214
	v_fma_f32 v41, v41, v215, v215
	v_fma_f32 v42, v42, v216, v216
	v_fma_f32 v43, v43, v217, v217
	v_fma_f32 v44, v44, v218, v218
	v_fma_f32 v45, v45, v219, v219
	v_fma_f32 v46, v46, v222, v222
	v_fma_f32 v47, v47, v223, v223
	s_mov_b32 s98, 0xc0135761
	v_pk_mul_f32 v[32:33], v[32:33], s[98:99] op_sel_hi:[1,0]
	v_pk_mul_f32 v[34:35], v[34:35], s[98:99] op_sel_hi:[1,0]
	v_pk_mul_f32 v[36:37], v[36:37], s[98:99] op_sel_hi:[1,0]
	v_pk_mul_f32 v[38:39], v[38:39], s[98:99] op_sel_hi:[1,0]
	v_pk_mul_f32 v[40:41], v[40:41], s[98:99] op_sel_hi:[1,0]
	v_pk_mul_f32 v[42:43], v[42:43], s[98:99] op_sel_hi:[1,0]
	v_pk_mul_f32 v[44:45], v[44:45], s[98:99] op_sel_hi:[1,0]
	v_pk_mul_f32 v[46:47], v[46:47], s[98:99] op_sel_hi:[1,0]
	v_exp_f32_e32 v32, v32
	v_exp_f32_e32 v33, v33
; __device__ __forceinline__ float sigmoid_f(float x) { return rcpf_(1.f + __expf(-x)); }
; __device__ __forceinline__ float gelu_tanh_f(float x) { const float y = 0.7978845608028654f * (x + 0.044715f * x * x * x); return x * sigmoid_f(2.f * y); }
; template <bool FINAL, int D>
; __device__ __forceinline__ void rg_dir(PREF p, int l, int h, int ch, int sidx, int rowbase  , LAS bf16_t* sXc, LAS float* stg, int lane) {
;     ...
;         float av[16], iv[16];
; #pragma unroll
;         for (int ti = 0; ti < 16; ++ti) { const int tk = D ? 15 - ti : ti;
;             const float zr = stg[tk * 64 + lane] + ba, zi = stg[1024 + tk * 64 + lane] + bi;
;             const float r = sigmoid_f(zr), ig = sigmoid_f(zi);
;             const float a = __builtin_amdgcn_exp2f(r * sp8);
;             const float xc = bf2f(sXc[(mt * 16 + tk) * 72 + lane]);
;             av[ti] = a; iv[ti] = __builtin_amdgcn_sqrtf(fmaxf(1.f - a * a, 0.f)) * ig * xc;
;             if (FINAL && D == 1) grv[ti] = gelu_tanh_f(grv[ti]);
	v_exp_f32_e32 v34, v34
	v_exp_f32_e32 v35, v35
	v_exp_f32_e32 v36, v36
	v_exp_f32_e32 v37, v37
	v_exp_f32_e32 v38, v38
	v_exp_f32_e32 v39, v39
	v_exp_f32_e32 v40, v40
	v_exp_f32_e32 v41, v41
	v_exp_f32_e32 v42, v42
	v_exp_f32_e32 v43, v43
	v_exp_f32_e32 v44, v44
	v_exp_f32_e32 v45, v45
	v_exp_f32_e32 v46, v46
	v_exp_f32_e32 v47, v47
	v_pk_add_f32 v[32:33], v[32:33], 1.0 op_sel_hi:[1,0]
	v_pk_add_f32 v[34:35], v[34:35], 1.0 op_sel_hi:[1,0]
	v_pk_add_f32 v[36:37], v[36:37], 1.0 op_sel_hi:[1,0]
	v_pk_add_f32 v[38:39], v[38:39], 1.0 op_sel_hi:[1,0]
	v_pk_add_f32 v[40:41], v[40:41], 1.0 op_sel_hi:[1,0]
	v_pk_add_f32 v[42:43], v[42:43], 1.0 op_sel_hi:[1,0]
	v_pk_add_f32 v[44:45], v[44:45], 1.0 op_sel_hi:[1,0]
	v_pk_add_f32 v[46:47], v[46:47], 1.0 op_sel_hi:[1,0]
	v_rcp_f32_e32 v32, v32
	v_rcp_f32_e32 v33, v33
	v_rcp_f32_e32 v34, v34
	v_rcp_f32_e32 v35, v35
	v_rcp_f32_e32 v36, v36
	v_rcp_f32_e32 v37, v37
	v_rcp_f32_e32 v38, v38
	v_rcp_f32_e32 v39, v39
	v_rcp_f32_e32 v40, v40
	v_rcp_f32_e32 v41, v41
	v_rcp_f32_e32 v42, v42
	v_rcp_f32_e32 v43, v43
	v_rcp_f32_e32 v44, v44
	v_rcp_f32_e32 v45, v45
	v_rcp_f32_e32 v46, v46
	v_rcp_f32_e32 v47, v47
	s_nop 0
	v_pk_mul_f32 v[206:207], v[32:33], v[206:207]
	v_pk_mul_f32 v[208:209], v[34:35], v[208:209]
	v_pk_mul_f32 v[210:211], v[36:37], v[210:211]
	v_pk_mul_f32 v[212:213], v[38:39], v[212:213]
	v_pk_mul_f32 v[214:215], v[40:41], v[214:215]
	v_pk_mul_f32 v[216:217], v[42:43], v[216:217]
	v_pk_mul_f32 v[218:219], v[44:45], v[218:219]
	v_pk_mul_f32 v[222:223], v[46:47], v[222:223]
	s_waitcnt lgkmcnt(0)
	v_pk_fma_f32 v[0:1], v[0:1], v[248:249], v[242:243]
	v_pk_fma_f32 v[2:3], v[2:3], v[248:249], v[242:243]
	v_pk_fma_f32 v[4:5], v[4:5], v[248:249], v[242:243]
	v_pk_fma_f32 v[6:7], v[6:7], v[248:249], v[242:243]
	v_pk_fma_f32 v[8:9], v[8:9], v[248:249], v[242:243]
	v_pk_fma_f32 v[10:11], v[10:11], v[248:249], v[242:243]
	v_pk_fma_f32 v[12:13], v[12:13], v[248:249], v[242:243]
	v_pk_fma_f32 v[14:15], v[14:15], v[248:249], v[242:243]
	v_pk_fma_f32 v[16:17], v[16:17], v[248:249], v[244:245]
	v_pk_fma_f32 v[18:19], v[18:19], v[248:249], v[244:245]
	v_pk_fma_f32 v[20:21], v[20:21], v[248:249], v[244:245]
	v_pk_fma_f32 v[22:23], v[22:23], v[248:249], v[244:245]
	v_pk_fma_f32 v[24:25], v[24:25], v[248:249], v[244:245]
	v_pk_fma_f32 v[26:27], v[26:27], v[248:249], v[244:245]
	v_pk_fma_f32 v[28:29], v[28:29], v[248:249], v[244:245]
	v_pk_fma_f32 v[30:31], v[30:31], v[248:249], v[244:245]
	v_exp_f32_e32 v0, v0
	v_exp_f32_e32 v1, v1
	v_exp_f32_e32 v2, v2
	v_exp_f32_e32 v3, v3
	v_exp_f32_e32 v4, v4
	v_exp_f32_e32 v5, v5
	v_exp_f32_e32 v6, v6
	v_exp_f32_e32 v7, v7
	v_exp_f32_e32 v8, v8
	v_exp_f32_e32 v9, v9
	v_exp_f32_e32 v10, v10
	v_exp_f32_e32 v11, v11
	v_exp_f32_e32 v12, v12
	v_exp_f32_e32 v13, v13
	v_exp_f32_e32 v14, v14
	v_exp_f32_e32 v15, v15
	v_exp_f32_e32 v16, v16
	v_exp_f32_e32 v17, v17
	v_exp_f32_e32 v18, v18
	v_exp_f32_e32 v19, v19
	v_exp_f32_e32 v20, v20
	v_exp_f32_e32 v21, v21
	v_exp_f32_e32 v22, v22
	v_exp_f32_e32 v23, v23
	v_exp_f32_e32 v24, v24
	v_exp_f32_e32 v25, v25
	v_exp_f32_e32 v26, v26
	v_exp_f32_e32 v27, v27
	v_exp_f32_e32 v28, v28
	v_exp_f32_e32 v29, v29
	v_exp_f32_e32 v30, v30
	v_exp_f32_e32 v31, v31
	v_pk_add_f32 v[0:1], v[0:1], 1.0 op_sel_hi:[1,0]
	v_pk_add_f32 v[2:3], v[2:3], 1.0 op_sel_hi:[1,0]
	v_pk_add_f32 v[4:5], v[4:5], 1.0 op_sel_hi:[1,0]
	v_pk_add_f32 v[6:7], v[6:7], 1.0 op_sel_hi:[1,0]
	v_pk_add_f32 v[8:9], v[8:9], 1.0 op_sel_hi:[1,0]
	v_pk_add_f32 v[10:11], v[10:11], 1.0 op_sel_hi:[1,0]
	v_pk_add_f32 v[12:13], v[12:13], 1.0 op_sel_hi:[1,0]
	v_pk_add_f32 v[14:15], v[14:15], 1.0 op_sel_hi:[1,0]
	v_pk_add_f32 v[16:17], v[16:17], 1.0 op_sel_hi:[1,0]
	v_pk_add_f32 v[18:19], v[18:19], 1.0 op_sel_hi:[1,0]
	v_pk_add_f32 v[20:21], v[20:21], 1.0 op_sel_hi:[1,0]
	v_pk_add_f32 v[22:23], v[22:23], 1.0 op_sel_hi:[1,0]
	v_pk_add_f32 v[24:25], v[24:25], 1.0 op_sel_hi:[1,0]
	v_pk_add_f32 v[26:27], v[26:27], 1.0 op_sel_hi:[1,0]
	v_pk_add_f32 v[28:29], v[28:29], 1.0 op_sel_hi:[1,0]
	v_pk_add_f32 v[30:31], v[30:31], 1.0 op_sel_hi:[1,0]
	v_rcp_f32_e32 v0, v0
	v_rcp_f32_e32 v1, v1
	v_rcp_f32_e32 v2, v2
	v_rcp_f32_e32 v3, v3
	v_rcp_f32_e32 v4, v4
	v_rcp_f32_e32 v5, v5
	v_rcp_f32_e32 v6, v6
	v_rcp_f32_e32 v7, v7
	v_rcp_f32_e32 v8, v8
	v_rcp_f32_e32 v9, v9
	v_rcp_f32_e32 v10, v10
	v_rcp_f32_e32 v11, v11
	v_rcp_f32_e32 v12, v12
	v_rcp_f32_e32 v13, v13
	v_rcp_f32_e32 v14, v14
	v_rcp_f32_e32 v15, v15
	v_rcp_f32_e32 v16, v16
	v_rcp_f32_e32 v17, v17
	v_rcp_f32_e32 v18, v18
	v_rcp_f32_e32 v19, v19
	v_rcp_f32_e32 v20, v20
	v_rcp_f32_e32 v21, v21
	v_rcp_f32_e32 v22, v22
	v_rcp_f32_e32 v23, v23
	v_rcp_f32_e32 v24, v24
	v_rcp_f32_e32 v25, v25
	v_rcp_f32_e32 v26, v26
	v_rcp_f32_e32 v27, v27
	v_rcp_f32_e32 v28, v28
	v_rcp_f32_e32 v29, v29
	v_rcp_f32_e32 v30, v30
	v_rcp_f32_e32 v31, v31
	v_pk_mul_f32 v[0:1], v[246:247], v[0:1]
	v_pk_mul_f32 v[2:3], v[246:247], v[2:3]
	v_pk_mul_f32 v[4:5], v[246:247], v[4:5]
	v_pk_mul_f32 v[6:7], v[246:247], v[6:7]
	v_pk_mul_f32 v[8:9], v[246:247], v[8:9]
	v_pk_mul_f32 v[10:11], v[246:247], v[10:11]
	v_pk_mul_f32 v[12:13], v[246:247], v[12:13]
	v_pk_mul_f32 v[14:15], v[246:247], v[14:15]
	v_lshlrev_b32_e32 v48, 16, v48
	v_lshlrev_b32_e32 v49, 16, v49
	v_lshlrev_b32_e32 v50, 16, v50
	v_lshlrev_b32_e32 v51, 16, v51
	v_lshlrev_b32_e32 v52, 16, v52
	v_lshlrev_b32_e32 v53, 16, v53
	v_lshlrev_b32_e32 v54, 16, v54
	v_lshlrev_b32_e32 v55, 16, v55
	v_lshlrev_b32_e32 v56, 16, v56
	v_lshlrev_b32_e32 v57, 16, v57
	v_lshlrev_b32_e32 v58, 16, v58
	v_lshlrev_b32_e32 v59, 16, v59
	v_lshlrev_b32_e32 v60, 16, v60
	v_lshlrev_b32_e32 v61, 16, v61
	v_lshlrev_b32_e32 v62, 16, v62
	v_lshlrev_b32_e32 v63, 16, v63
; __device__ __forceinline__ unsigned f2bf(float f) { unsigned r; asm("v_cvt_pk_bf16_f32 %0, %1, %1" : "=v"(r) : "v"(f)); return r & 0xffffu; }
; __device__ __forceinline__ float sigmoid_f(float x) { return rcpf_(1.f + __expf(-x)); }
; __device__ __forceinline__ float gelu_tanh_f(float x) { const float y = 0.7978845608028654f * (x + 0.044715f * x * x * x); return x * sigmoid_f(2.f * y); }
; template <bool FINAL, int D>
; __device__ __forceinline__ void rg_dir(PREF p, int l, int h, int ch, int sidx, int rowbase  , LAS bf16_t* sXc, LAS float* stg, int lane) {
;     ...
;             const float r = sigmoid_f(zr), ig = sigmoid_f(zi);
;             const float a = __builtin_amdgcn_exp2f(r * sp8);
;             const float xc = bf2f(sXc[(mt * 16 + tk) * 72 + lane]);
;             av[ti] = a; iv[ti] = __builtin_amdgcn_sqrtf(fmaxf(1.f - a * a, 0.f)) * ig * xc;
;             if (FINAL && D == 1) grv[ti] = gelu_tanh_f(grv[ti]);
;         }
; #pragma unroll
;         for (int ti = 0; ti < 16; ++ti) { const int tk = D ? 15 - ti : ti;
;             hc = av[ti] * hc + iv[ti]; Ap *= av[ti];
;             if (FINAL) { const size_t row = (size_t)(rowbase + mt * 16 + tk);
;                 if (D == 0) TMP[row * 512 + ch] = (bf16_t)f2bf(hc);
;                 else MIX[row * DM + ch] = (bf16_t)f2bf(grv[ti] * (hfv[ti] + hc)); }
; __global__ void __launch_bounds__(NTHREADS, 2) mega_fwd(Params p_arg) {
;     ...
;             for (int item = gw; item < nrg; item += NGW) rg_item<true>(p, l, item, lds + wave * 18432, lane);
	v_exp_f32_e32 v0, v0
	v_exp_f32_e32 v1, v1
	v_exp_f32_e32 v2, v2
	v_exp_f32_e32 v3, v3
	v_exp_f32_e32 v4, v4
	v_exp_f32_e32 v5, v5
	v_exp_f32_e32 v6, v6
	v_exp_f32_e32 v7, v7
	v_exp_f32_e32 v8, v8
	v_exp_f32_e32 v9, v9
	v_exp_f32_e32 v10, v10
	v_exp_f32_e32 v11, v11
	v_exp_f32_e32 v12, v12
	v_exp_f32_e32 v13, v13
	v_exp_f32_e32 v14, v14
	v_exp_f32_e32 v15, v15
	v_fma_f32 v32, -v0, v0, 1.0
	v_fma_f32 v33, -v1, v1, 1.0
	v_fma_f32 v34, -v2, v2, 1.0
	v_fma_f32 v35, -v3, v3, 1.0
	v_fma_f32 v36, -v4, v4, 1.0
	v_fma_f32 v37, -v5, v5, 1.0
	v_fma_f32 v38, -v6, v6, 1.0
	v_fma_f32 v39, -v7, v7, 1.0
	v_fma_f32 v40, -v8, v8, 1.0
	v_fma_f32 v41, -v9, v9, 1.0
	v_fma_f32 v42, -v10, v10, 1.0
	v_fma_f32 v43, -v11, v11, 1.0
	v_fma_f32 v44, -v12, v12, 1.0
	v_fma_f32 v45, -v13, v13, 1.0
	v_fma_f32 v46, -v14, v14, 1.0
	v_fma_f32 v47, -v15, v15, 1.0
	v_max_f32_e32 v32, 0, v32
	v_max_f32_e32 v33, 0, v33
	v_max_f32_e32 v34, 0, v34
	v_max_f32_e32 v35, 0, v35
	v_max_f32_e32 v36, 0, v36
	v_max_f32_e32 v37, 0, v37
	v_max_f32_e32 v38, 0, v38
	v_max_f32_e32 v39, 0, v39
	v_max_f32_e32 v40, 0, v40
	v_max_f32_e32 v41, 0, v41
	v_max_f32_e32 v42, 0, v42
	v_max_f32_e32 v43, 0, v43
	v_max_f32_e32 v44, 0, v44
	v_max_f32_e32 v45, 0, v45
	v_max_f32_e32 v46, 0, v46
	v_max_f32_e32 v47, 0, v47
	v_sqrt_f32_e32 v32, v32
	v_sqrt_f32_e32 v33, v33
	v_sqrt_f32_e32 v34, v34
	v_sqrt_f32_e32 v35, v35
	v_sqrt_f32_e32 v36, v36
	v_sqrt_f32_e32 v37, v37
	v_sqrt_f32_e32 v38, v38
	v_sqrt_f32_e32 v39, v39
	v_sqrt_f32_e32 v40, v40
	v_sqrt_f32_e32 v41, v41
	v_sqrt_f32_e32 v42, v42
	v_sqrt_f32_e32 v43, v43
	v_sqrt_f32_e32 v44, v44
	v_sqrt_f32_e32 v45, v45
	v_sqrt_f32_e32 v46, v46
	v_sqrt_f32_e32 v47, v47
	s_nop 0
	v_pk_mul_f32 v[16:17], v[16:17], v[32:33]
	v_pk_mul_f32 v[18:19], v[18:19], v[34:35]
	v_pk_mul_f32 v[20:21], v[20:21], v[36:37]
	v_pk_mul_f32 v[22:23], v[22:23], v[38:39]
	v_pk_mul_f32 v[24:25], v[24:25], v[40:41]
	v_pk_mul_f32 v[26:27], v[26:27], v[42:43]
	v_pk_mul_f32 v[28:29], v[28:29], v[44:45]
	v_pk_mul_f32 v[30:31], v[30:31], v[46:47]
	v_pk_mul_f32 v[16:17], v[16:17], v[48:49]
	v_pk_mul_f32 v[18:19], v[18:19], v[50:51]
	v_pk_mul_f32 v[20:21], v[20:21], v[52:53]
	v_pk_mul_f32 v[22:23], v[22:23], v[54:55]
	v_pk_mul_f32 v[24:25], v[24:25], v[56:57]
	v_pk_mul_f32 v[26:27], v[26:27], v[58:59]
	v_pk_mul_f32 v[28:29], v[28:29], v[60:61]
	v_pk_mul_f32 v[30:31], v[30:31], v[62:63]
	s_add_i32 s39, s15, 15
	s_lshl_b32 s39, s39, 11
	s_add_u32 s90, s0, 0x7b00000
	s_addc_u32 s91, s1, 0
	s_add_u32 s90, s90, s39
	s_addc_u32 s91, s91, 0
	v_lshlrev_b32_e32 v48, 16, v158
	v_and_b32_e32 v49, 0xffff0000, v158
	v_lshlrev_b32_e32 v50, 16, v159
	v_and_b32_e32 v51, 0xffff0000, v159
	v_lshlrev_b32_e32 v52, 16, v160
	v_and_b32_e32 v53, 0xffff0000, v160
	v_lshlrev_b32_e32 v54, 16, v161
	v_and_b32_e32 v55, 0xffff0000, v161
	v_lshlrev_b32_e32 v56, 16, v162
	v_and_b32_e32 v57, 0xffff0000, v162
	v_lshlrev_b32_e32 v58, 16, v163
	v_and_b32_e32 v59, 0xffff0000, v163
	v_lshlrev_b32_e32 v60, 16, v164
	v_and_b32_e32 v61, 0xffff0000, v164
	v_lshlrev_b32_e32 v62, 16, v165
	v_and_b32_e32 v63, 0xffff0000, v165
	v_fma_f32 v47, v15, v250, v31
	v_fma_f32 v46, v14, v47, v30
	v_fma_f32 v45, v13, v46, v29
	v_fma_f32 v44, v12, v45, v28
	v_fma_f32 v43, v11, v44, v27
	v_fma_f32 v42, v10, v43, v26
	v_fma_f32 v41, v9, v42, v25
	v_fma_f32 v40, v8, v41, v24
	v_fma_f32 v39, v7, v40, v23
	v_fma_f32 v38, v6, v39, v22
	v_fma_f32 v37, v5, v38, v21
	v_fma_f32 v36, v4, v37, v20
	v_fma_f32 v35, v3, v36, v19
	v_fma_f32 v34, v2, v35, v18
	v_fma_f32 v33, v1, v34, v17
	v_fma_f32 v32, v0, v33, v16
	v_mov_b32_e32 v250, v32
	v_pk_add_f32 v[48:49], v[48:49], v[32:33]
	v_pk_add_f32 v[50:51], v[50:51], v[34:35]
	v_pk_add_f32 v[52:53], v[52:53], v[36:37]
	v_pk_add_f32 v[54:55], v[54:55], v[38:39]
	v_pk_add_f32 v[56:57], v[56:57], v[40:41]
	v_pk_add_f32 v[58:59], v[58:59], v[42:43]
	v_pk_add_f32 v[60:61], v[60:61], v[44:45]
	v_pk_add_f32 v[62:63], v[62:63], v[46:47]
	v_pk_mul_f32 v[48:49], v[206:207], v[48:49]
	v_pk_mul_f32 v[50:51], v[208:209], v[50:51]
	v_pk_mul_f32 v[52:53], v[210:211], v[52:53]
	v_pk_mul_f32 v[54:55], v[212:213], v[54:55]
	v_pk_mul_f32 v[56:57], v[214:215], v[56:57]
	v_pk_mul_f32 v[58:59], v[216:217], v[58:59]
	v_pk_mul_f32 v[60:61], v[218:219], v[60:61]
	v_pk_mul_f32 v[62:63], v[222:223], v[62:63]
	v_cvt_pk_bf16_f32 v48, v48, v48
	v_cvt_pk_bf16_f32 v49, v49, v49
	v_cvt_pk_bf16_f32 v50, v50, v50
	v_cvt_pk_bf16_f32 v51, v51, v51
	v_cvt_pk_bf16_f32 v52, v52, v52
	v_cvt_pk_bf16_f32 v53, v53, v53
	v_cvt_pk_bf16_f32 v54, v54, v54
	v_cvt_pk_bf16_f32 v55, v55, v55
	v_cvt_pk_bf16_f32 v56, v56, v56
	v_cvt_pk_bf16_f32 v57, v57, v57
	v_cvt_pk_bf16_f32 v58, v58, v58
	v_cvt_pk_bf16_f32 v59, v59, v59
	v_cvt_pk_bf16_f32 v60, v60, v60
	v_cvt_pk_bf16_f32 v61, v61, v61
	v_cvt_pk_bf16_f32 v62, v62, v62
	v_cvt_pk_bf16_f32 v63, v63, v63
	global_store_short v234, v63, s[90:91]
	s_sub_u32 s90, s90, 0x800
	s_subb_u32 s91, s91, 0
	global_store_short v234, v62, s[90:91]
	s_sub_u32 s90, s90, 0x800
	s_subb_u32 s91, s91, 0
	global_store_short v234, v61, s[90:91]
	s_sub_u32 s90, s90, 0x800
	s_subb_u32 s91, s91, 0
	global_store_short v234, v60, s[90:91]
	s_sub_u32 s90, s90, 0x800
	s_subb_u32 s91, s91, 0
	global_store_short v234, v59, s[90:91]
	s_sub_u32 s90, s90, 0x800
	s_subb_u32 s91, s91, 0
	global_store_short v234, v58, s[90:91]
	s_sub_u32 s90, s90, 0x800
	s_subb_u32 s91, s91, 0
	global_store_short v234, v57, s[90:91]
	s_sub_u32 s90, s90, 0x800
	s_subb_u32 s91, s91, 0
	global_store_short v234, v56, s[90:91]
	s_sub_u32 s90, s90, 0x800
	s_subb_u32 s91, s91, 0
	global_store_short v234, v55, s[90:91]
	s_sub_u32 s90, s90, 0x800
	s_subb_u32 s91, s91, 0
	global_store_short v234, v54, s[90:91]
	s_sub_u32 s90, s90, 0x800
	s_subb_u32 s91, s91, 0
	global_store_short v234, v53, s[90:91]
	s_sub_u32 s90, s90, 0x800
	s_subb_u32 s91, s91, 0
	global_store_short v234, v52, s[90:91]
	s_sub_u32 s90, s90, 0x800
	s_subb_u32 s91, s91, 0
	global_store_short v234, v51, s[90:91]
	s_sub_u32 s90, s90, 0x800
	s_subb_u32 s91, s91, 0
	global_store_short v234, v50, s[90:91]
	s_sub_u32 s90, s90, 0x800
	s_subb_u32 s91, s91, 0
	global_store_short v234, v49, s[90:91]
	s_sub_u32 s90, s90, 0x800
	s_subb_u32 s91, s91, 0
	global_store_short v234, v48, s[90:91]
	s_waitcnt lgkmcnt(0)
	v_readlane_b32 s84, v253, 29
	s_add_i32 s12, s12, s84
	s_cmpk_lt_i32 s12, 0x1000
	s_cbranch_scc1 .Lrg7_keep
	s_sub_i32 s0, s12, 0x1000
	s_lshr_b32 s1, s0, 5
	s_and_b32 s0, s0, 31
	s_and_b32 s12, s1, 7
	s_add_i32 s1, s1, 0x1000
	s_cmp_eq_u32 s0, s12
	s_cselect_b32 s12, s1, 0x2000

; #define LAS __attribute__((address_space(3)))
; template <bool FINAL>
; __device__ __forceinline__ void rg_item(PREF p, int l, int item, LAS unsigned char* wl, int lane) {
;     ...
;     const int h = item & 7, rest = item >> 3;
;     const int ci = rest < 512 ? 4 + (rest & 255) : ((rest - 512) & 3), b = rest < 512 ? (rest >> 8) : ((rest - 512) >> 2);
;     const int seq_row0 = ci < 4 ? TL + b * 256 : b * 16384;
;     const int t0 = ci < 4 ? ci * 64 : (ci - 4) * 64;
;     const int seqlen = ci < 4 ? 256 : 16384;
;     const int ch = h * 64 + lane;
;     LAS bf16_t* sXc = (LAS bf16_t*)wl;
;     LAS float* stg = (LAS float*)(wl + 9216);
;     {
;         const float cw0 = p.conv_w[(l * 4 + 0) * 512 + ch], cw1 = p.conv_w[(l * 4 + 1) * 512 + ch], cw2 = p.conv_w[(l * 4 + 2) * 512 + ch], cw3 = p.conv_w[(l * 4 + 3) * 512 + ch];
;         const float cb = p.conv_b[l * 512 + ch];
;         float xv[67]; unsigned xr_[67];
; #pragma unroll
;         for (int i = 0; i < 67; ++i) { const int t = t0 - 2 + i; const int tc = t < 0 ? 0 : (t >= seqlen ? seqlen - 1 : t);
;             xr_[i] = P[(size_t)(seq_row0 + tc) * PW + ch]; }
.Lrg5_dec:
	s_add_i32 s15, s11, s10
	s_mul_i32 s36, s9, 0x104
	s_add_i32 s36, s36, s8
	s_lshl_b32 s36, s36, 12
	s_cmp_eq_u32 s10, 0
	s_cselect_b32 s37, 0, -1
	s_add_i32 s38, s10, 64
	s_cmp_eq_u32 s38, s14
	s_cselect_b32 s38, 0, -1
	s_bfe_u32 s44, s44, 0x30006
	s_mul_i32 s44, s44, 0x4800
	v_lshl_or_b32 v234, s7, 6, v233
	v_lshlrev_b32_e32 v235, 2, v234
	v_lshlrev_b32_e32 v234, 1, v234
	v_and_b32_e32 v236, 15, v233
	v_lshrrev_b32_e32 v241, 4, v233
	s_movk_i32 s39, 0x90
	v_mul_u32_u24_e32 v237, 0x90, v236
	v_lshl_add_u32 v237, v241, 4, v237
	v_lshlrev_b32_e32 v238, 7, v236
	v_lshl_add_u32 v238, v241, 4, v238
	v_lshlrev_b32_e32 v239, 10, v241
	v_lshl_add_u32 v239, v236, 2, v239
	v_mov_b32_e32 v241, v238
	v_add_u32_e32 v236, s44, v237
	s_add_i32 s39, s44, 0x2400
	v_add_u32_e32 v237, s39, v239
	v_add_u32_e32 v238, 0x1000, v237
	v_lshl_add_u32 v239, v233, 2, s44
	v_lshl_add_u32 v240, v233, 1, s44
	s_add_i32 s39, s15, -2
	s_mul_hi_i32 s83, s39, 0x1600
	s_mul_i32 s82, s39, 0x1600
	s_waitcnt lgkmcnt(0)
	s_add_u32 s82, s82, s0
	s_addc_u32 s83, s83, s1
	s_add_u32 s82, s82, 0xbc00000
	s_addc_u32 s83, s83, 0
	global_load_ushort v158, v234, s[82:83]
	s_add_u32 s82, s82, 0x1600
	s_addc_u32 s83, s83, 0
	global_load_ushort v159, v234, s[82:83]
	s_add_u32 s82, s82, 0x1600
	s_addc_u32 s83, s83, 0
	global_load_ushort v160, v234, s[82:83]
	s_add_u32 s82, s82, 0x1600
	s_addc_u32 s83, s83, 0
	global_load_ushort v161, v234, s[82:83]
	s_add_u32 s82, s82, 0x1600
	s_addc_u32 s83, s83, 0
	global_load_ushort v162, v234, s[82:83]
	s_add_u32 s82, s82, 0x1600
	s_addc_u32 s83, s83, 0
	global_load_ushort v163, v234, s[82:83]
	s_add_u32 s82, s82, 0x1600
	s_addc_u32 s83, s83, 0
	global_load_ushort v164, v234, s[82:83]
	s_add_u32 s82, s82, 0x1600
	s_addc_u32 s83, s83, 0
	global_load_ushort v165, v234, s[82:83]
	s_add_u32 s82, s82, 0x1600
	s_addc_u32 s83, s83, 0
	global_load_ushort v166, v234, s[82:83]
	s_add_u32 s82, s82, 0x1600
	s_addc_u32 s83, s83, 0
	global_load_ushort v167, v234, s[82:83]
	s_add_u32 s82, s82, 0x1600
	s_addc_u32 s83, s83, 0
	global_load_ushort v168, v234, s[82:83]
	s_add_u32 s82, s82, 0x1600
	s_addc_u32 s83, s83, 0
	global_load_ushort v169, v234, s[82:83]
	s_add_u32 s82, s82, 0x1600
	s_addc_u32 s83, s83, 0
	global_load_ushort v170, v234, s[82:83]
	s_add_u32 s82, s82, 0x1600
	s_addc_u32 s83, s83, 0
	global_load_ushort v171, v234, s[82:83]
	s_add_u32 s82, s82, 0x1600
	s_addc_u32 s83, s83, 0
	global_load_ushort v172, v234, s[82:83]
	s_add_u32 s82, s82, 0x1600
	s_addc_u32 s83, s83, 0
	global_load_ushort v173, v234, s[82:83]
	s_add_u32 s82, s82, 0x1600
	s_addc_u32 s83, s83, 0
	global_load_ushort v174, v234, s[82:83]
	s_add_u32 s82, s82, 0x1600
	s_addc_u32 s83, s83, 0
	global_load_ushort v175, v234, s[82:83]
	s_add_u32 s82, s82, 0x1600
	s_addc_u32 s83, s83, 0
	global_load_ushort v176, v234, s[82:83]
	s_add_u32 s82, s82, 0x1600
	s_addc_u32 s83, s83, 0
	global_load_ushort v177, v234, s[82:83]
	s_add_u32 s82, s82, 0x1600
	s_addc_u32 s83, s83, 0
	global_load_ushort v178, v234, s[82:83]
	s_add_u32 s82, s82, 0x1600
	s_addc_u32 s83, s83, 0
	global_load_ushort v179, v234, s[82:83]
	s_add_u32 s82, s82, 0x1600
	s_addc_u32 s83, s83, 0
	global_load_ushort v180, v234, s[82:83]
	s_add_u32 s82, s82, 0x1600
	s_addc_u32 s83, s83, 0
	global_load_ushort v181, v234, s[82:83]
	s_add_u32 s82, s82, 0x1600
	s_addc_u32 s83, s83, 0
	global_load_ushort v182, v234, s[82:83]
	s_add_u32 s82, s82, 0x1600
	s_addc_u32 s83, s83, 0
	global_load_ushort v183, v234, s[82:83]
	s_add_u32 s82, s82, 0x1600
	s_addc_u32 s83, s83, 0
	global_load_ushort v184, v234, s[82:83]
	s_add_u32 s82, s82, 0x1600
	s_addc_u32 s83, s83, 0
	global_load_ushort v185, v234, s[82:83]
	s_add_u32 s82, s82, 0x1600
	s_addc_u32 s83, s83, 0
	global_load_ushort v186, v234, s[82:83]
	s_add_u32 s82, s82, 0x1600
	s_addc_u32 s83, s83, 0
	global_load_ushort v187, v234, s[82:83]
	s_add_u32 s82, s82, 0x1600
	s_addc_u32 s83, s83, 0
	global_load_ushort v188, v234, s[82:83]
	s_add_u32 s82, s82, 0x1600
	s_addc_u32 s83, s83, 0
	global_load_ushort v189, v234, s[82:83]
	s_add_u32 s82, s82, 0x1600
	s_addc_u32 s83, s83, 0
	global_load_ushort v190, v234, s[82:83]
	s_add_u32 s82, s82, 0x1600
	s_addc_u32 s83, s83, 0
	global_load_ushort v191, v234, s[82:83]
	s_add_u32 s82, s82, 0x1600
	s_addc_u32 s83, s83, 0
	global_load_ushort v192, v234, s[82:83]
	s_add_u32 s82, s82, 0x1600
	s_addc_u32 s83, s83, 0
	global_load_ushort v193, v234, s[82:83]
	s_add_u32 s82, s82, 0x1600
	s_addc_u32 s83, s83, 0
	global_load_ushort v194, v234, s[82:83]
	s_add_u32 s82, s82, 0x1600
	s_addc_u32 s83, s83, 0
	global_load_ushort v195, v234, s[82:83]
	s_add_u32 s82, s82, 0x1600
	s_addc_u32 s83, s83, 0
	global_load_ushort v196, v234, s[82:83]
	s_add_u32 s82, s82, 0x1600
	s_addc_u32 s83, s83, 0
	global_load_ushort v197, v234, s[82:83]
	s_add_u32 s82, s82, 0x1600
	s_addc_u32 s83, s83, 0
	global_load_ushort v198, v234, s[82:83]
	s_add_u32 s82, s82, 0x1600
	s_addc_u32 s83, s83, 0
	global_load_ushort v199, v234, s[82:83]
	s_add_u32 s82, s82, 0x1600
	s_addc_u32 s83, s83, 0
	global_load_ushort v200, v234, s[82:83]
	s_add_u32 s82, s82, 0x1600
	s_addc_u32 s83, s83, 0
	global_load_ushort v201, v234, s[82:83]
	s_add_u32 s82, s82, 0x1600
	s_addc_u32 s83, s83, 0
	global_load_ushort v202, v234, s[82:83]
	s_add_u32 s82, s82, 0x1600
	s_addc_u32 s83, s83, 0
	global_load_ushort v203, v234, s[82:83]
	s_add_u32 s82, s82, 0x1600
	s_addc_u32 s83, s83, 0
	global_load_ushort v204, v234, s[82:83]
	s_add_u32 s82, s82, 0x1600
	s_addc_u32 s83, s83, 0
	global_load_ushort v205, v234, s[82:83]
	s_add_u32 s82, s82, 0x1600
	s_addc_u32 s83, s83, 0
	global_load_ushort v206, v234, s[82:83]
	s_add_u32 s82, s82, 0x1600
; __device__ __forceinline__ float rcpf_(float x) { return __builtin_amdgcn_rcpf(x); }
; template <bool FINAL, int D>
; __device__ __forceinline__ void rg_dir(PREF p, int l, int h, int ch, int sidx, int rowbase  , LAS bf16_t* sXc, LAS float* stg, int lane) {
;     ...
;     const float ba = p.rg_ba[(l * 2 + D) * 512 + ch], bi = p.rg_bi[(l * 2 + D) * 512 + ch], lam = p.rg_lam[(l * 2 + D) * 512 + ch];
;     const float e_ = __expf(-lam), u_ = 1.f + e_;
;     const float l1p = (u_ == 1.f) ? e_ : __logf(u_) * e_ * rcpf_(u_ - 1.f);
;     const float sp8 = -8.f * 1.4426950408889634f * l1p;
;     float hc = FINAL ? RGC[sidx] : 0.f, Ap = 1.f;
;     bf16x8 Br[4][2], Bi[4][2];
; #pragma unroll
;     for (int nt = 0; nt < 4; ++nt) { const int o0 = (nt * 16 + (lane & 15)) * 64 + (lane >> 4) * 8;
;         Br[nt][0] = *(const bf16x8*)(wr_ + o0); Br[nt][1] = *(const bf16x8*)(wr_ + o0 + 32); Bi[nt][0] = *(const bf16x8*)(wi_ + o0); Bi[nt][1] = *(const bf16x8*)(wi_ + o0 + 32); }
; template <bool FINAL>
; __device__ __forceinline__ void rg_item(PREF p, int l, int item, LAS unsigned char* wl, int lane) {
;     ...
;         const float cw0 = p.conv_w[(l * 4 + 0) * 512 + ch], cw1 = p.conv_w[(l * 4 + 1) * 512 + ch], cw2 = p.conv_w[(l * 4 + 2) * 512 + ch], cw3 = p.conv_w[(l * 4 + 3) * 512 + ch];
;         const float cb = p.conv_b[l * 512 + ch];
;         float xv[67]; unsigned xr_[67];
; #pragma unroll
;         for (int i = 0; i < 67; ++i) { const int t = t0 - 2 + i; const int tc = t < 0 ? 0 : (t >= seqlen ? seqlen - 1 : t);
;             xr_[i] = P[(size_t)(seq_row0 + tc) * PW + ch]; }
;         __builtin_amdgcn_sched_barrier(0);
; #pragma unroll
;         for (int i = 0; i < 67; ++i) { const int t = t0 - 2 + i; const int tc = t < 0 ? 0 : (t >= seqlen ? seqlen - 1 : t); xv[i] = (t == tc) ? bf2f(xr_[i]) : 0.f; }
	s_addc_u32 s83, s83, 0
	global_load_ushort v207, v234, s[82:83]
	s_add_u32 s82, s82, 0x1600
	s_addc_u32 s83, s83, 0
	global_load_ushort v208, v234, s[82:83]
	s_add_u32 s82, s82, 0x1600
	s_addc_u32 s83, s83, 0
	global_load_ushort v209, v234, s[82:83]
	s_add_u32 s82, s82, 0x1600
	s_addc_u32 s83, s83, 0
	global_load_ushort v210, v234, s[82:83]
	s_add_u32 s82, s82, 0x1600
	s_addc_u32 s83, s83, 0
	global_load_ushort v211, v234, s[82:83]
	s_add_u32 s82, s82, 0x1600
	s_addc_u32 s83, s83, 0
	global_load_ushort v212, v234, s[82:83]
	s_add_u32 s82, s82, 0x1600
	s_addc_u32 s83, s83, 0
	global_load_ushort v213, v234, s[82:83]
	s_add_u32 s82, s82, 0x1600
	s_addc_u32 s83, s83, 0
	global_load_ushort v214, v234, s[82:83]
	s_add_u32 s82, s82, 0x1600
	s_addc_u32 s83, s83, 0
	global_load_ushort v215, v234, s[82:83]
	s_add_u32 s82, s82, 0x1600
	s_addc_u32 s83, s83, 0
	global_load_ushort v216, v234, s[82:83]
	s_add_u32 s82, s82, 0x1600
	s_addc_u32 s83, s83, 0
	global_load_ushort v217, v234, s[82:83]
	s_add_u32 s82, s82, 0x1600
	s_addc_u32 s83, s83, 0
	global_load_ushort v218, v234, s[82:83]
	s_add_u32 s82, s82, 0x1600
	s_addc_u32 s83, s83, 0
	global_load_ushort v219, v234, s[82:83]
	s_add_u32 s82, s82, 0x1600
	s_addc_u32 s83, s83, 0
	global_load_ushort v222, v234, s[82:83]
	s_add_u32 s82, s82, 0x1600
	s_addc_u32 s83, s83, 0
	global_load_ushort v223, v234, s[82:83]
	s_add_u32 s82, s82, 0x1600
	s_addc_u32 s83, s83, 0
	global_load_ushort v140, v234, s[82:83]
	s_add_u32 s82, s82, 0x1600
	s_addc_u32 s83, s83, 0
	global_load_ushort v141, v234, s[82:83]
	s_add_u32 s82, s82, 0x1600
	s_addc_u32 s83, s83, 0
	global_load_ushort v232, v234, s[82:83]
	s_lshl_b32 s39, s57, 13
	s_add_u32 s72, s72, s39
	s_addc_u32 s73, s73, 0
	global_load_dword v40, v235, s[72:73]
	global_load_dword v41, v235, s[72:73] offset:2048
	s_add_u32 s72, s72, 0x1000
	s_addc_u32 s73, s73, 0
	global_load_dword v42, v235, s[72:73]
	global_load_dword v43, v235, s[72:73] offset:2048
	s_lshl_b32 s39, s57, 11
	s_add_u32 s74, s74, s39
	s_addc_u32 s75, s75, 0
	global_load_dword v44, v235, s[74:75]
	s_lshl_b32 s39, s57, 12
	s_add_u32 s76, s76, s39
	s_addc_u32 s77, s77, 0
	s_add_u32 s78, s78, s39
	s_addc_u32 s79, s79, 0
	s_add_u32 s80, s80, s39
	s_addc_u32 s81, s81, 0
	s_lshl_b32 s39, s57, 5
	s_add_i32 s39, s39, s7
	s_lshl_b32 s39, s39, 13
	s_add_u32 s92, s0, 0x300000
	s_addc_u32 s93, s1, 0
	s_add_u32 s92, s92, s39
	s_addc_u32 s93, s93, 0
	global_load_dword v45, v235, s[76:77]
	global_load_dword v46, v235, s[78:79]
	global_load_dword v47, v235, s[80:81]
	s_add_u32 s90, s92, 0x0
	s_addc_u32 s91, s93, 0
	global_load_dwordx4 v[80:83], v241, s[90:91]
	global_load_dwordx4 v[84:87], v241, s[90:91] offset:64
	global_load_dwordx4 v[88:91], v241, s[90:91] offset:2048
	global_load_dwordx4 v[92:95], v241, s[90:91] offset:2112
	s_add_u32 s90, s92, 0x1000
	s_addc_u32 s91, s93, 0
	global_load_dwordx4 v[96:99], v241, s[90:91]
	global_load_dwordx4 v[100:103], v241, s[90:91] offset:64
	global_load_dwordx4 v[104:107], v241, s[90:91] offset:2048
	global_load_dwordx4 v[108:111], v241, s[90:91] offset:2112
	s_add_u32 s90, s92, 0x10000
	s_addc_u32 s91, s93, 0
	global_load_dwordx4 v[112:115], v241, s[90:91]
	global_load_dwordx4 v[148:151], v241, s[90:91] offset:64
	global_load_dwordx4 v[120:123], v241, s[90:91] offset:2048
	global_load_dwordx4 v[124:127], v241, s[90:91] offset:2112
	s_add_u32 s90, s92, 0x11000
	s_addc_u32 s91, s93, 0
	global_load_dwordx4 v[128:131], v241, s[90:91]
	global_load_dwordx4 v[132:135], v241, s[90:91] offset:64
	global_load_dwordx4 v[136:139], v241, s[90:91] offset:2048
	global_load_dwordx4 v[228:231], v241, s[90:91] offset:2112
	s_waitcnt vmcnt(19)
	v_lshlrev_b32_e32 v158, 16, v158
	v_lshlrev_b32_e32 v159, 16, v159
	v_lshlrev_b32_e32 v160, 16, v160
	v_lshlrev_b32_e32 v161, 16, v161
	v_lshlrev_b32_e32 v162, 16, v162
	v_lshlrev_b32_e32 v163, 16, v163
	v_lshlrev_b32_e32 v164, 16, v164
	v_lshlrev_b32_e32 v165, 16, v165
	v_lshlrev_b32_e32 v166, 16, v166
	v_lshlrev_b32_e32 v167, 16, v167
	v_lshlrev_b32_e32 v168, 16, v168
	v_lshlrev_b32_e32 v169, 16, v169
	v_lshlrev_b32_e32 v170, 16, v170
	v_lshlrev_b32_e32 v171, 16, v171
	v_lshlrev_b32_e32 v172, 16, v172
	v_lshlrev_b32_e32 v173, 16, v173
	v_lshlrev_b32_e32 v174, 16, v174
	v_lshlrev_b32_e32 v175, 16, v175
	v_lshlrev_b32_e32 v176, 16, v176
	v_lshlrev_b32_e32 v177, 16, v177
	v_lshlrev_b32_e32 v178, 16, v178
	v_lshlrev_b32_e32 v179, 16, v179
	v_lshlrev_b32_e32 v180, 16, v180
	v_lshlrev_b32_e32 v181, 16, v181
	v_lshlrev_b32_e32 v182, 16, v182
	v_lshlrev_b32_e32 v183, 16, v183
	v_lshlrev_b32_e32 v184, 16, v184
	v_lshlrev_b32_e32 v185, 16, v185
	v_lshlrev_b32_e32 v186, 16, v186
	v_lshlrev_b32_e32 v187, 16, v187
	v_lshlrev_b32_e32 v188, 16, v188
	v_lshlrev_b32_e32 v189, 16, v189
	v_lshlrev_b32_e32 v190, 16, v190
	v_lshlrev_b32_e32 v191, 16, v191
	v_lshlrev_b32_e32 v192, 16, v192
	v_lshlrev_b32_e32 v193, 16, v193
	v_lshlrev_b32_e32 v194, 16, v194
	v_lshlrev_b32_e32 v195, 16, v195
	v_lshlrev_b32_e32 v196, 16, v196
	v_lshlrev_b32_e32 v197, 16, v197
	v_lshlrev_b32_e32 v198, 16, v198
	v_lshlrev_b32_e32 v199, 16, v199
	v_lshlrev_b32_e32 v200, 16, v200
	v_lshlrev_b32_e32 v201, 16, v201
	v_lshlrev_b32_e32 v202, 16, v202
	v_lshlrev_b32_e32 v203, 16, v203
	v_lshlrev_b32_e32 v204, 16, v204
	v_lshlrev_b32_e32 v205, 16, v205
	v_lshlrev_b32_e32 v206, 16, v206
	v_lshlrev_b32_e32 v207, 16, v207
	v_lshlrev_b32_e32 v208, 16, v208
	v_lshlrev_b32_e32 v209, 16, v209
	v_lshlrev_b32_e32 v210, 16, v210
	v_lshlrev_b32_e32 v211, 16, v211
	v_lshlrev_b32_e32 v212, 16, v212
	v_lshlrev_b32_e32 v213, 16, v213
	v_lshlrev_b32_e32 v214, 16, v214
	v_lshlrev_b32_e32 v215, 16, v215
	v_lshlrev_b32_e32 v216, 16, v216
; __device__ __forceinline__ unsigned f2bf(float f) { unsigned r; asm("v_cvt_pk_bf16_f32 %0, %1, %1" : "=v"(r) : "v"(f)); return r & 0xffffu; }
; template <bool FINAL>
; __device__ __forceinline__ void rg_item(PREF p, int l, int item, LAS unsigned char* wl, int lane) {
;     ...
;         for (int i = 0; i < 67; ++i) { const int t = t0 - 2 + i; const int tc = t < 0 ? 0 : (t >= seqlen ? seqlen - 1 : t); xv[i] = (t == tc) ? bf2f(xr_[i]) : 0.f; }
; #pragma unroll
;         for (int tt = 0; tt < 64; ++tt) { const float xc = xv[tt] * cw0 + xv[tt + 1] * cw1 + xv[tt + 2] * cw2 + xv[tt + 3] * cw3 + cb; sXc[tt * 72 + lane] = (bf16_t)f2bf(xc); }
	v_lshlrev_b32_e32 v217, 16, v217
	v_lshlrev_b32_e32 v218, 16, v218
	v_lshlrev_b32_e32 v219, 16, v219
	v_lshlrev_b32_e32 v222, 16, v222
	v_lshlrev_b32_e32 v223, 16, v223
	v_lshlrev_b32_e32 v140, 16, v140
	v_lshlrev_b32_e32 v141, 16, v141
	v_lshlrev_b32_e32 v232, 16, v232
	v_and_b32_e32 v158, s37, v158
	v_and_b32_e32 v159, s37, v159
	v_and_b32_e32 v232, s38, v232
	v_mul_f32_e32 v32, v41, v159
	v_mul_f32_e32 v33, v41, v160
	v_mul_f32_e32 v34, v41, v161
	v_mul_f32_e32 v35, v41, v162
	v_mul_f32_e32 v36, v41, v163
	v_mul_f32_e32 v37, v41, v164
	v_mul_f32_e32 v38, v41, v165
	v_mul_f32_e32 v39, v41, v166
	v_fmac_f32_e32 v32, v40, v158
	v_fmac_f32_e32 v33, v40, v159
	v_fmac_f32_e32 v34, v40, v160
	v_fmac_f32_e32 v35, v40, v161
	v_fmac_f32_e32 v36, v40, v162
	v_fmac_f32_e32 v37, v40, v163
	v_fmac_f32_e32 v38, v40, v164
	v_fmac_f32_e32 v39, v40, v165
	v_fmac_f32_e32 v32, v42, v160
	v_fmac_f32_e32 v33, v42, v161
	v_fmac_f32_e32 v34, v42, v162
	v_fmac_f32_e32 v35, v42, v163
	v_fmac_f32_e32 v36, v42, v164
	v_fmac_f32_e32 v37, v42, v165
	v_fmac_f32_e32 v38, v42, v166
	v_fmac_f32_e32 v39, v42, v167
	v_fmac_f32_e32 v32, v43, v161
	v_fmac_f32_e32 v33, v43, v162
	v_fmac_f32_e32 v34, v43, v163
	v_fmac_f32_e32 v35, v43, v164
	v_fmac_f32_e32 v36, v43, v165
	v_fmac_f32_e32 v37, v43, v166
	v_fmac_f32_e32 v38, v43, v167
	v_fmac_f32_e32 v39, v43, v168
	v_add_f32_e32 v32, v44, v32
	v_add_f32_e32 v33, v44, v33
	v_add_f32_e32 v34, v44, v34
	v_add_f32_e32 v35, v44, v35
	v_add_f32_e32 v36, v44, v36
	v_add_f32_e32 v37, v44, v37
	v_add_f32_e32 v38, v44, v38
	v_add_f32_e32 v39, v44, v39
	v_cvt_pk_bf16_f32 v32, v32, v33
	v_cvt_pk_bf16_f32 v34, v34, v35
	v_cvt_pk_bf16_f32 v36, v36, v37
	v_cvt_pk_bf16_f32 v38, v38, v39
	ds_write_b16 v240, v32 offset:0
	ds_write_b16_d16_hi v240, v32 offset:144
	ds_write_b16 v240, v34 offset:288
	ds_write_b16_d16_hi v240, v34 offset:432
	ds_write_b16 v240, v36 offset:576
	ds_write_b16_d16_hi v240, v36 offset:720
	ds_write_b16 v240, v38 offset:864
	ds_write_b16_d16_hi v240, v38 offset:1008
	v_mul_f32_e32 v32, v41, v167
	v_mul_f32_e32 v33, v41, v168
	v_mul_f32_e32 v34, v41, v169
	v_mul_f32_e32 v35, v41, v170
	v_mul_f32_e32 v36, v41, v171
	v_mul_f32_e32 v37, v41, v172
	v_mul_f32_e32 v38, v41, v173
	v_mul_f32_e32 v39, v41, v174
	v_fmac_f32_e32 v32, v40, v166
	v_fmac_f32_e32 v33, v40, v167
	v_fmac_f32_e32 v34, v40, v168
	v_fmac_f32_e32 v35, v40, v169
	v_fmac_f32_e32 v36, v40, v170
	v_fmac_f32_e32 v37, v40, v171
	v_fmac_f32_e32 v38, v40, v172
	v_fmac_f32_e32 v39, v40, v173
	v_fmac_f32_e32 v32, v42, v168
	v_fmac_f32_e32 v33, v42, v169
	v_fmac_f32_e32 v34, v42, v170
	v_fmac_f32_e32 v35, v42, v171
	v_fmac_f32_e32 v36, v42, v172
	v_fmac_f32_e32 v37, v42, v173
	v_fmac_f32_e32 v38, v42, v174
	v_fmac_f32_e32 v39, v42, v175
	v_fmac_f32_e32 v32, v43, v169
	v_fmac_f32_e32 v33, v43, v170
	v_fmac_f32_e32 v34, v43, v171
	v_fmac_f32_e32 v35, v43, v172
	v_fmac_f32_e32 v36, v43, v173
	v_fmac_f32_e32 v37, v43, v174
	v_fmac_f32_e32 v38, v43, v175
	v_fmac_f32_e32 v39, v43, v176
	v_add_f32_e32 v32, v44, v32
	v_add_f32_e32 v33, v44, v33
	v_add_f32_e32 v34, v44, v34
	v_add_f32_e32 v35, v44, v35
	v_add_f32_e32 v36, v44, v36
	v_add_f32_e32 v37, v44, v37
	v_add_f32_e32 v38, v44, v38
	v_add_f32_e32 v39, v44, v39
	v_cvt_pk_bf16_f32 v32, v32, v33
	v_cvt_pk_bf16_f32 v34, v34, v35
	v_cvt_pk_bf16_f32 v36, v36, v37
	v_cvt_pk_bf16_f32 v38, v38, v39
	ds_write_b16 v240, v32 offset:1152
	ds_write_b16_d16_hi v240, v32 offset:1296
	ds_write_b16 v240, v34 offset:1440
	ds_write_b16_d16_hi v240, v34 offset:1584
	ds_write_b16 v240, v36 offset:1728
	ds_write_b16_d16_hi v240, v36 offset:1872
	ds_write_b16 v240, v38 offset:2016
	ds_write_b16_d16_hi v240, v38 offset:2160
	v_mul_f32_e32 v32, v41, v175
	v_mul_f32_e32 v33, v41, v176
	v_mul_f32_e32 v34, v41, v177
	v_mul_f32_e32 v35, v41, v178
	v_mul_f32_e32 v36, v41, v179
	v_mul_f32_e32 v37, v41, v180
	v_mul_f32_e32 v38, v41, v181
	v_mul_f32_e32 v39, v41, v182
	v_fmac_f32_e32 v32, v40, v174
	v_fmac_f32_e32 v33, v40, v175
	v_fmac_f32_e32 v34, v40, v176
	v_fmac_f32_e32 v35, v40, v177
	v_fmac_f32_e32 v36, v40, v178
	v_fmac_f32_e32 v37, v40, v179
	v_fmac_f32_e32 v38, v40, v180
	v_fmac_f32_e32 v39, v40, v181
	v_fmac_f32_e32 v32, v42, v176
	v_fmac_f32_e32 v33, v42, v177
	v_fmac_f32_e32 v34, v42, v178
	v_fmac_f32_e32 v35, v42, v179
	v_fmac_f32_e32 v36, v42, v180
	v_fmac_f32_e32 v37, v42, v181
	v_fmac_f32_e32 v38, v42, v182
	v_fmac_f32_e32 v39, v42, v183
	v_fmac_f32_e32 v32, v43, v177
	v_fmac_f32_e32 v33, v43, v178
	v_fmac_f32_e32 v34, v43, v179
	v_fmac_f32_e32 v35, v43, v180
	v_fmac_f32_e32 v36, v43, v181
	v_fmac_f32_e32 v37, v43, v182
	v_fmac_f32_e32 v38, v43, v183
	v_fmac_f32_e32 v39, v43, v184
	v_add_f32_e32 v32, v44, v32
	v_add_f32_e32 v33, v44, v33
	v_add_f32_e32 v34, v44, v34
	v_add_f32_e32 v35, v44, v35
	v_add_f32_e32 v36, v44, v36
	v_add_f32_e32 v37, v44, v37
	v_add_f32_e32 v38, v44, v38
	v_add_f32_e32 v39, v44, v39
	v_cvt_pk_bf16_f32 v32, v32, v33
	v_cvt_pk_bf16_f32 v34, v34, v35
	v_cvt_pk_bf16_f32 v36, v36, v37
	v_cvt_pk_bf16_f32 v38, v38, v39
	ds_write_b16 v240, v32 offset:2304
	ds_write_b16_d16_hi v240, v32 offset:2448
	ds_write_b16 v240, v34 offset:2592
	ds_write_b16_d16_hi v240, v34 offset:2736
	ds_write_b16 v240, v36 offset:2880
	ds_write_b16_d16_hi v240, v36 offset:3024
	ds_write_b16 v240, v38 offset:3168
	ds_write_b16_d16_hi v240, v38 offset:3312
	v_mul_f32_e32 v32, v41, v183
	v_mul_f32_e32 v33, v41, v184
	v_mul_f32_e32 v34, v41, v185
	v_mul_f32_e32 v35, v41, v186
	v_mul_f32_e32 v36, v41, v187
	v_mul_f32_e32 v37, v41, v188
	v_mul_f32_e32 v38, v41, v189
	v_mul_f32_e32 v39, v41, v190
	v_fmac_f32_e32 v32, v40, v182
	v_fmac_f32_e32 v33, v40, v183
; __device__ __forceinline__ unsigned f2bf(float f) { unsigned r; asm("v_cvt_pk_bf16_f32 %0, %1, %1" : "=v"(r) : "v"(f)); return r & 0xffffu; }
; template <bool FINAL>
; __device__ __forceinline__ void rg_item(PREF p, int l, int item, LAS unsigned char* wl, int lane) {
;     ...
;         for (int i = 0; i < 67; ++i) { const int t = t0 - 2 + i; const int tc = t < 0 ? 0 : (t >= seqlen ? seqlen - 1 : t); xv[i] = (t == tc) ? bf2f(xr_[i]) : 0.f; }
; #pragma unroll
;         for (int tt = 0; tt < 64; ++tt) { const float xc = xv[tt] * cw0 + xv[tt + 1] * cw1 + xv[tt + 2] * cw2 + xv[tt + 3] * cw3 + cb; sXc[tt * 72 + lane] = (bf16_t)f2bf(xc); }
	v_fmac_f32_e32 v34, v40, v184
	v_fmac_f32_e32 v35, v40, v185
	v_fmac_f32_e32 v36, v40, v186
	v_fmac_f32_e32 v37, v40, v187
	v_fmac_f32_e32 v38, v40, v188
	v_fmac_f32_e32 v39, v40, v189
	v_fmac_f32_e32 v32, v42, v184
	v_fmac_f32_e32 v33, v42, v185
	v_fmac_f32_e32 v34, v42, v186
	v_fmac_f32_e32 v35, v42, v187
	v_fmac_f32_e32 v36, v42, v188
	v_fmac_f32_e32 v37, v42, v189
	v_fmac_f32_e32 v38, v42, v190
	v_fmac_f32_e32 v39, v42, v191
	v_fmac_f32_e32 v32, v43, v185
	v_fmac_f32_e32 v33, v43, v186
	v_fmac_f32_e32 v34, v43, v187
	v_fmac_f32_e32 v35, v43, v188
	v_fmac_f32_e32 v36, v43, v189
	v_fmac_f32_e32 v37, v43, v190
	v_fmac_f32_e32 v38, v43, v191
	v_fmac_f32_e32 v39, v43, v192
	v_add_f32_e32 v32, v44, v32
	v_add_f32_e32 v33, v44, v33
	v_add_f32_e32 v34, v44, v34
	v_add_f32_e32 v35, v44, v35
	v_add_f32_e32 v36, v44, v36
	v_add_f32_e32 v37, v44, v37
	v_add_f32_e32 v38, v44, v38
	v_add_f32_e32 v39, v44, v39
	v_cvt_pk_bf16_f32 v32, v32, v33
	v_cvt_pk_bf16_f32 v34, v34, v35
	v_cvt_pk_bf16_f32 v36, v36, v37
	v_cvt_pk_bf16_f32 v38, v38, v39
	ds_write_b16 v240, v32 offset:3456
	ds_write_b16_d16_hi v240, v32 offset:3600
	ds_write_b16 v240, v34 offset:3744
	ds_write_b16_d16_hi v240, v34 offset:3888
	ds_write_b16 v240, v36 offset:4032
	ds_write_b16_d16_hi v240, v36 offset:4176
	ds_write_b16 v240, v38 offset:4320
	ds_write_b16_d16_hi v240, v38 offset:4464
	v_mul_f32_e32 v32, v41, v191
	v_mul_f32_e32 v33, v41, v192
	v_mul_f32_e32 v34, v41, v193
	v_mul_f32_e32 v35, v41, v194
	v_mul_f32_e32 v36, v41, v195
	v_mul_f32_e32 v37, v41, v196
	v_mul_f32_e32 v38, v41, v197
	v_mul_f32_e32 v39, v41, v198
	v_fmac_f32_e32 v32, v40, v190
	v_fmac_f32_e32 v33, v40, v191
	v_fmac_f32_e32 v34, v40, v192
	v_fmac_f32_e32 v35, v40, v193
	v_fmac_f32_e32 v36, v40, v194
	v_fmac_f32_e32 v37, v40, v195
	v_fmac_f32_e32 v38, v40, v196
	v_fmac_f32_e32 v39, v40, v197
	v_fmac_f32_e32 v32, v42, v192
	v_fmac_f32_e32 v33, v42, v193
	v_fmac_f32_e32 v34, v42, v194
	v_fmac_f32_e32 v35, v42, v195
	v_fmac_f32_e32 v36, v42, v196
	v_fmac_f32_e32 v37, v42, v197
	v_fmac_f32_e32 v38, v42, v198
	v_fmac_f32_e32 v39, v42, v199
	v_fmac_f32_e32 v32, v43, v193
	v_fmac_f32_e32 v33, v43, v194
	v_fmac_f32_e32 v34, v43, v195
	v_fmac_f32_e32 v35, v43, v196
	v_fmac_f32_e32 v36, v43, v197
	v_fmac_f32_e32 v37, v43, v198
	v_fmac_f32_e32 v38, v43, v199
	v_fmac_f32_e32 v39, v43, v200
	v_add_f32_e32 v32, v44, v32
	v_add_f32_e32 v33, v44, v33
	v_add_f32_e32 v34, v44, v34
	v_add_f32_e32 v35, v44, v35
	v_add_f32_e32 v36, v44, v36
	v_add_f32_e32 v37, v44, v37
	v_add_f32_e32 v38, v44, v38
	v_add_f32_e32 v39, v44, v39
	v_cvt_pk_bf16_f32 v32, v32, v33
	v_cvt_pk_bf16_f32 v34, v34, v35
	v_cvt_pk_bf16_f32 v36, v36, v37
	v_cvt_pk_bf16_f32 v38, v38, v39
	ds_write_b16 v240, v32 offset:4608
	ds_write_b16_d16_hi v240, v32 offset:4752
	ds_write_b16 v240, v34 offset:4896
	ds_write_b16_d16_hi v240, v34 offset:5040
	ds_write_b16 v240, v36 offset:5184
	ds_write_b16_d16_hi v240, v36 offset:5328
	ds_write_b16 v240, v38 offset:5472
	ds_write_b16_d16_hi v240, v38 offset:5616
	v_mul_f32_e32 v32, v41, v199
	v_mul_f32_e32 v33, v41, v200
	v_mul_f32_e32 v34, v41, v201
	v_mul_f32_e32 v35, v41, v202
	v_mul_f32_e32 v36, v41, v203
	v_mul_f32_e32 v37, v41, v204
	v_mul_f32_e32 v38, v41, v205
	v_mul_f32_e32 v39, v41, v206
	v_fmac_f32_e32 v32, v40, v198
	v_fmac_f32_e32 v33, v40, v199
	v_fmac_f32_e32 v34, v40, v200
	v_fmac_f32_e32 v35, v40, v201
	v_fmac_f32_e32 v36, v40, v202
	v_fmac_f32_e32 v37, v40, v203
	v_fmac_f32_e32 v38, v40, v204
	v_fmac_f32_e32 v39, v40, v205
	v_fmac_f32_e32 v32, v42, v200
	v_fmac_f32_e32 v33, v42, v201
	v_fmac_f32_e32 v34, v42, v202
	v_fmac_f32_e32 v35, v42, v203
	v_fmac_f32_e32 v36, v42, v204
	v_fmac_f32_e32 v37, v42, v205
	v_fmac_f32_e32 v38, v42, v206
	v_fmac_f32_e32 v39, v42, v207
	v_fmac_f32_e32 v32, v43, v201
	v_fmac_f32_e32 v33, v43, v202
	v_fmac_f32_e32 v34, v43, v203
	v_fmac_f32_e32 v35, v43, v204
	v_fmac_f32_e32 v36, v43, v205
	v_fmac_f32_e32 v37, v43, v206
	v_fmac_f32_e32 v38, v43, v207
	v_fmac_f32_e32 v39, v43, v208
	v_add_f32_e32 v32, v44, v32
	v_add_f32_e32 v33, v44, v33
	v_add_f32_e32 v34, v44, v34
	v_add_f32_e32 v35, v44, v35
	v_add_f32_e32 v36, v44, v36
	v_add_f32_e32 v37, v44, v37
	v_add_f32_e32 v38, v44, v38
	v_add_f32_e32 v39, v44, v39
	v_cvt_pk_bf16_f32 v32, v32, v33
	v_cvt_pk_bf16_f32 v34, v34, v35
	v_cvt_pk_bf16_f32 v36, v36, v37
	v_cvt_pk_bf16_f32 v38, v38, v39
	ds_write_b16 v240, v32 offset:5760
	ds_write_b16_d16_hi v240, v32 offset:5904
	ds_write_b16 v240, v34 offset:6048
	ds_write_b16_d16_hi v240, v34 offset:6192
	ds_write_b16 v240, v36 offset:6336
	ds_write_b16_d16_hi v240, v36 offset:6480
	ds_write_b16 v240, v38 offset:6624
	ds_write_b16_d16_hi v240, v38 offset:6768
	v_mul_f32_e32 v32, v41, v207
	v_mul_f32_e32 v33, v41, v208
	v_mul_f32_e32 v34, v41, v209
	v_mul_f32_e32 v35, v41, v210
	v_mul_f32_e32 v36, v41, v211
	v_mul_f32_e32 v37, v41, v212
	v_mul_f32_e32 v38, v41, v213
	v_mul_f32_e32 v39, v41, v214
	v_fmac_f32_e32 v32, v40, v206
	v_fmac_f32_e32 v33, v40, v207
	v_fmac_f32_e32 v34, v40, v208
	v_fmac_f32_e32 v35, v40, v209
	v_fmac_f32_e32 v36, v40, v210
	v_fmac_f32_e32 v37, v40, v211
	v_fmac_f32_e32 v38, v40, v212
	v_fmac_f32_e32 v39, v40, v213
	v_fmac_f32_e32 v32, v42, v208
	v_fmac_f32_e32 v33, v42, v209
	v_fmac_f32_e32 v34, v42, v210
	v_fmac_f32_e32 v35, v42, v211
	v_fmac_f32_e32 v36, v42, v212
	v_fmac_f32_e32 v37, v42, v213
	v_fmac_f32_e32 v38, v42, v214
	v_fmac_f32_e32 v39, v42, v215
	v_fmac_f32_e32 v32, v43, v209
	v_fmac_f32_e32 v33, v43, v210
	v_fmac_f32_e32 v34, v43, v211
	v_fmac_f32_e32 v35, v43, v212
	v_fmac_f32_e32 v36, v43, v213
	v_fmac_f32_e32 v37, v43, v214
	v_fmac_f32_e32 v38, v43, v215
; #define LAS __attribute__((address_space(3)))
; template <bool FINAL, int D>
; __device__ __forceinline__ void rg_dir(PREF p, int l, int h, int ch, int sidx, int rowbase  , LAS bf16_t* sXc, LAS float* stg, int lane) {
;     ...
;     const float ba = p.rg_ba[(l * 2 + D) * 512 + ch], bi = p.rg_bi[(l * 2 + D) * 512 + ch], lam = p.rg_lam[(l * 2 + D) * 512 + ch];
;     const float e_ = __expf(-lam), u_ = 1.f + e_;
;     const float l1p = (u_ == 1.f) ? e_ : __logf(u_) * e_ * rcpf_(u_ - 1.f);
;     const float sp8 = -8.f * 1.4426950408889634f * l1p;
;     float hc = FINAL ? RGC[sidx] : 0.f, Ap = 1.f;
;     bf16x8 Br[4][2], Bi[4][2];
; #pragma unroll
;     for (int nt = 0; nt < 4; ++nt) { const int o0 = (nt * 16 + (lane & 15)) * 64 + (lane >> 4) * 8;
;         Br[nt][0] = *(const bf16x8*)(wr_ + o0); Br[nt][1] = *(const bf16x8*)(wr_ + o0 + 32); Bi[nt][0] = *(const bf16x8*)(wi_ + o0); Bi[nt][1] = *(const bf16x8*)(wi_ + o0 + 32); }
;     if (FINAL && D == 1) asm volatile("s_waitcnt vmcnt(0)" ::: "memory");
; #pragma unroll 1
;     for (int mi = 0; mi < 4; ++mi) { const int mt = D ? 3 - mi : mi;
;         float grv[16], hfv[16];
;         if (FINAL && D == 1) {
; #pragma unroll
;             for (int ti = 0; ti < 16; ++ti) { const size_t row = (size_t)(rowbase + mt * 16 + 15 - ti); grv[ti] = __builtin_bit_cast(float, (unsigned)P[row * PW + 512 + ch]); hfv[ti] = __builtin_bit_cast(float, (unsigned)TMP[row * 512 + ch]); }
;             __builtin_amdgcn_sched_barrier(0);
; #pragma unroll
;             for (int ti = 0; ti < 16; ++ti) { grv[ti] = bf2f(__builtin_bit_cast(unsigned, grv[ti])); hfv[ti] = bf2f(__builtin_bit_cast(unsigned, hfv[ti])); }
;         }
;         const bf16x8 A0 = *(const LAS bf16x8*)(sXc + (mt * 16 + (lane & 15)) * 72 + (lane >> 4) * 8), A1 = *(const LAS bf16x8*)(sXc + (mt * 16 + (lane & 15)) * 72 + 32 + (lane >> 4) * 8);
;         f32x4 ar[4], ai[4];
; #pragma unroll
; template <bool FINAL>
; __device__ __forceinline__ void rg_item(PREF p, int l, int item, LAS unsigned char* wl, int lane) {
;     ...
;         for (int i = 0; i < 67; ++i) { const int t = t0 - 2 + i; const int tc = t < 0 ? 0 : (t >= seqlen ? seqlen - 1 : t); xv[i] = (t == tc) ? bf2f(xr_[i]) : 0.f; }
; #pragma unroll
;         for (int tt = 0; tt < 64; ++tt) { const float xc = xv[tt] * cw0 + xv[tt + 1] * cw1 + xv[tt + 2] * cw2 + xv[tt + 3] * cw3 + cb; sXc[tt * 72 + lane] = (bf16_t)f2bf(xc); }
	v_fmac_f32_e32 v39, v43, v216
	v_add_f32_e32 v32, v44, v32
	v_add_f32_e32 v33, v44, v33
	v_add_f32_e32 v34, v44, v34
	v_add_f32_e32 v35, v44, v35
	v_add_f32_e32 v36, v44, v36
	v_add_f32_e32 v37, v44, v37
	v_add_f32_e32 v38, v44, v38
	v_add_f32_e32 v39, v44, v39
	v_cvt_pk_bf16_f32 v32, v32, v33
	v_cvt_pk_bf16_f32 v34, v34, v35
	v_cvt_pk_bf16_f32 v36, v36, v37
	v_cvt_pk_bf16_f32 v38, v38, v39
	ds_write_b16 v240, v32 offset:6912
	ds_write_b16_d16_hi v240, v32 offset:7056
	ds_write_b16 v240, v34 offset:7200
	ds_write_b16_d16_hi v240, v34 offset:7344
	ds_write_b16 v240, v36 offset:7488
	ds_write_b16_d16_hi v240, v36 offset:7632
	ds_write_b16 v240, v38 offset:7776
	ds_write_b16_d16_hi v240, v38 offset:7920
	v_mul_f32_e32 v32, v41, v215
	v_mul_f32_e32 v33, v41, v216
	v_mul_f32_e32 v34, v41, v217
	v_mul_f32_e32 v35, v41, v218
	v_mul_f32_e32 v36, v41, v219
	v_mul_f32_e32 v37, v41, v222
	v_mul_f32_e32 v38, v41, v223
	v_mul_f32_e32 v39, v41, v140
	v_fmac_f32_e32 v32, v40, v214
	v_fmac_f32_e32 v33, v40, v215
	v_fmac_f32_e32 v34, v40, v216
	v_fmac_f32_e32 v35, v40, v217
	v_fmac_f32_e32 v36, v40, v218
	v_fmac_f32_e32 v37, v40, v219
	v_fmac_f32_e32 v38, v40, v222
	v_fmac_f32_e32 v39, v40, v223
	v_fmac_f32_e32 v32, v42, v216
	v_fmac_f32_e32 v33, v42, v217
	v_fmac_f32_e32 v34, v42, v218
	v_fmac_f32_e32 v35, v42, v219
	v_fmac_f32_e32 v36, v42, v222
	v_fmac_f32_e32 v37, v42, v223
	v_fmac_f32_e32 v38, v42, v140
	v_fmac_f32_e32 v39, v42, v141
	v_fmac_f32_e32 v32, v43, v217
	v_fmac_f32_e32 v33, v43, v218
	v_fmac_f32_e32 v34, v43, v219
	v_fmac_f32_e32 v35, v43, v222
	v_fmac_f32_e32 v36, v43, v223
	v_fmac_f32_e32 v37, v43, v140
	v_fmac_f32_e32 v38, v43, v141
	v_fmac_f32_e32 v39, v43, v232
	v_add_f32_e32 v32, v44, v32
	v_add_f32_e32 v33, v44, v33
	v_add_f32_e32 v34, v44, v34
	v_add_f32_e32 v35, v44, v35
	v_add_f32_e32 v36, v44, v36
	v_add_f32_e32 v37, v44, v37
	v_add_f32_e32 v38, v44, v38
	v_add_f32_e32 v39, v44, v39
	v_cvt_pk_bf16_f32 v32, v32, v33
	v_cvt_pk_bf16_f32 v34, v34, v35
	v_cvt_pk_bf16_f32 v36, v36, v37
	v_cvt_pk_bf16_f32 v38, v38, v39
	ds_write_b16 v240, v32 offset:8064
	ds_write_b16_d16_hi v240, v32 offset:8208
	ds_write_b16 v240, v34 offset:8352
	ds_write_b16_d16_hi v240, v34 offset:8496
	ds_write_b16 v240, v36 offset:8640
	ds_write_b16_d16_hi v240, v36 offset:8784
	ds_write_b16 v240, v38 offset:8928
	ds_write_b16_d16_hi v240, v38 offset:9072
	v_mov_b32_e32 v248, 0xbfb8aa3b
	v_mov_b32_e32 v249, 0xbfb8aa3b
	s_waitcnt vmcnt(16)
	s_mov_b32 s8, 0x800000
	s_mov_b32 s9, 0x3f317217
	s_mov_b32 s14, 0x7f800000
	v_mul_f32_e32 v32, 0xbfb8aa3b, v45
	v_exp_f32_e32 v32, v32
	s_nop 0
	v_add_f32_e32 v33, 1.0, v32
	v_cmp_gt_f32_e32 vcc, s8, v33
	s_nop 1
	v_cndmask_b32_e64 v34, 0, 32, vcc
	v_ldexp_f32 v34, v33, v34
	v_log_f32_e32 v34, v34
	v_cndmask_b32_e32 v36, 0, v226, vcc
	v_cmp_eq_f32_e32 vcc, 1.0, v33
	v_mul_f32_e32 v35, 0x3f317217, v34
	v_fma_f32 v35, v34, s9, -v35
	v_fmac_f32_e32 v35, 0x3377d1cf, v34
	v_fmac_f32_e32 v35, 0x3f317217, v34
	v_cmp_lt_f32_e64 s[10:11], |v34|, s14
	s_nop 1
	v_cndmask_b32_e64 v34, v34, v35, s[10:11]
	v_add_f32_e32 v35, -1.0, v33
	v_rcp_f32_e32 v35, v35
	v_sub_f32_e32 v34, v34, v36
	v_mul_f32_e32 v34, v32, v34
	v_mul_f32_e32 v34, v34, v35
	v_cndmask_b32_e32 v32, v34, v32, vcc
	v_mul_f32_e32 v246, 0xc138aa3b, v32
	v_mov_b32_e32 v247, v246
	v_mul_f32_e32 v242, 0xbfb8aa3b, v46
	v_mul_f32_e32 v244, 0xbfb8aa3b, v47
	v_mov_b32_e32 v243, v242
	v_mov_b32_e32 v245, v244
	v_mov_b32_e32 v250, 0
	v_mov_b32_e32 v232, 1.0
	s_waitcnt vmcnt(0)
	ds_read_b128 v[32:35], v236 offset:0
	ds_read_b128 v[36:39], v236 offset:64
	s_waitcnt lgkmcnt(0)
	v_mfma_f32_16x16x32_bf16 v[0:3], v[32:35], v[80:83], 0
	v_mfma_f32_16x16x32_bf16 v[4:7], v[32:35], v[88:91], 0
	v_mfma_f32_16x16x32_bf16 v[8:11], v[32:35], v[96:99], 0
	v_mfma_f32_16x16x32_bf16 v[12:15], v[32:35], v[104:107], 0
	v_mfma_f32_16x16x32_bf16 v[16:19], v[32:35], v[112:115], 0
	v_mfma_f32_16x16x32_bf16 v[20:23], v[32:35], v[120:123], 0
	v_mfma_f32_16x16x32_bf16 v[24:27], v[32:35], v[128:131], 0
	v_mfma_f32_16x16x32_bf16 v[28:31], v[32:35], v[136:139], 0
	v_mfma_f32_16x16x32_bf16 v[0:3], v[36:39], v[84:87], v[0:3]
	v_mfma_f32_16x16x32_bf16 v[4:7], v[36:39], v[92:95], v[4:7]
	v_mfma_f32_16x16x32_bf16 v[8:11], v[36:39], v[100:103], v[8:11]
	v_mfma_f32_16x16x32_bf16 v[12:15], v[36:39], v[108:111], v[12:15]
	v_mfma_f32_16x16x32_bf16 v[16:19], v[36:39], v[148:151], v[16:19]
	v_mfma_f32_16x16x32_bf16 v[20:23], v[36:39], v[124:127], v[20:23]
	v_mfma_f32_16x16x32_bf16 v[24:27], v[36:39], v[132:135], v[24:27]
	v_mfma_f32_16x16x32_bf16 v[28:31], v[36:39], v[228:231], v[28:31]
	s_nop 3
	ds_write2_b32 v237, v0, v4 offset0:0 offset1:16
	ds_write2_b32 v237, v8, v12 offset0:32 offset1:48
	ds_write2_b32 v237, v1, v5 offset0:64 offset1:80
	ds_write2_b32 v237, v9, v13 offset0:96 offset1:112
	ds_write2_b32 v237, v2, v6 offset0:128 offset1:144
	ds_write2_b32 v237, v10, v14 offset0:160 offset1:176
	ds_write2_b32 v237, v3, v7 offset0:192 offset1:208
	ds_write2_b32 v237, v11, v15 offset0:224 offset1:240
	ds_write2_b32 v238, v16, v20 offset0:0 offset1:16
	ds_write2_b32 v238, v24, v28 offset0:32 offset1:48
	ds_write2_b32 v238, v17, v21 offset0:64 offset1:80
	ds_write2_b32 v238, v25, v29 offset0:96 offset1:112
	ds_write2_b32 v238, v18, v22 offset0:128 offset1:144
	ds_write2_b32 v238, v26, v30 offset0:160 offset1:176
	ds_write2_b32 v238, v19, v23 offset0:192 offset1:208
	ds_write2_b32 v238, v27, v31 offset0:224 offset1:240
	s_waitcnt lgkmcnt(0)
; __device__ __forceinline__ float sigmoid_f(float x) { return rcpf_(1.f + __expf(-x)); }
; template <bool FINAL, int D>
; __device__ __forceinline__ void rg_dir(PREF p, int l, int h, int ch, int sidx, int rowbase  , LAS bf16_t* sXc, LAS float* stg, int lane) {
;     ...
;         float av[16], iv[16];
; #pragma unroll
;         for (int ti = 0; ti < 16; ++ti) { const int tk = D ? 15 - ti : ti;
;             const float zr = stg[tk * 64 + lane] + ba, zi = stg[1024 + tk * 64 + lane] + bi;
;             const float r = sigmoid_f(zr), ig = sigmoid_f(zi);
;             const float a = __builtin_amdgcn_exp2f(r * sp8);
;             const float xc = bf2f(sXc[(mt * 16 + tk) * 72 + lane]);
;             av[ti] = a; iv[ti] = __builtin_amdgcn_sqrtf(fmaxf(1.f - a * a, 0.f)) * ig * xc;
	ds_read2st64_b32 v[0:1], v239 offset0:36 offset1:37
	ds_read2st64_b32 v[2:3], v239 offset0:38 offset1:39
	ds_read2st64_b32 v[4:5], v239 offset0:40 offset1:41
	ds_read2st64_b32 v[6:7], v239 offset0:42 offset1:43
	ds_read2st64_b32 v[8:9], v239 offset0:44 offset1:45
	ds_read2st64_b32 v[10:11], v239 offset0:46 offset1:47
	ds_read2st64_b32 v[12:13], v239 offset0:48 offset1:49
	ds_read2st64_b32 v[14:15], v239 offset0:50 offset1:51
	ds_read2st64_b32 v[16:17], v239 offset0:52 offset1:53
	ds_read2st64_b32 v[18:19], v239 offset0:54 offset1:55
	ds_read2st64_b32 v[20:21], v239 offset0:56 offset1:57
	ds_read2st64_b32 v[22:23], v239 offset0:58 offset1:59
	ds_read2st64_b32 v[24:25], v239 offset0:60 offset1:61
	ds_read2st64_b32 v[26:27], v239 offset0:62 offset1:63
	ds_read2st64_b32 v[28:29], v239 offset0:64 offset1:65
	ds_read2st64_b32 v[30:31], v239 offset0:66 offset1:67
	ds_read_u16 v48, v240 offset:0
	ds_read_u16 v49, v240 offset:144
	ds_read_u16 v50, v240 offset:288
	ds_read_u16 v51, v240 offset:432
	ds_read_u16 v52, v240 offset:576
	ds_read_u16 v53, v240 offset:720
	ds_read_u16 v54, v240 offset:864
	ds_read_u16 v55, v240 offset:1008
	ds_read_u16 v56, v240 offset:1152
	ds_read_u16 v57, v240 offset:1296
	ds_read_u16 v58, v240 offset:1440
	ds_read_u16 v59, v240 offset:1584
	ds_read_u16 v60, v240 offset:1728
	ds_read_u16 v61, v240 offset:1872
	ds_read_u16 v62, v240 offset:2016
	ds_read_u16 v63, v240 offset:2160
	s_waitcnt lgkmcnt(0)
	v_pk_fma_f32 v[0:1], v[0:1], v[248:249], v[242:243]
	v_pk_fma_f32 v[2:3], v[2:3], v[248:249], v[242:243]
	v_pk_fma_f32 v[4:5], v[4:5], v[248:249], v[242:243]
	v_pk_fma_f32 v[6:7], v[6:7], v[248:249], v[242:243]
	v_pk_fma_f32 v[8:9], v[8:9], v[248:249], v[242:243]
	v_pk_fma_f32 v[10:11], v[10:11], v[248:249], v[242:243]
	v_pk_fma_f32 v[12:13], v[12:13], v[248:249], v[242:243]
	v_pk_fma_f32 v[14:15], v[14:15], v[248:249], v[242:243]
	v_pk_fma_f32 v[16:17], v[16:17], v[248:249], v[244:245]
	v_pk_fma_f32 v[18:19], v[18:19], v[248:249], v[244:245]
	v_pk_fma_f32 v[20:21], v[20:21], v[248:249], v[244:245]
	v_pk_fma_f32 v[22:23], v[22:23], v[248:249], v[244:245]
	v_pk_fma_f32 v[24:25], v[24:25], v[248:249], v[244:245]
	v_pk_fma_f32 v[26:27], v[26:27], v[248:249], v[244:245]
	v_pk_fma_f32 v[28:29], v[28:29], v[248:249], v[244:245]
	v_pk_fma_f32 v[30:31], v[30:31], v[248:249], v[244:245]
	v_exp_f32_e32 v0, v0
	v_exp_f32_e32 v1, v1
	v_exp_f32_e32 v2, v2
	v_exp_f32_e32 v3, v3
	v_exp_f32_e32 v4, v4
	v_exp_f32_e32 v5, v5
	v_exp_f32_e32 v6, v6
	v_exp_f32_e32 v7, v7
	v_exp_f32_e32 v8, v8
	v_exp_f32_e32 v9, v9
	v_exp_f32_e32 v10, v10
	v_exp_f32_e32 v11, v11
	v_exp_f32_e32 v12, v12
	v_exp_f32_e32 v13, v13
	v_exp_f32_e32 v14, v14
	v_exp_f32_e32 v15, v15
	v_exp_f32_e32 v16, v16
	v_exp_f32_e32 v17, v17
	v_exp_f32_e32 v18, v18
	v_exp_f32_e32 v19, v19
	v_exp_f32_e32 v20, v20
	v_exp_f32_e32 v21, v21
	v_exp_f32_e32 v22, v22
	v_exp_f32_e32 v23, v23
	v_exp_f32_e32 v24, v24
	v_exp_f32_e32 v25, v25
	v_exp_f32_e32 v26, v26
	v_exp_f32_e32 v27, v27
	v_exp_f32_e32 v28, v28
	v_exp_f32_e32 v29, v29
	v_exp_f32_e32 v30, v30
	v_exp_f32_e32 v31, v31
	v_pk_add_f32 v[0:1], v[0:1], 1.0 op_sel_hi:[1,0]
	v_pk_add_f32 v[2:3], v[2:3], 1.0 op_sel_hi:[1,0]
	v_pk_add_f32 v[4:5], v[4:5], 1.0 op_sel_hi:[1,0]
	v_pk_add_f32 v[6:7], v[6:7], 1.0 op_sel_hi:[1,0]
	v_pk_add_f32 v[8:9], v[8:9], 1.0 op_sel_hi:[1,0]
	v_pk_add_f32 v[10:11], v[10:11], 1.0 op_sel_hi:[1,0]
	v_pk_add_f32 v[12:13], v[12:13], 1.0 op_sel_hi:[1,0]
	v_pk_add_f32 v[14:15], v[14:15], 1.0 op_sel_hi:[1,0]
	v_pk_add_f32 v[16:17], v[16:17], 1.0 op_sel_hi:[1,0]
	v_pk_add_f32 v[18:19], v[18:19], 1.0 op_sel_hi:[1,0]
	v_pk_add_f32 v[20:21], v[20:21], 1.0 op_sel_hi:[1,0]
	v_pk_add_f32 v[22:23], v[22:23], 1.0 op_sel_hi:[1,0]
	v_pk_add_f32 v[24:25], v[24:25], 1.0 op_sel_hi:[1,0]
	v_pk_add_f32 v[26:27], v[26:27], 1.0 op_sel_hi:[1,0]
	v_pk_add_f32 v[28:29], v[28:29], 1.0 op_sel_hi:[1,0]
	v_pk_add_f32 v[30:31], v[30:31], 1.0 op_sel_hi:[1,0]
	v_rcp_f32_e32 v0, v0
	v_rcp_f32_e32 v1, v1
	v_rcp_f32_e32 v2, v2
	v_rcp_f32_e32 v3, v3
	v_rcp_f32_e32 v4, v4
	v_rcp_f32_e32 v5, v5
	v_rcp_f32_e32 v6, v6
	v_rcp_f32_e32 v7, v7
	v_rcp_f32_e32 v8, v8
	v_rcp_f32_e32 v9, v9
	v_rcp_f32_e32 v10, v10
	v_rcp_f32_e32 v11, v11
	v_rcp_f32_e32 v12, v12
	v_rcp_f32_e32 v13, v13
	v_rcp_f32_e32 v14, v14
	v_rcp_f32_e32 v15, v15
	v_rcp_f32_e32 v16, v16
	v_rcp_f32_e32 v17, v17
	v_rcp_f32_e32 v18, v18
	v_rcp_f32_e32 v19, v19
	v_rcp_f32_e32 v20, v20
	v_rcp_f32_e32 v21, v21
	v_rcp_f32_e32 v22, v22
	v_rcp_f32_e32 v23, v23
	v_rcp_f32_e32 v24, v24
	v_rcp_f32_e32 v25, v25
	v_rcp_f32_e32 v26, v26
	v_rcp_f32_e32 v27, v27
	v_rcp_f32_e32 v28, v28
	v_rcp_f32_e32 v29, v29
	v_rcp_f32_e32 v30, v30
	v_rcp_f32_e32 v31, v31
	v_pk_mul_f32 v[0:1], v[246:247], v[0:1]
	v_pk_mul_f32 v[2:3], v[246:247], v[2:3]
	v_pk_mul_f32 v[4:5], v[246:247], v[4:5]
	v_pk_mul_f32 v[6:7], v[246:247], v[6:7]
	v_pk_mul_f32 v[8:9], v[246:247], v[8:9]
	v_pk_mul_f32 v[10:11], v[246:247], v[10:11]
	v_pk_mul_f32 v[12:13], v[246:247], v[12:13]
	v_pk_mul_f32 v[14:15], v[246:247], v[14:15]
	v_lshlrev_b32_e32 v48, 16, v48
	v_lshlrev_b32_e32 v49, 16, v49
	v_lshlrev_b32_e32 v50, 16, v50
	v_lshlrev_b32_e32 v51, 16, v51
	v_lshlrev_b32_e32 v52, 16, v52
	v_lshlrev_b32_e32 v53, 16, v53
	v_lshlrev_b32_e32 v54, 16, v54
	v_lshlrev_b32_e32 v55, 16, v55
	v_lshlrev_b32_e32 v56, 16, v56
	v_lshlrev_b32_e32 v57, 16, v57
	v_lshlrev_b32_e32 v58, 16, v58
	v_lshlrev_b32_e32 v59, 16, v59
	v_lshlrev_b32_e32 v60, 16, v60
	v_lshlrev_b32_e32 v61, 16, v61
	v_lshlrev_b32_e32 v62, 16, v62
	v_lshlrev_b32_e32 v63, 16, v63
	v_exp_f32_e32 v0, v0
	v_exp_f32_e32 v1, v1
	v_exp_f32_e32 v2, v2
	v_exp_f32_e32 v3, v3
	v_exp_f32_e32 v4, v4
; #define LAS __attribute__((address_space(3)))
; #define WAVE_SYNC() asm volatile("s_waitcnt lgkmcnt(0)" ::: "memory")
; __device__ __forceinline__ float sigmoid_f(float x) { return rcpf_(1.f + __expf(-x)); }
; __device__ __forceinline__ float gelu_tanh_f(float x) { const float y = 0.7978845608028654f * (x + 0.044715f * x * x * x); return x * sigmoid_f(2.f * y); }
; __device__ __forceinline__ f32x4 mfma16(bf16x8 a, bf16x8 b, f32x4 c) { return __builtin_amdgcn_mfma_f32_16x16x32_bf16(a, b, c, 0, 0, 0); }
; template <bool FINAL, int D>
; __device__ __forceinline__ void rg_dir(PREF p, int l, int h, int ch, int sidx, int rowbase  , LAS bf16_t* sXc, LAS float* stg, int lane) {
;     ...
;         const bf16x8 A0 = *(const LAS bf16x8*)(sXc + (mt * 16 + (lane & 15)) * 72 + (lane >> 4) * 8), A1 = *(const LAS bf16x8*)(sXc + (mt * 16 + (lane & 15)) * 72 + 32 + (lane >> 4) * 8);
;         f32x4 ar[4], ai[4];
; #pragma unroll
;         for (int nt = 0; nt < 4; ++nt) { const f32x4 z = {0.f, 0.f, 0.f, 0.f};
;             ar[nt] = mfma16(A0, Br[nt][0], z); ar[nt] = mfma16(A1, Br[nt][1], ar[nt]); ai[nt] = mfma16(A0, Bi[nt][0], z); ai[nt] = mfma16(A1, Bi[nt][1], ai[nt]); }
;         WAVE_SYNC();
; #pragma unroll
;         for (int nt = 0; nt < 4; ++nt)
; #pragma unroll
;             for (int j = 0; j < 4; ++j) { const int o = ((lane >> 4) * 4 + j) * 64 + nt * 16 + (lane & 15); stg[o] = ar[nt][j]; stg[1024 + o] = ai[nt][j]; }
;         WAVE_SYNC();
;         float av[16], iv[16];
; #pragma unroll
;         for (int ti = 0; ti < 16; ++ti) { const int tk = D ? 15 - ti : ti;
;             const float zr = stg[tk * 64 + lane] + ba, zi = stg[1024 + tk * 64 + lane] + bi;
;             const float r = sigmoid_f(zr), ig = sigmoid_f(zi);
;             const float a = __builtin_amdgcn_exp2f(r * sp8);
;             const float xc = bf2f(sXc[(mt * 16 + tk) * 72 + lane]);
;             av[ti] = a; iv[ti] = __builtin_amdgcn_sqrtf(fmaxf(1.f - a * a, 0.f)) * ig * xc;
;             if (FINAL && D == 1) grv[ti] = gelu_tanh_f(grv[ti]);
;         }
; #pragma unroll
;         for (int ti = 0; ti < 16; ++ti) { const int tk = D ? 15 - ti : ti;
;             hc = av[ti] * hc + iv[ti]; Ap *= av[ti];
	v_exp_f32_e32 v5, v5
	v_exp_f32_e32 v6, v6
	v_exp_f32_e32 v7, v7
	v_exp_f32_e32 v8, v8
	v_exp_f32_e32 v9, v9
	v_exp_f32_e32 v10, v10
	v_exp_f32_e32 v11, v11
	v_exp_f32_e32 v12, v12
	v_exp_f32_e32 v13, v13
	v_exp_f32_e32 v14, v14
	v_exp_f32_e32 v15, v15
	v_fma_f32 v32, -v0, v0, 1.0
	v_fma_f32 v33, -v1, v1, 1.0
	v_fma_f32 v34, -v2, v2, 1.0
	v_fma_f32 v35, -v3, v3, 1.0
	v_fma_f32 v36, -v4, v4, 1.0
	v_fma_f32 v37, -v5, v5, 1.0
	v_fma_f32 v38, -v6, v6, 1.0
	v_fma_f32 v39, -v7, v7, 1.0
	v_fma_f32 v40, -v8, v8, 1.0
	v_fma_f32 v41, -v9, v9, 1.0
	v_fma_f32 v42, -v10, v10, 1.0
	v_fma_f32 v43, -v11, v11, 1.0
	v_fma_f32 v44, -v12, v12, 1.0
	v_fma_f32 v45, -v13, v13, 1.0
	v_fma_f32 v46, -v14, v14, 1.0
	v_fma_f32 v47, -v15, v15, 1.0
	v_max_f32_e32 v32, 0, v32
	v_max_f32_e32 v33, 0, v33
	v_max_f32_e32 v34, 0, v34
	v_max_f32_e32 v35, 0, v35
	v_max_f32_e32 v36, 0, v36
	v_max_f32_e32 v37, 0, v37
	v_max_f32_e32 v38, 0, v38
	v_max_f32_e32 v39, 0, v39
	v_max_f32_e32 v40, 0, v40
	v_max_f32_e32 v41, 0, v41
	v_max_f32_e32 v42, 0, v42
	v_max_f32_e32 v43, 0, v43
	v_max_f32_e32 v44, 0, v44
	v_max_f32_e32 v45, 0, v45
	v_max_f32_e32 v46, 0, v46
	v_max_f32_e32 v47, 0, v47
	v_sqrt_f32_e32 v32, v32
	v_sqrt_f32_e32 v33, v33
	v_sqrt_f32_e32 v34, v34
	v_sqrt_f32_e32 v35, v35
	v_sqrt_f32_e32 v36, v36
	v_sqrt_f32_e32 v37, v37
	v_sqrt_f32_e32 v38, v38
	v_sqrt_f32_e32 v39, v39
	v_sqrt_f32_e32 v40, v40
	v_sqrt_f32_e32 v41, v41
	v_sqrt_f32_e32 v42, v42
	v_sqrt_f32_e32 v43, v43
	v_sqrt_f32_e32 v44, v44
	v_sqrt_f32_e32 v45, v45
	v_sqrt_f32_e32 v46, v46
	v_sqrt_f32_e32 v47, v47
	s_nop 0
	v_pk_mul_f32 v[16:17], v[16:17], v[32:33]
	v_pk_mul_f32 v[18:19], v[18:19], v[34:35]
	v_pk_mul_f32 v[20:21], v[20:21], v[36:37]
	v_pk_mul_f32 v[22:23], v[22:23], v[38:39]
	v_pk_mul_f32 v[24:25], v[24:25], v[40:41]
	v_pk_mul_f32 v[26:27], v[26:27], v[42:43]
	v_pk_mul_f32 v[28:29], v[28:29], v[44:45]
	v_pk_mul_f32 v[30:31], v[30:31], v[46:47]
	v_pk_mul_f32 v[16:17], v[16:17], v[48:49]
	v_pk_mul_f32 v[18:19], v[18:19], v[50:51]
	v_pk_mul_f32 v[20:21], v[20:21], v[52:53]
	v_pk_mul_f32 v[22:23], v[22:23], v[54:55]
	v_pk_mul_f32 v[24:25], v[24:25], v[56:57]
	v_pk_mul_f32 v[26:27], v[26:27], v[58:59]
	v_pk_mul_f32 v[28:29], v[28:29], v[60:61]
	v_pk_mul_f32 v[30:31], v[30:31], v[62:63]
	v_fma_f32 v32, v0, v250, v16
	v_mul_f32_e32 v232, v232, v0
	v_fma_f32 v250, v1, v32, v17
	v_mul_f32_e32 v232, v232, v1
	v_fma_f32 v32, v2, v250, v18
	v_mul_f32_e32 v232, v232, v2
	v_fma_f32 v250, v3, v32, v19
	v_mul_f32_e32 v232, v232, v3
	v_fma_f32 v32, v4, v250, v20
	v_mul_f32_e32 v232, v232, v4
	v_fma_f32 v250, v5, v32, v21
	v_mul_f32_e32 v232, v232, v5
	v_fma_f32 v32, v6, v250, v22
	v_mul_f32_e32 v232, v232, v6
	v_fma_f32 v250, v7, v32, v23
	v_mul_f32_e32 v232, v232, v7
	v_fma_f32 v32, v8, v250, v24
	v_mul_f32_e32 v232, v232, v8
	v_fma_f32 v250, v9, v32, v25
	v_mul_f32_e32 v232, v232, v9
	v_fma_f32 v32, v10, v250, v26
	v_mul_f32_e32 v232, v232, v10
	v_fma_f32 v250, v11, v32, v27
	v_mul_f32_e32 v232, v232, v11
	v_fma_f32 v32, v12, v250, v28
	v_mul_f32_e32 v232, v232, v12
	v_fma_f32 v250, v13, v32, v29
	v_mul_f32_e32 v232, v232, v13
	v_fma_f32 v32, v14, v250, v30
	v_mul_f32_e32 v232, v232, v14
	v_fma_f32 v250, v15, v32, v31
	v_mul_f32_e32 v232, v232, v15
	ds_read_b128 v[32:35], v236 offset:2304
	ds_read_b128 v[36:39], v236 offset:2368
	s_waitcnt lgkmcnt(0)
	v_mfma_f32_16x16x32_bf16 v[0:3], v[32:35], v[80:83], 0
	v_mfma_f32_16x16x32_bf16 v[4:7], v[32:35], v[88:91], 0
	v_mfma_f32_16x16x32_bf16 v[8:11], v[32:35], v[96:99], 0
	v_mfma_f32_16x16x32_bf16 v[12:15], v[32:35], v[104:107], 0
	v_mfma_f32_16x16x32_bf16 v[16:19], v[32:35], v[112:115], 0
	v_mfma_f32_16x16x32_bf16 v[20:23], v[32:35], v[120:123], 0
	v_mfma_f32_16x16x32_bf16 v[24:27], v[32:35], v[128:131], 0
	v_mfma_f32_16x16x32_bf16 v[28:31], v[32:35], v[136:139], 0
	v_mfma_f32_16x16x32_bf16 v[0:3], v[36:39], v[84:87], v[0:3]
	v_mfma_f32_16x16x32_bf16 v[4:7], v[36:39], v[92:95], v[4:7]
	v_mfma_f32_16x16x32_bf16 v[8:11], v[36:39], v[100:103], v[8:11]
	v_mfma_f32_16x16x32_bf16 v[12:15], v[36:39], v[108:111], v[12:15]
	v_mfma_f32_16x16x32_bf16 v[16:19], v[36:39], v[148:151], v[16:19]
	v_mfma_f32_16x16x32_bf16 v[20:23], v[36:39], v[124:127], v[20:23]
	v_mfma_f32_16x16x32_bf16 v[24:27], v[36:39], v[132:135], v[24:27]
	v_mfma_f32_16x16x32_bf16 v[28:31], v[36:39], v[228:231], v[28:31]
	s_nop 3
	ds_write2_b32 v237, v0, v4 offset0:0 offset1:16
	ds_write2_b32 v237, v8, v12 offset0:32 offset1:48
	ds_write2_b32 v237, v1, v5 offset0:64 offset1:80
	ds_write2_b32 v237, v9, v13 offset0:96 offset1:112
	ds_write2_b32 v237, v2, v6 offset0:128 offset1:144
	ds_write2_b32 v237, v10, v14 offset0:160 offset1:176
	ds_write2_b32 v237, v3, v7 offset0:192 offset1:208
	ds_write2_b32 v237, v11, v15 offset0:224 offset1:240
	ds_write2_b32 v238, v16, v20 offset0:0 offset1:16
	ds_write2_b32 v238, v24, v28 offset0:32 offset1:48
	ds_write2_b32 v238, v17, v21 offset0:64 offset1:80
	ds_write2_b32 v238, v25, v29 offset0:96 offset1:112
	ds_write2_b32 v238, v18, v22 offset0:128 offset1:144
	ds_write2_b32 v238, v26, v30 offset0:160 offset1:176
	ds_write2_b32 v238, v19, v23 offset0:192 offset1:208
	ds_write2_b32 v238, v27, v31 offset0:224 offset1:240
	s_waitcnt lgkmcnt(0)
; __device__ __forceinline__ float sigmoid_f(float x) { return rcpf_(1.f + __expf(-x)); }
; template <bool FINAL, int D>
; __device__ __forceinline__ void rg_dir(PREF p, int l, int h, int ch, int sidx, int rowbase  , LAS bf16_t* sXc, LAS float* stg, int lane) {
;     ...
;         float av[16], iv[16];
; #pragma unroll
;         for (int ti = 0; ti < 16; ++ti) { const int tk = D ? 15 - ti : ti;
;             const float zr = stg[tk * 64 + lane] + ba, zi = stg[1024 + tk * 64 + lane] + bi;
;             const float r = sigmoid_f(zr), ig = sigmoid_f(zi);
;             const float a = __builtin_amdgcn_exp2f(r * sp8);
;             const float xc = bf2f(sXc[(mt * 16 + tk) * 72 + lane]);
;             av[ti] = a; iv[ti] = __builtin_amdgcn_sqrtf(fmaxf(1.f - a * a, 0.f)) * ig * xc;
	ds_read2st64_b32 v[0:1], v239 offset0:36 offset1:37
	ds_read2st64_b32 v[2:3], v239 offset0:38 offset1:39
	ds_read2st64_b32 v[4:5], v239 offset0:40 offset1:41
	ds_read2st64_b32 v[6:7], v239 offset0:42 offset1:43
	ds_read2st64_b32 v[8:9], v239 offset0:44 offset1:45
	ds_read2st64_b32 v[10:11], v239 offset0:46 offset1:47
	ds_read2st64_b32 v[12:13], v239 offset0:48 offset1:49
	ds_read2st64_b32 v[14:15], v239 offset0:50 offset1:51
	ds_read2st64_b32 v[16:17], v239 offset0:52 offset1:53
	ds_read2st64_b32 v[18:19], v239 offset0:54 offset1:55
	ds_read2st64_b32 v[20:21], v239 offset0:56 offset1:57
	ds_read2st64_b32 v[22:23], v239 offset0:58 offset1:59
	ds_read2st64_b32 v[24:25], v239 offset0:60 offset1:61
	ds_read2st64_b32 v[26:27], v239 offset0:62 offset1:63
	ds_read2st64_b32 v[28:29], v239 offset0:64 offset1:65
	ds_read2st64_b32 v[30:31], v239 offset0:66 offset1:67
	ds_read_u16 v48, v240 offset:2304
	ds_read_u16 v49, v240 offset:2448
	ds_read_u16 v50, v240 offset:2592
	ds_read_u16 v51, v240 offset:2736
	ds_read_u16 v52, v240 offset:2880
	ds_read_u16 v53, v240 offset:3024
	ds_read_u16 v54, v240 offset:3168
	ds_read_u16 v55, v240 offset:3312
	ds_read_u16 v56, v240 offset:3456
	ds_read_u16 v57, v240 offset:3600
	ds_read_u16 v58, v240 offset:3744
	ds_read_u16 v59, v240 offset:3888
	ds_read_u16 v60, v240 offset:4032
	ds_read_u16 v61, v240 offset:4176
	ds_read_u16 v62, v240 offset:4320
	ds_read_u16 v63, v240 offset:4464
	s_waitcnt lgkmcnt(0)
	v_pk_fma_f32 v[0:1], v[0:1], v[248:249], v[242:243]
	v_pk_fma_f32 v[2:3], v[2:3], v[248:249], v[242:243]
	v_pk_fma_f32 v[4:5], v[4:5], v[248:249], v[242:243]
	v_pk_fma_f32 v[6:7], v[6:7], v[248:249], v[242:243]
	v_pk_fma_f32 v[8:9], v[8:9], v[248:249], v[242:243]
	v_pk_fma_f32 v[10:11], v[10:11], v[248:249], v[242:243]
	v_pk_fma_f32 v[12:13], v[12:13], v[248:249], v[242:243]
	v_pk_fma_f32 v[14:15], v[14:15], v[248:249], v[242:243]
	v_pk_fma_f32 v[16:17], v[16:17], v[248:249], v[244:245]
	v_pk_fma_f32 v[18:19], v[18:19], v[248:249], v[244:245]
	v_pk_fma_f32 v[20:21], v[20:21], v[248:249], v[244:245]
	v_pk_fma_f32 v[22:23], v[22:23], v[248:249], v[244:245]
	v_pk_fma_f32 v[24:25], v[24:25], v[248:249], v[244:245]
	v_pk_fma_f32 v[26:27], v[26:27], v[248:249], v[244:245]
	v_pk_fma_f32 v[28:29], v[28:29], v[248:249], v[244:245]
	v_pk_fma_f32 v[30:31], v[30:31], v[248:249], v[244:245]
	v_exp_f32_e32 v0, v0
	v_exp_f32_e32 v1, v1
	v_exp_f32_e32 v2, v2
	v_exp_f32_e32 v3, v3
	v_exp_f32_e32 v4, v4
	v_exp_f32_e32 v5, v5
	v_exp_f32_e32 v6, v6
	v_exp_f32_e32 v7, v7
	v_exp_f32_e32 v8, v8
	v_exp_f32_e32 v9, v9
	v_exp_f32_e32 v10, v10
	v_exp_f32_e32 v11, v11
	v_exp_f32_e32 v12, v12
	v_exp_f32_e32 v13, v13
	v_exp_f32_e32 v14, v14
	v_exp_f32_e32 v15, v15
	v_exp_f32_e32 v16, v16
	v_exp_f32_e32 v17, v17
	v_exp_f32_e32 v18, v18
	v_exp_f32_e32 v19, v19
	v_exp_f32_e32 v20, v20
	v_exp_f32_e32 v21, v21
	v_exp_f32_e32 v22, v22
	v_exp_f32_e32 v23, v23
	v_exp_f32_e32 v24, v24
	v_exp_f32_e32 v25, v25
	v_exp_f32_e32 v26, v26
	v_exp_f32_e32 v27, v27
	v_exp_f32_e32 v28, v28
	v_exp_f32_e32 v29, v29
	v_exp_f32_e32 v30, v30
	v_exp_f32_e32 v31, v31
	v_pk_add_f32 v[0:1], v[0:1], 1.0 op_sel_hi:[1,0]
	v_pk_add_f32 v[2:3], v[2:3], 1.0 op_sel_hi:[1,0]
	v_pk_add_f32 v[4:5], v[4:5], 1.0 op_sel_hi:[1,0]
	v_pk_add_f32 v[6:7], v[6:7], 1.0 op_sel_hi:[1,0]
	v_pk_add_f32 v[8:9], v[8:9], 1.0 op_sel_hi:[1,0]
	v_pk_add_f32 v[10:11], v[10:11], 1.0 op_sel_hi:[1,0]
	v_pk_add_f32 v[12:13], v[12:13], 1.0 op_sel_hi:[1,0]
	v_pk_add_f32 v[14:15], v[14:15], 1.0 op_sel_hi:[1,0]
	v_pk_add_f32 v[16:17], v[16:17], 1.0 op_sel_hi:[1,0]
	v_pk_add_f32 v[18:19], v[18:19], 1.0 op_sel_hi:[1,0]
	v_pk_add_f32 v[20:21], v[20:21], 1.0 op_sel_hi:[1,0]
	v_pk_add_f32 v[22:23], v[22:23], 1.0 op_sel_hi:[1,0]
	v_pk_add_f32 v[24:25], v[24:25], 1.0 op_sel_hi:[1,0]
	v_pk_add_f32 v[26:27], v[26:27], 1.0 op_sel_hi:[1,0]
	v_pk_add_f32 v[28:29], v[28:29], 1.0 op_sel_hi:[1,0]
	v_pk_add_f32 v[30:31], v[30:31], 1.0 op_sel_hi:[1,0]
	v_rcp_f32_e32 v0, v0
	v_rcp_f32_e32 v1, v1
	v_rcp_f32_e32 v2, v2
	v_rcp_f32_e32 v3, v3
	v_rcp_f32_e32 v4, v4
	v_rcp_f32_e32 v5, v5
	v_rcp_f32_e32 v6, v6
	v_rcp_f32_e32 v7, v7
	v_rcp_f32_e32 v8, v8
	v_rcp_f32_e32 v9, v9
	v_rcp_f32_e32 v10, v10
	v_rcp_f32_e32 v11, v11
	v_rcp_f32_e32 v12, v12
	v_rcp_f32_e32 v13, v13
	v_rcp_f32_e32 v14, v14
	v_rcp_f32_e32 v15, v15
	v_rcp_f32_e32 v16, v16
	v_rcp_f32_e32 v17, v17
	v_rcp_f32_e32 v18, v18
	v_rcp_f32_e32 v19, v19
	v_rcp_f32_e32 v20, v20
	v_rcp_f32_e32 v21, v21
	v_rcp_f32_e32 v22, v22
	v_rcp_f32_e32 v23, v23
	v_rcp_f32_e32 v24, v24
	v_rcp_f32_e32 v25, v25
	v_rcp_f32_e32 v26, v26
	v_rcp_f32_e32 v27, v27
	v_rcp_f32_e32 v28, v28
	v_rcp_f32_e32 v29, v29
	v_rcp_f32_e32 v30, v30
	v_rcp_f32_e32 v31, v31
	v_pk_mul_f32 v[0:1], v[246:247], v[0:1]
	v_pk_mul_f32 v[2:3], v[246:247], v[2:3]
	v_pk_mul_f32 v[4:5], v[246:247], v[4:5]
	v_pk_mul_f32 v[6:7], v[246:247], v[6:7]
	v_pk_mul_f32 v[8:9], v[246:247], v[8:9]
	v_pk_mul_f32 v[10:11], v[246:247], v[10:11]
	v_pk_mul_f32 v[12:13], v[246:247], v[12:13]
	v_pk_mul_f32 v[14:15], v[246:247], v[14:15]
	v_lshlrev_b32_e32 v48, 16, v48
	v_lshlrev_b32_e32 v49, 16, v49
	v_lshlrev_b32_e32 v50, 16, v50
	v_lshlrev_b32_e32 v51, 16, v51
	v_lshlrev_b32_e32 v52, 16, v52
	v_lshlrev_b32_e32 v53, 16, v53
	v_lshlrev_b32_e32 v54, 16, v54
	v_lshlrev_b32_e32 v55, 16, v55
	v_lshlrev_b32_e32 v56, 16, v56
	v_lshlrev_b32_e32 v57, 16, v57
	v_lshlrev_b32_e32 v58, 16, v58
	v_lshlrev_b32_e32 v59, 16, v59
	v_lshlrev_b32_e32 v60, 16, v60
	v_lshlrev_b32_e32 v61, 16, v61
	v_lshlrev_b32_e32 v62, 16, v62
	v_lshlrev_b32_e32 v63, 16, v63
	v_exp_f32_e32 v0, v0
	v_exp_f32_e32 v1, v1
	v_exp_f32_e32 v2, v2
	v_exp_f32_e32 v3, v3
	v_exp_f32_e32 v4, v4
; #define LAS __attribute__((address_space(3)))
; #define WAVE_SYNC() asm volatile("s_waitcnt lgkmcnt(0)" ::: "memory")
; __device__ __forceinline__ float sigmoid_f(float x) { return rcpf_(1.f + __expf(-x)); }
; __device__ __forceinline__ float gelu_tanh_f(float x) { const float y = 0.7978845608028654f * (x + 0.044715f * x * x * x); return x * sigmoid_f(2.f * y); }
; __device__ __forceinline__ f32x4 mfma16(bf16x8 a, bf16x8 b, f32x4 c) { return __builtin_amdgcn_mfma_f32_16x16x32_bf16(a, b, c, 0, 0, 0); }
; template <bool FINAL, int D>
; __device__ __forceinline__ void rg_dir(PREF p, int l, int h, int ch, int sidx, int rowbase  , LAS bf16_t* sXc, LAS float* stg, int lane) {
;     ...
;         const bf16x8 A0 = *(const LAS bf16x8*)(sXc + (mt * 16 + (lane & 15)) * 72 + (lane >> 4) * 8), A1 = *(const LAS bf16x8*)(sXc + (mt * 16 + (lane & 15)) * 72 + 32 + (lane >> 4) * 8);
;         f32x4 ar[4], ai[4];
; #pragma unroll
;         for (int nt = 0; nt < 4; ++nt) { const f32x4 z = {0.f, 0.f, 0.f, 0.f};
;             ar[nt] = mfma16(A0, Br[nt][0], z); ar[nt] = mfma16(A1, Br[nt][1], ar[nt]); ai[nt] = mfma16(A0, Bi[nt][0], z); ai[nt] = mfma16(A1, Bi[nt][1], ai[nt]); }
;         WAVE_SYNC();
; #pragma unroll
;         for (int nt = 0; nt < 4; ++nt)
; #pragma unroll
;             for (int j = 0; j < 4; ++j) { const int o = ((lane >> 4) * 4 + j) * 64 + nt * 16 + (lane & 15); stg[o] = ar[nt][j]; stg[1024 + o] = ai[nt][j]; }
;         WAVE_SYNC();
;         float av[16], iv[16];
; #pragma unroll
;         for (int ti = 0; ti < 16; ++ti) { const int tk = D ? 15 - ti : ti;
;             const float zr = stg[tk * 64 + lane] + ba, zi = stg[1024 + tk * 64 + lane] + bi;
;             const float r = sigmoid_f(zr), ig = sigmoid_f(zi);
;             const float a = __builtin_amdgcn_exp2f(r * sp8);
;             const float xc = bf2f(sXc[(mt * 16 + tk) * 72 + lane]);
;             av[ti] = a; iv[ti] = __builtin_amdgcn_sqrtf(fmaxf(1.f - a * a, 0.f)) * ig * xc;
;             if (FINAL && D == 1) grv[ti] = gelu_tanh_f(grv[ti]);
;         }
; #pragma unroll
;         for (int ti = 0; ti < 16; ++ti) { const int tk = D ? 15 - ti : ti;
;             hc = av[ti] * hc + iv[ti]; Ap *= av[ti];
	v_exp_f32_e32 v5, v5
	v_exp_f32_e32 v6, v6
	v_exp_f32_e32 v7, v7
	v_exp_f32_e32 v8, v8
	v_exp_f32_e32 v9, v9
	v_exp_f32_e32 v10, v10
	v_exp_f32_e32 v11, v11
	v_exp_f32_e32 v12, v12
	v_exp_f32_e32 v13, v13
	v_exp_f32_e32 v14, v14
	v_exp_f32_e32 v15, v15
	v_fma_f32 v32, -v0, v0, 1.0
	v_fma_f32 v33, -v1, v1, 1.0
	v_fma_f32 v34, -v2, v2, 1.0
	v_fma_f32 v35, -v3, v3, 1.0
	v_fma_f32 v36, -v4, v4, 1.0
	v_fma_f32 v37, -v5, v5, 1.0
	v_fma_f32 v38, -v6, v6, 1.0
	v_fma_f32 v39, -v7, v7, 1.0
	v_fma_f32 v40, -v8, v8, 1.0
	v_fma_f32 v41, -v9, v9, 1.0
	v_fma_f32 v42, -v10, v10, 1.0
	v_fma_f32 v43, -v11, v11, 1.0
	v_fma_f32 v44, -v12, v12, 1.0
	v_fma_f32 v45, -v13, v13, 1.0
	v_fma_f32 v46, -v14, v14, 1.0
	v_fma_f32 v47, -v15, v15, 1.0
	v_max_f32_e32 v32, 0, v32
	v_max_f32_e32 v33, 0, v33
	v_max_f32_e32 v34, 0, v34
	v_max_f32_e32 v35, 0, v35
	v_max_f32_e32 v36, 0, v36
	v_max_f32_e32 v37, 0, v37
	v_max_f32_e32 v38, 0, v38
	v_max_f32_e32 v39, 0, v39
	v_max_f32_e32 v40, 0, v40
	v_max_f32_e32 v41, 0, v41
	v_max_f32_e32 v42, 0, v42
	v_max_f32_e32 v43, 0, v43
	v_max_f32_e32 v44, 0, v44
	v_max_f32_e32 v45, 0, v45
	v_max_f32_e32 v46, 0, v46
	v_max_f32_e32 v47, 0, v47
	v_sqrt_f32_e32 v32, v32
	v_sqrt_f32_e32 v33, v33
	v_sqrt_f32_e32 v34, v34
	v_sqrt_f32_e32 v35, v35
	v_sqrt_f32_e32 v36, v36
	v_sqrt_f32_e32 v37, v37
	v_sqrt_f32_e32 v38, v38
	v_sqrt_f32_e32 v39, v39
	v_sqrt_f32_e32 v40, v40
	v_sqrt_f32_e32 v41, v41
	v_sqrt_f32_e32 v42, v42
	v_sqrt_f32_e32 v43, v43
	v_sqrt_f32_e32 v44, v44
	v_sqrt_f32_e32 v45, v45
	v_sqrt_f32_e32 v46, v46
	v_sqrt_f32_e32 v47, v47
	s_nop 0
	v_pk_mul_f32 v[16:17], v[16:17], v[32:33]
	v_pk_mul_f32 v[18:19], v[18:19], v[34:35]
	v_pk_mul_f32 v[20:21], v[20:21], v[36:37]
	v_pk_mul_f32 v[22:23], v[22:23], v[38:39]
	v_pk_mul_f32 v[24:25], v[24:25], v[40:41]
	v_pk_mul_f32 v[26:27], v[26:27], v[42:43]
	v_pk_mul_f32 v[28:29], v[28:29], v[44:45]
	v_pk_mul_f32 v[30:31], v[30:31], v[46:47]
	v_pk_mul_f32 v[16:17], v[16:17], v[48:49]
	v_pk_mul_f32 v[18:19], v[18:19], v[50:51]
	v_pk_mul_f32 v[20:21], v[20:21], v[52:53]
	v_pk_mul_f32 v[22:23], v[22:23], v[54:55]
	v_pk_mul_f32 v[24:25], v[24:25], v[56:57]
	v_pk_mul_f32 v[26:27], v[26:27], v[58:59]
	v_pk_mul_f32 v[28:29], v[28:29], v[60:61]
	v_pk_mul_f32 v[30:31], v[30:31], v[62:63]
	v_fma_f32 v32, v0, v250, v16
	v_mul_f32_e32 v232, v232, v0
	v_fma_f32 v250, v1, v32, v17
	v_mul_f32_e32 v232, v232, v1
	v_fma_f32 v32, v2, v250, v18
	v_mul_f32_e32 v232, v232, v2
	v_fma_f32 v250, v3, v32, v19
	v_mul_f32_e32 v232, v232, v3
	v_fma_f32 v32, v4, v250, v20
	v_mul_f32_e32 v232, v232, v4
	v_fma_f32 v250, v5, v32, v21
	v_mul_f32_e32 v232, v232, v5
	v_fma_f32 v32, v6, v250, v22
	v_mul_f32_e32 v232, v232, v6
	v_fma_f32 v250, v7, v32, v23
	v_mul_f32_e32 v232, v232, v7
	v_fma_f32 v32, v8, v250, v24
	v_mul_f32_e32 v232, v232, v8
	v_fma_f32 v250, v9, v32, v25
	v_mul_f32_e32 v232, v232, v9
	v_fma_f32 v32, v10, v250, v26
	v_mul_f32_e32 v232, v232, v10
	v_fma_f32 v250, v11, v32, v27
	v_mul_f32_e32 v232, v232, v11
	v_fma_f32 v32, v12, v250, v28
	v_mul_f32_e32 v232, v232, v12
	v_fma_f32 v250, v13, v32, v29
	v_mul_f32_e32 v232, v232, v13
	v_fma_f32 v32, v14, v250, v30
	v_mul_f32_e32 v232, v232, v14
	v_fma_f32 v250, v15, v32, v31
	v_mul_f32_e32 v232, v232, v15
	ds_read_b128 v[32:35], v236 offset:4608
	ds_read_b128 v[36:39], v236 offset:4672
	s_waitcnt lgkmcnt(0)
	v_mfma_f32_16x16x32_bf16 v[0:3], v[32:35], v[80:83], 0
	v_mfma_f32_16x16x32_bf16 v[4:7], v[32:35], v[88:91], 0
	v_mfma_f32_16x16x32_bf16 v[8:11], v[32:35], v[96:99], 0
	v_mfma_f32_16x16x32_bf16 v[12:15], v[32:35], v[104:107], 0
	v_mfma_f32_16x16x32_bf16 v[16:19], v[32:35], v[112:115], 0
	v_mfma_f32_16x16x32_bf16 v[20:23], v[32:35], v[120:123], 0
	v_mfma_f32_16x16x32_bf16 v[24:27], v[32:35], v[128:131], 0
	v_mfma_f32_16x16x32_bf16 v[28:31], v[32:35], v[136:139], 0
	v_mfma_f32_16x16x32_bf16 v[0:3], v[36:39], v[84:87], v[0:3]
	v_mfma_f32_16x16x32_bf16 v[4:7], v[36:39], v[92:95], v[4:7]
	v_mfma_f32_16x16x32_bf16 v[8:11], v[36:39], v[100:103], v[8:11]
	v_mfma_f32_16x16x32_bf16 v[12:15], v[36:39], v[108:111], v[12:15]
	v_mfma_f32_16x16x32_bf16 v[16:19], v[36:39], v[148:151], v[16:19]
	v_mfma_f32_16x16x32_bf16 v[20:23], v[36:39], v[124:127], v[20:23]
	v_mfma_f32_16x16x32_bf16 v[24:27], v[36:39], v[132:135], v[24:27]
	v_mfma_f32_16x16x32_bf16 v[28:31], v[36:39], v[228:231], v[28:31]
	s_nop 3
	ds_write2_b32 v237, v0, v4 offset0:0 offset1:16
	ds_write2_b32 v237, v8, v12 offset0:32 offset1:48
	ds_write2_b32 v237, v1, v5 offset0:64 offset1:80
	ds_write2_b32 v237, v9, v13 offset0:96 offset1:112
	ds_write2_b32 v237, v2, v6 offset0:128 offset1:144
	ds_write2_b32 v237, v10, v14 offset0:160 offset1:176
	ds_write2_b32 v237, v3, v7 offset0:192 offset1:208
	ds_write2_b32 v237, v11, v15 offset0:224 offset1:240
	ds_write2_b32 v238, v16, v20 offset0:0 offset1:16
	ds_write2_b32 v238, v24, v28 offset0:32 offset1:48
	ds_write2_b32 v238, v17, v21 offset0:64 offset1:80
	ds_write2_b32 v238, v25, v29 offset0:96 offset1:112
	ds_write2_b32 v238, v18, v22 offset0:128 offset1:144
	ds_write2_b32 v238, v26, v30 offset0:160 offset1:176
	ds_write2_b32 v238, v19, v23 offset0:192 offset1:208
	ds_write2_b32 v238, v27, v31 offset0:224 offset1:240
	s_waitcnt lgkmcnt(0)
; __device__ __forceinline__ float sigmoid_f(float x) { return rcpf_(1.f + __expf(-x)); }
; template <bool FINAL, int D>
; __device__ __forceinline__ void rg_dir(PREF p, int l, int h, int ch, int sidx, int rowbase  , LAS bf16_t* sXc, LAS float* stg, int lane) {
;     ...
;         float av[16], iv[16];
; #pragma unroll
;         for (int ti = 0; ti < 16; ++ti) { const int tk = D ? 15 - ti : ti;
;             const float zr = stg[tk * 64 + lane] + ba, zi = stg[1024 + tk * 64 + lane] + bi;
;             const float r = sigmoid_f(zr), ig = sigmoid_f(zi);
;             const float a = __builtin_amdgcn_exp2f(r * sp8);
;             const float xc = bf2f(sXc[(mt * 16 + tk) * 72 + lane]);
;             av[ti] = a; iv[ti] = __builtin_amdgcn_sqrtf(fmaxf(1.f - a * a, 0.f)) * ig * xc;
	ds_read2st64_b32 v[0:1], v239 offset0:36 offset1:37
	ds_read2st64_b32 v[2:3], v239 offset0:38 offset1:39
	ds_read2st64_b32 v[4:5], v239 offset0:40 offset1:41
	ds_read2st64_b32 v[6:7], v239 offset0:42 offset1:43
	ds_read2st64_b32 v[8:9], v239 offset0:44 offset1:45
	ds_read2st64_b32 v[10:11], v239 offset0:46 offset1:47
	ds_read2st64_b32 v[12:13], v239 offset0:48 offset1:49
	ds_read2st64_b32 v[14:15], v239 offset0:50 offset1:51
	ds_read2st64_b32 v[16:17], v239 offset0:52 offset1:53
	ds_read2st64_b32 v[18:19], v239 offset0:54 offset1:55
	ds_read2st64_b32 v[20:21], v239 offset0:56 offset1:57
	ds_read2st64_b32 v[22:23], v239 offset0:58 offset1:59
	ds_read2st64_b32 v[24:25], v239 offset0:60 offset1:61
	ds_read2st64_b32 v[26:27], v239 offset0:62 offset1:63
	ds_read2st64_b32 v[28:29], v239 offset0:64 offset1:65
	ds_read2st64_b32 v[30:31], v239 offset0:66 offset1:67
	ds_read_u16 v48, v240 offset:4608
	ds_read_u16 v49, v240 offset:4752
	ds_read_u16 v50, v240 offset:4896
	ds_read_u16 v51, v240 offset:5040
	ds_read_u16 v52, v240 offset:5184
	ds_read_u16 v53, v240 offset:5328
	ds_read_u16 v54, v240 offset:5472
	ds_read_u16 v55, v240 offset:5616
	ds_read_u16 v56, v240 offset:5760
	ds_read_u16 v57, v240 offset:5904
	ds_read_u16 v58, v240 offset:6048
	ds_read_u16 v59, v240 offset:6192
	ds_read_u16 v60, v240 offset:6336
	ds_read_u16 v61, v240 offset:6480
	ds_read_u16 v62, v240 offset:6624
	ds_read_u16 v63, v240 offset:6768
	s_waitcnt lgkmcnt(0)
	v_pk_fma_f32 v[0:1], v[0:1], v[248:249], v[242:243]
	v_pk_fma_f32 v[2:3], v[2:3], v[248:249], v[242:243]
	v_pk_fma_f32 v[4:5], v[4:5], v[248:249], v[242:243]
	v_pk_fma_f32 v[6:7], v[6:7], v[248:249], v[242:243]
	v_pk_fma_f32 v[8:9], v[8:9], v[248:249], v[242:243]
	v_pk_fma_f32 v[10:11], v[10:11], v[248:249], v[242:243]
	v_pk_fma_f32 v[12:13], v[12:13], v[248:249], v[242:243]
	v_pk_fma_f32 v[14:15], v[14:15], v[248:249], v[242:243]
	v_pk_fma_f32 v[16:17], v[16:17], v[248:249], v[244:245]
	v_pk_fma_f32 v[18:19], v[18:19], v[248:249], v[244:245]
	v_pk_fma_f32 v[20:21], v[20:21], v[248:249], v[244:245]
	v_pk_fma_f32 v[22:23], v[22:23], v[248:249], v[244:245]
	v_pk_fma_f32 v[24:25], v[24:25], v[248:249], v[244:245]
	v_pk_fma_f32 v[26:27], v[26:27], v[248:249], v[244:245]
	v_pk_fma_f32 v[28:29], v[28:29], v[248:249], v[244:245]
	v_pk_fma_f32 v[30:31], v[30:31], v[248:249], v[244:245]
	v_exp_f32_e32 v0, v0
	v_exp_f32_e32 v1, v1
	v_exp_f32_e32 v2, v2
	v_exp_f32_e32 v3, v3
	v_exp_f32_e32 v4, v4
	v_exp_f32_e32 v5, v5
	v_exp_f32_e32 v6, v6
	v_exp_f32_e32 v7, v7
	v_exp_f32_e32 v8, v8
	v_exp_f32_e32 v9, v9
	v_exp_f32_e32 v10, v10
	v_exp_f32_e32 v11, v11
	v_exp_f32_e32 v12, v12
	v_exp_f32_e32 v13, v13
	v_exp_f32_e32 v14, v14
	v_exp_f32_e32 v15, v15
	v_exp_f32_e32 v16, v16
	v_exp_f32_e32 v17, v17
	v_exp_f32_e32 v18, v18
	v_exp_f32_e32 v19, v19
	v_exp_f32_e32 v20, v20
	v_exp_f32_e32 v21, v21
	v_exp_f32_e32 v22, v22
	v_exp_f32_e32 v23, v23
	v_exp_f32_e32 v24, v24
	v_exp_f32_e32 v25, v25
	v_exp_f32_e32 v26, v26
	v_exp_f32_e32 v27, v27
	v_exp_f32_e32 v28, v28
	v_exp_f32_e32 v29, v29
	v_exp_f32_e32 v30, v30
	v_exp_f32_e32 v31, v31
	v_pk_add_f32 v[0:1], v[0:1], 1.0 op_sel_hi:[1,0]
	v_pk_add_f32 v[2:3], v[2:3], 1.0 op_sel_hi:[1,0]
	v_pk_add_f32 v[4:5], v[4:5], 1.0 op_sel_hi:[1,0]
	v_pk_add_f32 v[6:7], v[6:7], 1.0 op_sel_hi:[1,0]
	v_pk_add_f32 v[8:9], v[8:9], 1.0 op_sel_hi:[1,0]
	v_pk_add_f32 v[10:11], v[10:11], 1.0 op_sel_hi:[1,0]
	v_pk_add_f32 v[12:13], v[12:13], 1.0 op_sel_hi:[1,0]
	v_pk_add_f32 v[14:15], v[14:15], 1.0 op_sel_hi:[1,0]
	v_pk_add_f32 v[16:17], v[16:17], 1.0 op_sel_hi:[1,0]
	v_pk_add_f32 v[18:19], v[18:19], 1.0 op_sel_hi:[1,0]
	v_pk_add_f32 v[20:21], v[20:21], 1.0 op_sel_hi:[1,0]
	v_pk_add_f32 v[22:23], v[22:23], 1.0 op_sel_hi:[1,0]
	v_pk_add_f32 v[24:25], v[24:25], 1.0 op_sel_hi:[1,0]
	v_pk_add_f32 v[26:27], v[26:27], 1.0 op_sel_hi:[1,0]
	v_pk_add_f32 v[28:29], v[28:29], 1.0 op_sel_hi:[1,0]
	v_pk_add_f32 v[30:31], v[30:31], 1.0 op_sel_hi:[1,0]
	v_rcp_f32_e32 v0, v0
	v_rcp_f32_e32 v1, v1
	v_rcp_f32_e32 v2, v2
	v_rcp_f32_e32 v3, v3
	v_rcp_f32_e32 v4, v4
	v_rcp_f32_e32 v5, v5
	v_rcp_f32_e32 v6, v6
	v_rcp_f32_e32 v7, v7
	v_rcp_f32_e32 v8, v8
	v_rcp_f32_e32 v9, v9
	v_rcp_f32_e32 v10, v10
	v_rcp_f32_e32 v11, v11
	v_rcp_f32_e32 v12, v12
	v_rcp_f32_e32 v13, v13
	v_rcp_f32_e32 v14, v14
	v_rcp_f32_e32 v15, v15
	v_rcp_f32_e32 v16, v16
	v_rcp_f32_e32 v17, v17
	v_rcp_f32_e32 v18, v18
	v_rcp_f32_e32 v19, v19
	v_rcp_f32_e32 v20, v20
	v_rcp_f32_e32 v21, v21
	v_rcp_f32_e32 v22, v22
	v_rcp_f32_e32 v23, v23
	v_rcp_f32_e32 v24, v24
	v_rcp_f32_e32 v25, v25
	v_rcp_f32_e32 v26, v26
	v_rcp_f32_e32 v27, v27
	v_rcp_f32_e32 v28, v28
	v_rcp_f32_e32 v29, v29
	v_rcp_f32_e32 v30, v30
	v_rcp_f32_e32 v31, v31
	v_pk_mul_f32 v[0:1], v[246:247], v[0:1]
	v_pk_mul_f32 v[2:3], v[246:247], v[2:3]
	v_pk_mul_f32 v[4:5], v[246:247], v[4:5]
	v_pk_mul_f32 v[6:7], v[246:247], v[6:7]
	v_pk_mul_f32 v[8:9], v[246:247], v[8:9]
	v_pk_mul_f32 v[10:11], v[246:247], v[10:11]
	v_pk_mul_f32 v[12:13], v[246:247], v[12:13]
	v_pk_mul_f32 v[14:15], v[246:247], v[14:15]
	v_lshlrev_b32_e32 v48, 16, v48
	v_lshlrev_b32_e32 v49, 16, v49
	v_lshlrev_b32_e32 v50, 16, v50
	v_lshlrev_b32_e32 v51, 16, v51
	v_lshlrev_b32_e32 v52, 16, v52
	v_lshlrev_b32_e32 v53, 16, v53
	v_lshlrev_b32_e32 v54, 16, v54
	v_lshlrev_b32_e32 v55, 16, v55
	v_lshlrev_b32_e32 v56, 16, v56
	v_lshlrev_b32_e32 v57, 16, v57
	v_lshlrev_b32_e32 v58, 16, v58
	v_lshlrev_b32_e32 v59, 16, v59
	v_lshlrev_b32_e32 v60, 16, v60
	v_lshlrev_b32_e32 v61, 16, v61
	v_lshlrev_b32_e32 v62, 16, v62
	v_lshlrev_b32_e32 v63, 16, v63
	v_exp_f32_e32 v0, v0
	v_exp_f32_e32 v1, v1
	v_exp_f32_e32 v2, v2
	v_exp_f32_e32 v3, v3
	v_exp_f32_e32 v4, v4
; #define LAS __attribute__((address_space(3)))
; #define WAVE_SYNC() asm volatile("s_waitcnt lgkmcnt(0)" ::: "memory")
; __device__ __forceinline__ float sigmoid_f(float x) { return rcpf_(1.f + __expf(-x)); }
; __device__ __forceinline__ float gelu_tanh_f(float x) { const float y = 0.7978845608028654f * (x + 0.044715f * x * x * x); return x * sigmoid_f(2.f * y); }
; __device__ __forceinline__ f32x4 mfma16(bf16x8 a, bf16x8 b, f32x4 c) { return __builtin_amdgcn_mfma_f32_16x16x32_bf16(a, b, c, 0, 0, 0); }
; template <bool FINAL, int D>
; __device__ __forceinline__ void rg_dir(PREF p, int l, int h, int ch, int sidx, int rowbase  , LAS bf16_t* sXc, LAS float* stg, int lane) {
;     ...
;         const bf16x8 A0 = *(const LAS bf16x8*)(sXc + (mt * 16 + (lane & 15)) * 72 + (lane >> 4) * 8), A1 = *(const LAS bf16x8*)(sXc + (mt * 16 + (lane & 15)) * 72 + 32 + (lane >> 4) * 8);
;         f32x4 ar[4], ai[4];
; #pragma unroll
;         for (int nt = 0; nt < 4; ++nt) { const f32x4 z = {0.f, 0.f, 0.f, 0.f};
;             ar[nt] = mfma16(A0, Br[nt][0], z); ar[nt] = mfma16(A1, Br[nt][1], ar[nt]); ai[nt] = mfma16(A0, Bi[nt][0], z); ai[nt] = mfma16(A1, Bi[nt][1], ai[nt]); }
;         WAVE_SYNC();
; #pragma unroll
;         for (int nt = 0; nt < 4; ++nt)
; #pragma unroll
;             for (int j = 0; j < 4; ++j) { const int o = ((lane >> 4) * 4 + j) * 64 + nt * 16 + (lane & 15); stg[o] = ar[nt][j]; stg[1024 + o] = ai[nt][j]; }
;         WAVE_SYNC();
;         float av[16], iv[16];
; #pragma unroll
;         for (int ti = 0; ti < 16; ++ti) { const int tk = D ? 15 - ti : ti;
;             const float zr = stg[tk * 64 + lane] + ba, zi = stg[1024 + tk * 64 + lane] + bi;
;             const float r = sigmoid_f(zr), ig = sigmoid_f(zi);
;             const float a = __builtin_amdgcn_exp2f(r * sp8);
;             const float xc = bf2f(sXc[(mt * 16 + tk) * 72 + lane]);
;             av[ti] = a; iv[ti] = __builtin_amdgcn_sqrtf(fmaxf(1.f - a * a, 0.f)) * ig * xc;
;             if (FINAL && D == 1) grv[ti] = gelu_tanh_f(grv[ti]);
;         }
; #pragma unroll
;         for (int ti = 0; ti < 16; ++ti) { const int tk = D ? 15 - ti : ti;
;             hc = av[ti] * hc + iv[ti]; Ap *= av[ti];
	v_exp_f32_e32 v5, v5
	v_exp_f32_e32 v6, v6
	v_exp_f32_e32 v7, v7
	v_exp_f32_e32 v8, v8
	v_exp_f32_e32 v9, v9
	v_exp_f32_e32 v10, v10
	v_exp_f32_e32 v11, v11
	v_exp_f32_e32 v12, v12
	v_exp_f32_e32 v13, v13
	v_exp_f32_e32 v14, v14
	v_exp_f32_e32 v15, v15
	v_fma_f32 v32, -v0, v0, 1.0
	v_fma_f32 v33, -v1, v1, 1.0
	v_fma_f32 v34, -v2, v2, 1.0
	v_fma_f32 v35, -v3, v3, 1.0
	v_fma_f32 v36, -v4, v4, 1.0
	v_fma_f32 v37, -v5, v5, 1.0
	v_fma_f32 v38, -v6, v6, 1.0
	v_fma_f32 v39, -v7, v7, 1.0
	v_fma_f32 v40, -v8, v8, 1.0
	v_fma_f32 v41, -v9, v9, 1.0
	v_fma_f32 v42, -v10, v10, 1.0
	v_fma_f32 v43, -v11, v11, 1.0
	v_fma_f32 v44, -v12, v12, 1.0
	v_fma_f32 v45, -v13, v13, 1.0
	v_fma_f32 v46, -v14, v14, 1.0
	v_fma_f32 v47, -v15, v15, 1.0
	v_max_f32_e32 v32, 0, v32
	v_max_f32_e32 v33, 0, v33
	v_max_f32_e32 v34, 0, v34
	v_max_f32_e32 v35, 0, v35
	v_max_f32_e32 v36, 0, v36
	v_max_f32_e32 v37, 0, v37
	v_max_f32_e32 v38, 0, v38
	v_max_f32_e32 v39, 0, v39
	v_max_f32_e32 v40, 0, v40
	v_max_f32_e32 v41, 0, v41
	v_max_f32_e32 v42, 0, v42
	v_max_f32_e32 v43, 0, v43
	v_max_f32_e32 v44, 0, v44
	v_max_f32_e32 v45, 0, v45
	v_max_f32_e32 v46, 0, v46
	v_max_f32_e32 v47, 0, v47
	v_sqrt_f32_e32 v32, v32
	v_sqrt_f32_e32 v33, v33
	v_sqrt_f32_e32 v34, v34
	v_sqrt_f32_e32 v35, v35
	v_sqrt_f32_e32 v36, v36
	v_sqrt_f32_e32 v37, v37
	v_sqrt_f32_e32 v38, v38
	v_sqrt_f32_e32 v39, v39
	v_sqrt_f32_e32 v40, v40
	v_sqrt_f32_e32 v41, v41
	v_sqrt_f32_e32 v42, v42
	v_sqrt_f32_e32 v43, v43
	v_sqrt_f32_e32 v44, v44
	v_sqrt_f32_e32 v45, v45
	v_sqrt_f32_e32 v46, v46
	v_sqrt_f32_e32 v47, v47
	s_nop 0
	v_pk_mul_f32 v[16:17], v[16:17], v[32:33]
	v_pk_mul_f32 v[18:19], v[18:19], v[34:35]
	v_pk_mul_f32 v[20:21], v[20:21], v[36:37]
	v_pk_mul_f32 v[22:23], v[22:23], v[38:39]
	v_pk_mul_f32 v[24:25], v[24:25], v[40:41]
	v_pk_mul_f32 v[26:27], v[26:27], v[42:43]
	v_pk_mul_f32 v[28:29], v[28:29], v[44:45]
	v_pk_mul_f32 v[30:31], v[30:31], v[46:47]
	v_pk_mul_f32 v[16:17], v[16:17], v[48:49]
	v_pk_mul_f32 v[18:19], v[18:19], v[50:51]
	v_pk_mul_f32 v[20:21], v[20:21], v[52:53]
	v_pk_mul_f32 v[22:23], v[22:23], v[54:55]
	v_pk_mul_f32 v[24:25], v[24:25], v[56:57]
	v_pk_mul_f32 v[26:27], v[26:27], v[58:59]
	v_pk_mul_f32 v[28:29], v[28:29], v[60:61]
	v_pk_mul_f32 v[30:31], v[30:31], v[62:63]
	v_fma_f32 v32, v0, v250, v16
	v_mul_f32_e32 v232, v232, v0
	v_fma_f32 v250, v1, v32, v17
	v_mul_f32_e32 v232, v232, v1
	v_fma_f32 v32, v2, v250, v18
	v_mul_f32_e32 v232, v232, v2
	v_fma_f32 v250, v3, v32, v19
	v_mul_f32_e32 v232, v232, v3
	v_fma_f32 v32, v4, v250, v20
	v_mul_f32_e32 v232, v232, v4
	v_fma_f32 v250, v5, v32, v21
	v_mul_f32_e32 v232, v232, v5
	v_fma_f32 v32, v6, v250, v22
	v_mul_f32_e32 v232, v232, v6
	v_fma_f32 v250, v7, v32, v23
	v_mul_f32_e32 v232, v232, v7
	v_fma_f32 v32, v8, v250, v24
	v_mul_f32_e32 v232, v232, v8
	v_fma_f32 v250, v9, v32, v25
	v_mul_f32_e32 v232, v232, v9
	v_fma_f32 v32, v10, v250, v26
	v_mul_f32_e32 v232, v232, v10
	v_fma_f32 v250, v11, v32, v27
	v_mul_f32_e32 v232, v232, v11
	v_fma_f32 v32, v12, v250, v28
	v_mul_f32_e32 v232, v232, v12
	v_fma_f32 v250, v13, v32, v29
	v_mul_f32_e32 v232, v232, v13
	v_fma_f32 v32, v14, v250, v30
	v_mul_f32_e32 v232, v232, v14
	v_fma_f32 v250, v15, v32, v31
	v_mul_f32_e32 v232, v232, v15
	ds_read_b128 v[32:35], v236 offset:6912
	ds_read_b128 v[36:39], v236 offset:6976
	s_waitcnt lgkmcnt(0)
	v_mfma_f32_16x16x32_bf16 v[0:3], v[32:35], v[80:83], 0
	v_mfma_f32_16x16x32_bf16 v[4:7], v[32:35], v[88:91], 0
	v_mfma_f32_16x16x32_bf16 v[8:11], v[32:35], v[96:99], 0
	v_mfma_f32_16x16x32_bf16 v[12:15], v[32:35], v[104:107], 0
	v_mfma_f32_16x16x32_bf16 v[16:19], v[32:35], v[112:115], 0
	v_mfma_f32_16x16x32_bf16 v[20:23], v[32:35], v[120:123], 0
	v_mfma_f32_16x16x32_bf16 v[24:27], v[32:35], v[128:131], 0
	v_mfma_f32_16x16x32_bf16 v[28:31], v[32:35], v[136:139], 0
	v_mfma_f32_16x16x32_bf16 v[0:3], v[36:39], v[84:87], v[0:3]
	v_mfma_f32_16x16x32_bf16 v[4:7], v[36:39], v[92:95], v[4:7]
	v_mfma_f32_16x16x32_bf16 v[8:11], v[36:39], v[100:103], v[8:11]
	v_mfma_f32_16x16x32_bf16 v[12:15], v[36:39], v[108:111], v[12:15]
	v_mfma_f32_16x16x32_bf16 v[16:19], v[36:39], v[148:151], v[16:19]
	v_mfma_f32_16x16x32_bf16 v[20:23], v[36:39], v[124:127], v[20:23]
	v_mfma_f32_16x16x32_bf16 v[24:27], v[36:39], v[132:135], v[24:27]
	v_mfma_f32_16x16x32_bf16 v[28:31], v[36:39], v[228:231], v[28:31]
	s_nop 3
	ds_write2_b32 v237, v0, v4 offset0:0 offset1:16
	ds_write2_b32 v237, v8, v12 offset0:32 offset1:48
	ds_write2_b32 v237, v1, v5 offset0:64 offset1:80
	ds_write2_b32 v237, v9, v13 offset0:96 offset1:112
	ds_write2_b32 v237, v2, v6 offset0:128 offset1:144
	ds_write2_b32 v237, v10, v14 offset0:160 offset1:176
	ds_write2_b32 v237, v3, v7 offset0:192 offset1:208
	ds_write2_b32 v237, v11, v15 offset0:224 offset1:240
	ds_write2_b32 v238, v16, v20 offset0:0 offset1:16
	ds_write2_b32 v238, v24, v28 offset0:32 offset1:48
	ds_write2_b32 v238, v17, v21 offset0:64 offset1:80
	ds_write2_b32 v238, v25, v29 offset0:96 offset1:112
	ds_write2_b32 v238, v18, v22 offset0:128 offset1:144
	ds_write2_b32 v238, v26, v30 offset0:160 offset1:176
	ds_write2_b32 v238, v19, v23 offset0:192 offset1:208
	ds_write2_b32 v238, v27, v31 offset0:224 offset1:240
	s_waitcnt lgkmcnt(0)
; #define WAVE_SYNC() asm volatile("s_waitcnt lgkmcnt(0)" ::: "memory")
; __device__ __forceinline__ float sigmoid_f(float x) { return rcpf_(1.f + __expf(-x)); }
; template <bool FINAL, int D>
; __device__ __forceinline__ void rg_dir(PREF p, int l, int h, int ch, int sidx, int rowbase  , LAS bf16_t* sXc, LAS float* stg, int lane) {
;     ...
;     bf16x8 Br[4][2], Bi[4][2];
; #pragma unroll
;     for (int nt = 0; nt < 4; ++nt) { const int o0 = (nt * 16 + (lane & 15)) * 64 + (lane >> 4) * 8;
;         Br[nt][0] = *(const bf16x8*)(wr_ + o0); Br[nt][1] = *(const bf16x8*)(wr_ + o0 + 32); Bi[nt][0] = *(const bf16x8*)(wi_ + o0); Bi[nt][1] = *(const bf16x8*)(wi_ + o0 + 32); }
;     ...
;             for (int j = 0; j < 4; ++j) { const int o = ((lane >> 4) * 4 + j) * 64 + nt * 16 + (lane & 15); stg[o] = ar[nt][j]; stg[1024 + o] = ai[nt][j]; }
;         WAVE_SYNC();
;         float av[16], iv[16];
; #pragma unroll
;         for (int ti = 0; ti < 16; ++ti) { const int tk = D ? 15 - ti : ti;
;             const float zr = stg[tk * 64 + lane] + ba, zi = stg[1024 + tk * 64 + lane] + bi;
;             const float r = sigmoid_f(zr), ig = sigmoid_f(zi);
;             const float a = __builtin_amdgcn_exp2f(r * sp8);
;             const float xc = bf2f(sXc[(mt * 16 + tk) * 72 + lane]);
;             av[ti] = a; iv[ti] = __builtin_amdgcn_sqrtf(fmaxf(1.f - a * a, 0.f)) * ig * xc;
	ds_read2st64_b32 v[0:1], v239 offset0:36 offset1:37
	ds_read2st64_b32 v[2:3], v239 offset0:38 offset1:39
	ds_read2st64_b32 v[4:5], v239 offset0:40 offset1:41
	ds_read2st64_b32 v[6:7], v239 offset0:42 offset1:43
	ds_read2st64_b32 v[8:9], v239 offset0:44 offset1:45
	ds_read2st64_b32 v[10:11], v239 offset0:46 offset1:47
	ds_read2st64_b32 v[12:13], v239 offset0:48 offset1:49
	ds_read2st64_b32 v[14:15], v239 offset0:50 offset1:51
	ds_read2st64_b32 v[16:17], v239 offset0:52 offset1:53
	ds_read2st64_b32 v[18:19], v239 offset0:54 offset1:55
	ds_read2st64_b32 v[20:21], v239 offset0:56 offset1:57
	ds_read2st64_b32 v[22:23], v239 offset0:58 offset1:59
	ds_read2st64_b32 v[24:25], v239 offset0:60 offset1:61
	ds_read2st64_b32 v[26:27], v239 offset0:62 offset1:63
	ds_read2st64_b32 v[28:29], v239 offset0:64 offset1:65
	ds_read2st64_b32 v[30:31], v239 offset0:66 offset1:67
	ds_read_u16 v48, v240 offset:6912
	ds_read_u16 v49, v240 offset:7056
	ds_read_u16 v50, v240 offset:7200
	ds_read_u16 v51, v240 offset:7344
	ds_read_u16 v52, v240 offset:7488
	ds_read_u16 v53, v240 offset:7632
	ds_read_u16 v54, v240 offset:7776
	ds_read_u16 v55, v240 offset:7920
	ds_read_u16 v56, v240 offset:8064
	ds_read_u16 v57, v240 offset:8208
	ds_read_u16 v58, v240 offset:8352
	ds_read_u16 v59, v240 offset:8496
	ds_read_u16 v60, v240 offset:8640
	ds_read_u16 v61, v240 offset:8784
	ds_read_u16 v62, v240 offset:8928
	ds_read_u16 v63, v240 offset:9072
	s_add_u32 s90, s92, 0x20000
	s_addc_u32 s91, s93, 0
	global_load_dwordx4 v[80:83], v241, s[90:91]
	global_load_dwordx4 v[84:87], v241, s[90:91] offset:64
	global_load_dwordx4 v[88:91], v241, s[90:91] offset:2048
	global_load_dwordx4 v[92:95], v241, s[90:91] offset:2112
	s_add_u32 s90, s92, 0x21000
	s_addc_u32 s91, s93, 0
	global_load_dwordx4 v[96:99], v241, s[90:91]
	global_load_dwordx4 v[100:103], v241, s[90:91] offset:64
	global_load_dwordx4 v[104:107], v241, s[90:91] offset:2048
	global_load_dwordx4 v[108:111], v241, s[90:91] offset:2112
	s_add_u32 s90, s92, 0x30000
	s_addc_u32 s91, s93, 0
	global_load_dwordx4 v[112:115], v241, s[90:91]
	global_load_dwordx4 v[148:151], v241, s[90:91] offset:64
	global_load_dwordx4 v[120:123], v241, s[90:91] offset:2048
	global_load_dwordx4 v[124:127], v241, s[90:91] offset:2112
	s_add_u32 s90, s92, 0x31000
	s_addc_u32 s91, s93, 0
	global_load_dwordx4 v[128:131], v241, s[90:91]
	global_load_dwordx4 v[132:135], v241, s[90:91] offset:64
	global_load_dwordx4 v[136:139], v241, s[90:91] offset:2048
	global_load_dwordx4 v[228:231], v241, s[90:91] offset:2112
	s_waitcnt lgkmcnt(0)
	v_pk_fma_f32 v[0:1], v[0:1], v[248:249], v[242:243]
	v_pk_fma_f32 v[2:3], v[2:3], v[248:249], v[242:243]
	v_pk_fma_f32 v[4:5], v[4:5], v[248:249], v[242:243]
	v_pk_fma_f32 v[6:7], v[6:7], v[248:249], v[242:243]
	v_pk_fma_f32 v[8:9], v[8:9], v[248:249], v[242:243]
	v_pk_fma_f32 v[10:11], v[10:11], v[248:249], v[242:243]
	v_pk_fma_f32 v[12:13], v[12:13], v[248:249], v[242:243]
	v_pk_fma_f32 v[14:15], v[14:15], v[248:249], v[242:243]
	v_pk_fma_f32 v[16:17], v[16:17], v[248:249], v[244:245]
	v_pk_fma_f32 v[18:19], v[18:19], v[248:249], v[244:245]
	v_pk_fma_f32 v[20:21], v[20:21], v[248:249], v[244:245]
	v_pk_fma_f32 v[22:23], v[22:23], v[248:249], v[244:245]
	v_pk_fma_f32 v[24:25], v[24:25], v[248:249], v[244:245]
	v_pk_fma_f32 v[26:27], v[26:27], v[248:249], v[244:245]
	v_pk_fma_f32 v[28:29], v[28:29], v[248:249], v[244:245]
	v_pk_fma_f32 v[30:31], v[30:31], v[248:249], v[244:245]
	v_exp_f32_e32 v0, v0
	v_exp_f32_e32 v1, v1
	v_exp_f32_e32 v2, v2
	v_exp_f32_e32 v3, v3
	v_exp_f32_e32 v4, v4
	v_exp_f32_e32 v5, v5
	v_exp_f32_e32 v6, v6
	v_exp_f32_e32 v7, v7
	v_exp_f32_e32 v8, v8
	v_exp_f32_e32 v9, v9
	v_exp_f32_e32 v10, v10
	v_exp_f32_e32 v11, v11
	v_exp_f32_e32 v12, v12
	v_exp_f32_e32 v13, v13
	v_exp_f32_e32 v14, v14
	v_exp_f32_e32 v15, v15
	v_exp_f32_e32 v16, v16
	v_exp_f32_e32 v17, v17
	v_exp_f32_e32 v18, v18
	v_exp_f32_e32 v19, v19
	v_exp_f32_e32 v20, v20
	v_exp_f32_e32 v21, v21
	v_exp_f32_e32 v22, v22
	v_exp_f32_e32 v23, v23
	v_exp_f32_e32 v24, v24
	v_exp_f32_e32 v25, v25
	v_exp_f32_e32 v26, v26
	v_exp_f32_e32 v27, v27
	v_exp_f32_e32 v28, v28
	v_exp_f32_e32 v29, v29
	v_exp_f32_e32 v30, v30
	v_exp_f32_e32 v31, v31
	v_pk_add_f32 v[0:1], v[0:1], 1.0 op_sel_hi:[1,0]
	v_pk_add_f32 v[2:3], v[2:3], 1.0 op_sel_hi:[1,0]
	v_pk_add_f32 v[4:5], v[4:5], 1.0 op_sel_hi:[1,0]
	v_pk_add_f32 v[6:7], v[6:7], 1.0 op_sel_hi:[1,0]
	v_pk_add_f32 v[8:9], v[8:9], 1.0 op_sel_hi:[1,0]
	v_pk_add_f32 v[10:11], v[10:11], 1.0 op_sel_hi:[1,0]
	v_pk_add_f32 v[12:13], v[12:13], 1.0 op_sel_hi:[1,0]
	v_pk_add_f32 v[14:15], v[14:15], 1.0 op_sel_hi:[1,0]
	v_pk_add_f32 v[16:17], v[16:17], 1.0 op_sel_hi:[1,0]
	v_pk_add_f32 v[18:19], v[18:19], 1.0 op_sel_hi:[1,0]
	v_pk_add_f32 v[20:21], v[20:21], 1.0 op_sel_hi:[1,0]
	v_pk_add_f32 v[22:23], v[22:23], 1.0 op_sel_hi:[1,0]
	v_pk_add_f32 v[24:25], v[24:25], 1.0 op_sel_hi:[1,0]
	v_pk_add_f32 v[26:27], v[26:27], 1.0 op_sel_hi:[1,0]
	v_pk_add_f32 v[28:29], v[28:29], 1.0 op_sel_hi:[1,0]
	v_pk_add_f32 v[30:31], v[30:31], 1.0 op_sel_hi:[1,0]
	v_rcp_f32_e32 v0, v0
	v_rcp_f32_e32 v1, v1
	v_rcp_f32_e32 v2, v2
	v_rcp_f32_e32 v3, v3
	v_rcp_f32_e32 v4, v4
	v_rcp_f32_e32 v5, v5
	v_rcp_f32_e32 v6, v6
	v_rcp_f32_e32 v7, v7
	v_rcp_f32_e32 v8, v8
	v_rcp_f32_e32 v9, v9
	v_rcp_f32_e32 v10, v10
	v_rcp_f32_e32 v11, v11
	v_rcp_f32_e32 v12, v12
	v_rcp_f32_e32 v13, v13
	v_rcp_f32_e32 v14, v14
	v_rcp_f32_e32 v15, v15
	v_rcp_f32_e32 v16, v16
	v_rcp_f32_e32 v17, v17
	v_rcp_f32_e32 v18, v18
	v_rcp_f32_e32 v19, v19
	v_rcp_f32_e32 v20, v20
	v_rcp_f32_e32 v21, v21
	v_rcp_f32_e32 v22, v22
	v_rcp_f32_e32 v23, v23
	v_rcp_f32_e32 v24, v24
	v_rcp_f32_e32 v25, v25
; template <bool FINAL, int D>
; __device__ __forceinline__ void rg_dir(PREF p, int l, int h, int ch, int sidx, int rowbase  , LAS bf16_t* sXc, LAS float* stg, int lane) {
;     ...
;     const float ba = p.rg_ba[(l * 2 + D) * 512 + ch], bi = p.rg_bi[(l * 2 + D) * 512 + ch], lam = p.rg_lam[(l * 2 + D) * 512 + ch];
;     const float e_ = __expf(-lam), u_ = 1.f + e_;
;     const float l1p = (u_ == 1.f) ? e_ : __logf(u_) * e_ * rcpf_(u_ - 1.f);
;     const float sp8 = -8.f * 1.4426950408889634f * l1p;
;     float hc = FINAL ? RGC[sidx] : 0.f, Ap = 1.f;
;     bf16x8 Br[4][2], Bi[4][2];
; #pragma unroll
;     for (int nt = 0; nt < 4; ++nt) { const int o0 = (nt * 16 + (lane & 15)) * 64 + (lane >> 4) * 8;
;         Br[nt][0] = *(const bf16x8*)(wr_ + o0); Br[nt][1] = *(const bf16x8*)(wr_ + o0 + 32); Bi[nt][0] = *(const bf16x8*)(wi_ + o0); Bi[nt][1] = *(const bf16x8*)(wi_ + o0 + 32); }
;     if (FINAL && D == 1) asm volatile("s_waitcnt vmcnt(0)" ::: "memory");
; #pragma unroll 1
;     for (int mi = 0; mi < 4; ++mi) { const int mt = D ? 3 - mi : mi;
;         float grv[16], hfv[16];
;         if (FINAL && D == 1) {
; #pragma unroll
;             for (int ti = 0; ti < 16; ++ti) { const size_t row = (size_t)(rowbase + mt * 16 + 15 - ti); grv[ti] = __builtin_bit_cast(float, (unsigned)P[row * PW + 512 + ch]); hfv[ti] = __builtin_bit_cast(float, (unsigned)TMP[row * 512 + ch]); }
;             __builtin_amdgcn_sched_barrier(0);
; #pragma unroll
;             for (int ti = 0; ti < 16; ++ti) { grv[ti] = bf2f(__builtin_bit_cast(unsigned, grv[ti])); hfv[ti] = bf2f(__builtin_bit_cast(unsigned, hfv[ti])); }
;         }
;         const bf16x8 A0 = *(const LAS bf16x8*)(sXc + (mt * 16 + (lane & 15)) * 72 + (lane >> 4) * 8), A1 = *(const LAS bf16x8*)(sXc + (mt * 16 + (lane & 15)) * 72 + 32 + (lane >> 4) * 8);
;         f32x4 ar[4], ai[4];
; #pragma unroll
;         for (int nt = 0; nt < 4; ++nt) { const f32x4 z = {0.f, 0.f, 0.f, 0.f};
;             ar[nt] = mfma16(A0, Br[nt][0], z); ar[nt] = mfma16(A1, Br[nt][1], ar[nt]); ai[nt] = mfma16(A0, Bi[nt][0], z); ai[nt] = mfma16(A1, Bi[nt][1], ai[nt]); }
;         WAVE_SYNC();
; #pragma unroll
;         for (int nt = 0; nt < 4; ++nt)
; #pragma unroll
;             for (int j = 0; j < 4; ++j) { const int o = ((lane >> 4) * 4 + j) * 64 + nt * 16 + (lane & 15); stg[o] = ar[nt][j]; stg[1024 + o] = ai[nt][j]; }
;         WAVE_SYNC();
	v_rcp_f32_e32 v26, v26
	v_rcp_f32_e32 v27, v27
	v_rcp_f32_e32 v28, v28
	v_rcp_f32_e32 v29, v29
	v_rcp_f32_e32 v30, v30
	v_rcp_f32_e32 v31, v31
	v_pk_mul_f32 v[0:1], v[246:247], v[0:1]
	v_pk_mul_f32 v[2:3], v[246:247], v[2:3]
	v_pk_mul_f32 v[4:5], v[246:247], v[4:5]
	v_pk_mul_f32 v[6:7], v[246:247], v[6:7]
	v_pk_mul_f32 v[8:9], v[246:247], v[8:9]
	v_pk_mul_f32 v[10:11], v[246:247], v[10:11]
	v_pk_mul_f32 v[12:13], v[246:247], v[12:13]
	v_pk_mul_f32 v[14:15], v[246:247], v[14:15]
	v_lshlrev_b32_e32 v48, 16, v48
	v_lshlrev_b32_e32 v49, 16, v49
	v_lshlrev_b32_e32 v50, 16, v50
	v_lshlrev_b32_e32 v51, 16, v51
	v_lshlrev_b32_e32 v52, 16, v52
	v_lshlrev_b32_e32 v53, 16, v53
	v_lshlrev_b32_e32 v54, 16, v54
	v_lshlrev_b32_e32 v55, 16, v55
	v_lshlrev_b32_e32 v56, 16, v56
	v_lshlrev_b32_e32 v57, 16, v57
	v_lshlrev_b32_e32 v58, 16, v58
	v_lshlrev_b32_e32 v59, 16, v59
	v_lshlrev_b32_e32 v60, 16, v60
	v_lshlrev_b32_e32 v61, 16, v61
	v_lshlrev_b32_e32 v62, 16, v62
	v_lshlrev_b32_e32 v63, 16, v63
	v_exp_f32_e32 v0, v0
	v_exp_f32_e32 v1, v1
	v_exp_f32_e32 v2, v2
	v_exp_f32_e32 v3, v3
	v_exp_f32_e32 v4, v4
	v_exp_f32_e32 v5, v5
	v_exp_f32_e32 v6, v6
	v_exp_f32_e32 v7, v7
	v_exp_f32_e32 v8, v8
	v_exp_f32_e32 v9, v9
	v_exp_f32_e32 v10, v10
	v_exp_f32_e32 v11, v11
	v_exp_f32_e32 v12, v12
	v_exp_f32_e32 v13, v13
	v_exp_f32_e32 v14, v14
	v_exp_f32_e32 v15, v15
	v_fma_f32 v32, -v0, v0, 1.0
	v_fma_f32 v33, -v1, v1, 1.0
	v_fma_f32 v34, -v2, v2, 1.0
	v_fma_f32 v35, -v3, v3, 1.0
	v_fma_f32 v36, -v4, v4, 1.0
	v_fma_f32 v37, -v5, v5, 1.0
	v_fma_f32 v38, -v6, v6, 1.0
	v_fma_f32 v39, -v7, v7, 1.0
	v_fma_f32 v40, -v8, v8, 1.0
	v_fma_f32 v41, -v9, v9, 1.0
	v_fma_f32 v42, -v10, v10, 1.0
	v_fma_f32 v43, -v11, v11, 1.0
	v_fma_f32 v44, -v12, v12, 1.0
	v_fma_f32 v45, -v13, v13, 1.0
	v_fma_f32 v46, -v14, v14, 1.0
	v_fma_f32 v47, -v15, v15, 1.0
	v_max_f32_e32 v32, 0, v32
	v_max_f32_e32 v33, 0, v33
	v_max_f32_e32 v34, 0, v34
	v_max_f32_e32 v35, 0, v35
	v_max_f32_e32 v36, 0, v36
	v_max_f32_e32 v37, 0, v37
	v_max_f32_e32 v38, 0, v38
	v_max_f32_e32 v39, 0, v39
	v_max_f32_e32 v40, 0, v40
	v_max_f32_e32 v41, 0, v41
	v_max_f32_e32 v42, 0, v42
	v_max_f32_e32 v43, 0, v43
	v_max_f32_e32 v44, 0, v44
	v_max_f32_e32 v45, 0, v45
	v_max_f32_e32 v46, 0, v46
	v_max_f32_e32 v47, 0, v47
	v_sqrt_f32_e32 v32, v32
	v_sqrt_f32_e32 v33, v33
	v_sqrt_f32_e32 v34, v34
	v_sqrt_f32_e32 v35, v35
	v_sqrt_f32_e32 v36, v36
	v_sqrt_f32_e32 v37, v37
	v_sqrt_f32_e32 v38, v38
	v_sqrt_f32_e32 v39, v39
	v_sqrt_f32_e32 v40, v40
	v_sqrt_f32_e32 v41, v41
	v_sqrt_f32_e32 v42, v42
	v_sqrt_f32_e32 v43, v43
	v_sqrt_f32_e32 v44, v44
	v_sqrt_f32_e32 v45, v45
	v_sqrt_f32_e32 v46, v46
	v_sqrt_f32_e32 v47, v47
	s_nop 0
	v_pk_mul_f32 v[16:17], v[16:17], v[32:33]
	v_pk_mul_f32 v[18:19], v[18:19], v[34:35]
	v_pk_mul_f32 v[20:21], v[20:21], v[36:37]
	v_pk_mul_f32 v[22:23], v[22:23], v[38:39]
	v_pk_mul_f32 v[24:25], v[24:25], v[40:41]
	v_pk_mul_f32 v[26:27], v[26:27], v[42:43]
	v_pk_mul_f32 v[28:29], v[28:29], v[44:45]
	v_pk_mul_f32 v[30:31], v[30:31], v[46:47]
	v_pk_mul_f32 v[16:17], v[16:17], v[48:49]
	v_pk_mul_f32 v[18:19], v[18:19], v[50:51]
	v_pk_mul_f32 v[20:21], v[20:21], v[52:53]
	v_pk_mul_f32 v[22:23], v[22:23], v[54:55]
	v_pk_mul_f32 v[24:25], v[24:25], v[56:57]
	v_pk_mul_f32 v[26:27], v[26:27], v[58:59]
	v_pk_mul_f32 v[28:29], v[28:29], v[60:61]
	v_pk_mul_f32 v[30:31], v[30:31], v[62:63]
	v_fma_f32 v32, v0, v250, v16
	v_mul_f32_e32 v232, v232, v0
	v_fma_f32 v250, v1, v32, v17
	v_mul_f32_e32 v232, v232, v1
	v_fma_f32 v32, v2, v250, v18
	v_mul_f32_e32 v232, v232, v2
	v_fma_f32 v250, v3, v32, v19
	v_mul_f32_e32 v232, v232, v3
	v_fma_f32 v32, v4, v250, v20
	v_mul_f32_e32 v232, v232, v4
	v_fma_f32 v250, v5, v32, v21
	v_mul_f32_e32 v232, v232, v5
	v_fma_f32 v32, v6, v250, v22
	v_mul_f32_e32 v232, v232, v6
	v_fma_f32 v250, v7, v32, v23
	v_mul_f32_e32 v232, v232, v7
	v_fma_f32 v32, v8, v250, v24
	v_mul_f32_e32 v232, v232, v8
	v_fma_f32 v250, v9, v32, v25
	v_mul_f32_e32 v232, v232, v9
	v_fma_f32 v32, v10, v250, v26
	v_mul_f32_e32 v232, v232, v10
	v_fma_f32 v250, v11, v32, v27
	v_mul_f32_e32 v232, v232, v11
	v_fma_f32 v32, v12, v250, v28
	v_mul_f32_e32 v232, v232, v12
	v_fma_f32 v250, v13, v32, v29
	v_mul_f32_e32 v232, v232, v13
	v_fma_f32 v32, v14, v250, v30
	v_mul_f32_e32 v232, v232, v14
	v_fma_f32 v250, v15, v32, v31
	v_mul_f32_e32 v232, v232, v15
	s_add_u32 s96, s0, 0x400000
	s_addc_u32 s97, s1, 0
	s_add_u32 s96, s96, s36
	s_addc_u32 s97, s97, 0
	global_store_dword v235, v232, s[96:97]
	s_add_u32 s96, s96, 0x300000
	s_addc_u32 s97, s97, 0
	global_store_dword v235, v250, s[96:97]
	global_load_dword v45, v235, s[76:77] offset:2048
	global_load_dword v46, v235, s[78:79] offset:2048
	global_load_dword v47, v235, s[80:81] offset:2048
	s_waitcnt vmcnt(0)
	s_mov_b32 s8, 0x800000
	s_mov_b32 s9, 0x3f317217
	s_mov_b32 s14, 0x7f800000
	v_mul_f32_e32 v32, 0xbfb8aa3b, v45
	v_exp_f32_e32 v32, v32
	s_nop 0
	v_add_f32_e32 v33, 1.0, v32
	v_cmp_gt_f32_e32 vcc, s8, v33
	s_nop 1
	v_cndmask_b32_e64 v34, 0, 32, vcc
	v_ldexp_f32 v34, v33, v34
	v_log_f32_e32 v34, v34
	v_cndmask_b32_e32 v36, 0, v226, vcc
	v_cmp_eq_f32_e32 vcc, 1.0, v33
	v_mul_f32_e32 v35, 0x3f317217, v34
	v_fma_f32 v35, v34, s9, -v35
	v_fmac_f32_e32 v35, 0x3377d1cf, v34
	v_fmac_f32_e32 v35, 0x3f317217, v34
	v_cmp_lt_f32_e64 s[10:11], |v34|, s14
	s_nop 1
	v_cndmask_b32_e64 v34, v34, v35, s[10:11]
	v_add_f32_e32 v35, -1.0, v33
	v_rcp_f32_e32 v35, v35
	v_sub_f32_e32 v34, v34, v36
	v_mul_f32_e32 v34, v32, v34
	v_mul_f32_e32 v34, v34, v35
	v_cndmask_b32_e32 v32, v34, v32, vcc
	v_mul_f32_e32 v246, 0xc138aa3b, v32
	v_mov_b32_e32 v247, v246
	v_mul_f32_e32 v242, 0xbfb8aa3b, v46
	v_mul_f32_e32 v244, 0xbfb8aa3b, v47
	v_mov_b32_e32 v243, v242
	v_mov_b32_e32 v245, v244
	v_mov_b32_e32 v250, 0
	v_mov_b32_e32 v232, 1.0
	ds_read_b128 v[32:35], v236 offset:6912
	ds_read_b128 v[36:39], v236 offset:6976
	s_waitcnt lgkmcnt(0)
; #define LAS __attribute__((address_space(3)))
; #define WAVE_SYNC() asm volatile("s_waitcnt lgkmcnt(0)" ::: "memory")
; __device__ __forceinline__ float sigmoid_f(float x) { return rcpf_(1.f + __expf(-x)); }
; __device__ __forceinline__ f32x4 mfma16(bf16x8 a, bf16x8 b, f32x4 c) { return __builtin_amdgcn_mfma_f32_16x16x32_bf16(a, b, c, 0, 0, 0); }
; template <bool FINAL, int D>
; __device__ __forceinline__ void rg_dir(PREF p, int l, int h, int ch, int sidx, int rowbase  , LAS bf16_t* sXc, LAS float* stg, int lane) {
;     ...
;         const bf16x8 A0 = *(const LAS bf16x8*)(sXc + (mt * 16 + (lane & 15)) * 72 + (lane >> 4) * 8), A1 = *(const LAS bf16x8*)(sXc + (mt * 16 + (lane & 15)) * 72 + 32 + (lane >> 4) * 8);
;         f32x4 ar[4], ai[4];
; #pragma unroll
;         for (int nt = 0; nt < 4; ++nt) { const f32x4 z = {0.f, 0.f, 0.f, 0.f};
;             ar[nt] = mfma16(A0, Br[nt][0], z); ar[nt] = mfma16(A1, Br[nt][1], ar[nt]); ai[nt] = mfma16(A0, Bi[nt][0], z); ai[nt] = mfma16(A1, Bi[nt][1], ai[nt]); }
;         WAVE_SYNC();
; #pragma unroll
;         for (int nt = 0; nt < 4; ++nt)
; #pragma unroll
;             for (int j = 0; j < 4; ++j) { const int o = ((lane >> 4) * 4 + j) * 64 + nt * 16 + (lane & 15); stg[o] = ar[nt][j]; stg[1024 + o] = ai[nt][j]; }
;         WAVE_SYNC();
;         float av[16], iv[16];
; #pragma unroll
;         for (int ti = 0; ti < 16; ++ti) { const int tk = D ? 15 - ti : ti;
;             const float zr = stg[tk * 64 + lane] + ba, zi = stg[1024 + tk * 64 + lane] + bi;
;             const float r = sigmoid_f(zr), ig = sigmoid_f(zi);
;             const float a = __builtin_amdgcn_exp2f(r * sp8);
;             const float xc = bf2f(sXc[(mt * 16 + tk) * 72 + lane]);
;             av[ti] = a; iv[ti] = __builtin_amdgcn_sqrtf(fmaxf(1.f - a * a, 0.f)) * ig * xc;
	v_mfma_f32_16x16x32_bf16 v[0:3], v[32:35], v[80:83], 0
	v_mfma_f32_16x16x32_bf16 v[4:7], v[32:35], v[88:91], 0
	v_mfma_f32_16x16x32_bf16 v[8:11], v[32:35], v[96:99], 0
	v_mfma_f32_16x16x32_bf16 v[12:15], v[32:35], v[104:107], 0
	v_mfma_f32_16x16x32_bf16 v[16:19], v[32:35], v[112:115], 0
	v_mfma_f32_16x16x32_bf16 v[20:23], v[32:35], v[120:123], 0
	v_mfma_f32_16x16x32_bf16 v[24:27], v[32:35], v[128:131], 0
	v_mfma_f32_16x16x32_bf16 v[28:31], v[32:35], v[136:139], 0
	v_mfma_f32_16x16x32_bf16 v[0:3], v[36:39], v[84:87], v[0:3]
	v_mfma_f32_16x16x32_bf16 v[4:7], v[36:39], v[92:95], v[4:7]
	v_mfma_f32_16x16x32_bf16 v[8:11], v[36:39], v[100:103], v[8:11]
	v_mfma_f32_16x16x32_bf16 v[12:15], v[36:39], v[108:111], v[12:15]
	v_mfma_f32_16x16x32_bf16 v[16:19], v[36:39], v[148:151], v[16:19]
	v_mfma_f32_16x16x32_bf16 v[20:23], v[36:39], v[124:127], v[20:23]
	v_mfma_f32_16x16x32_bf16 v[24:27], v[36:39], v[132:135], v[24:27]
	v_mfma_f32_16x16x32_bf16 v[28:31], v[36:39], v[228:231], v[28:31]
	s_nop 3
	ds_write2_b32 v237, v0, v4 offset0:0 offset1:16
	ds_write2_b32 v237, v8, v12 offset0:32 offset1:48
	ds_write2_b32 v237, v1, v5 offset0:64 offset1:80
	ds_write2_b32 v237, v9, v13 offset0:96 offset1:112
	ds_write2_b32 v237, v2, v6 offset0:128 offset1:144
	ds_write2_b32 v237, v10, v14 offset0:160 offset1:176
	ds_write2_b32 v237, v3, v7 offset0:192 offset1:208
	ds_write2_b32 v237, v11, v15 offset0:224 offset1:240
	ds_write2_b32 v238, v16, v20 offset0:0 offset1:16
	ds_write2_b32 v238, v24, v28 offset0:32 offset1:48
	ds_write2_b32 v238, v17, v21 offset0:64 offset1:80
	ds_write2_b32 v238, v25, v29 offset0:96 offset1:112
	ds_write2_b32 v238, v18, v22 offset0:128 offset1:144
	ds_write2_b32 v238, v26, v30 offset0:160 offset1:176
	ds_write2_b32 v238, v19, v23 offset0:192 offset1:208
	ds_write2_b32 v238, v27, v31 offset0:224 offset1:240
	s_waitcnt lgkmcnt(0)
	ds_read2st64_b32 v[0:1], v239 offset0:36 offset1:37
	ds_read2st64_b32 v[2:3], v239 offset0:38 offset1:39
	ds_read2st64_b32 v[4:5], v239 offset0:40 offset1:41
	ds_read2st64_b32 v[6:7], v239 offset0:42 offset1:43
	ds_read2st64_b32 v[8:9], v239 offset0:44 offset1:45
	ds_read2st64_b32 v[10:11], v239 offset0:46 offset1:47
	ds_read2st64_b32 v[12:13], v239 offset0:48 offset1:49
	ds_read2st64_b32 v[14:15], v239 offset0:50 offset1:51
	ds_read2st64_b32 v[16:17], v239 offset0:52 offset1:53
	ds_read2st64_b32 v[18:19], v239 offset0:54 offset1:55
	ds_read2st64_b32 v[20:21], v239 offset0:56 offset1:57
	ds_read2st64_b32 v[22:23], v239 offset0:58 offset1:59
	ds_read2st64_b32 v[24:25], v239 offset0:60 offset1:61
	ds_read2st64_b32 v[26:27], v239 offset0:62 offset1:63
	ds_read2st64_b32 v[28:29], v239 offset0:64 offset1:65
	ds_read2st64_b32 v[30:31], v239 offset0:66 offset1:67
	ds_read_u16 v48, v240 offset:6912
	ds_read_u16 v49, v240 offset:7056
	ds_read_u16 v50, v240 offset:7200
	ds_read_u16 v51, v240 offset:7344
	ds_read_u16 v52, v240 offset:7488
	ds_read_u16 v53, v240 offset:7632
	ds_read_u16 v54, v240 offset:7776
	ds_read_u16 v55, v240 offset:7920
	ds_read_u16 v56, v240 offset:8064
	ds_read_u16 v57, v240 offset:8208
	ds_read_u16 v58, v240 offset:8352
	ds_read_u16 v59, v240 offset:8496
	ds_read_u16 v60, v240 offset:8640
	ds_read_u16 v61, v240 offset:8784
	ds_read_u16 v62, v240 offset:8928
	ds_read_u16 v63, v240 offset:9072
	s_waitcnt lgkmcnt(0)
	v_pk_fma_f32 v[0:1], v[0:1], v[248:249], v[242:243]
	v_pk_fma_f32 v[2:3], v[2:3], v[248:249], v[242:243]
	v_pk_fma_f32 v[4:5], v[4:5], v[248:249], v[242:243]
	v_pk_fma_f32 v[6:7], v[6:7], v[248:249], v[242:243]
	v_pk_fma_f32 v[8:9], v[8:9], v[248:249], v[242:243]
	v_pk_fma_f32 v[10:11], v[10:11], v[248:249], v[242:243]
	v_pk_fma_f32 v[12:13], v[12:13], v[248:249], v[242:243]
	v_pk_fma_f32 v[14:15], v[14:15], v[248:249], v[242:243]
	v_pk_fma_f32 v[16:17], v[16:17], v[248:249], v[244:245]
	v_pk_fma_f32 v[18:19], v[18:19], v[248:249], v[244:245]
	v_pk_fma_f32 v[20:21], v[20:21], v[248:249], v[244:245]
	v_pk_fma_f32 v[22:23], v[22:23], v[248:249], v[244:245]
	v_pk_fma_f32 v[24:25], v[24:25], v[248:249], v[244:245]
	v_pk_fma_f32 v[26:27], v[26:27], v[248:249], v[244:245]
	v_pk_fma_f32 v[28:29], v[28:29], v[248:249], v[244:245]
	v_pk_fma_f32 v[30:31], v[30:31], v[248:249], v[244:245]
	v_exp_f32_e32 v0, v0
	v_exp_f32_e32 v1, v1
	v_exp_f32_e32 v2, v2
	v_exp_f32_e32 v3, v3
	v_exp_f32_e32 v4, v4
	v_exp_f32_e32 v5, v5
	v_exp_f32_e32 v6, v6
	v_exp_f32_e32 v7, v7
	v_exp_f32_e32 v8, v8
	v_exp_f32_e32 v9, v9
	v_exp_f32_e32 v10, v10
	v_exp_f32_e32 v11, v11
	v_exp_f32_e32 v12, v12
	v_exp_f32_e32 v13, v13
	v_exp_f32_e32 v14, v14
	v_exp_f32_e32 v15, v15
	v_exp_f32_e32 v16, v16
	v_exp_f32_e32 v17, v17
	v_exp_f32_e32 v18, v18
	v_exp_f32_e32 v19, v19
	v_exp_f32_e32 v20, v20
	v_exp_f32_e32 v21, v21
	v_exp_f32_e32 v22, v22
	v_exp_f32_e32 v23, v23
	v_exp_f32_e32 v24, v24
	v_exp_f32_e32 v25, v25
	v_exp_f32_e32 v26, v26
	v_exp_f32_e32 v27, v27
	v_exp_f32_e32 v28, v28
	v_exp_f32_e32 v29, v29
	v_exp_f32_e32 v30, v30
	v_exp_f32_e32 v31, v31
	v_pk_add_f32 v[0:1], v[0:1], 1.0 op_sel_hi:[1,0]
	v_pk_add_f32 v[2:3], v[2:3], 1.0 op_sel_hi:[1,0]
	v_pk_add_f32 v[4:5], v[4:5], 1.0 op_sel_hi:[1,0]
	v_pk_add_f32 v[6:7], v[6:7], 1.0 op_sel_hi:[1,0]
	v_pk_add_f32 v[8:9], v[8:9], 1.0 op_sel_hi:[1,0]
	v_pk_add_f32 v[10:11], v[10:11], 1.0 op_sel_hi:[1,0]
	v_pk_add_f32 v[12:13], v[12:13], 1.0 op_sel_hi:[1,0]
	v_pk_add_f32 v[14:15], v[14:15], 1.0 op_sel_hi:[1,0]
	v_pk_add_f32 v[16:17], v[16:17], 1.0 op_sel_hi:[1,0]
	v_pk_add_f32 v[18:19], v[18:19], 1.0 op_sel_hi:[1,0]
	v_pk_add_f32 v[20:21], v[20:21], 1.0 op_sel_hi:[1,0]
	v_pk_add_f32 v[22:23], v[22:23], 1.0 op_sel_hi:[1,0]
	v_pk_add_f32 v[24:25], v[24:25], 1.0 op_sel_hi:[1,0]
; __device__ __forceinline__ unsigned f2bf(float f) { unsigned r; asm("v_cvt_pk_bf16_f32 %0, %1, %1" : "=v"(r) : "v"(f)); return r & 0xffffu; }
; __device__ __forceinline__ float sigmoid_f(float x) { return rcpf_(1.f + __expf(-x)); }
; __device__ __forceinline__ float gelu_tanh_f(float x) { const float y = 0.7978845608028654f * (x + 0.044715f * x * x * x); return x * sigmoid_f(2.f * y); }
; template <bool FINAL, int D>
; __device__ __forceinline__ void rg_dir(PREF p, int l, int h, int ch, int sidx, int rowbase  , LAS bf16_t* sXc, LAS float* stg, int lane) {
;     ...
;         float av[16], iv[16];
; #pragma unroll
;         for (int ti = 0; ti < 16; ++ti) { const int tk = D ? 15 - ti : ti;
;             const float zr = stg[tk * 64 + lane] + ba, zi = stg[1024 + tk * 64 + lane] + bi;
;             const float r = sigmoid_f(zr), ig = sigmoid_f(zi);
;             const float a = __builtin_amdgcn_exp2f(r * sp8);
;             const float xc = bf2f(sXc[(mt * 16 + tk) * 72 + lane]);
;             av[ti] = a; iv[ti] = __builtin_amdgcn_sqrtf(fmaxf(1.f - a * a, 0.f)) * ig * xc;
;             if (FINAL && D == 1) grv[ti] = gelu_tanh_f(grv[ti]);
;         }
; #pragma unroll
;         for (int ti = 0; ti < 16; ++ti) { const int tk = D ? 15 - ti : ti;
;             hc = av[ti] * hc + iv[ti]; Ap *= av[ti];
;             if (FINAL) { const size_t row = (size_t)(rowbase + mt * 16 + tk);
;                 if (D == 0) TMP[row * 512 + ch] = (bf16_t)f2bf(hc);
;                 else MIX[row * DM + ch] = (bf16_t)f2bf(grv[ti] * (hfv[ti] + hc)); }
;         }
	v_pk_add_f32 v[26:27], v[26:27], 1.0 op_sel_hi:[1,0]
	v_pk_add_f32 v[28:29], v[28:29], 1.0 op_sel_hi:[1,0]
	v_pk_add_f32 v[30:31], v[30:31], 1.0 op_sel_hi:[1,0]
	v_rcp_f32_e32 v0, v0
	v_rcp_f32_e32 v1, v1
	v_rcp_f32_e32 v2, v2
	v_rcp_f32_e32 v3, v3
	v_rcp_f32_e32 v4, v4
	v_rcp_f32_e32 v5, v5
	v_rcp_f32_e32 v6, v6
	v_rcp_f32_e32 v7, v7
	v_rcp_f32_e32 v8, v8
	v_rcp_f32_e32 v9, v9
	v_rcp_f32_e32 v10, v10
	v_rcp_f32_e32 v11, v11
	v_rcp_f32_e32 v12, v12
	v_rcp_f32_e32 v13, v13
	v_rcp_f32_e32 v14, v14
	v_rcp_f32_e32 v15, v15
	v_rcp_f32_e32 v16, v16
	v_rcp_f32_e32 v17, v17
	v_rcp_f32_e32 v18, v18
	v_rcp_f32_e32 v19, v19
	v_rcp_f32_e32 v20, v20
	v_rcp_f32_e32 v21, v21
	v_rcp_f32_e32 v22, v22
	v_rcp_f32_e32 v23, v23
	v_rcp_f32_e32 v24, v24
	v_rcp_f32_e32 v25, v25
	v_rcp_f32_e32 v26, v26
	v_rcp_f32_e32 v27, v27
	v_rcp_f32_e32 v28, v28
	v_rcp_f32_e32 v29, v29
	v_rcp_f32_e32 v30, v30
	v_rcp_f32_e32 v31, v31
	v_pk_mul_f32 v[0:1], v[246:247], v[0:1]
	v_pk_mul_f32 v[2:3], v[246:247], v[2:3]
	v_pk_mul_f32 v[4:5], v[246:247], v[4:5]
	v_pk_mul_f32 v[6:7], v[246:247], v[6:7]
	v_pk_mul_f32 v[8:9], v[246:247], v[8:9]
	v_pk_mul_f32 v[10:11], v[246:247], v[10:11]
	v_pk_mul_f32 v[12:13], v[246:247], v[12:13]
	v_pk_mul_f32 v[14:15], v[246:247], v[14:15]
	v_lshlrev_b32_e32 v48, 16, v48
	v_lshlrev_b32_e32 v49, 16, v49
	v_lshlrev_b32_e32 v50, 16, v50
	v_lshlrev_b32_e32 v51, 16, v51
	v_lshlrev_b32_e32 v52, 16, v52
	v_lshlrev_b32_e32 v53, 16, v53
	v_lshlrev_b32_e32 v54, 16, v54
	v_lshlrev_b32_e32 v55, 16, v55
	v_lshlrev_b32_e32 v56, 16, v56
	v_lshlrev_b32_e32 v57, 16, v57
	v_lshlrev_b32_e32 v58, 16, v58
	v_lshlrev_b32_e32 v59, 16, v59
	v_lshlrev_b32_e32 v60, 16, v60
	v_lshlrev_b32_e32 v61, 16, v61
	v_lshlrev_b32_e32 v62, 16, v62
	v_lshlrev_b32_e32 v63, 16, v63
	v_exp_f32_e32 v0, v0
	v_exp_f32_e32 v1, v1
	v_exp_f32_e32 v2, v2
	v_exp_f32_e32 v3, v3
	v_exp_f32_e32 v4, v4
	v_exp_f32_e32 v5, v5
	v_exp_f32_e32 v6, v6
	v_exp_f32_e32 v7, v7
	v_exp_f32_e32 v8, v8
	v_exp_f32_e32 v9, v9
	v_exp_f32_e32 v10, v10
	v_exp_f32_e32 v11, v11
	v_exp_f32_e32 v12, v12
	v_exp_f32_e32 v13, v13
	v_exp_f32_e32 v14, v14
	v_exp_f32_e32 v15, v15
	v_fma_f32 v32, -v0, v0, 1.0
	v_fma_f32 v33, -v1, v1, 1.0
	v_fma_f32 v34, -v2, v2, 1.0
	v_fma_f32 v35, -v3, v3, 1.0
	v_fma_f32 v36, -v4, v4, 1.0
	v_fma_f32 v37, -v5, v5, 1.0
	v_fma_f32 v38, -v6, v6, 1.0
	v_fma_f32 v39, -v7, v7, 1.0
	v_fma_f32 v40, -v8, v8, 1.0
	v_fma_f32 v41, -v9, v9, 1.0
	v_fma_f32 v42, -v10, v10, 1.0
	v_fma_f32 v43, -v11, v11, 1.0
	v_fma_f32 v44, -v12, v12, 1.0
	v_fma_f32 v45, -v13, v13, 1.0
	v_fma_f32 v46, -v14, v14, 1.0
	v_fma_f32 v47, -v15, v15, 1.0
	v_max_f32_e32 v32, 0, v32
	v_max_f32_e32 v33, 0, v33
	v_max_f32_e32 v34, 0, v34
	v_max_f32_e32 v35, 0, v35
	v_max_f32_e32 v36, 0, v36
	v_max_f32_e32 v37, 0, v37
	v_max_f32_e32 v38, 0, v38
	v_max_f32_e32 v39, 0, v39
	v_max_f32_e32 v40, 0, v40
	v_max_f32_e32 v41, 0, v41
	v_max_f32_e32 v42, 0, v42
	v_max_f32_e32 v43, 0, v43
	v_max_f32_e32 v44, 0, v44
	v_max_f32_e32 v45, 0, v45
	v_max_f32_e32 v46, 0, v46
	v_max_f32_e32 v47, 0, v47
	v_sqrt_f32_e32 v32, v32
	v_sqrt_f32_e32 v33, v33
	v_sqrt_f32_e32 v34, v34
	v_sqrt_f32_e32 v35, v35
	v_sqrt_f32_e32 v36, v36
	v_sqrt_f32_e32 v37, v37
	v_sqrt_f32_e32 v38, v38
	v_sqrt_f32_e32 v39, v39
	v_sqrt_f32_e32 v40, v40
	v_sqrt_f32_e32 v41, v41
	v_sqrt_f32_e32 v42, v42
	v_sqrt_f32_e32 v43, v43
	v_sqrt_f32_e32 v44, v44
	v_sqrt_f32_e32 v45, v45
	v_sqrt_f32_e32 v46, v46
	v_sqrt_f32_e32 v47, v47
	s_nop 0
	v_pk_mul_f32 v[16:17], v[16:17], v[32:33]
	v_pk_mul_f32 v[18:19], v[18:19], v[34:35]
	v_pk_mul_f32 v[20:21], v[20:21], v[36:37]
	v_pk_mul_f32 v[22:23], v[22:23], v[38:39]
	v_pk_mul_f32 v[24:25], v[24:25], v[40:41]
	v_pk_mul_f32 v[26:27], v[26:27], v[42:43]
	v_pk_mul_f32 v[28:29], v[28:29], v[44:45]
	v_pk_mul_f32 v[30:31], v[30:31], v[46:47]
	v_pk_mul_f32 v[16:17], v[16:17], v[48:49]
	v_pk_mul_f32 v[18:19], v[18:19], v[50:51]
	v_pk_mul_f32 v[20:21], v[20:21], v[52:53]
	v_pk_mul_f32 v[22:23], v[22:23], v[54:55]
	v_pk_mul_f32 v[24:25], v[24:25], v[56:57]
	v_pk_mul_f32 v[26:27], v[26:27], v[58:59]
	v_pk_mul_f32 v[28:29], v[28:29], v[60:61]
	v_pk_mul_f32 v[30:31], v[30:31], v[62:63]
	v_fma_f32 v250, v15, v250, v31
	v_mul_f32_e32 v232, v232, v15
	v_fma_f32 v250, v14, v250, v30
	v_mul_f32_e32 v232, v232, v14
	v_fma_f32 v250, v13, v250, v29
	v_mul_f32_e32 v232, v232, v13
	v_fma_f32 v250, v12, v250, v28
	v_mul_f32_e32 v232, v232, v12
	v_fma_f32 v250, v11, v250, v27
	v_mul_f32_e32 v232, v232, v11
	v_fma_f32 v250, v10, v250, v26
	v_mul_f32_e32 v232, v232, v10
	v_fma_f32 v250, v9, v250, v25
	v_mul_f32_e32 v232, v232, v9
	v_fma_f32 v250, v8, v250, v24
	v_mul_f32_e32 v232, v232, v8
	v_fma_f32 v250, v7, v250, v23
	v_mul_f32_e32 v232, v232, v7
	v_fma_f32 v250, v6, v250, v22
	v_mul_f32_e32 v232, v232, v6
	v_fma_f32 v250, v5, v250, v21
	v_mul_f32_e32 v232, v232, v5
	v_fma_f32 v250, v4, v250, v20
	v_mul_f32_e32 v232, v232, v4
	v_fma_f32 v250, v3, v250, v19
	v_mul_f32_e32 v232, v232, v3
	v_fma_f32 v250, v2, v250, v18
	v_mul_f32_e32 v232, v232, v2
	v_fma_f32 v250, v1, v250, v17
	v_mul_f32_e32 v232, v232, v1
	v_fma_f32 v250, v0, v250, v16
	v_mul_f32_e32 v232, v232, v0
	ds_read_b128 v[32:35], v236 offset:4608
	ds_read_b128 v[36:39], v236 offset:4672
	s_waitcnt lgkmcnt(0)
; #define LAS __attribute__((address_space(3)))
; #define WAVE_SYNC() asm volatile("s_waitcnt lgkmcnt(0)" ::: "memory")
; __device__ __forceinline__ float sigmoid_f(float x) { return rcpf_(1.f + __expf(-x)); }
; __device__ __forceinline__ f32x4 mfma16(bf16x8 a, bf16x8 b, f32x4 c) { return __builtin_amdgcn_mfma_f32_16x16x32_bf16(a, b, c, 0, 0, 0); }
; template <bool FINAL, int D>
; __device__ __forceinline__ void rg_dir(PREF p, int l, int h, int ch, int sidx, int rowbase  , LAS bf16_t* sXc, LAS float* stg, int lane) {
;     ...
;         const bf16x8 A0 = *(const LAS bf16x8*)(sXc + (mt * 16 + (lane & 15)) * 72 + (lane >> 4) * 8), A1 = *(const LAS bf16x8*)(sXc + (mt * 16 + (lane & 15)) * 72 + 32 + (lane >> 4) * 8);
;         f32x4 ar[4], ai[4];
; #pragma unroll
;         for (int nt = 0; nt < 4; ++nt) { const f32x4 z = {0.f, 0.f, 0.f, 0.f};
;             ar[nt] = mfma16(A0, Br[nt][0], z); ar[nt] = mfma16(A1, Br[nt][1], ar[nt]); ai[nt] = mfma16(A0, Bi[nt][0], z); ai[nt] = mfma16(A1, Bi[nt][1], ai[nt]); }
;         WAVE_SYNC();
; #pragma unroll
;         for (int nt = 0; nt < 4; ++nt)
; #pragma unroll
;             for (int j = 0; j < 4; ++j) { const int o = ((lane >> 4) * 4 + j) * 64 + nt * 16 + (lane & 15); stg[o] = ar[nt][j]; stg[1024 + o] = ai[nt][j]; }
;         WAVE_SYNC();
;         float av[16], iv[16];
; #pragma unroll
;         for (int ti = 0; ti < 16; ++ti) { const int tk = D ? 15 - ti : ti;
;             const float zr = stg[tk * 64 + lane] + ba, zi = stg[1024 + tk * 64 + lane] + bi;
;             const float r = sigmoid_f(zr), ig = sigmoid_f(zi);
;             const float a = __builtin_amdgcn_exp2f(r * sp8);
;             const float xc = bf2f(sXc[(mt * 16 + tk) * 72 + lane]);
;             av[ti] = a; iv[ti] = __builtin_amdgcn_sqrtf(fmaxf(1.f - a * a, 0.f)) * ig * xc;
	v_mfma_f32_16x16x32_bf16 v[0:3], v[32:35], v[80:83], 0
	v_mfma_f32_16x16x32_bf16 v[4:7], v[32:35], v[88:91], 0
	v_mfma_f32_16x16x32_bf16 v[8:11], v[32:35], v[96:99], 0
	v_mfma_f32_16x16x32_bf16 v[12:15], v[32:35], v[104:107], 0
	v_mfma_f32_16x16x32_bf16 v[16:19], v[32:35], v[112:115], 0
	v_mfma_f32_16x16x32_bf16 v[20:23], v[32:35], v[120:123], 0
	v_mfma_f32_16x16x32_bf16 v[24:27], v[32:35], v[128:131], 0
	v_mfma_f32_16x16x32_bf16 v[28:31], v[32:35], v[136:139], 0
	v_mfma_f32_16x16x32_bf16 v[0:3], v[36:39], v[84:87], v[0:3]
	v_mfma_f32_16x16x32_bf16 v[4:7], v[36:39], v[92:95], v[4:7]
	v_mfma_f32_16x16x32_bf16 v[8:11], v[36:39], v[100:103], v[8:11]
	v_mfma_f32_16x16x32_bf16 v[12:15], v[36:39], v[108:111], v[12:15]
	v_mfma_f32_16x16x32_bf16 v[16:19], v[36:39], v[148:151], v[16:19]
	v_mfma_f32_16x16x32_bf16 v[20:23], v[36:39], v[124:127], v[20:23]
	v_mfma_f32_16x16x32_bf16 v[24:27], v[36:39], v[132:135], v[24:27]
	v_mfma_f32_16x16x32_bf16 v[28:31], v[36:39], v[228:231], v[28:31]
	s_nop 3
	ds_write2_b32 v237, v0, v4 offset0:0 offset1:16
	ds_write2_b32 v237, v8, v12 offset0:32 offset1:48
	ds_write2_b32 v237, v1, v5 offset0:64 offset1:80
	ds_write2_b32 v237, v9, v13 offset0:96 offset1:112
	ds_write2_b32 v237, v2, v6 offset0:128 offset1:144
	ds_write2_b32 v237, v10, v14 offset0:160 offset1:176
	ds_write2_b32 v237, v3, v7 offset0:192 offset1:208
	ds_write2_b32 v237, v11, v15 offset0:224 offset1:240
	ds_write2_b32 v238, v16, v20 offset0:0 offset1:16
	ds_write2_b32 v238, v24, v28 offset0:32 offset1:48
	ds_write2_b32 v238, v17, v21 offset0:64 offset1:80
	ds_write2_b32 v238, v25, v29 offset0:96 offset1:112
	ds_write2_b32 v238, v18, v22 offset0:128 offset1:144
	ds_write2_b32 v238, v26, v30 offset0:160 offset1:176
	ds_write2_b32 v238, v19, v23 offset0:192 offset1:208
	ds_write2_b32 v238, v27, v31 offset0:224 offset1:240
	s_waitcnt lgkmcnt(0)
	ds_read2st64_b32 v[0:1], v239 offset0:36 offset1:37
	ds_read2st64_b32 v[2:3], v239 offset0:38 offset1:39
	ds_read2st64_b32 v[4:5], v239 offset0:40 offset1:41
	ds_read2st64_b32 v[6:7], v239 offset0:42 offset1:43
	ds_read2st64_b32 v[8:9], v239 offset0:44 offset1:45
	ds_read2st64_b32 v[10:11], v239 offset0:46 offset1:47
	ds_read2st64_b32 v[12:13], v239 offset0:48 offset1:49
	ds_read2st64_b32 v[14:15], v239 offset0:50 offset1:51
	ds_read2st64_b32 v[16:17], v239 offset0:52 offset1:53
	ds_read2st64_b32 v[18:19], v239 offset0:54 offset1:55
	ds_read2st64_b32 v[20:21], v239 offset0:56 offset1:57
	ds_read2st64_b32 v[22:23], v239 offset0:58 offset1:59
	ds_read2st64_b32 v[24:25], v239 offset0:60 offset1:61
	ds_read2st64_b32 v[26:27], v239 offset0:62 offset1:63
	ds_read2st64_b32 v[28:29], v239 offset0:64 offset1:65
	ds_read2st64_b32 v[30:31], v239 offset0:66 offset1:67
	ds_read_u16 v48, v240 offset:4608
	ds_read_u16 v49, v240 offset:4752
	ds_read_u16 v50, v240 offset:4896
	ds_read_u16 v51, v240 offset:5040
	ds_read_u16 v52, v240 offset:5184
	ds_read_u16 v53, v240 offset:5328
	ds_read_u16 v54, v240 offset:5472
	ds_read_u16 v55, v240 offset:5616
	ds_read_u16 v56, v240 offset:5760
	ds_read_u16 v57, v240 offset:5904
	ds_read_u16 v58, v240 offset:6048
	ds_read_u16 v59, v240 offset:6192
	ds_read_u16 v60, v240 offset:6336
	ds_read_u16 v61, v240 offset:6480
	ds_read_u16 v62, v240 offset:6624
	ds_read_u16 v63, v240 offset:6768
	s_waitcnt lgkmcnt(0)
	v_pk_fma_f32 v[0:1], v[0:1], v[248:249], v[242:243]
	v_pk_fma_f32 v[2:3], v[2:3], v[248:249], v[242:243]
	v_pk_fma_f32 v[4:5], v[4:5], v[248:249], v[242:243]
	v_pk_fma_f32 v[6:7], v[6:7], v[248:249], v[242:243]
	v_pk_fma_f32 v[8:9], v[8:9], v[248:249], v[242:243]
	v_pk_fma_f32 v[10:11], v[10:11], v[248:249], v[242:243]
	v_pk_fma_f32 v[12:13], v[12:13], v[248:249], v[242:243]
	v_pk_fma_f32 v[14:15], v[14:15], v[248:249], v[242:243]
	v_pk_fma_f32 v[16:17], v[16:17], v[248:249], v[244:245]
	v_pk_fma_f32 v[18:19], v[18:19], v[248:249], v[244:245]
	v_pk_fma_f32 v[20:21], v[20:21], v[248:249], v[244:245]
	v_pk_fma_f32 v[22:23], v[22:23], v[248:249], v[244:245]
	v_pk_fma_f32 v[24:25], v[24:25], v[248:249], v[244:245]
	v_pk_fma_f32 v[26:27], v[26:27], v[248:249], v[244:245]
	v_pk_fma_f32 v[28:29], v[28:29], v[248:249], v[244:245]
	v_pk_fma_f32 v[30:31], v[30:31], v[248:249], v[244:245]
	v_exp_f32_e32 v0, v0
	v_exp_f32_e32 v1, v1
	v_exp_f32_e32 v2, v2
	v_exp_f32_e32 v3, v3
	v_exp_f32_e32 v4, v4
	v_exp_f32_e32 v5, v5
	v_exp_f32_e32 v6, v6
	v_exp_f32_e32 v7, v7
	v_exp_f32_e32 v8, v8
	v_exp_f32_e32 v9, v9
	v_exp_f32_e32 v10, v10
	v_exp_f32_e32 v11, v11
	v_exp_f32_e32 v12, v12
	v_exp_f32_e32 v13, v13
	v_exp_f32_e32 v14, v14
	v_exp_f32_e32 v15, v15
	v_exp_f32_e32 v16, v16
	v_exp_f32_e32 v17, v17
	v_exp_f32_e32 v18, v18
	v_exp_f32_e32 v19, v19
	v_exp_f32_e32 v20, v20
	v_exp_f32_e32 v21, v21
	v_exp_f32_e32 v22, v22
	v_exp_f32_e32 v23, v23
	v_exp_f32_e32 v24, v24
	v_exp_f32_e32 v25, v25
	v_exp_f32_e32 v26, v26
	v_exp_f32_e32 v27, v27
	v_exp_f32_e32 v28, v28
	v_exp_f32_e32 v29, v29
	v_exp_f32_e32 v30, v30
	v_exp_f32_e32 v31, v31
	v_pk_add_f32 v[0:1], v[0:1], 1.0 op_sel_hi:[1,0]
	v_pk_add_f32 v[2:3], v[2:3], 1.0 op_sel_hi:[1,0]
	v_pk_add_f32 v[4:5], v[4:5], 1.0 op_sel_hi:[1,0]
	v_pk_add_f32 v[6:7], v[6:7], 1.0 op_sel_hi:[1,0]
	v_pk_add_f32 v[8:9], v[8:9], 1.0 op_sel_hi:[1,0]
	v_pk_add_f32 v[10:11], v[10:11], 1.0 op_sel_hi:[1,0]
	v_pk_add_f32 v[12:13], v[12:13], 1.0 op_sel_hi:[1,0]
	v_pk_add_f32 v[14:15], v[14:15], 1.0 op_sel_hi:[1,0]
	v_pk_add_f32 v[16:17], v[16:17], 1.0 op_sel_hi:[1,0]
	v_pk_add_f32 v[18:19], v[18:19], 1.0 op_sel_hi:[1,0]
	v_pk_add_f32 v[20:21], v[20:21], 1.0 op_sel_hi:[1,0]
	v_pk_add_f32 v[22:23], v[22:23], 1.0 op_sel_hi:[1,0]
	v_pk_add_f32 v[24:25], v[24:25], 1.0 op_sel_hi:[1,0]
; __device__ __forceinline__ unsigned f2bf(float f) { unsigned r; asm("v_cvt_pk_bf16_f32 %0, %1, %1" : "=v"(r) : "v"(f)); return r & 0xffffu; }
; __device__ __forceinline__ float sigmoid_f(float x) { return rcpf_(1.f + __expf(-x)); }
; __device__ __forceinline__ float gelu_tanh_f(float x) { const float y = 0.7978845608028654f * (x + 0.044715f * x * x * x); return x * sigmoid_f(2.f * y); }
; template <bool FINAL, int D>
; __device__ __forceinline__ void rg_dir(PREF p, int l, int h, int ch, int sidx, int rowbase  , LAS bf16_t* sXc, LAS float* stg, int lane) {
;     ...
;         float av[16], iv[16];
; #pragma unroll
;         for (int ti = 0; ti < 16; ++ti) { const int tk = D ? 15 - ti : ti;
;             const float zr = stg[tk * 64 + lane] + ba, zi = stg[1024 + tk * 64 + lane] + bi;
;             const float r = sigmoid_f(zr), ig = sigmoid_f(zi);
;             const float a = __builtin_amdgcn_exp2f(r * sp8);
;             const float xc = bf2f(sXc[(mt * 16 + tk) * 72 + lane]);
;             av[ti] = a; iv[ti] = __builtin_amdgcn_sqrtf(fmaxf(1.f - a * a, 0.f)) * ig * xc;
;             if (FINAL && D == 1) grv[ti] = gelu_tanh_f(grv[ti]);
;         }
; #pragma unroll
;         for (int ti = 0; ti < 16; ++ti) { const int tk = D ? 15 - ti : ti;
;             hc = av[ti] * hc + iv[ti]; Ap *= av[ti];
;             if (FINAL) { const size_t row = (size_t)(rowbase + mt * 16 + tk);
;                 if (D == 0) TMP[row * 512 + ch] = (bf16_t)f2bf(hc);
;                 else MIX[row * DM + ch] = (bf16_t)f2bf(grv[ti] * (hfv[ti] + hc)); }
;         }
	v_pk_add_f32 v[26:27], v[26:27], 1.0 op_sel_hi:[1,0]
	v_pk_add_f32 v[28:29], v[28:29], 1.0 op_sel_hi:[1,0]
	v_pk_add_f32 v[30:31], v[30:31], 1.0 op_sel_hi:[1,0]
	v_rcp_f32_e32 v0, v0
	v_rcp_f32_e32 v1, v1
	v_rcp_f32_e32 v2, v2
	v_rcp_f32_e32 v3, v3
	v_rcp_f32_e32 v4, v4
	v_rcp_f32_e32 v5, v5
	v_rcp_f32_e32 v6, v6
	v_rcp_f32_e32 v7, v7
	v_rcp_f32_e32 v8, v8
	v_rcp_f32_e32 v9, v9
	v_rcp_f32_e32 v10, v10
	v_rcp_f32_e32 v11, v11
	v_rcp_f32_e32 v12, v12
	v_rcp_f32_e32 v13, v13
	v_rcp_f32_e32 v14, v14
	v_rcp_f32_e32 v15, v15
	v_rcp_f32_e32 v16, v16
	v_rcp_f32_e32 v17, v17
	v_rcp_f32_e32 v18, v18
	v_rcp_f32_e32 v19, v19
	v_rcp_f32_e32 v20, v20
	v_rcp_f32_e32 v21, v21
	v_rcp_f32_e32 v22, v22
	v_rcp_f32_e32 v23, v23
	v_rcp_f32_e32 v24, v24
	v_rcp_f32_e32 v25, v25
	v_rcp_f32_e32 v26, v26
	v_rcp_f32_e32 v27, v27
	v_rcp_f32_e32 v28, v28
	v_rcp_f32_e32 v29, v29
	v_rcp_f32_e32 v30, v30
	v_rcp_f32_e32 v31, v31
	v_pk_mul_f32 v[0:1], v[246:247], v[0:1]
	v_pk_mul_f32 v[2:3], v[246:247], v[2:3]
	v_pk_mul_f32 v[4:5], v[246:247], v[4:5]
	v_pk_mul_f32 v[6:7], v[246:247], v[6:7]
	v_pk_mul_f32 v[8:9], v[246:247], v[8:9]
	v_pk_mul_f32 v[10:11], v[246:247], v[10:11]
	v_pk_mul_f32 v[12:13], v[246:247], v[12:13]
	v_pk_mul_f32 v[14:15], v[246:247], v[14:15]
	v_lshlrev_b32_e32 v48, 16, v48
	v_lshlrev_b32_e32 v49, 16, v49
	v_lshlrev_b32_e32 v50, 16, v50
	v_lshlrev_b32_e32 v51, 16, v51
	v_lshlrev_b32_e32 v52, 16, v52
	v_lshlrev_b32_e32 v53, 16, v53
	v_lshlrev_b32_e32 v54, 16, v54
	v_lshlrev_b32_e32 v55, 16, v55
	v_lshlrev_b32_e32 v56, 16, v56
	v_lshlrev_b32_e32 v57, 16, v57
	v_lshlrev_b32_e32 v58, 16, v58
	v_lshlrev_b32_e32 v59, 16, v59
	v_lshlrev_b32_e32 v60, 16, v60
	v_lshlrev_b32_e32 v61, 16, v61
	v_lshlrev_b32_e32 v62, 16, v62
	v_lshlrev_b32_e32 v63, 16, v63
	v_exp_f32_e32 v0, v0
	v_exp_f32_e32 v1, v1
	v_exp_f32_e32 v2, v2
	v_exp_f32_e32 v3, v3
	v_exp_f32_e32 v4, v4
	v_exp_f32_e32 v5, v5
	v_exp_f32_e32 v6, v6
	v_exp_f32_e32 v7, v7
	v_exp_f32_e32 v8, v8
	v_exp_f32_e32 v9, v9
	v_exp_f32_e32 v10, v10
	v_exp_f32_e32 v11, v11
	v_exp_f32_e32 v12, v12
	v_exp_f32_e32 v13, v13
	v_exp_f32_e32 v14, v14
	v_exp_f32_e32 v15, v15
	v_fma_f32 v32, -v0, v0, 1.0
	v_fma_f32 v33, -v1, v1, 1.0
	v_fma_f32 v34, -v2, v2, 1.0
	v_fma_f32 v35, -v3, v3, 1.0
	v_fma_f32 v36, -v4, v4, 1.0
	v_fma_f32 v37, -v5, v5, 1.0
	v_fma_f32 v38, -v6, v6, 1.0
	v_fma_f32 v39, -v7, v7, 1.0
	v_fma_f32 v40, -v8, v8, 1.0
	v_fma_f32 v41, -v9, v9, 1.0
	v_fma_f32 v42, -v10, v10, 1.0
	v_fma_f32 v43, -v11, v11, 1.0
	v_fma_f32 v44, -v12, v12, 1.0
	v_fma_f32 v45, -v13, v13, 1.0
	v_fma_f32 v46, -v14, v14, 1.0
	v_fma_f32 v47, -v15, v15, 1.0
	v_max_f32_e32 v32, 0, v32
	v_max_f32_e32 v33, 0, v33
	v_max_f32_e32 v34, 0, v34
	v_max_f32_e32 v35, 0, v35
	v_max_f32_e32 v36, 0, v36
	v_max_f32_e32 v37, 0, v37
	v_max_f32_e32 v38, 0, v38
	v_max_f32_e32 v39, 0, v39
	v_max_f32_e32 v40, 0, v40
	v_max_f32_e32 v41, 0, v41
	v_max_f32_e32 v42, 0, v42
	v_max_f32_e32 v43, 0, v43
	v_max_f32_e32 v44, 0, v44
	v_max_f32_e32 v45, 0, v45
	v_max_f32_e32 v46, 0, v46
	v_max_f32_e32 v47, 0, v47
	v_sqrt_f32_e32 v32, v32
	v_sqrt_f32_e32 v33, v33
	v_sqrt_f32_e32 v34, v34
	v_sqrt_f32_e32 v35, v35
	v_sqrt_f32_e32 v36, v36
	v_sqrt_f32_e32 v37, v37
	v_sqrt_f32_e32 v38, v38
	v_sqrt_f32_e32 v39, v39
	v_sqrt_f32_e32 v40, v40
	v_sqrt_f32_e32 v41, v41
	v_sqrt_f32_e32 v42, v42
	v_sqrt_f32_e32 v43, v43
	v_sqrt_f32_e32 v44, v44
	v_sqrt_f32_e32 v45, v45
	v_sqrt_f32_e32 v46, v46
	v_sqrt_f32_e32 v47, v47
	s_nop 0
	v_pk_mul_f32 v[16:17], v[16:17], v[32:33]
	v_pk_mul_f32 v[18:19], v[18:19], v[34:35]
	v_pk_mul_f32 v[20:21], v[20:21], v[36:37]
	v_pk_mul_f32 v[22:23], v[22:23], v[38:39]
	v_pk_mul_f32 v[24:25], v[24:25], v[40:41]
	v_pk_mul_f32 v[26:27], v[26:27], v[42:43]
	v_pk_mul_f32 v[28:29], v[28:29], v[44:45]
	v_pk_mul_f32 v[30:31], v[30:31], v[46:47]
	v_pk_mul_f32 v[16:17], v[16:17], v[48:49]
	v_pk_mul_f32 v[18:19], v[18:19], v[50:51]
	v_pk_mul_f32 v[20:21], v[20:21], v[52:53]
	v_pk_mul_f32 v[22:23], v[22:23], v[54:55]
	v_pk_mul_f32 v[24:25], v[24:25], v[56:57]
	v_pk_mul_f32 v[26:27], v[26:27], v[58:59]
	v_pk_mul_f32 v[28:29], v[28:29], v[60:61]
	v_pk_mul_f32 v[30:31], v[30:31], v[62:63]
	v_fma_f32 v250, v15, v250, v31
	v_mul_f32_e32 v232, v232, v15
	v_fma_f32 v250, v14, v250, v30
	v_mul_f32_e32 v232, v232, v14
	v_fma_f32 v250, v13, v250, v29
	v_mul_f32_e32 v232, v232, v13
	v_fma_f32 v250, v12, v250, v28
	v_mul_f32_e32 v232, v232, v12
	v_fma_f32 v250, v11, v250, v27
	v_mul_f32_e32 v232, v232, v11
	v_fma_f32 v250, v10, v250, v26
	v_mul_f32_e32 v232, v232, v10
	v_fma_f32 v250, v9, v250, v25
	v_mul_f32_e32 v232, v232, v9
	v_fma_f32 v250, v8, v250, v24
	v_mul_f32_e32 v232, v232, v8
	v_fma_f32 v250, v7, v250, v23
	v_mul_f32_e32 v232, v232, v7
	v_fma_f32 v250, v6, v250, v22
	v_mul_f32_e32 v232, v232, v6
	v_fma_f32 v250, v5, v250, v21
	v_mul_f32_e32 v232, v232, v5
	v_fma_f32 v250, v4, v250, v20
	v_mul_f32_e32 v232, v232, v4
	v_fma_f32 v250, v3, v250, v19
	v_mul_f32_e32 v232, v232, v3
	v_fma_f32 v250, v2, v250, v18
	v_mul_f32_e32 v232, v232, v2
	v_fma_f32 v250, v1, v250, v17
	v_mul_f32_e32 v232, v232, v1
	v_fma_f32 v250, v0, v250, v16
	v_mul_f32_e32 v232, v232, v0
	ds_read_b128 v[32:35], v236 offset:2304
	ds_read_b128 v[36:39], v236 offset:2368
	s_waitcnt lgkmcnt(0)
; #define LAS __attribute__((address_space(3)))
; #define WAVE_SYNC() asm volatile("s_waitcnt lgkmcnt(0)" ::: "memory")
; __device__ __forceinline__ float sigmoid_f(float x) { return rcpf_(1.f + __expf(-x)); }
; __device__ __forceinline__ f32x4 mfma16(bf16x8 a, bf16x8 b, f32x4 c) { return __builtin_amdgcn_mfma_f32_16x16x32_bf16(a, b, c, 0, 0, 0); }
; template <bool FINAL, int D>
; __device__ __forceinline__ void rg_dir(PREF p, int l, int h, int ch, int sidx, int rowbase  , LAS bf16_t* sXc, LAS float* stg, int lane) {
;     ...
;         const bf16x8 A0 = *(const LAS bf16x8*)(sXc + (mt * 16 + (lane & 15)) * 72 + (lane >> 4) * 8), A1 = *(const LAS bf16x8*)(sXc + (mt * 16 + (lane & 15)) * 72 + 32 + (lane >> 4) * 8);
;         f32x4 ar[4], ai[4];
; #pragma unroll
;         for (int nt = 0; nt < 4; ++nt) { const f32x4 z = {0.f, 0.f, 0.f, 0.f};
;             ar[nt] = mfma16(A0, Br[nt][0], z); ar[nt] = mfma16(A1, Br[nt][1], ar[nt]); ai[nt] = mfma16(A0, Bi[nt][0], z); ai[nt] = mfma16(A1, Bi[nt][1], ai[nt]); }
;         WAVE_SYNC();
; #pragma unroll
;         for (int nt = 0; nt < 4; ++nt)
; #pragma unroll
;             for (int j = 0; j < 4; ++j) { const int o = ((lane >> 4) * 4 + j) * 64 + nt * 16 + (lane & 15); stg[o] = ar[nt][j]; stg[1024 + o] = ai[nt][j]; }
;         WAVE_SYNC();
;         float av[16], iv[16];
; #pragma unroll
;         for (int ti = 0; ti < 16; ++ti) { const int tk = D ? 15 - ti : ti;
;             const float zr = stg[tk * 64 + lane] + ba, zi = stg[1024 + tk * 64 + lane] + bi;
;             const float r = sigmoid_f(zr), ig = sigmoid_f(zi);
;             const float a = __builtin_amdgcn_exp2f(r * sp8);
;             const float xc = bf2f(sXc[(mt * 16 + tk) * 72 + lane]);
;             av[ti] = a; iv[ti] = __builtin_amdgcn_sqrtf(fmaxf(1.f - a * a, 0.f)) * ig * xc;
	v_mfma_f32_16x16x32_bf16 v[0:3], v[32:35], v[80:83], 0
	v_mfma_f32_16x16x32_bf16 v[4:7], v[32:35], v[88:91], 0
	v_mfma_f32_16x16x32_bf16 v[8:11], v[32:35], v[96:99], 0
	v_mfma_f32_16x16x32_bf16 v[12:15], v[32:35], v[104:107], 0
	v_mfma_f32_16x16x32_bf16 v[16:19], v[32:35], v[112:115], 0
	v_mfma_f32_16x16x32_bf16 v[20:23], v[32:35], v[120:123], 0
	v_mfma_f32_16x16x32_bf16 v[24:27], v[32:35], v[128:131], 0
	v_mfma_f32_16x16x32_bf16 v[28:31], v[32:35], v[136:139], 0
	v_mfma_f32_16x16x32_bf16 v[0:3], v[36:39], v[84:87], v[0:3]
	v_mfma_f32_16x16x32_bf16 v[4:7], v[36:39], v[92:95], v[4:7]
	v_mfma_f32_16x16x32_bf16 v[8:11], v[36:39], v[100:103], v[8:11]
	v_mfma_f32_16x16x32_bf16 v[12:15], v[36:39], v[108:111], v[12:15]
	v_mfma_f32_16x16x32_bf16 v[16:19], v[36:39], v[148:151], v[16:19]
	v_mfma_f32_16x16x32_bf16 v[20:23], v[36:39], v[124:127], v[20:23]
	v_mfma_f32_16x16x32_bf16 v[24:27], v[36:39], v[132:135], v[24:27]
	v_mfma_f32_16x16x32_bf16 v[28:31], v[36:39], v[228:231], v[28:31]
	s_nop 3
	ds_write2_b32 v237, v0, v4 offset0:0 offset1:16
	ds_write2_b32 v237, v8, v12 offset0:32 offset1:48
	ds_write2_b32 v237, v1, v5 offset0:64 offset1:80
	ds_write2_b32 v237, v9, v13 offset0:96 offset1:112
	ds_write2_b32 v237, v2, v6 offset0:128 offset1:144
	ds_write2_b32 v237, v10, v14 offset0:160 offset1:176
	ds_write2_b32 v237, v3, v7 offset0:192 offset1:208
	ds_write2_b32 v237, v11, v15 offset0:224 offset1:240
	ds_write2_b32 v238, v16, v20 offset0:0 offset1:16
	ds_write2_b32 v238, v24, v28 offset0:32 offset1:48
	ds_write2_b32 v238, v17, v21 offset0:64 offset1:80
	ds_write2_b32 v238, v25, v29 offset0:96 offset1:112
	ds_write2_b32 v238, v18, v22 offset0:128 offset1:144
	ds_write2_b32 v238, v26, v30 offset0:160 offset1:176
	ds_write2_b32 v238, v19, v23 offset0:192 offset1:208
	ds_write2_b32 v238, v27, v31 offset0:224 offset1:240
	s_waitcnt lgkmcnt(0)
	ds_read2st64_b32 v[0:1], v239 offset0:36 offset1:37
	ds_read2st64_b32 v[2:3], v239 offset0:38 offset1:39
	ds_read2st64_b32 v[4:5], v239 offset0:40 offset1:41
	ds_read2st64_b32 v[6:7], v239 offset0:42 offset1:43
	ds_read2st64_b32 v[8:9], v239 offset0:44 offset1:45
	ds_read2st64_b32 v[10:11], v239 offset0:46 offset1:47
	ds_read2st64_b32 v[12:13], v239 offset0:48 offset1:49
	ds_read2st64_b32 v[14:15], v239 offset0:50 offset1:51
	ds_read2st64_b32 v[16:17], v239 offset0:52 offset1:53
	ds_read2st64_b32 v[18:19], v239 offset0:54 offset1:55
	ds_read2st64_b32 v[20:21], v239 offset0:56 offset1:57
	ds_read2st64_b32 v[22:23], v239 offset0:58 offset1:59
	ds_read2st64_b32 v[24:25], v239 offset0:60 offset1:61
	ds_read2st64_b32 v[26:27], v239 offset0:62 offset1:63
	ds_read2st64_b32 v[28:29], v239 offset0:64 offset1:65
	ds_read2st64_b32 v[30:31], v239 offset0:66 offset1:67
	ds_read_u16 v48, v240 offset:2304
	ds_read_u16 v49, v240 offset:2448
	ds_read_u16 v50, v240 offset:2592
	ds_read_u16 v51, v240 offset:2736
	ds_read_u16 v52, v240 offset:2880
	ds_read_u16 v53, v240 offset:3024
	ds_read_u16 v54, v240 offset:3168
	ds_read_u16 v55, v240 offset:3312
	ds_read_u16 v56, v240 offset:3456
	ds_read_u16 v57, v240 offset:3600
	ds_read_u16 v58, v240 offset:3744
	ds_read_u16 v59, v240 offset:3888
	ds_read_u16 v60, v240 offset:4032
	ds_read_u16 v61, v240 offset:4176
	ds_read_u16 v62, v240 offset:4320
	ds_read_u16 v63, v240 offset:4464
	s_waitcnt lgkmcnt(0)
	v_pk_fma_f32 v[0:1], v[0:1], v[248:249], v[242:243]
	v_pk_fma_f32 v[2:3], v[2:3], v[248:249], v[242:243]
	v_pk_fma_f32 v[4:5], v[4:5], v[248:249], v[242:243]
	v_pk_fma_f32 v[6:7], v[6:7], v[248:249], v[242:243]
	v_pk_fma_f32 v[8:9], v[8:9], v[248:249], v[242:243]
	v_pk_fma_f32 v[10:11], v[10:11], v[248:249], v[242:243]
	v_pk_fma_f32 v[12:13], v[12:13], v[248:249], v[242:243]
	v_pk_fma_f32 v[14:15], v[14:15], v[248:249], v[242:243]
	v_pk_fma_f32 v[16:17], v[16:17], v[248:249], v[244:245]
	v_pk_fma_f32 v[18:19], v[18:19], v[248:249], v[244:245]
	v_pk_fma_f32 v[20:21], v[20:21], v[248:249], v[244:245]
	v_pk_fma_f32 v[22:23], v[22:23], v[248:249], v[244:245]
	v_pk_fma_f32 v[24:25], v[24:25], v[248:249], v[244:245]
	v_pk_fma_f32 v[26:27], v[26:27], v[248:249], v[244:245]
	v_pk_fma_f32 v[28:29], v[28:29], v[248:249], v[244:245]
	v_pk_fma_f32 v[30:31], v[30:31], v[248:249], v[244:245]
	v_exp_f32_e32 v0, v0
	v_exp_f32_e32 v1, v1
	v_exp_f32_e32 v2, v2
	v_exp_f32_e32 v3, v3
	v_exp_f32_e32 v4, v4
	v_exp_f32_e32 v5, v5
	v_exp_f32_e32 v6, v6
	v_exp_f32_e32 v7, v7
	v_exp_f32_e32 v8, v8
	v_exp_f32_e32 v9, v9
	v_exp_f32_e32 v10, v10
	v_exp_f32_e32 v11, v11
	v_exp_f32_e32 v12, v12
	v_exp_f32_e32 v13, v13
	v_exp_f32_e32 v14, v14
	v_exp_f32_e32 v15, v15
	v_exp_f32_e32 v16, v16
	v_exp_f32_e32 v17, v17
	v_exp_f32_e32 v18, v18
	v_exp_f32_e32 v19, v19
	v_exp_f32_e32 v20, v20
	v_exp_f32_e32 v21, v21
	v_exp_f32_e32 v22, v22
	v_exp_f32_e32 v23, v23
	v_exp_f32_e32 v24, v24
	v_exp_f32_e32 v25, v25
	v_exp_f32_e32 v26, v26
	v_exp_f32_e32 v27, v27
	v_exp_f32_e32 v28, v28
	v_exp_f32_e32 v29, v29
	v_exp_f32_e32 v30, v30
	v_exp_f32_e32 v31, v31
	v_pk_add_f32 v[0:1], v[0:1], 1.0 op_sel_hi:[1,0]
	v_pk_add_f32 v[2:3], v[2:3], 1.0 op_sel_hi:[1,0]
	v_pk_add_f32 v[4:5], v[4:5], 1.0 op_sel_hi:[1,0]
	v_pk_add_f32 v[6:7], v[6:7], 1.0 op_sel_hi:[1,0]
	v_pk_add_f32 v[8:9], v[8:9], 1.0 op_sel_hi:[1,0]
	v_pk_add_f32 v[10:11], v[10:11], 1.0 op_sel_hi:[1,0]
	v_pk_add_f32 v[12:13], v[12:13], 1.0 op_sel_hi:[1,0]
	v_pk_add_f32 v[14:15], v[14:15], 1.0 op_sel_hi:[1,0]
	v_pk_add_f32 v[16:17], v[16:17], 1.0 op_sel_hi:[1,0]
	v_pk_add_f32 v[18:19], v[18:19], 1.0 op_sel_hi:[1,0]
	v_pk_add_f32 v[20:21], v[20:21], 1.0 op_sel_hi:[1,0]
	v_pk_add_f32 v[22:23], v[22:23], 1.0 op_sel_hi:[1,0]
	v_pk_add_f32 v[24:25], v[24:25], 1.0 op_sel_hi:[1,0]
; __device__ __forceinline__ unsigned f2bf(float f) { unsigned r; asm("v_cvt_pk_bf16_f32 %0, %1, %1" : "=v"(r) : "v"(f)); return r & 0xffffu; }
; __device__ __forceinline__ float sigmoid_f(float x) { return rcpf_(1.f + __expf(-x)); }
; __device__ __forceinline__ float gelu_tanh_f(float x) { const float y = 0.7978845608028654f * (x + 0.044715f * x * x * x); return x * sigmoid_f(2.f * y); }
; template <bool FINAL, int D>
; __device__ __forceinline__ void rg_dir(PREF p, int l, int h, int ch, int sidx, int rowbase  , LAS bf16_t* sXc, LAS float* stg, int lane) {
;     ...
;         float av[16], iv[16];
; #pragma unroll
;         for (int ti = 0; ti < 16; ++ti) { const int tk = D ? 15 - ti : ti;
;             const float zr = stg[tk * 64 + lane] + ba, zi = stg[1024 + tk * 64 + lane] + bi;
;             const float r = sigmoid_f(zr), ig = sigmoid_f(zi);
;             const float a = __builtin_amdgcn_exp2f(r * sp8);
;             const float xc = bf2f(sXc[(mt * 16 + tk) * 72 + lane]);
;             av[ti] = a; iv[ti] = __builtin_amdgcn_sqrtf(fmaxf(1.f - a * a, 0.f)) * ig * xc;
;             if (FINAL && D == 1) grv[ti] = gelu_tanh_f(grv[ti]);
;         }
; #pragma unroll
;         for (int ti = 0; ti < 16; ++ti) { const int tk = D ? 15 - ti : ti;
;             hc = av[ti] * hc + iv[ti]; Ap *= av[ti];
;             if (FINAL) { const size_t row = (size_t)(rowbase + mt * 16 + tk);
;                 if (D == 0) TMP[row * 512 + ch] = (bf16_t)f2bf(hc);
;                 else MIX[row * DM + ch] = (bf16_t)f2bf(grv[ti] * (hfv[ti] + hc)); }
;         }
	v_pk_add_f32 v[26:27], v[26:27], 1.0 op_sel_hi:[1,0]
	v_pk_add_f32 v[28:29], v[28:29], 1.0 op_sel_hi:[1,0]
	v_pk_add_f32 v[30:31], v[30:31], 1.0 op_sel_hi:[1,0]
	v_rcp_f32_e32 v0, v0
	v_rcp_f32_e32 v1, v1
	v_rcp_f32_e32 v2, v2
	v_rcp_f32_e32 v3, v3
	v_rcp_f32_e32 v4, v4
	v_rcp_f32_e32 v5, v5
	v_rcp_f32_e32 v6, v6
	v_rcp_f32_e32 v7, v7
	v_rcp_f32_e32 v8, v8
	v_rcp_f32_e32 v9, v9
	v_rcp_f32_e32 v10, v10
	v_rcp_f32_e32 v11, v11
	v_rcp_f32_e32 v12, v12
	v_rcp_f32_e32 v13, v13
	v_rcp_f32_e32 v14, v14
	v_rcp_f32_e32 v15, v15
	v_rcp_f32_e32 v16, v16
	v_rcp_f32_e32 v17, v17
	v_rcp_f32_e32 v18, v18
	v_rcp_f32_e32 v19, v19
	v_rcp_f32_e32 v20, v20
	v_rcp_f32_e32 v21, v21
	v_rcp_f32_e32 v22, v22
	v_rcp_f32_e32 v23, v23
	v_rcp_f32_e32 v24, v24
	v_rcp_f32_e32 v25, v25
	v_rcp_f32_e32 v26, v26
	v_rcp_f32_e32 v27, v27
	v_rcp_f32_e32 v28, v28
	v_rcp_f32_e32 v29, v29
	v_rcp_f32_e32 v30, v30
	v_rcp_f32_e32 v31, v31
	v_pk_mul_f32 v[0:1], v[246:247], v[0:1]
	v_pk_mul_f32 v[2:3], v[246:247], v[2:3]
	v_pk_mul_f32 v[4:5], v[246:247], v[4:5]
	v_pk_mul_f32 v[6:7], v[246:247], v[6:7]
	v_pk_mul_f32 v[8:9], v[246:247], v[8:9]
	v_pk_mul_f32 v[10:11], v[246:247], v[10:11]
	v_pk_mul_f32 v[12:13], v[246:247], v[12:13]
	v_pk_mul_f32 v[14:15], v[246:247], v[14:15]
	v_lshlrev_b32_e32 v48, 16, v48
	v_lshlrev_b32_e32 v49, 16, v49
	v_lshlrev_b32_e32 v50, 16, v50
	v_lshlrev_b32_e32 v51, 16, v51
	v_lshlrev_b32_e32 v52, 16, v52
	v_lshlrev_b32_e32 v53, 16, v53
	v_lshlrev_b32_e32 v54, 16, v54
	v_lshlrev_b32_e32 v55, 16, v55
	v_lshlrev_b32_e32 v56, 16, v56
	v_lshlrev_b32_e32 v57, 16, v57
	v_lshlrev_b32_e32 v58, 16, v58
	v_lshlrev_b32_e32 v59, 16, v59
	v_lshlrev_b32_e32 v60, 16, v60
	v_lshlrev_b32_e32 v61, 16, v61
	v_lshlrev_b32_e32 v62, 16, v62
	v_lshlrev_b32_e32 v63, 16, v63
	v_exp_f32_e32 v0, v0
	v_exp_f32_e32 v1, v1
	v_exp_f32_e32 v2, v2
	v_exp_f32_e32 v3, v3
	v_exp_f32_e32 v4, v4
	v_exp_f32_e32 v5, v5
	v_exp_f32_e32 v6, v6
	v_exp_f32_e32 v7, v7
	v_exp_f32_e32 v8, v8
	v_exp_f32_e32 v9, v9
	v_exp_f32_e32 v10, v10
	v_exp_f32_e32 v11, v11
	v_exp_f32_e32 v12, v12
	v_exp_f32_e32 v13, v13
	v_exp_f32_e32 v14, v14
	v_exp_f32_e32 v15, v15
	v_fma_f32 v32, -v0, v0, 1.0
	v_fma_f32 v33, -v1, v1, 1.0
	v_fma_f32 v34, -v2, v2, 1.0
	v_fma_f32 v35, -v3, v3, 1.0
	v_fma_f32 v36, -v4, v4, 1.0
	v_fma_f32 v37, -v5, v5, 1.0
	v_fma_f32 v38, -v6, v6, 1.0
	v_fma_f32 v39, -v7, v7, 1.0
	v_fma_f32 v40, -v8, v8, 1.0
	v_fma_f32 v41, -v9, v9, 1.0
	v_fma_f32 v42, -v10, v10, 1.0
	v_fma_f32 v43, -v11, v11, 1.0
	v_fma_f32 v44, -v12, v12, 1.0
	v_fma_f32 v45, -v13, v13, 1.0
	v_fma_f32 v46, -v14, v14, 1.0
	v_fma_f32 v47, -v15, v15, 1.0
	v_max_f32_e32 v32, 0, v32
	v_max_f32_e32 v33, 0, v33
	v_max_f32_e32 v34, 0, v34
	v_max_f32_e32 v35, 0, v35
	v_max_f32_e32 v36, 0, v36
	v_max_f32_e32 v37, 0, v37
	v_max_f32_e32 v38, 0, v38
	v_max_f32_e32 v39, 0, v39
	v_max_f32_e32 v40, 0, v40
	v_max_f32_e32 v41, 0, v41
	v_max_f32_e32 v42, 0, v42
	v_max_f32_e32 v43, 0, v43
	v_max_f32_e32 v44, 0, v44
	v_max_f32_e32 v45, 0, v45
	v_max_f32_e32 v46, 0, v46
	v_max_f32_e32 v47, 0, v47
	v_sqrt_f32_e32 v32, v32
	v_sqrt_f32_e32 v33, v33
	v_sqrt_f32_e32 v34, v34
	v_sqrt_f32_e32 v35, v35
	v_sqrt_f32_e32 v36, v36
	v_sqrt_f32_e32 v37, v37
	v_sqrt_f32_e32 v38, v38
	v_sqrt_f32_e32 v39, v39
	v_sqrt_f32_e32 v40, v40
	v_sqrt_f32_e32 v41, v41
	v_sqrt_f32_e32 v42, v42
	v_sqrt_f32_e32 v43, v43
	v_sqrt_f32_e32 v44, v44
	v_sqrt_f32_e32 v45, v45
	v_sqrt_f32_e32 v46, v46
	v_sqrt_f32_e32 v47, v47
	s_nop 0
	v_pk_mul_f32 v[16:17], v[16:17], v[32:33]
	v_pk_mul_f32 v[18:19], v[18:19], v[34:35]
	v_pk_mul_f32 v[20:21], v[20:21], v[36:37]
	v_pk_mul_f32 v[22:23], v[22:23], v[38:39]
	v_pk_mul_f32 v[24:25], v[24:25], v[40:41]
	v_pk_mul_f32 v[26:27], v[26:27], v[42:43]
	v_pk_mul_f32 v[28:29], v[28:29], v[44:45]
	v_pk_mul_f32 v[30:31], v[30:31], v[46:47]
	v_pk_mul_f32 v[16:17], v[16:17], v[48:49]
	v_pk_mul_f32 v[18:19], v[18:19], v[50:51]
	v_pk_mul_f32 v[20:21], v[20:21], v[52:53]
	v_pk_mul_f32 v[22:23], v[22:23], v[54:55]
	v_pk_mul_f32 v[24:25], v[24:25], v[56:57]
	v_pk_mul_f32 v[26:27], v[26:27], v[58:59]
	v_pk_mul_f32 v[28:29], v[28:29], v[60:61]
	v_pk_mul_f32 v[30:31], v[30:31], v[62:63]
	v_fma_f32 v250, v15, v250, v31
	v_mul_f32_e32 v232, v232, v15
	v_fma_f32 v250, v14, v250, v30
	v_mul_f32_e32 v232, v232, v14
	v_fma_f32 v250, v13, v250, v29
	v_mul_f32_e32 v232, v232, v13
	v_fma_f32 v250, v12, v250, v28
	v_mul_f32_e32 v232, v232, v12
	v_fma_f32 v250, v11, v250, v27
	v_mul_f32_e32 v232, v232, v11
	v_fma_f32 v250, v10, v250, v26
	v_mul_f32_e32 v232, v232, v10
	v_fma_f32 v250, v9, v250, v25
	v_mul_f32_e32 v232, v232, v9
	v_fma_f32 v250, v8, v250, v24
	v_mul_f32_e32 v232, v232, v8
	v_fma_f32 v250, v7, v250, v23
	v_mul_f32_e32 v232, v232, v7
	v_fma_f32 v250, v6, v250, v22
	v_mul_f32_e32 v232, v232, v6
	v_fma_f32 v250, v5, v250, v21
	v_mul_f32_e32 v232, v232, v5
	v_fma_f32 v250, v4, v250, v20
	v_mul_f32_e32 v232, v232, v4
	v_fma_f32 v250, v3, v250, v19
	v_mul_f32_e32 v232, v232, v3
	v_fma_f32 v250, v2, v250, v18
	v_mul_f32_e32 v232, v232, v2
	v_fma_f32 v250, v1, v250, v17
	v_mul_f32_e32 v232, v232, v1
	v_fma_f32 v250, v0, v250, v16
	v_mul_f32_e32 v232, v232, v0
	ds_read_b128 v[32:35], v236 offset:0
	ds_read_b128 v[36:39], v236 offset:64
	s_waitcnt lgkmcnt(0)
; #define LAS __attribute__((address_space(3)))
; #define WAVE_SYNC() asm volatile("s_waitcnt lgkmcnt(0)" ::: "memory")
; __device__ __forceinline__ float sigmoid_f(float x) { return rcpf_(1.f + __expf(-x)); }
; __device__ __forceinline__ f32x4 mfma16(bf16x8 a, bf16x8 b, f32x4 c) { return __builtin_amdgcn_mfma_f32_16x16x32_bf16(a, b, c, 0, 0, 0); }
; template <bool FINAL, int D>
; __device__ __forceinline__ void rg_dir(PREF p, int l, int h, int ch, int sidx, int rowbase  , LAS bf16_t* sXc, LAS float* stg, int lane) {
;     ...
;         const bf16x8 A0 = *(const LAS bf16x8*)(sXc + (mt * 16 + (lane & 15)) * 72 + (lane >> 4) * 8), A1 = *(const LAS bf16x8*)(sXc + (mt * 16 + (lane & 15)) * 72 + 32 + (lane >> 4) * 8);
;         f32x4 ar[4], ai[4];
; #pragma unroll
;         for (int nt = 0; nt < 4; ++nt) { const f32x4 z = {0.f, 0.f, 0.f, 0.f};
;             ar[nt] = mfma16(A0, Br[nt][0], z); ar[nt] = mfma16(A1, Br[nt][1], ar[nt]); ai[nt] = mfma16(A0, Bi[nt][0], z); ai[nt] = mfma16(A1, Bi[nt][1], ai[nt]); }
;         WAVE_SYNC();
; #pragma unroll
;         for (int nt = 0; nt < 4; ++nt)
; #pragma unroll
;             for (int j = 0; j < 4; ++j) { const int o = ((lane >> 4) * 4 + j) * 64 + nt * 16 + (lane & 15); stg[o] = ar[nt][j]; stg[1024 + o] = ai[nt][j]; }
;         WAVE_SYNC();
;         float av[16], iv[16];
; #pragma unroll
;         for (int ti = 0; ti < 16; ++ti) { const int tk = D ? 15 - ti : ti;
;             const float zr = stg[tk * 64 + lane] + ba, zi = stg[1024 + tk * 64 + lane] + bi;
;             const float r = sigmoid_f(zr), ig = sigmoid_f(zi);
;             const float a = __builtin_amdgcn_exp2f(r * sp8);
;             const float xc = bf2f(sXc[(mt * 16 + tk) * 72 + lane]);
;             av[ti] = a; iv[ti] = __builtin_amdgcn_sqrtf(fmaxf(1.f - a * a, 0.f)) * ig * xc;
	v_mfma_f32_16x16x32_bf16 v[0:3], v[32:35], v[80:83], 0
	v_mfma_f32_16x16x32_bf16 v[4:7], v[32:35], v[88:91], 0
	v_mfma_f32_16x16x32_bf16 v[8:11], v[32:35], v[96:99], 0
	v_mfma_f32_16x16x32_bf16 v[12:15], v[32:35], v[104:107], 0
	v_mfma_f32_16x16x32_bf16 v[16:19], v[32:35], v[112:115], 0
	v_mfma_f32_16x16x32_bf16 v[20:23], v[32:35], v[120:123], 0
	v_mfma_f32_16x16x32_bf16 v[24:27], v[32:35], v[128:131], 0
	v_mfma_f32_16x16x32_bf16 v[28:31], v[32:35], v[136:139], 0
	v_mfma_f32_16x16x32_bf16 v[0:3], v[36:39], v[84:87], v[0:3]
	v_mfma_f32_16x16x32_bf16 v[4:7], v[36:39], v[92:95], v[4:7]
	v_mfma_f32_16x16x32_bf16 v[8:11], v[36:39], v[100:103], v[8:11]
	v_mfma_f32_16x16x32_bf16 v[12:15], v[36:39], v[108:111], v[12:15]
	v_mfma_f32_16x16x32_bf16 v[16:19], v[36:39], v[148:151], v[16:19]
	v_mfma_f32_16x16x32_bf16 v[20:23], v[36:39], v[124:127], v[20:23]
	v_mfma_f32_16x16x32_bf16 v[24:27], v[36:39], v[132:135], v[24:27]
	v_mfma_f32_16x16x32_bf16 v[28:31], v[36:39], v[228:231], v[28:31]
	s_nop 3
	ds_write2_b32 v237, v0, v4 offset0:0 offset1:16
	ds_write2_b32 v237, v8, v12 offset0:32 offset1:48
	ds_write2_b32 v237, v1, v5 offset0:64 offset1:80
	ds_write2_b32 v237, v9, v13 offset0:96 offset1:112
	ds_write2_b32 v237, v2, v6 offset0:128 offset1:144
	ds_write2_b32 v237, v10, v14 offset0:160 offset1:176
	ds_write2_b32 v237, v3, v7 offset0:192 offset1:208
	ds_write2_b32 v237, v11, v15 offset0:224 offset1:240
	ds_write2_b32 v238, v16, v20 offset0:0 offset1:16
	ds_write2_b32 v238, v24, v28 offset0:32 offset1:48
	ds_write2_b32 v238, v17, v21 offset0:64 offset1:80
	ds_write2_b32 v238, v25, v29 offset0:96 offset1:112
	ds_write2_b32 v238, v18, v22 offset0:128 offset1:144
	ds_write2_b32 v238, v26, v30 offset0:160 offset1:176
	ds_write2_b32 v238, v19, v23 offset0:192 offset1:208
	ds_write2_b32 v238, v27, v31 offset0:224 offset1:240
	s_waitcnt lgkmcnt(0)
	ds_read2st64_b32 v[0:1], v239 offset0:36 offset1:37
	ds_read2st64_b32 v[2:3], v239 offset0:38 offset1:39
	ds_read2st64_b32 v[4:5], v239 offset0:40 offset1:41
	ds_read2st64_b32 v[6:7], v239 offset0:42 offset1:43
	ds_read2st64_b32 v[8:9], v239 offset0:44 offset1:45
	ds_read2st64_b32 v[10:11], v239 offset0:46 offset1:47
	ds_read2st64_b32 v[12:13], v239 offset0:48 offset1:49
	ds_read2st64_b32 v[14:15], v239 offset0:50 offset1:51
	ds_read2st64_b32 v[16:17], v239 offset0:52 offset1:53
	ds_read2st64_b32 v[18:19], v239 offset0:54 offset1:55
	ds_read2st64_b32 v[20:21], v239 offset0:56 offset1:57
	ds_read2st64_b32 v[22:23], v239 offset0:58 offset1:59
	ds_read2st64_b32 v[24:25], v239 offset0:60 offset1:61
	ds_read2st64_b32 v[26:27], v239 offset0:62 offset1:63
	ds_read2st64_b32 v[28:29], v239 offset0:64 offset1:65
	ds_read2st64_b32 v[30:31], v239 offset0:66 offset1:67
	ds_read_u16 v48, v240 offset:0
	ds_read_u16 v49, v240 offset:144
	ds_read_u16 v50, v240 offset:288
	ds_read_u16 v51, v240 offset:432
	ds_read_u16 v52, v240 offset:576
	ds_read_u16 v53, v240 offset:720
	ds_read_u16 v54, v240 offset:864
	ds_read_u16 v55, v240 offset:1008
	ds_read_u16 v56, v240 offset:1152
	ds_read_u16 v57, v240 offset:1296
	ds_read_u16 v58, v240 offset:1440
	ds_read_u16 v59, v240 offset:1584
	ds_read_u16 v60, v240 offset:1728
	ds_read_u16 v61, v240 offset:1872
	ds_read_u16 v62, v240 offset:2016
	ds_read_u16 v63, v240 offset:2160
	s_waitcnt lgkmcnt(0)
	v_pk_fma_f32 v[0:1], v[0:1], v[248:249], v[242:243]
	v_pk_fma_f32 v[2:3], v[2:3], v[248:249], v[242:243]
	v_pk_fma_f32 v[4:5], v[4:5], v[248:249], v[242:243]
	v_pk_fma_f32 v[6:7], v[6:7], v[248:249], v[242:243]
	v_pk_fma_f32 v[8:9], v[8:9], v[248:249], v[242:243]
	v_pk_fma_f32 v[10:11], v[10:11], v[248:249], v[242:243]
	v_pk_fma_f32 v[12:13], v[12:13], v[248:249], v[242:243]
	v_pk_fma_f32 v[14:15], v[14:15], v[248:249], v[242:243]
	v_pk_fma_f32 v[16:17], v[16:17], v[248:249], v[244:245]
	v_pk_fma_f32 v[18:19], v[18:19], v[248:249], v[244:245]
	v_pk_fma_f32 v[20:21], v[20:21], v[248:249], v[244:245]
	v_pk_fma_f32 v[22:23], v[22:23], v[248:249], v[244:245]
	v_pk_fma_f32 v[24:25], v[24:25], v[248:249], v[244:245]
	v_pk_fma_f32 v[26:27], v[26:27], v[248:249], v[244:245]
	v_pk_fma_f32 v[28:29], v[28:29], v[248:249], v[244:245]
	v_pk_fma_f32 v[30:31], v[30:31], v[248:249], v[244:245]
	v_exp_f32_e32 v0, v0
	v_exp_f32_e32 v1, v1
	v_exp_f32_e32 v2, v2
	v_exp_f32_e32 v3, v3
	v_exp_f32_e32 v4, v4
	v_exp_f32_e32 v5, v5
	v_exp_f32_e32 v6, v6
	v_exp_f32_e32 v7, v7
	v_exp_f32_e32 v8, v8
	v_exp_f32_e32 v9, v9
	v_exp_f32_e32 v10, v10
	v_exp_f32_e32 v11, v11
	v_exp_f32_e32 v12, v12
	v_exp_f32_e32 v13, v13
	v_exp_f32_e32 v14, v14
	v_exp_f32_e32 v15, v15
	v_exp_f32_e32 v16, v16
	v_exp_f32_e32 v17, v17
	v_exp_f32_e32 v18, v18
	v_exp_f32_e32 v19, v19
	v_exp_f32_e32 v20, v20
	v_exp_f32_e32 v21, v21
	v_exp_f32_e32 v22, v22
	v_exp_f32_e32 v23, v23
	v_exp_f32_e32 v24, v24
	v_exp_f32_e32 v25, v25
	v_exp_f32_e32 v26, v26
	v_exp_f32_e32 v27, v27
	v_exp_f32_e32 v28, v28
	v_exp_f32_e32 v29, v29
	v_exp_f32_e32 v30, v30
	v_exp_f32_e32 v31, v31
	v_pk_add_f32 v[0:1], v[0:1], 1.0 op_sel_hi:[1,0]
	v_pk_add_f32 v[2:3], v[2:3], 1.0 op_sel_hi:[1,0]
	v_pk_add_f32 v[4:5], v[4:5], 1.0 op_sel_hi:[1,0]
	v_pk_add_f32 v[6:7], v[6:7], 1.0 op_sel_hi:[1,0]
	v_pk_add_f32 v[8:9], v[8:9], 1.0 op_sel_hi:[1,0]
	v_pk_add_f32 v[10:11], v[10:11], 1.0 op_sel_hi:[1,0]
	v_pk_add_f32 v[12:13], v[12:13], 1.0 op_sel_hi:[1,0]
	v_pk_add_f32 v[14:15], v[14:15], 1.0 op_sel_hi:[1,0]
	v_pk_add_f32 v[16:17], v[16:17], 1.0 op_sel_hi:[1,0]
	v_pk_add_f32 v[18:19], v[18:19], 1.0 op_sel_hi:[1,0]
	v_pk_add_f32 v[20:21], v[20:21], 1.0 op_sel_hi:[1,0]
	v_pk_add_f32 v[22:23], v[22:23], 1.0 op_sel_hi:[1,0]
	v_pk_add_f32 v[24:25], v[24:25], 1.0 op_sel_hi:[1,0]
; __device__ __forceinline__ unsigned f2bf(float f) { unsigned r; asm("v_cvt_pk_bf16_f32 %0, %1, %1" : "=v"(r) : "v"(f)); return r & 0xffffu; }
; __device__ __forceinline__ float sigmoid_f(float x) { return rcpf_(1.f + __expf(-x)); }
; __device__ __forceinline__ float gelu_tanh_f(float x) { const float y = 0.7978845608028654f * (x + 0.044715f * x * x * x); return x * sigmoid_f(2.f * y); }
; template <bool FINAL, int D>
; __device__ __forceinline__ void rg_dir(PREF p, int l, int h, int ch, int sidx, int rowbase  , LAS bf16_t* sXc, LAS float* stg, int lane) {
;     ...
;         float av[16], iv[16];
; #pragma unroll
;         for (int ti = 0; ti < 16; ++ti) { const int tk = D ? 15 - ti : ti;
;             const float zr = stg[tk * 64 + lane] + ba, zi = stg[1024 + tk * 64 + lane] + bi;
;             const float r = sigmoid_f(zr), ig = sigmoid_f(zi);
;             const float a = __builtin_amdgcn_exp2f(r * sp8);
;             const float xc = bf2f(sXc[(mt * 16 + tk) * 72 + lane]);
;             av[ti] = a; iv[ti] = __builtin_amdgcn_sqrtf(fmaxf(1.f - a * a, 0.f)) * ig * xc;
;             if (FINAL && D == 1) grv[ti] = gelu_tanh_f(grv[ti]);
;         }
; #pragma unroll
;         for (int ti = 0; ti < 16; ++ti) { const int tk = D ? 15 - ti : ti;
;             hc = av[ti] * hc + iv[ti]; Ap *= av[ti];
;             if (FINAL) { const size_t row = (size_t)(rowbase + mt * 16 + tk);
;                 if (D == 0) TMP[row * 512 + ch] = (bf16_t)f2bf(hc);
;                 else MIX[row * DM + ch] = (bf16_t)f2bf(grv[ti] * (hfv[ti] + hc)); }
;         }
;     }
;     if (!FINAL) { RGA[sidx] = Ap; RGH[sidx] = hc; }
; __global__ void __launch_bounds__(NTHREADS, 2) mega_fwd(Params p_arg) {
;     ...
;             for (int item = gw; item < 2 * NCH * 8; item += NGW) rg_item<false>(p, l, item, lds + wave * 18432, lane);
	v_pk_add_f32 v[26:27], v[26:27], 1.0 op_sel_hi:[1,0]
	v_pk_add_f32 v[28:29], v[28:29], 1.0 op_sel_hi:[1,0]
	v_pk_add_f32 v[30:31], v[30:31], 1.0 op_sel_hi:[1,0]
	v_rcp_f32_e32 v0, v0
	v_rcp_f32_e32 v1, v1
	v_rcp_f32_e32 v2, v2
	v_rcp_f32_e32 v3, v3
	v_rcp_f32_e32 v4, v4
	v_rcp_f32_e32 v5, v5
	v_rcp_f32_e32 v6, v6
	v_rcp_f32_e32 v7, v7
	v_rcp_f32_e32 v8, v8
	v_rcp_f32_e32 v9, v9
	v_rcp_f32_e32 v10, v10
	v_rcp_f32_e32 v11, v11
	v_rcp_f32_e32 v12, v12
	v_rcp_f32_e32 v13, v13
	v_rcp_f32_e32 v14, v14
	v_rcp_f32_e32 v15, v15
	v_rcp_f32_e32 v16, v16
	v_rcp_f32_e32 v17, v17
	v_rcp_f32_e32 v18, v18
	v_rcp_f32_e32 v19, v19
	v_rcp_f32_e32 v20, v20
	v_rcp_f32_e32 v21, v21
	v_rcp_f32_e32 v22, v22
	v_rcp_f32_e32 v23, v23
	v_rcp_f32_e32 v24, v24
	v_rcp_f32_e32 v25, v25
	v_rcp_f32_e32 v26, v26
	v_rcp_f32_e32 v27, v27
	v_rcp_f32_e32 v28, v28
	v_rcp_f32_e32 v29, v29
	v_rcp_f32_e32 v30, v30
	v_rcp_f32_e32 v31, v31
	v_pk_mul_f32 v[0:1], v[246:247], v[0:1]
	v_pk_mul_f32 v[2:3], v[246:247], v[2:3]
	v_pk_mul_f32 v[4:5], v[246:247], v[4:5]
	v_pk_mul_f32 v[6:7], v[246:247], v[6:7]
	v_pk_mul_f32 v[8:9], v[246:247], v[8:9]
	v_pk_mul_f32 v[10:11], v[246:247], v[10:11]
	v_pk_mul_f32 v[12:13], v[246:247], v[12:13]
	v_pk_mul_f32 v[14:15], v[246:247], v[14:15]
	v_lshlrev_b32_e32 v48, 16, v48
	v_lshlrev_b32_e32 v49, 16, v49
	v_lshlrev_b32_e32 v50, 16, v50
	v_lshlrev_b32_e32 v51, 16, v51
	v_lshlrev_b32_e32 v52, 16, v52
	v_lshlrev_b32_e32 v53, 16, v53
	v_lshlrev_b32_e32 v54, 16, v54
	v_lshlrev_b32_e32 v55, 16, v55
	v_lshlrev_b32_e32 v56, 16, v56
	v_lshlrev_b32_e32 v57, 16, v57
	v_lshlrev_b32_e32 v58, 16, v58
	v_lshlrev_b32_e32 v59, 16, v59
	v_lshlrev_b32_e32 v60, 16, v60
	v_lshlrev_b32_e32 v61, 16, v61
	v_lshlrev_b32_e32 v62, 16, v62
	v_lshlrev_b32_e32 v63, 16, v63
	v_exp_f32_e32 v0, v0
	v_exp_f32_e32 v1, v1
	v_exp_f32_e32 v2, v2
	v_exp_f32_e32 v3, v3
	v_exp_f32_e32 v4, v4
	v_exp_f32_e32 v5, v5
	v_exp_f32_e32 v6, v6
	v_exp_f32_e32 v7, v7
	v_exp_f32_e32 v8, v8
	v_exp_f32_e32 v9, v9
	v_exp_f32_e32 v10, v10
	v_exp_f32_e32 v11, v11
	v_exp_f32_e32 v12, v12
	v_exp_f32_e32 v13, v13
	v_exp_f32_e32 v14, v14
	v_exp_f32_e32 v15, v15
	v_fma_f32 v32, -v0, v0, 1.0
	v_fma_f32 v33, -v1, v1, 1.0
	v_fma_f32 v34, -v2, v2, 1.0
	v_fma_f32 v35, -v3, v3, 1.0
	v_fma_f32 v36, -v4, v4, 1.0
	v_fma_f32 v37, -v5, v5, 1.0
	v_fma_f32 v38, -v6, v6, 1.0
	v_fma_f32 v39, -v7, v7, 1.0
	v_fma_f32 v40, -v8, v8, 1.0
	v_fma_f32 v41, -v9, v9, 1.0
	v_fma_f32 v42, -v10, v10, 1.0
	v_fma_f32 v43, -v11, v11, 1.0
	v_fma_f32 v44, -v12, v12, 1.0
	v_fma_f32 v45, -v13, v13, 1.0
	v_fma_f32 v46, -v14, v14, 1.0
	v_fma_f32 v47, -v15, v15, 1.0
	v_max_f32_e32 v32, 0, v32
	v_max_f32_e32 v33, 0, v33
	v_max_f32_e32 v34, 0, v34
	v_max_f32_e32 v35, 0, v35
	v_max_f32_e32 v36, 0, v36
	v_max_f32_e32 v37, 0, v37
	v_max_f32_e32 v38, 0, v38
	v_max_f32_e32 v39, 0, v39
	v_max_f32_e32 v40, 0, v40
	v_max_f32_e32 v41, 0, v41
	v_max_f32_e32 v42, 0, v42
	v_max_f32_e32 v43, 0, v43
	v_max_f32_e32 v44, 0, v44
	v_max_f32_e32 v45, 0, v45
	v_max_f32_e32 v46, 0, v46
	v_max_f32_e32 v47, 0, v47
	v_sqrt_f32_e32 v32, v32
	v_sqrt_f32_e32 v33, v33
	v_sqrt_f32_e32 v34, v34
	v_sqrt_f32_e32 v35, v35
	v_sqrt_f32_e32 v36, v36
	v_sqrt_f32_e32 v37, v37
	v_sqrt_f32_e32 v38, v38
	v_sqrt_f32_e32 v39, v39
	v_sqrt_f32_e32 v40, v40
	v_sqrt_f32_e32 v41, v41
	v_sqrt_f32_e32 v42, v42
	v_sqrt_f32_e32 v43, v43
	v_sqrt_f32_e32 v44, v44
	v_sqrt_f32_e32 v45, v45
	v_sqrt_f32_e32 v46, v46
	v_sqrt_f32_e32 v47, v47
	s_nop 0
	v_pk_mul_f32 v[16:17], v[16:17], v[32:33]
	v_pk_mul_f32 v[18:19], v[18:19], v[34:35]
	v_pk_mul_f32 v[20:21], v[20:21], v[36:37]
	v_pk_mul_f32 v[22:23], v[22:23], v[38:39]
	v_pk_mul_f32 v[24:25], v[24:25], v[40:41]
	v_pk_mul_f32 v[26:27], v[26:27], v[42:43]
	v_pk_mul_f32 v[28:29], v[28:29], v[44:45]
	v_pk_mul_f32 v[30:31], v[30:31], v[46:47]
	v_pk_mul_f32 v[16:17], v[16:17], v[48:49]
	v_pk_mul_f32 v[18:19], v[18:19], v[50:51]
	v_pk_mul_f32 v[20:21], v[20:21], v[52:53]
	v_pk_mul_f32 v[22:23], v[22:23], v[54:55]
	v_pk_mul_f32 v[24:25], v[24:25], v[56:57]
	v_pk_mul_f32 v[26:27], v[26:27], v[58:59]
	v_pk_mul_f32 v[28:29], v[28:29], v[60:61]
	v_pk_mul_f32 v[30:31], v[30:31], v[62:63]
	v_fma_f32 v250, v15, v250, v31
	v_mul_f32_e32 v232, v232, v15
	v_fma_f32 v250, v14, v250, v30
	v_mul_f32_e32 v232, v232, v14
	v_fma_f32 v250, v13, v250, v29
	v_mul_f32_e32 v232, v232, v13
	v_fma_f32 v250, v12, v250, v28
	v_mul_f32_e32 v232, v232, v12
	v_fma_f32 v250, v11, v250, v27
	v_mul_f32_e32 v232, v232, v11
	v_fma_f32 v250, v10, v250, v26
	v_mul_f32_e32 v232, v232, v10
	v_fma_f32 v250, v9, v250, v25
	v_mul_f32_e32 v232, v232, v9
	v_fma_f32 v250, v8, v250, v24
	v_mul_f32_e32 v232, v232, v8
	v_fma_f32 v250, v7, v250, v23
	v_mul_f32_e32 v232, v232, v7
	v_fma_f32 v250, v6, v250, v22
	v_mul_f32_e32 v232, v232, v6
	v_fma_f32 v250, v5, v250, v21
	v_mul_f32_e32 v232, v232, v5
	v_fma_f32 v250, v4, v250, v20
	v_mul_f32_e32 v232, v232, v4
	v_fma_f32 v250, v3, v250, v19
	v_mul_f32_e32 v232, v232, v3
	v_fma_f32 v250, v2, v250, v18
	v_mul_f32_e32 v232, v232, v2
	v_fma_f32 v250, v1, v250, v17
	v_mul_f32_e32 v232, v232, v1
	v_fma_f32 v250, v0, v250, v16
	v_mul_f32_e32 v232, v232, v0
	s_add_u32 s96, s0, 0x400800
	s_addc_u32 s97, s1, 0
	s_add_u32 s96, s96, s36
	s_addc_u32 s97, s97, 0
	global_store_dword v235, v232, s[96:97]
	s_add_u32 s96, s96, 0x300000
	s_addc_u32 s97, s97, 0
	global_store_dword v235, v250, s[96:97]
	s_waitcnt lgkmcnt(0)
	v_readlane_b32 s84, v253, 29
	s_add_i32 s12, s12, s84
	s_cmpk_lt_i32 s12, 0x1000
	s_cbranch_scc1 .Lrg5_keep
	s_sub_i32 s0, s12, 0x1000
	s_lshr_b32 s1, s0, 5
	s_and_b32 s0, s0, 31
	s_and_b32 s12, s1, 7
	s_add_i32 s1, s1, 0x1000
	s_cmp_eq_u32 s0, s12
	s_cselect_b32 s12, s1, 0x2000
